# all non-DMA vector loads in the layer loop made L1-bypassing (sc1); seam L1 invalidates removed (DMA tile streams self-evict from the 32 KiB L1)
# speedup vs baseline: 1.0236x; 1.0094x over previous
.LBB0_328:
	v_readlane_b32 s4, v255, 18
	s_or_b32 s4, s96, s4
	s_cmp_eq_u32 s4, 0
	s_cselect_b64 s[12:13], -1, 0
	s_cmp_lg_u32 s4, 0
	s_cselect_b64 s[6:7], -1, 0
	s_and_b64 vcc, exec, s[12:13]
	v_readlane_b32 s5, v255, 19
	s_cbranch_vccnz .LBB0_347
	s_mov_b32 s4, 0x22170
	s_add_i32 s4, s4, 0
	v_mov_b32_e32 v0, s4
	ds_read_b32 v0, v0
	s_waitcnt lgkmcnt(0)
	v_cmp_ne_u32_e32 vcc, 0, v0
	s_cbranch_vccnz .LBB0_347
	s_mov_b64 s[4:5], s[20:21]
	s_mov_b32 s10, s33
	s_mov_b32 s11, -1
	s_nop 0
	v_mbcnt_lo_u32_b32 v0, s11, 0
	v_mbcnt_hi_u32_b32 v0, s11, v0
	v_lshl_or_b32 v0, s10, 6, v0
	s_mov_b32 s10, 0x22174
	s_add_i32 s10, s10, 0
	s_waitcnt vmcnt(0)
	v_mov_b32_e32 v2, s10
	s_add_u32 s40, s4, 0x6400000
	ds_read_b32 v2, v2
	s_addc_u32 s41, s5, 0
	s_add_u32 s24, s4, 0x6300000
	s_addc_u32 s25, s5, 0
	s_add_u32 s42, s4, 0x5000000
	s_addc_u32 s43, s5, 0
	s_waitcnt lgkmcnt(0)
	v_readfirstlane_b32 s10, v2
	s_add_u32 s26, s4, 0x6000000
	s_addc_u32 s37, s5, 0
	s_lshl_b32 s4, s10, 3
	s_and_b32 s4, s4, 56
	s_bfe_u32 s5, s10, 0x30003
	s_or_b32 s4, s4, s5
	v_readfirstlane_b32 s5, v0
	s_ashr_i32 s5, s5, 3
	s_andn2_b32 s10, s10, 63
	s_and_b32 s5, s5, -8
	s_lshl_b32 s4, s4, 8
	s_add_i32 s5, s5, s10
	s_add_i32 s94, s5, s4
	s_ashr_i32 s95, s94, 31
	s_lshl_b64 s[4:5], s[94:95], 11
	v_and_b32_e32 v0, 63, v0
	s_add_u32 s4, s40, s4
	s_addc_u32 s5, s41, s5
	v_lshlrev_b32_e32 v10, 3, v0
	global_load_dwordx2 v[8:9], v10, s[4:5] sc1
	global_load_dwordx2 v[6:7], v10, s[4:5] offset:512 sc1
	global_load_dwordx2 v[4:5], v10, s[4:5] offset:1024 sc1
	global_load_dwordx2 v[2:3], v10, s[4:5] offset:1536 sc1
	s_or_b32 s58, s94, 1
	s_ashr_i32 s59, s58, 31
	s_lshl_b64 s[4:5], s[58:59], 11
	s_add_u32 s4, s40, s4
	s_addc_u32 s5, s41, s5
	s_or_b32 s50, s94, 2
	s_ashr_i32 s51, s50, 31
	global_load_dwordx2 v[184:185], v10, s[4:5] sc1
	global_load_dwordx2 v[182:183], v10, s[4:5] offset:512 sc1
	global_load_dwordx2 v[180:181], v10, s[4:5] offset:1024 sc1
	global_load_dwordx2 v[178:179], v10, s[4:5] offset:1536 sc1
	s_lshl_b64 s[4:5], s[50:51], 11
	s_add_u32 s4, s40, s4
	s_addc_u32 s5, s41, s5
	s_or_b32 s48, s94, 3
	s_ashr_i32 s49, s48, 31
	global_load_dwordx2 v[176:177], v10, s[4:5] sc1
	global_load_dwordx2 v[174:175], v10, s[4:5] offset:512 sc1
	global_load_dwordx2 v[172:173], v10, s[4:5] offset:1024 sc1
	global_load_dwordx2 v[170:171], v10, s[4:5] offset:1536 sc1
	s_lshl_b64 s[4:5], s[48:49], 11
	s_add_u32 s4, s40, s4
	s_addc_u32 s5, s41, s5
	s_or_b32 s22, s94, 4
	s_ashr_i32 s23, s22, 31
	global_load_dwordx2 v[168:169], v10, s[4:5] sc1
	global_load_dwordx2 v[166:167], v10, s[4:5] offset:512 sc1
	global_load_dwordx2 v[164:165], v10, s[4:5] offset:1024 sc1
	global_load_dwordx2 v[162:163], v10, s[4:5] offset:1536 sc1
	s_lshl_b64 s[4:5], s[22:23], 11
	s_add_u32 s4, s40, s4
	s_addc_u32 s5, s41, s5
	s_or_b32 s16, s94, 5
	s_ashr_i32 s17, s16, 31
	global_load_dwordx2 v[160:161], v10, s[4:5] sc1
	global_load_dwordx2 v[158:159], v10, s[4:5] offset:512 sc1
	global_load_dwordx2 v[156:157], v10, s[4:5] offset:1024 sc1
	global_load_dwordx2 v[154:155], v10, s[4:5] offset:1536 sc1
	s_lshl_b64 s[4:5], s[16:17], 11
	s_add_u32 s4, s40, s4
	s_addc_u32 s5, s41, s5
	s_or_b32 s14, s94, 6
	s_ashr_i32 s15, s14, 31
	global_load_dwordx2 v[152:153], v10, s[4:5] sc1
	global_load_dwordx2 v[150:151], v10, s[4:5] offset:512 sc1
	global_load_dwordx2 v[148:149], v10, s[4:5] offset:1024 sc1
	global_load_dwordx2 v[146:147], v10, s[4:5] offset:1536 sc1
	s_lshl_b64 s[4:5], s[14:15], 11
	s_add_u32 s4, s40, s4
	s_addc_u32 s5, s41, s5
	s_or_b32 s10, s94, 7
	s_ashr_i32 s11, s10, 31
	global_load_dwordx2 v[144:145], v10, s[4:5] sc1
	global_load_dwordx2 v[142:143], v10, s[4:5] offset:512 sc1
	global_load_dwordx2 v[140:141], v10, s[4:5] offset:1024 sc1
	global_load_dwordx2 v[138:139], v10, s[4:5] offset:1536 sc1
	s_lshl_b64 s[4:5], s[10:11], 11
	s_add_u32 s4, s40, s4
	s_addc_u32 s5, s41, s5
	global_load_dwordx2 v[136:137], v10, s[4:5] sc1
	global_load_dwordx2 v[134:135], v10, s[4:5] offset:512 sc1
	global_load_dwordx2 v[132:133], v10, s[4:5] offset:1024 sc1
	global_load_dwordx2 v[130:131], v10, s[4:5] offset:1536 sc1
	s_lshl_b64 s[4:5], s[94:95], 6
	s_add_u32 s4, s24, s4
	s_addc_u32 s5, s25, s5
	global_load_dwordx4 v[114:117], v1, s[4:5] offset:48 sc1
	global_load_dwordx4 v[122:125], v1, s[4:5] offset:32 sc1
	global_load_dwordx4 v[118:121], v1, s[4:5] offset:16 sc1
	global_load_dwordx4 v[126:129], v1, s[4:5] sc1
	s_lshl_b64 s[4:5], s[58:59], 6
	s_add_u32 s4, s24, s4
	s_addc_u32 s5, s25, s5
	global_load_dwordx4 v[98:101], v1, s[4:5] offset:48 sc1
	global_load_dwordx4 v[102:105], v1, s[4:5] offset:32 sc1
	global_load_dwordx4 v[106:109], v1, s[4:5] offset:16 sc1
	global_load_dwordx4 v[110:113], v1, s[4:5] sc1
	s_lshl_b64 s[4:5], s[50:51], 6
	s_add_u32 s4, s24, s4
	s_addc_u32 s5, s25, s5
	global_load_dwordx4 v[82:85], v1, s[4:5] offset:48 sc1
	global_load_dwordx4 v[86:89], v1, s[4:5] offset:32 sc1
	global_load_dwordx4 v[90:93], v1, s[4:5] offset:16 sc1
	global_load_dwordx4 v[94:97], v1, s[4:5] sc1
	s_lshl_b64 s[4:5], s[48:49], 6
	s_add_u32 s4, s24, s4
	s_addc_u32 s5, s25, s5
	global_load_dwordx4 v[66:69], v1, s[4:5] offset:48 sc1
	global_load_dwordx4 v[70:73], v1, s[4:5] offset:32 sc1
	global_load_dwordx4 v[74:77], v1, s[4:5] offset:16 sc1
	global_load_dwordx4 v[78:81], v1, s[4:5] sc1
	s_lshl_b64 s[4:5], s[22:23], 6
	s_add_u32 s4, s24, s4
	s_addc_u32 s5, s25, s5
	global_load_dwordx4 v[50:53], v1, s[4:5] offset:48 sc1
	global_load_dwordx4 v[54:57], v1, s[4:5] offset:32 sc1
	global_load_dwordx4 v[58:61], v1, s[4:5] offset:16 sc1
	global_load_dwordx4 v[62:65], v1, s[4:5] sc1
	s_lshl_b64 s[4:5], s[16:17], 6
	s_add_u32 s4, s24, s4
	s_addc_u32 s5, s25, s5
	global_load_dwordx4 v[34:37], v1, s[4:5] offset:48 sc1
	global_load_dwordx4 v[38:41], v1, s[4:5] offset:32 sc1
	global_load_dwordx4 v[42:45], v1, s[4:5] offset:16 sc1
	global_load_dwordx4 v[46:49], v1, s[4:5] sc1
	s_lshl_b64 s[4:5], s[14:15], 6
	s_add_u32 s4, s24, s4
	s_addc_u32 s5, s25, s5
	global_load_dwordx4 v[18:21], v1, s[4:5] offset:48 sc1
	global_load_dwordx4 v[22:25], v1, s[4:5] offset:32 sc1
	global_load_dwordx4 v[26:29], v1, s[4:5] offset:16 sc1
	global_load_dwordx4 v[30:33], v1, s[4:5] sc1
	s_lshl_b64 s[4:5], s[10:11], 6
	s_add_u32 s4, s24, s4
	s_addc_u32 s5, s25, s5
	s_lshl_b64 s[24:25], s[94:95], 10
	s_waitcnt vmcnt(59)
	v_lshlrev_b32_e32 v187, 16, v8
	v_and_b32_e32 v188, 0xffff0000, v8
	v_lshlrev_b32_e32 v189, 16, v9
	v_and_b32_e32 v190, 0xffff0000, v9
	v_max_f32_e64 v8, |v188|, |v188|
	v_max_f32_e64 v9, |v187|, |v187|
	v_max_f32_e32 v8, v9, v8
	v_max_f32_e64 v9, |v190|, |v190|
	v_max_f32_e64 v10, |v189|, |v189|
	s_waitcnt vmcnt(58)
	v_lshlrev_b32_e32 v191, 16, v6
	v_and_b32_e32 v192, 0xffff0000, v6
	v_max_f32_e32 v9, v10, v9
	v_lshlrev_b32_e32 v193, 16, v7
	v_and_b32_e32 v194, 0xffff0000, v7
	v_max_f32_e64 v6, |v192|, |v192|
	v_max_f32_e64 v7, |v191|, |v191|
	v_max3_f32 v8, v8, 0, v9
	v_max_f32_e32 v6, v7, v6
	v_max_f32_e64 v7, |v194|, |v194|
	v_max_f32_e64 v9, |v193|, |v193|
	s_waitcnt vmcnt(57)
	v_lshlrev_b32_e32 v195, 16, v4
	v_and_b32_e32 v196, 0xffff0000, v4
	v_max_f32_e32 v7, v9, v7
	v_lshlrev_b32_e32 v197, 16, v5
	v_and_b32_e32 v198, 0xffff0000, v5
	v_max_f32_e64 v4, |v196|, |v196|
	v_max_f32_e64 v5, |v195|, |v195|
	v_max3_f32 v6, v8, v6, v7
	v_max_f32_e32 v4, v5, v4
	v_max_f32_e64 v5, |v198|, |v198|
	v_max_f32_e64 v7, |v197|, |v197|
	s_waitcnt vmcnt(56)
	v_lshlrev_b32_e32 v199, 16, v2
	v_and_b32_e32 v200, 0xffff0000, v2
	v_max_f32_e32 v5, v7, v5
	v_lshlrev_b32_e32 v201, 16, v3
	v_and_b32_e32 v202, 0xffff0000, v3
	v_max_f32_e64 v2, |v200|, |v200|
	v_max_f32_e64 v3, |v199|, |v199|
	v_max3_f32 v4, v6, v4, v5
	v_max_f32_e32 v2, v3, v2
	v_max_f32_e64 v3, |v202|, |v202|
	v_max_f32_e64 v5, |v201|, |v201|
	v_max_f32_e32 v3, v5, v3
	v_max3_f32 v2, v4, v2, v3
	ds_swizzle_b32 v3, v2 offset:swizzle(SWAP,1)
	s_waitcnt lgkmcnt(0)
	v_max_f32_e32 v3, v3, v3
	v_max_f32_e32 v2, v2, v3
	ds_swizzle_b32 v3, v2 offset:swizzle(SWAP,2)
	s_waitcnt lgkmcnt(0)
	v_max_f32_e32 v3, v3, v3
	v_max_f32_e32 v2, v2, v3
	ds_swizzle_b32 v3, v2 offset:swizzle(SWAP,4)
	s_waitcnt lgkmcnt(0)
	v_max_f32_e32 v3, v3, v3
	v_max_f32_e32 v10, v2, v3
	ds_swizzle_b32 v11, v10 offset:swizzle(SWAP,8)
	global_load_dwordx4 v[2:5], v1, s[4:5] offset:48 sc1
	global_load_dwordx4 v[6:9], v1, s[4:5] offset:32 sc1
	s_waitcnt lgkmcnt(0)
	v_max_f32_e32 v11, v11, v11
	v_max_f32_e32 v186, v10, v11
	global_load_dwordx4 v[10:13], v1, s[4:5] offset:16 sc1
	global_load_dwordx4 v[14:17], v1, s[4:5] sc1
	ds_swizzle_b32 v203, v186 offset:swizzle(SWAP,16)
	v_cmp_eq_u32_e64 s[4:5], 0, v0
	v_lshlrev_b32_e32 v0, 2, v0
	s_waitcnt lgkmcnt(0)
	v_max_f32_e32 v203, v203, v203
	v_max_f32_e32 v186, v186, v203
	v_mov_b32_e32 v203, v186
	s_nop 1
	v_permlane32_swap_b32_e32 v186, v203
	v_max_f32_e32 v203, v203, v203
	v_max_f32_e32 v186, v186, v186
	v_max_f32_e32 v186, v186, v203
	v_div_scale_f32 v203, s[40:41], v186, v186, s34
	v_rcp_f32_e32 v204, v203
	s_add_u32 s40, s42, s24
	s_addc_u32 s41, s43, s25
	v_fma_f32 v205, -v203, v204, 1.0
	v_fmac_f32_e32 v204, v205, v204
	v_div_scale_f32 v205, vcc, s34, v186, s34
	v_mul_f32_e32 v206, v205, v204
	v_fma_f32 v207, -v203, v206, v205
	v_fmac_f32_e32 v206, v207, v204
	v_fma_f32 v203, -v203, v206, v205
	v_div_fmas_f32 v203, v203, v204, v206
	v_div_fixup_f32 v203, v203, v186, s34
	v_cmp_lt_f32_e32 vcc, 0, v186
	s_nop 1
	v_cndmask_b32_e32 v203, 0, v203, vcc
	v_mul_f32_e32 v188, v203, v188
	v_mul_f32_e32 v187, v203, v187
	v_mul_f32_e32 v189, v203, v189
	v_mul_f32_e32 v190, v203, v190
	v_rndne_f32_e32 v188, v188
	v_rndne_f32_e32 v187, v187
	v_cvt_i32_f32_e32 v188, v188
	v_rndne_f32_e32 v189, v189
	v_rndne_f32_e32 v190, v190
	v_cvt_i32_f32_e32 v187, v187
	v_cvt_i32_f32_sdwa v189, v189 dst_sel:WORD_1 dst_unused:UNUSED_PAD src0_sel:DWORD
	v_cvt_i32_f32_e32 v190, v190
	v_lshlrev_b32_e32 v188, 8, v188
	v_and_b32_e32 v188, 0xff00, v188
	v_and_b32_e32 v189, 0xff0000, v189
	v_perm_b32 v187, v190, v187, s35
	v_or3_b32 v187, v187, v188, v189
	v_mul_f32_e32 v188, v203, v192
	global_store_dword v0, v187, s[40:41]
	v_mul_f32_e32 v187, v203, v191
	v_mul_f32_e32 v189, v203, v193
	v_mul_f32_e32 v190, v203, v194
	v_rndne_f32_e32 v188, v188
	v_rndne_f32_e32 v187, v187
	v_cvt_i32_f32_e32 v188, v188
	v_rndne_f32_e32 v189, v189
	v_rndne_f32_e32 v190, v190
	v_cvt_i32_f32_e32 v187, v187
	v_cvt_i32_f32_sdwa v189, v189 dst_sel:WORD_1 dst_unused:UNUSED_PAD src0_sel:DWORD
	v_cvt_i32_f32_e32 v190, v190
	v_lshlrev_b32_e32 v188, 8, v188
	v_and_b32_e32 v188, 0xff00, v188
	v_and_b32_e32 v189, 0xff0000, v189
	v_perm_b32 v187, v190, v187, s35
	v_or3_b32 v187, v187, v188, v189
	v_mul_f32_e32 v188, v203, v196
	global_store_dword v0, v187, s[40:41] offset:256
	v_mul_f32_e32 v187, v203, v195
	v_mul_f32_e32 v189, v203, v197
	v_mul_f32_e32 v190, v203, v198
	v_rndne_f32_e32 v188, v188
	v_rndne_f32_e32 v187, v187
	v_cvt_i32_f32_e32 v188, v188
	v_rndne_f32_e32 v189, v189
	v_rndne_f32_e32 v190, v190
	v_cvt_i32_f32_e32 v187, v187
	v_cvt_i32_f32_sdwa v189, v189 dst_sel:WORD_1 dst_unused:UNUSED_PAD src0_sel:DWORD
	v_cvt_i32_f32_e32 v190, v190
	v_lshlrev_b32_e32 v188, 8, v188
	v_and_b32_e32 v188, 0xff00, v188
	v_and_b32_e32 v189, 0xff0000, v189
	v_perm_b32 v187, v190, v187, s35
	v_or3_b32 v187, v187, v188, v189
	v_mul_f32_e32 v188, v203, v200
	global_store_dword v0, v187, s[40:41] offset:512
	v_mul_f32_e32 v187, v203, v199
	v_mul_f32_e32 v189, v203, v201
	v_mul_f32_e32 v190, v203, v202
	v_rndne_f32_e32 v188, v188
	v_rndne_f32_e32 v187, v187
	v_cvt_i32_f32_e32 v188, v188
	v_rndne_f32_e32 v189, v189
	v_rndne_f32_e32 v190, v190
	v_cvt_i32_f32_e32 v187, v187
	v_cvt_i32_f32_sdwa v189, v189 dst_sel:WORD_1 dst_unused:UNUSED_PAD src0_sel:DWORD
	v_cvt_i32_f32_e32 v190, v190
	v_lshlrev_b32_e32 v188, 8, v188
	v_and_b32_e32 v188, 0xff00, v188
	v_and_b32_e32 v189, 0xff0000, v189
	v_perm_b32 v187, v190, v187, s35
	v_or3_b32 v187, v187, v188, v189
	global_store_dword v0, v187, s[40:41] offset:768
	s_and_saveexec_b64 s[24:25], s[4:5]
	s_cbranch_execz .LBB0_332
	s_waitcnt vmcnt(32)
	v_mov_b32_e32 v188, v126
	v_mov_b32_e32 v189, v122
	v_mov_b32_e32 v122, v127
	v_mov_b32_e32 v126, v128
	v_mov_b32_e32 v127, v124
	v_mov_b32_e32 v124, v129
	v_pk_add_f32 v[122:123], v[188:189], v[122:123]
	v_pk_add_f32 v[124:125], v[126:127], v[124:125]
	s_lshl_b64 s[40:41], s[94:95], 2
	v_pk_add_f32 v[122:123], v[122:123], v[124:125]
	v_mov_b32_e32 v124, v118
	v_mov_b32_e32 v125, v114
	v_mov_b32_e32 v114, v119
	v_mov_b32_e32 v118, v120
	v_mov_b32_e32 v119, v116
	v_mov_b32_e32 v116, v121
	v_pk_add_f32 v[114:115], v[124:125], v[114:115]
	v_pk_add_f32 v[116:117], v[118:119], v[116:117]
	s_add_u32 s40, s26, s40
	v_pk_add_f32 v[114:115], v[114:115], v[116:117]
	s_addc_u32 s41, s37, s41
	v_pk_add_f32 v[114:115], v[122:123], v[114:115]
	s_nop 0
	v_add_f32_e32 v114, v114, v115
	v_fmamk_f32 v114, v114, 0x3a800000, v231
	v_rsq_f32_e32 v114, v114
	v_mul_f32_e32 v115, 0x3c010204, v186
	v_mul_f32_e32 v114, v114, v115
	global_store_dword v1, v114, s[40:41]

.LBB0_355:
	s_or_b64 exec, exec, s[40:41]
	s_waitcnt vmcnt(0)
	v_readfirstlane_b32 s4, v2
	s_nop 1
	v_add_u32_e32 v0, s4, v0
	v_and_b32_e32 v2, -4, v0
	v_and_b32_e32 v0, 3, v0
	v_cmp_eq_u32_e64 s[4:5], 3, v0
	v_add_u32_e32 v2, 4, v2
	s_and_b64 s[4:5], s[4:5], exec

.LBB0_436:
	s_mov_b32 s4, s33
	s_mov_b32 s5, -1
	s_andn2_b64 vcc, exec, s[14:15]
	v_mbcnt_lo_u32_b32 v0, s5, 0
	v_mbcnt_hi_u32_b32 v0, s5, v0
	v_lshl_or_b32 v0, s4, 6, v0
	s_nop 0
	v_readfirstlane_b32 s14, v0
	s_cbranch_vccnz .LBB0_454
	s_waitcnt vmcnt(0)
	v_ashrrev_i32_e32 v2, 31, v0
	v_lshrrev_b32_e32 v2, 26, v2
	v_add_u32_e32 v2, v0, v2
	v_ashrrev_i32_e32 v4, 6, v2
	v_bfe_i32 v2, v0, 27, 1
	v_lshlrev_b32_e32 v5, 4, v0
	v_lshrrev_b32_e32 v2, 22, v2
	v_add_u32_e32 v2, v5, v2
	v_and_b32_e32 v2, 0xfffffc00, v2
	v_sub_u32_e32 v2, v5, v2
	v_lshrrev_b32_e32 v3, 4, v2
	v_bitop3_b32 v6, v3, v2, 32 bitop3:0x6c
	v_lshlrev_b32_e32 v2, 3, v4
	v_and_b32_e32 v3, -16, v2
	v_ashrrev_i32_e32 v2, 31, v6
	v_lshrrev_b32_e32 v2, 26, v2
	v_add_u32_e32 v7, v6, v2
	v_ashrrev_i32_e32 v2, 6, v7
	v_and_b32_e32 v7, 0xc0, v7
	s_add_u32 s4, s10, 0x6000000
	v_sub_u32_e32 v6, v6, v7
	s_addc_u32 s5, s11, 0
	s_ashr_i32 s15, s14, 6
	v_lshlrev_b32_e32 v4, 5, v4
	v_ashrrev_i16_sdwa v6, v230, sext(v6) dst_sel:DWORD dst_unused:UNUSED_PAD src0_sel:DWORD src1_sel:BYTE_0
	s_ashr_i32 s16, s14, 8
	v_and_b32_e32 v4, 32, v4
	v_bfe_i32 v6, v6, 0, 16
	v_add_u32_e32 v5, 0x2000, v5
	s_lshl_b32 s40, s15, 10
	s_lshl_b32 s41, s16, 6
	v_add_lshl_u32 v4, v4, v6, 1
	v_ashrrev_i32_e32 v6, 31, v5
	s_add_u32 s42, s10, 0x5000000
	v_lshrrev_b32_e32 v6, 22, v6
	s_addc_u32 s43, s11, 0
	s_and_b32 s58, s37, 7
	v_add_u32_e32 v6, v5, v6
	s_lshr_b32 s6, s37, 3
	s_mulk_i32 s58, 0xb0
	v_ashrrev_i32_e32 v7, 10, v6
	s_add_i32 s6, s58, s6
	v_mul_i32_i24_e32 v6, 0x400, v7
	s_and_b32 s7, s6, 0xffff
	v_sub_u32_e32 v5, v5, v6
	s_mul_i32 s7, s7, 0xba2f
	v_lshrrev_b32_e32 v6, 4, v5
	s_lshr_b32 s7, s7, 23
	v_bitop3_b32 v8, v6, v5, 32 bitop3:0x6c
	v_lshlrev_b32_e32 v5, 3, v7
	s_lshl_b32 s22, s7, 3
	s_mulk_i32 s7, 0xb0
	v_and_b32_e32 v6, -16, v5
	v_ashrrev_i32_e32 v5, 31, v8
	s_sub_i32 s6, s6, s7
	v_lshrrev_b32_e32 v5, 26, v5
	s_and_b32 s17, s6, 0xffff
	s_and_b32 s6, s6, 7
	v_add_u32_e32 v9, v8, v5
	s_or_b32 s71, s6, s22
	v_ashrrev_i32_e32 v5, 6, v9
	v_and_b32_e32 v9, 0xc0, v9
	s_lshl_b32 s6, s71, 18
	v_sub_u32_e32 v8, v8, v9
	s_add_u32 s46, s42, s6
	v_lshlrev_b32_e32 v7, 5, v7
	v_ashrrev_i16_sdwa v8, v230, sext(v8) dst_sel:DWORD dst_unused:UNUSED_PAD src0_sel:DWORD src1_sel:BYTE_0
	s_addc_u32 s47, s43, 0
	s_lshl_b32 s6, s71, 8
	v_and_b32_e32 v7, 32, v7
	v_bfe_i32 v8, v8, 0, 16
	v_and_b32_e32 v134, 15, v0
	s_add_i32 s6, s41, s6
	v_add_lshl_u32 v7, v7, v8, 1
	v_or_b32_e32 v8, s6, v134
	v_add_u32_e32 v3, v2, v3
	v_ashrrev_i32_e32 v9, 31, v8
	v_lshl_add_u32 v132, v3, 10, v4
	v_lshl_add_u64 v[8:9], v[8:9], 2, s[4:5]
	v_add_u32_e32 v6, v5, v6
	global_load_dword v135, v[8:9], off sc1
	global_load_dword v136, v[8:9], off offset:64 sc1
	global_load_dword v137, v[8:9], off offset:128 sc1
	global_load_dword v138, v[8:9], off offset:192 sc1
	global_load_dword v139, v[8:9], off offset:512 sc1
	global_load_dword v140, v[8:9], off offset:576 sc1
	global_load_dword v141, v[8:9], off offset:640 sc1
	global_load_dword v142, v[8:9], off offset:704 sc1
	s_add_i32 s59, s40, 0
	v_mov_b32_e32 v8, v132
	v_lshl_add_u32 v133, v6, 10, v7
	s_mov_b32 m0, s59
	s_add_i32 s60, s59, 0x2000
	global_load_lds_dwordx4 v8, s[46:47]
	v_mov_b32_e32 v8, v133
	s_mov_b32 m0, s60
	s_add_u32 s6, s46, 0x20000
	global_load_lds_dwordx4 v8, s[46:47]
	s_addc_u32 s7, s47, 0
	s_add_i32 s61, s59, 0x4000
	v_mov_b32_e32 v8, v132
	s_mov_b32 m0, s61
	s_add_i32 s66, s59, 0x6000
	global_load_lds_dwordx4 v8, s[6:7]
	v_mov_b32_e32 v8, v133
	s_mov_b32 m0, s66
	s_cmp_eq_u32 s16, 1
	global_load_lds_dwordx4 v8, s[6:7]
	s_cselect_b64 s[6:7], -1, 0
	s_cmp_lg_u32 s16, 1
	s_cbranch_scc1 .LBB0_439
	s_barrier

.Lpeel_exit_445:
.LBB0_448:
	v_mov_b32_e32 v0, v145
	v_mov_b32_e32 v130, v134
	s_lshl_b32 s25, s24, 7
	s_or_b32 s25, s25, s74
	s_mul_i32 s46, s71, 0x180000
	v_add_u32_e32 v149, s41, v130
	v_lshl_add_u32 v130, v0, 3, s25
	s_mul_hi_i32 s25, s71, 0x180000
	s_add_u32 s46, s67, s46
	s_addc_u32 s47, s68, s25
	s_lshl_b32 s24, s24, 3
	s_or_b32 s24, s24, s70
	s_ashr_i32 s25, s24, 31
	s_lshl_b64 s[24:25], s[24:25], 2
	s_add_u32 s24, s26, s24
	s_addc_u32 s25, s69, s25
	global_load_dword v150, v1, s[24:25] sc1
	global_load_dword v151, v1, s[24:25] offset:16 sc1
	v_cvt_f32_i32_e32 v127, v127
	v_cvt_f32_i32_e32 v126, v126
	v_cvt_f32_i32_e32 v129, v129
	v_cvt_f32_i32_e32 v128, v128
	v_cvt_f32_i32_e32 v123, v123
	v_cvt_f32_i32_e32 v122, v122
	v_cvt_f32_i32_e32 v125, v125
	v_cvt_f32_i32_e32 v124, v124
	v_cvt_f32_i32_e32 v119, v119
	v_cvt_f32_i32_e32 v118, v118
	v_cvt_f32_i32_e32 v121, v121
	v_cvt_f32_i32_e32 v120, v120
	v_cvt_f32_i32_e32 v117, v117
	v_cvt_f32_i32_e32 v116, v116
	v_cvt_f32_i32_e32 v115, v115
	v_cvt_f32_i32_e32 v114, v114
	v_ashrrev_i32_e32 v131, 31, v130
	v_lshl_add_u64 v[130:131], v[130:131], 1, s[46:47]
	v_cvt_f32_i32_e32 v105, v105
	v_cvt_f32_i32_e32 v104, v104
	v_cvt_f32_i32_e32 v103, v103
	v_cvt_f32_i32_e32 v102, v102
	v_cvt_f32_i32_e32 v101, v101
	v_cvt_f32_i32_e32 v100, v100
	v_cvt_f32_i32_e32 v99, v99
	v_cvt_f32_i32_e32 v98, v98
	v_cvt_f32_i32_e32 v107, v107
	v_cvt_f32_i32_e32 v106, v106
	v_cvt_f32_i32_e32 v109, v109
	v_cvt_f32_i32_e32 v108, v108
	v_cvt_f32_i32_e32 v95, v95
	v_cvt_f32_i32_e32 v94, v94
	v_cvt_f32_i32_e32 v97, v97
	v_cvt_f32_i32_e32 v96, v96
	v_cvt_f32_i32_e32 v91, v91
	v_cvt_f32_i32_e32 v90, v90
	v_cvt_f32_i32_e32 v93, v93
	v_cvt_f32_i32_e32 v92, v92
	v_cvt_f32_i32_e32 v87, v87
	v_cvt_f32_i32_e32 v86, v86
	v_cvt_f32_i32_e32 v89, v89
	v_cvt_f32_i32_e32 v88, v88
	v_cvt_f32_i32_e32 v79, v79
	v_cvt_f32_i32_e32 v78, v78
	v_cvt_f32_i32_e32 v81, v81
	v_cvt_f32_i32_e32 v80, v80
	v_cvt_f32_i32_e32 v75, v75
	v_cvt_f32_i32_e32 v74, v74
	v_cvt_f32_i32_e32 v77, v77
	v_cvt_f32_i32_e32 v76, v76
	v_cvt_f32_i32_e32 v85, v85
	v_cvt_f32_i32_e32 v84, v84
	v_cvt_f32_i32_e32 v83, v83
	v_cvt_f32_i32_e32 v82, v82
	v_cvt_f32_i32_e32 v71, v71
	v_cvt_f32_i32_e32 v70, v70
	v_cvt_f32_i32_e32 v73, v73
	v_cvt_f32_i32_e32 v72, v72
	v_cvt_f32_i32_e32 v63, v63
	v_cvt_f32_i32_e32 v62, v62
	v_cvt_f32_i32_e32 v65, v65
	v_cvt_f32_i32_e32 v64, v64
	v_cvt_f32_i32_e32 v59, v59
	v_cvt_f32_i32_e32 v58, v58
	v_cvt_f32_i32_e32 v61, v61
	v_cvt_f32_i32_e32 v60, v60
	v_cvt_f32_i32_e32 v69, v69
	v_cvt_f32_i32_e32 v68, v68
	v_cvt_f32_i32_e32 v67, v67
	v_cvt_f32_i32_e32 v66, v66
	v_cvt_f32_i32_e32 v55, v55
	v_cvt_f32_i32_e32 v54, v54
	v_cvt_f32_i32_e32 v57, v57
	v_cvt_f32_i32_e32 v56, v56
	v_cvt_f32_i32_e32 v47, v47
	v_cvt_f32_i32_e32 v46, v46
	v_cvt_f32_i32_e32 v49, v49
	v_cvt_f32_i32_e32 v48, v48
	s_and_b64 vcc, exec, s[10:11]
	s_cbranch_vccz .Lepi_lead_448
	s_barrier
.Lepi_lead_448:
	s_waitcnt vmcnt(0)
	v_mul_f32_e32 v0, v135, v150
	v_pk_mul_f32 v[126:127], v[0:1], v[126:127] op_sel_hi:[0,1]
	v_pk_mul_f32 v[128:129], v[0:1], v[128:129] op_sel_hi:[0,1]
	v_pk_mul_f32 v[124:125], v[0:1], v[124:125] op_sel_hi:[0,1]
	v_pk_mul_f32 v[122:123], v[0:1], v[122:123] op_sel_hi:[0,1]
	v_mul_f32_e32 v0, 0xbfb8aa3b, v126
	v_exp_f32_e32 v0, v0
	v_mul_f32_e32 v152, v135, v151
	v_pk_mul_f32 v[118:119], v[152:153], v[118:119] op_sel_hi:[0,1]
	v_pk_mul_f32 v[120:121], v[152:153], v[120:121] op_sel_hi:[0,1]
	v_add_f32_e32 v0, 1.0, v0
	v_rcp_f32_e32 v154, v0
	v_mul_f32_e32 v0, 0xbfb8aa3b, v127
	v_exp_f32_e32 v0, v0
	v_pk_mul_f32 v[114:115], v[152:153], v[114:115] op_sel_hi:[0,1]
	v_pk_mul_f32 v[116:117], v[152:153], v[116:117] op_sel_hi:[0,1]
	v_mad_i64_i32 v[152:153], s[24:25], v149, s52, v[130:131]
	v_add_f32_e32 v0, 1.0, v0
	v_rcp_f32_e32 v155, v0
	v_mul_f32_e32 v0, 0xbfb8aa3b, v128
	v_exp_f32_e32 v0, v0
	v_cvt_f32_i32_e32 v43, v43
	v_pk_mul_f32 v[126:127], v[126:127], v[154:155]
	v_cvt_f32_i32_e32 v42, v42
	v_add_f32_e32 v0, 1.0, v0
	v_rcp_f32_e32 v156, v0
	v_mul_f32_e32 v0, 0xbfb8aa3b, v129
	v_exp_f32_e32 v0, v0
	v_pk_mul_f32 v[118:119], v[118:119], v[126:127]
	v_cvt_f32_i32_e32 v45, v45
	v_cvt_f32_i32_e32 v44, v44
	v_add_f32_e32 v0, 1.0, v0
	v_rcp_f32_e32 v157, v0
	v_mul_f32_e32 v0, 0xbfb8aa3b, v122
	v_exp_f32_e32 v0, v0
	v_cvt_f32_i32_e32 v53, v53
	v_pk_mul_f32 v[128:129], v[128:129], v[156:157]
	v_cvt_f32_i32_e32 v52, v52
	v_add_f32_e32 v0, 1.0, v0
	v_rcp_f32_e32 v126, v0
	v_mul_f32_e32 v0, 0xbfb8aa3b, v123
	v_exp_f32_e32 v0, v0
	v_pk_mul_f32 v[120:121], v[120:121], v[128:129]
	v_cvt_f32_i32_e32 v51, v51
	v_cvt_f32_i32_e32 v50, v50
	v_add_f32_e32 v0, 1.0, v0
	v_rcp_f32_e32 v127, v0
	v_mul_f32_e32 v0, 0xbfb8aa3b, v124
	v_exp_f32_e32 v0, v0
	v_cvt_f32_i32_e32 v39, v39
	v_pk_mul_f32 v[122:123], v[122:123], v[126:127]
	v_cvt_f32_i32_e32 v38, v38
	v_add_f32_e32 v0, 1.0, v0
	v_rcp_f32_e32 v128, v0
	v_mul_f32_e32 v0, 0xbfb8aa3b, v125
	v_exp_f32_e32 v0, v0
	v_cvt_f32_i32_e32 v41, v41
	v_cvt_f32_i32_e32 v40, v40
	v_cvt_f32_i32_e32 v31, v31
	v_add_f32_e32 v0, 1.0, v0
	v_rcp_f32_e32 v129, v0
	v_mul_f32_e32 v0, v136, v151
	v_pk_mul_f32 v[102:103], v[0:1], v[102:103] op_sel_hi:[0,1]
	v_pk_mul_f32 v[104:105], v[0:1], v[104:105] op_sel_hi:[0,1]
	v_pk_mul_f32 v[124:125], v[124:125], v[128:129]
	v_pk_mul_f32 v[98:99], v[0:1], v[98:99] op_sel_hi:[0,1]
	v_pk_mul_f32 v[124:125], v[116:117], v[124:125]
	v_pk_mul_f32 v[116:117], v[114:115], v[122:123]
	v_cvt_pk_bf16_f32 v114, v118, v119
	v_cvt_pk_bf16_f32 v115, v120, v121
	v_pk_mul_f32 v[100:101], v[0:1], v[100:101] op_sel_hi:[0,1]
	v_cvt_pk_bf16_f32 v116, v116, v117
	v_cvt_pk_bf16_f32 v117, v124, v125
	global_store_dwordx4 v[152:153], v[114:117], off
	v_cvt_f32_i32_e32 v30, v30
	v_cvt_f32_i32_e32 v33, v33
	v_cvt_f32_i32_e32 v117, v111
	v_cvt_f32_i32_e32 v116, v110
	v_add_u32_e32 v115, 16, v149
	v_mul_f32_e32 v114, v136, v150
	v_cvt_f32_i32_e32 v111, v113
	v_cvt_f32_i32_e32 v110, v112
	v_pk_mul_f32 v[112:113], v[114:115], v[116:117] op_sel_hi:[0,1]
	v_mul_f32_e32 v0, 0xbfb8aa3b, v112
	v_exp_f32_e32 v0, v0
	v_pk_mul_f32 v[110:111], v[114:115], v[110:111] op_sel_hi:[0,1]
	v_pk_mul_f32 v[106:107], v[114:115], v[106:107] op_sel_hi:[0,1]
	v_pk_mul_f32 v[108:109], v[114:115], v[108:109] op_sel_hi:[0,1]
	v_add_f32_e32 v0, 1.0, v0
	v_rcp_f32_e32 v116, v0
	v_mul_f32_e32 v0, 0xbfb8aa3b, v113
	v_exp_f32_e32 v0, v0
	v_mad_i64_i32 v[114:115], s[24:25], v115, s52, v[130:131]
	v_cvt_f32_i32_e32 v32, v32
	v_add_f32_e32 v0, 1.0, v0
	v_rcp_f32_e32 v117, v0
	v_mul_f32_e32 v0, 0xbfb8aa3b, v110
	v_exp_f32_e32 v0, v0
	v_cvt_f32_i32_e32 v27, v27
	v_pk_mul_f32 v[112:113], v[112:113], v[116:117]
	v_cvt_f32_i32_e32 v26, v26
	v_add_f32_e32 v0, 1.0, v0
	v_rcp_f32_e32 v118, v0
	v_mul_f32_e32 v0, 0xbfb8aa3b, v111
	v_exp_f32_e32 v0, v0
	v_pk_mul_f32 v[102:103], v[102:103], v[112:113]
	v_cvt_f32_i32_e32 v29, v29
	v_cvt_f32_i32_e32 v28, v28
	v_add_f32_e32 v0, 1.0, v0
	v_rcp_f32_e32 v119, v0
	v_mul_f32_e32 v0, 0xbfb8aa3b, v106
	v_exp_f32_e32 v0, v0
	v_cvt_f32_i32_e32 v37, v37
	v_pk_mul_f32 v[110:111], v[110:111], v[118:119]
	v_cvt_f32_i32_e32 v36, v36
	v_add_f32_e32 v0, 1.0, v0
	v_pk_mul_f32 v[104:105], v[104:105], v[110:111]
	v_rcp_f32_e32 v110, v0
	v_mul_f32_e32 v0, 0xbfb8aa3b, v107
	v_exp_f32_e32 v0, v0
	v_cvt_f32_i32_e32 v35, v35
	v_cvt_f32_i32_e32 v34, v34
	v_cvt_f32_i32_e32 v23, v23
	v_add_f32_e32 v0, 1.0, v0
	v_rcp_f32_e32 v111, v0
	v_mul_f32_e32 v0, 0xbfb8aa3b, v108
	v_exp_f32_e32 v0, v0
	v_cvt_f32_i32_e32 v22, v22
	v_pk_mul_f32 v[106:107], v[106:107], v[110:111]
	v_cvt_f32_i32_e32 v25, v25
	v_add_f32_e32 v0, 1.0, v0
	v_rcp_f32_e32 v112, v0
	v_mul_f32_e32 v0, 0xbfb8aa3b, v109
	v_exp_f32_e32 v0, v0
	v_cvt_f32_i32_e32 v24, v24
	v_cvt_f32_i32_e32 v15, v15
	v_cvt_f32_i32_e32 v14, v14
	v_add_f32_e32 v0, 1.0, v0
	v_rcp_f32_e32 v113, v0
	v_mul_f32_e32 v0, v137, v150
	v_pk_mul_f32 v[94:95], v[0:1], v[94:95] op_sel_hi:[0,1]
	v_pk_mul_f32 v[96:97], v[0:1], v[96:97] op_sel_hi:[0,1]
	v_pk_mul_f32 v[92:93], v[0:1], v[92:93] op_sel_hi:[0,1]
	v_pk_mul_f32 v[90:91], v[0:1], v[90:91] op_sel_hi:[0,1]
	v_mul_f32_e32 v0, 0xbfb8aa3b, v94
	v_exp_f32_e32 v0, v0
	v_pk_mul_f32 v[108:109], v[108:109], v[112:113]
	v_cvt_f32_i32_e32 v17, v17
	v_pk_mul_f32 v[108:109], v[100:101], v[108:109]
	v_pk_mul_f32 v[100:101], v[98:99], v[106:107]
	v_cvt_pk_bf16_f32 v98, v102, v103
	v_cvt_pk_bf16_f32 v99, v104, v105
	v_add_f32_e32 v0, 1.0, v0
	v_cvt_pk_bf16_f32 v100, v100, v101
	v_cvt_pk_bf16_f32 v101, v108, v109
	global_store_dwordx4 v[114:115], v[98:101], off
	v_cvt_f32_i32_e32 v16, v16
	v_cvt_f32_i32_e32 v11, v11
	v_rcp_f32_e32 v100, v0
	v_mul_f32_e32 v0, 0xbfb8aa3b, v95
	v_exp_f32_e32 v0, v0
	v_add_u32_e32 v99, 32, v149
	v_mul_f32_e32 v98, v137, v151
	v_pk_mul_f32 v[86:87], v[98:99], v[86:87] op_sel_hi:[0,1]
	v_add_f32_e32 v0, 1.0, v0
	v_rcp_f32_e32 v101, v0
	v_mul_f32_e32 v0, 0xbfb8aa3b, v96
	v_exp_f32_e32 v0, v0
	v_pk_mul_f32 v[88:89], v[98:99], v[88:89] op_sel_hi:[0,1]
	v_pk_mul_f32 v[94:95], v[94:95], v[100:101]
	v_pk_mul_f32 v[82:83], v[98:99], v[82:83] op_sel_hi:[0,1]
	v_add_f32_e32 v0, 1.0, v0
	v_rcp_f32_e32 v102, v0
	v_mul_f32_e32 v0, 0xbfb8aa3b, v97
	v_exp_f32_e32 v0, v0
	v_pk_mul_f32 v[86:87], v[86:87], v[94:95]
	v_pk_mul_f32 v[84:85], v[98:99], v[84:85] op_sel_hi:[0,1]
	v_mad_i64_i32 v[98:99], s[24:25], v99, s52, v[130:131]
	v_add_f32_e32 v0, 1.0, v0
	v_rcp_f32_e32 v103, v0
	v_mul_f32_e32 v0, 0xbfb8aa3b, v90
	v_exp_f32_e32 v0, v0
	v_cvt_f32_i32_e32 v10, v10
	v_pk_mul_f32 v[96:97], v[96:97], v[102:103]
	v_cvt_f32_i32_e32 v13, v13
	v_add_f32_e32 v0, 1.0, v0
	v_rcp_f32_e32 v94, v0
	v_mul_f32_e32 v0, 0xbfb8aa3b, v91
	v_exp_f32_e32 v0, v0
	v_pk_mul_f32 v[88:89], v[88:89], v[96:97]
	v_cvt_f32_i32_e32 v12, v12
	v_cvt_f32_i32_e32 v21, v21
	v_add_f32_e32 v0, 1.0, v0
	v_rcp_f32_e32 v95, v0
	v_mul_f32_e32 v0, 0xbfb8aa3b, v92
	v_exp_f32_e32 v0, v0
	v_cvt_f32_i32_e32 v20, v20
	v_pk_mul_f32 v[90:91], v[90:91], v[94:95]
	v_cvt_f32_i32_e32 v19, v19
	v_add_f32_e32 v0, 1.0, v0
	v_rcp_f32_e32 v96, v0
	v_mul_f32_e32 v0, 0xbfb8aa3b, v93
	v_exp_f32_e32 v0, v0
	v_cvt_f32_i32_e32 v18, v18
	v_cvt_f32_i32_e32 v7, v7
	v_cvt_f32_i32_e32 v6, v6
	v_add_f32_e32 v0, 1.0, v0
	v_rcp_f32_e32 v97, v0
	v_mul_f32_e32 v0, v138, v150
	v_pk_mul_f32 v[78:79], v[0:1], v[78:79] op_sel_hi:[0,1]
	v_pk_mul_f32 v[80:81], v[0:1], v[80:81] op_sel_hi:[0,1]
	v_pk_mul_f32 v[76:77], v[0:1], v[76:77] op_sel_hi:[0,1]
	v_pk_mul_f32 v[74:75], v[0:1], v[74:75] op_sel_hi:[0,1]
	v_mul_f32_e32 v0, 0xbfb8aa3b, v78
	v_exp_f32_e32 v0, v0
	v_pk_mul_f32 v[92:93], v[92:93], v[96:97]
	v_cvt_f32_i32_e32 v9, v9
	v_pk_mul_f32 v[92:93], v[84:85], v[92:93]
	v_pk_mul_f32 v[84:85], v[82:83], v[90:91]
	v_cvt_pk_bf16_f32 v82, v86, v87
	v_cvt_pk_bf16_f32 v83, v88, v89
	v_add_f32_e32 v0, 1.0, v0
	v_cvt_pk_bf16_f32 v84, v84, v85
	v_cvt_pk_bf16_f32 v85, v92, v93
	global_store_dwordx4 v[98:99], v[82:85], off
	v_cvt_f32_i32_e32 v8, v8
	v_cvt_f32_i32_e32 v5, v5
	v_rcp_f32_e32 v84, v0
	v_mul_f32_e32 v0, 0xbfb8aa3b, v79
	v_exp_f32_e32 v0, v0
	v_add_u32_e32 v83, 48, v149
	v_mul_f32_e32 v82, v138, v151
	v_pk_mul_f32 v[70:71], v[82:83], v[70:71] op_sel_hi:[0,1]
	v_add_f32_e32 v0, 1.0, v0
	v_rcp_f32_e32 v85, v0
	v_mul_f32_e32 v0, 0xbfb8aa3b, v80
	v_exp_f32_e32 v0, v0
	v_pk_mul_f32 v[72:73], v[82:83], v[72:73] op_sel_hi:[0,1]
	v_pk_mul_f32 v[78:79], v[78:79], v[84:85]
	v_pk_mul_f32 v[66:67], v[82:83], v[66:67] op_sel_hi:[0,1]
	v_add_f32_e32 v0, 1.0, v0
	v_rcp_f32_e32 v86, v0
	v_mul_f32_e32 v0, 0xbfb8aa3b, v81
	v_exp_f32_e32 v0, v0
	v_pk_mul_f32 v[70:71], v[70:71], v[78:79]
	v_pk_mul_f32 v[68:69], v[82:83], v[68:69] op_sel_hi:[0,1]
	v_mad_i64_i32 v[82:83], s[24:25], v83, s52, v[130:131]
	v_add_f32_e32 v0, 1.0, v0
	v_rcp_f32_e32 v87, v0
	v_mul_f32_e32 v0, 0xbfb8aa3b, v74
	v_exp_f32_e32 v0, v0
	v_cvt_f32_i32_e32 v4, v4
	v_pk_mul_f32 v[80:81], v[80:81], v[86:87]
	v_cvt_f32_i32_e32 v3, v3
	v_add_f32_e32 v0, 1.0, v0
	v_rcp_f32_e32 v78, v0
	v_mul_f32_e32 v0, 0xbfb8aa3b, v75
	v_exp_f32_e32 v0, v0
	v_pk_mul_f32 v[72:73], v[72:73], v[80:81]
	v_cvt_f32_i32_e32 v2, v2
	s_andn2_b64 vcc, exec, s[22:23]
	v_add_f32_e32 v0, 1.0, v0
	v_rcp_f32_e32 v79, v0
	v_mul_f32_e32 v0, 0xbfb8aa3b, v76
	v_exp_f32_e32 v0, v0
	v_pk_mul_f32 v[74:75], v[74:75], v[78:79]
	v_add_f32_e32 v0, 1.0, v0
	v_rcp_f32_e32 v80, v0
	v_mul_f32_e32 v0, 0xbfb8aa3b, v77
	v_exp_f32_e32 v0, v0
	s_nop 0
	v_add_f32_e32 v0, 1.0, v0
	v_rcp_f32_e32 v81, v0
	v_mul_f32_e32 v0, v139, v150
	v_pk_mul_f32 v[62:63], v[0:1], v[62:63] op_sel_hi:[0,1]
	v_pk_mul_f32 v[64:65], v[0:1], v[64:65] op_sel_hi:[0,1]
	v_pk_mul_f32 v[60:61], v[0:1], v[60:61] op_sel_hi:[0,1]
	v_pk_mul_f32 v[58:59], v[0:1], v[58:59] op_sel_hi:[0,1]
	v_mul_f32_e32 v0, 0xbfb8aa3b, v62
	v_exp_f32_e32 v0, v0
	v_pk_mul_f32 v[76:77], v[76:77], v[80:81]
	v_add_f32_e32 v0, 1.0, v0
	v_pk_mul_f32 v[76:77], v[68:69], v[76:77]
	v_pk_mul_f32 v[68:69], v[66:67], v[74:75]
	v_cvt_pk_bf16_f32 v66, v70, v71
	v_cvt_pk_bf16_f32 v67, v72, v73
	s_nop 0
	v_cvt_pk_bf16_f32 v68, v68, v69
	v_cvt_pk_bf16_f32 v69, v76, v77
	global_store_dwordx4 v[82:83], v[66:69], off
	s_nop 1
	v_rcp_f32_e32 v68, v0
	v_mul_f32_e32 v0, 0xbfb8aa3b, v63
	v_exp_f32_e32 v0, v0
	v_add_u32_e32 v67, 0x80, v149
	v_mul_f32_e32 v66, v139, v151
	v_pk_mul_f32 v[54:55], v[66:67], v[54:55] op_sel_hi:[0,1]
	v_add_f32_e32 v0, 1.0, v0
	v_rcp_f32_e32 v69, v0
	v_mul_f32_e32 v0, 0xbfb8aa3b, v64
	v_exp_f32_e32 v0, v0
	v_pk_mul_f32 v[56:57], v[66:67], v[56:57] op_sel_hi:[0,1]
	v_pk_mul_f32 v[62:63], v[62:63], v[68:69]
	v_pk_mul_f32 v[50:51], v[66:67], v[50:51] op_sel_hi:[0,1]
	v_add_f32_e32 v0, 1.0, v0
	v_rcp_f32_e32 v70, v0
	v_mul_f32_e32 v0, 0xbfb8aa3b, v65
	v_exp_f32_e32 v0, v0
	v_pk_mul_f32 v[54:55], v[54:55], v[62:63]
	v_pk_mul_f32 v[52:53], v[66:67], v[52:53] op_sel_hi:[0,1]
	v_mad_i64_i32 v[66:67], s[24:25], v67, s52, v[130:131]
	v_add_f32_e32 v0, 1.0, v0
	v_rcp_f32_e32 v71, v0
	v_mul_f32_e32 v0, 0xbfb8aa3b, v58
	v_exp_f32_e32 v0, v0
	v_pk_mul_f32 v[64:65], v[64:65], v[70:71]
	s_nop 0
	v_pk_mul_f32 v[56:57], v[56:57], v[64:65]
	v_add_f32_e32 v0, 1.0, v0
	v_rcp_f32_e32 v62, v0
	v_mul_f32_e32 v0, 0xbfb8aa3b, v59
	v_exp_f32_e32 v0, v0
	s_nop 0
	v_add_f32_e32 v0, 1.0, v0
	v_rcp_f32_e32 v63, v0
	v_mul_f32_e32 v0, 0xbfb8aa3b, v60
	v_exp_f32_e32 v0, v0
	v_pk_mul_f32 v[58:59], v[58:59], v[62:63]
	v_add_f32_e32 v0, 1.0, v0
	v_rcp_f32_e32 v64, v0
	v_mul_f32_e32 v0, 0xbfb8aa3b, v61
	v_exp_f32_e32 v0, v0
	s_nop 0
	v_add_f32_e32 v0, 1.0, v0
	v_rcp_f32_e32 v65, v0
	v_mul_f32_e32 v0, v140, v150
	v_pk_mul_f32 v[46:47], v[0:1], v[46:47] op_sel_hi:[0,1]
	v_pk_mul_f32 v[48:49], v[0:1], v[48:49] op_sel_hi:[0,1]
	v_pk_mul_f32 v[44:45], v[0:1], v[44:45] op_sel_hi:[0,1]
	v_pk_mul_f32 v[42:43], v[0:1], v[42:43] op_sel_hi:[0,1]
	v_mul_f32_e32 v0, 0xbfb8aa3b, v46
	v_exp_f32_e32 v0, v0
	v_pk_mul_f32 v[60:61], v[60:61], v[64:65]
	v_add_f32_e32 v0, 1.0, v0
	v_pk_mul_f32 v[60:61], v[52:53], v[60:61]
	v_pk_mul_f32 v[52:53], v[50:51], v[58:59]
	v_cvt_pk_bf16_f32 v50, v54, v55
	v_cvt_pk_bf16_f32 v51, v56, v57
	s_nop 0
	v_cvt_pk_bf16_f32 v52, v52, v53
	v_cvt_pk_bf16_f32 v53, v60, v61
	global_store_dwordx4 v[66:67], v[50:53], off
	s_nop 1
	v_rcp_f32_e32 v52, v0
	v_mul_f32_e32 v0, 0xbfb8aa3b, v47
	v_exp_f32_e32 v0, v0
	v_add_u32_e32 v51, 0x90, v149
	v_mul_f32_e32 v50, v140, v151
	v_pk_mul_f32 v[38:39], v[50:51], v[38:39] op_sel_hi:[0,1]
	v_add_f32_e32 v0, 1.0, v0
	v_rcp_f32_e32 v53, v0
	v_mul_f32_e32 v0, 0xbfb8aa3b, v48
	v_exp_f32_e32 v0, v0
	v_pk_mul_f32 v[40:41], v[50:51], v[40:41] op_sel_hi:[0,1]
	v_pk_mul_f32 v[46:47], v[46:47], v[52:53]
	v_pk_mul_f32 v[34:35], v[50:51], v[34:35] op_sel_hi:[0,1]
	v_add_f32_e32 v0, 1.0, v0
	v_rcp_f32_e32 v54, v0
	v_mul_f32_e32 v0, 0xbfb8aa3b, v49
	v_exp_f32_e32 v0, v0
	v_pk_mul_f32 v[38:39], v[38:39], v[46:47]
	v_pk_mul_f32 v[36:37], v[50:51], v[36:37] op_sel_hi:[0,1]
	v_mad_i64_i32 v[50:51], s[24:25], v51, s52, v[130:131]
	v_add_f32_e32 v0, 1.0, v0
	v_rcp_f32_e32 v55, v0
	v_mul_f32_e32 v0, 0xbfb8aa3b, v42
	v_exp_f32_e32 v0, v0
	v_pk_mul_f32 v[48:49], v[48:49], v[54:55]
	s_nop 0
	v_pk_mul_f32 v[40:41], v[40:41], v[48:49]
	v_add_f32_e32 v0, 1.0, v0
	v_rcp_f32_e32 v46, v0
	v_mul_f32_e32 v0, 0xbfb8aa3b, v43
	v_exp_f32_e32 v0, v0
	s_nop 0
	v_add_f32_e32 v0, 1.0, v0
	v_rcp_f32_e32 v47, v0
	v_mul_f32_e32 v0, 0xbfb8aa3b, v44
	v_exp_f32_e32 v0, v0
	v_pk_mul_f32 v[42:43], v[42:43], v[46:47]
	v_add_f32_e32 v0, 1.0, v0
	v_rcp_f32_e32 v48, v0
	v_mul_f32_e32 v0, 0xbfb8aa3b, v45
	v_exp_f32_e32 v0, v0
	s_nop 0
	v_add_f32_e32 v0, 1.0, v0
	v_rcp_f32_e32 v49, v0
	v_mul_f32_e32 v0, v141, v150
	v_pk_mul_f32 v[30:31], v[0:1], v[30:31] op_sel_hi:[0,1]
	v_pk_mul_f32 v[32:33], v[0:1], v[32:33] op_sel_hi:[0,1]
	v_pk_mul_f32 v[28:29], v[0:1], v[28:29] op_sel_hi:[0,1]
	v_pk_mul_f32 v[26:27], v[0:1], v[26:27] op_sel_hi:[0,1]
	v_mul_f32_e32 v0, 0xbfb8aa3b, v30
	v_exp_f32_e32 v0, v0
	v_pk_mul_f32 v[44:45], v[44:45], v[48:49]
	v_add_f32_e32 v0, 1.0, v0
	v_pk_mul_f32 v[44:45], v[36:37], v[44:45]
	v_pk_mul_f32 v[36:37], v[34:35], v[42:43]
	v_cvt_pk_bf16_f32 v34, v38, v39
	v_cvt_pk_bf16_f32 v35, v40, v41
	s_nop 0
	v_cvt_pk_bf16_f32 v36, v36, v37
	v_cvt_pk_bf16_f32 v37, v44, v45
	global_store_dwordx4 v[50:51], v[34:37], off
	s_nop 1
	v_rcp_f32_e32 v36, v0
	v_mul_f32_e32 v0, 0xbfb8aa3b, v31
	v_exp_f32_e32 v0, v0
	v_add_u32_e32 v35, 0xa0, v149
	v_mul_f32_e32 v34, v141, v151
	v_pk_mul_f32 v[22:23], v[34:35], v[22:23] op_sel_hi:[0,1]
	v_add_f32_e32 v0, 1.0, v0
	v_rcp_f32_e32 v37, v0
	v_mul_f32_e32 v0, 0xbfb8aa3b, v32
	v_exp_f32_e32 v0, v0
	v_pk_mul_f32 v[24:25], v[34:35], v[24:25] op_sel_hi:[0,1]
	v_pk_mul_f32 v[30:31], v[30:31], v[36:37]
	v_pk_mul_f32 v[18:19], v[34:35], v[18:19] op_sel_hi:[0,1]
	v_add_f32_e32 v0, 1.0, v0
	v_rcp_f32_e32 v38, v0
	v_mul_f32_e32 v0, 0xbfb8aa3b, v33
	v_exp_f32_e32 v0, v0
	v_pk_mul_f32 v[22:23], v[22:23], v[30:31]
	v_pk_mul_f32 v[20:21], v[34:35], v[20:21] op_sel_hi:[0,1]
	v_mad_i64_i32 v[34:35], s[24:25], v35, s52, v[130:131]
	v_add_f32_e32 v0, 1.0, v0
	v_rcp_f32_e32 v39, v0
	v_mul_f32_e32 v0, 0xbfb8aa3b, v26
	v_exp_f32_e32 v0, v0
	v_pk_mul_f32 v[32:33], v[32:33], v[38:39]
	s_nop 0
	v_pk_mul_f32 v[24:25], v[24:25], v[32:33]
	v_add_f32_e32 v0, 1.0, v0
	v_rcp_f32_e32 v30, v0
	v_mul_f32_e32 v0, 0xbfb8aa3b, v27
	v_exp_f32_e32 v0, v0
	s_nop 0
	v_add_f32_e32 v0, 1.0, v0
	v_rcp_f32_e32 v31, v0
	v_mul_f32_e32 v0, 0xbfb8aa3b, v28
	v_exp_f32_e32 v0, v0
	v_pk_mul_f32 v[26:27], v[26:27], v[30:31]
	v_add_f32_e32 v0, 1.0, v0
	v_rcp_f32_e32 v32, v0
	v_mul_f32_e32 v0, 0xbfb8aa3b, v29
	v_exp_f32_e32 v0, v0
	s_nop 0
	v_add_f32_e32 v0, 1.0, v0
	v_rcp_f32_e32 v33, v0
	v_mul_f32_e32 v0, v142, v150
	v_pk_mul_f32 v[14:15], v[0:1], v[14:15] op_sel_hi:[0,1]
	v_pk_mul_f32 v[16:17], v[0:1], v[16:17] op_sel_hi:[0,1]
	v_pk_mul_f32 v[12:13], v[0:1], v[12:13] op_sel_hi:[0,1]
	v_pk_mul_f32 v[10:11], v[0:1], v[10:11] op_sel_hi:[0,1]
	v_mul_f32_e32 v0, 0xbfb8aa3b, v14
	v_exp_f32_e32 v0, v0
	v_pk_mul_f32 v[28:29], v[28:29], v[32:33]
	v_add_f32_e32 v0, 1.0, v0
	v_pk_mul_f32 v[28:29], v[20:21], v[28:29]
	v_pk_mul_f32 v[20:21], v[18:19], v[26:27]
	v_cvt_pk_bf16_f32 v18, v22, v23
	v_cvt_pk_bf16_f32 v19, v24, v25
	s_nop 0
	v_cvt_pk_bf16_f32 v20, v20, v21
	v_cvt_pk_bf16_f32 v21, v28, v29
	global_store_dwordx4 v[34:35], v[18:21], off
	s_nop 1
	v_rcp_f32_e32 v20, v0
	v_mul_f32_e32 v0, 0xbfb8aa3b, v15
	v_exp_f32_e32 v0, v0
	v_add_u32_e32 v19, 0xb0, v149
	v_mul_f32_e32 v18, v142, v151
	v_pk_mul_f32 v[6:7], v[18:19], v[6:7] op_sel_hi:[0,1]
	v_add_f32_e32 v0, 1.0, v0
	v_rcp_f32_e32 v21, v0
	v_mul_f32_e32 v0, 0xbfb8aa3b, v16
	v_exp_f32_e32 v0, v0
	v_pk_mul_f32 v[8:9], v[18:19], v[8:9] op_sel_hi:[0,1]
	v_pk_mul_f32 v[14:15], v[14:15], v[20:21]
	v_pk_mul_f32 v[2:3], v[18:19], v[2:3] op_sel_hi:[0,1]
	v_add_f32_e32 v0, 1.0, v0
	v_rcp_f32_e32 v22, v0
	v_mul_f32_e32 v0, 0xbfb8aa3b, v17
	v_exp_f32_e32 v0, v0
	v_pk_mul_f32 v[6:7], v[6:7], v[14:15]
	v_pk_mul_f32 v[4:5], v[18:19], v[4:5] op_sel_hi:[0,1]
	v_mad_i64_i32 v[18:19], s[24:25], v19, s52, v[130:131]
	v_add_f32_e32 v0, 1.0, v0
	v_rcp_f32_e32 v23, v0
	v_mul_f32_e32 v0, 0xbfb8aa3b, v10
	v_exp_f32_e32 v0, v0
	s_mov_b64 s[24:25], -1
	v_pk_mul_f32 v[16:17], v[16:17], v[22:23]
	v_add_f32_e32 v0, 1.0, v0
	v_rcp_f32_e32 v14, v0
	v_mul_f32_e32 v0, 0xbfb8aa3b, v11
	v_exp_f32_e32 v0, v0
	v_pk_mul_f32 v[8:9], v[8:9], v[16:17]
	v_add_f32_e32 v0, 1.0, v0
	v_rcp_f32_e32 v15, v0
	v_mul_f32_e32 v0, 0xbfb8aa3b, v12
	v_exp_f32_e32 v0, v0
	v_pk_mul_f32 v[10:11], v[10:11], v[14:15]
	v_add_f32_e32 v0, 1.0, v0
	v_rcp_f32_e32 v16, v0
	v_mul_f32_e32 v0, 0xbfb8aa3b, v13
	v_exp_f32_e32 v0, v0
	s_nop 0
	v_add_f32_e32 v0, 1.0, v0
	v_rcp_f32_e32 v17, v0
	s_nop 0
	v_pk_mul_f32 v[12:13], v[12:13], v[16:17]
	s_nop 0
	v_pk_mul_f32 v[12:13], v[4:5], v[12:13]
	v_pk_mul_f32 v[4:5], v[2:3], v[10:11]
	v_cvt_pk_bf16_f32 v2, v6, v7
	v_cvt_pk_bf16_f32 v3, v8, v9
	s_nop 0
	v_cvt_pk_bf16_f32 v4, v4, v5
	v_cvt_pk_bf16_f32 v5, v12, v13
	global_store_dwordx4 v[18:19], v[2:5], off
	s_cbranch_vccnz .LBB0_441
	s_cmp_eq_u32 s83, s71
	s_cbranch_scc1 .LBB0_451
	v_lshl_add_u32 v2, s83, 8, v146
	v_ashrrev_i32_e32 v3, 31, v2
	v_lshl_add_u64 v[2:3], v[2:3], 2, s[4:5]
	global_load_dword v135, v[2:3], off sc1
	global_load_dword v136, v[2:3], off offset:64 sc1
	global_load_dword v137, v[2:3], off offset:128 sc1
	global_load_dword v138, v[2:3], off offset:192 sc1
	global_load_dword v139, v[2:3], off offset:512 sc1
	global_load_dword v140, v[2:3], off offset:576 sc1
	global_load_dword v141, v[2:3], off offset:640 sc1
	global_load_dword v142, v[2:3], off offset:704 sc1

.LBB0_458:
	s_add_i32 s4, s24, 0x200
	s_cmpk_lt_i32 s24, 0x910
	s_cselect_b32 s25, s24, s4
	s_mov_b64 s[14:15], s[20:21]
	s_cmpk_gt_i32 s25, 0x57f
	s_mov_b64 s[4:5], -1
	s_cbranch_scc0 .LBB0_613
	s_cmpk_gt_u32 s25, 0x80f
	s_cbranch_scc0 .LBB0_473
	s_cmpk_gt_u32 s25, 0x90f
	s_cbranch_scc0 .LBB0_470
	s_cmpk_gt_u32 s25, 0xb0f
	s_cbranch_scc0 .LBB0_467
	s_cmpk_gt_u32 s25, 0xc0f
	s_cbranch_scc0 .LBB0_464
	s_mov_b32 s4, 18
	s_ashr_i32 s5, s4, 31
	s_lshl_b64 s[4:5], s[4:5], 3
	s_add_u32 s4, s0, s4
	s_addc_u32 s5, s1, s5
	s_mov_b32 s16, 16
	s_load_dwordx2 s[4:5], s[4:5], 0x0
	s_ashr_i32 s17, s16, 31
	s_lshl_b64 s[16:17], s[16:17], 3
	s_add_u32 s16, s0, s16
	s_addc_u32 s17, s1, s17
	s_load_dwordx2 s[16:17], s[16:17], 0x0
	v_lshlrev_b32_e32 v0, 4, v62
	s_waitcnt lgkmcnt(0)
	v_lshl_add_u64 v[2:3], s[4:5], 0, v[0:1]
	s_mov_b64 s[4:5], 0x400000
	v_lshl_add_u64 v[2:3], v[2:3], 0, s[4:5]
	s_add_u32 s40, s16, 0x1000
	s_addc_u32 s41, s17, 0
	s_lshl_b32 s42, s25, 2
	s_add_i32 s26, s42, 0xffffcfc0
	s_lshl_b64 s[4:5], s[26:27], 12
	s_add_i32 s22, s42, 0xffffcfc1
	s_mov_b32 s23, s27
	v_lshl_add_u64 v[4:5], v[2:3], 0, s[4:5]
	s_lshl_b64 s[4:5], s[22:23], 12
	s_add_i32 s16, s42, 0xffffcfc2
	s_mov_b32 s17, s27
	global_load_dwordx4 v[68:71], v[4:5], off sc1 nt
	global_load_dwordx4 v[58:61], v[4:5], off offset:1024 sc1 nt
	global_load_dwordx4 v[54:57], v[4:5], off offset:2048 sc1 nt
	global_load_dwordx4 v[50:53], v[4:5], off offset:3072 sc1 nt
	v_lshl_add_u64 v[4:5], v[2:3], 0, s[4:5]
	s_lshl_b64 s[4:5], s[16:17], 12
	global_load_dwordx4 v[46:49], v[4:5], off sc1 nt
	global_load_dwordx4 v[42:45], v[4:5], off offset:1024 sc1 nt
	global_load_dwordx4 v[38:41], v[4:5], off offset:2048 sc1 nt
	global_load_dwordx4 v[34:37], v[4:5], off offset:3072 sc1 nt
	v_lshl_add_u64 v[4:5], v[2:3], 0, s[4:5]
	s_add_i32 s4, s42, 0xffffcfc3
	s_mov_b32 s5, s27
	s_lshl_b64 s[42:43], s[4:5], 12
	v_lshlrev_b32_e32 v0, 3, v62
	v_lshl_add_u64 v[2:3], v[2:3], 0, s[42:43]
	v_lshl_add_u64 v[64:65], s[14:15], 0, v[0:1]
	s_mov_b64 s[42:43], 0x3a00000
	v_lshl_add_u64 v[64:65], v[64:65], 0, s[42:43]
	s_lshl_b64 s[42:43], s[26:27], 2
	s_add_u32 s42, s40, s42
	s_addc_u32 s43, s41, s43
	global_load_dwordx4 v[30:33], v[4:5], off sc1 nt
	global_load_dwordx4 v[26:29], v[4:5], off offset:1024 sc1 nt
	global_load_dwordx4 v[22:25], v[4:5], off offset:2048 sc1 nt
	global_load_dwordx4 v[18:21], v[4:5], off offset:3072 sc1 nt
	global_load_dwordx4 v[14:17], v[2:3], off sc1 nt
	global_load_dwordx4 v[10:13], v[2:3], off offset:1024 sc1 nt
	global_load_dwordx4 v[6:9], v[2:3], off offset:2048 sc1 nt
	s_nop 0
	global_load_dwordx4 v[2:5], v[2:3], off offset:3072 sc1 nt
	s_nop 0
	global_load_dword v0, v1, s[42:43] sc1
	s_lshl_b64 s[42:43], s[26:27], 11
	v_lshl_add_u64 v[66:67], v[64:65], 0, s[42:43]
	s_lshl_b64 s[42:43], s[22:23], 2
	s_add_u32 s42, s40, s42
	s_addc_u32 s43, s41, s43
	s_lshl_b64 s[22:23], s[22:23], 11
	s_waitcnt vmcnt(0)
	v_mul_f32_e32 v0, 0x3db8aa3b, v0
	v_pk_mul_f32 v[68:69], v[0:1], v[68:69] op_sel_hi:[0,1]
	v_bfe_u32 v72, v68, 16, 1
	v_add3_u32 v68, v68, v72, s53
	v_bfe_u32 v72, v69, 16, 1
	v_pk_mul_f32 v[70:71], v[0:1], v[70:71] op_sel_hi:[0,1]
	v_lshrrev_b32_e32 v68, 16, v68
	v_add3_u32 v69, v69, v72, s53
	v_and_or_b32 v68, v69, s45, v68
	v_bfe_u32 v69, v70, 16, 1
	v_add3_u32 v69, v70, v69, s53
	v_bfe_u32 v70, v71, 16, 1
	v_lshrrev_b32_e32 v69, 16, v69
	v_add3_u32 v70, v71, v70, s53
	v_and_or_b32 v69, v70, s45, v69
	v_pk_mul_f32 v[58:59], v[0:1], v[58:59] op_sel_hi:[0,1]
	global_store_dwordx2 v[66:67], v[68:69], off sc1
	v_bfe_u32 v68, v58, 16, 1
	v_add3_u32 v58, v58, v68, s53
	v_bfe_u32 v68, v59, 16, 1
	v_pk_mul_f32 v[60:61], v[0:1], v[60:61] op_sel_hi:[0,1]
	v_lshrrev_b32_e32 v58, 16, v58
	v_add3_u32 v59, v59, v68, s53
	v_and_or_b32 v58, v59, s45, v58
	v_bfe_u32 v59, v60, 16, 1
	v_add3_u32 v59, v60, v59, s53
	v_bfe_u32 v60, v61, 16, 1
	v_lshrrev_b32_e32 v59, 16, v59
	v_add3_u32 v60, v61, v60, s53
	v_and_or_b32 v59, v60, s45, v59
	v_pk_mul_f32 v[54:55], v[0:1], v[54:55] op_sel_hi:[0,1]
	v_pk_mul_f32 v[50:51], v[0:1], v[50:51] op_sel_hi:[0,1]
	global_store_dwordx2 v[66:67], v[58:59], off offset:512 sc1
	v_pk_mul_f32 v[56:57], v[0:1], v[56:57] op_sel_hi:[0,1]
	v_bfe_u32 v58, v54, 16, 1
	v_pk_mul_f32 v[52:53], v[0:1], v[52:53] op_sel_hi:[0,1]
	v_bfe_u32 v0, v50, 16, 1
	v_add3_u32 v54, v54, v58, s53
	v_bfe_u32 v58, v55, 16, 1
	v_add3_u32 v0, v50, v0, s53
	v_bfe_u32 v50, v51, 16, 1
	v_lshrrev_b32_e32 v54, 16, v54
	v_add3_u32 v55, v55, v58, s53
	v_lshrrev_b32_e32 v0, 16, v0
	v_add3_u32 v50, v51, v50, s53
	v_and_or_b32 v54, v55, s45, v54
	v_bfe_u32 v55, v56, 16, 1
	v_and_or_b32 v50, v50, s45, v0
	v_bfe_u32 v0, v52, 16, 1
	v_add3_u32 v55, v56, v55, s53
	v_bfe_u32 v56, v57, 16, 1
	v_add3_u32 v0, v52, v0, s53
	v_bfe_u32 v51, v53, 16, 1
	v_lshrrev_b32_e32 v55, 16, v55
	v_add3_u32 v56, v57, v56, s53
	v_lshrrev_b32_e32 v0, 16, v0
	v_add3_u32 v51, v53, v51, s53
	v_and_or_b32 v55, v56, s45, v55
	v_and_or_b32 v51, v51, s45, v0
	global_store_dwordx2 v[66:67], v[54:55], off offset:1024 sc1
	global_store_dwordx2 v[66:67], v[50:51], off offset:1536 sc1
	global_load_dword v0, v1, s[42:43] sc1
	v_lshl_add_u64 v[50:51], v[64:65], 0, s[22:23]
	s_lshl_b64 s[22:23], s[16:17], 2
	s_add_u32 s22, s40, s22
	s_addc_u32 s23, s41, s23
	s_lshl_b64 s[16:17], s[16:17], 11
	s_waitcnt vmcnt(0)
	v_mul_f32_e32 v0, 0x3db8aa3b, v0
	v_pk_mul_f32 v[46:47], v[0:1], v[46:47] op_sel_hi:[0,1]
	v_bfe_u32 v52, v46, 16, 1
	v_add3_u32 v46, v46, v52, s53
	v_bfe_u32 v52, v47, 16, 1
	v_pk_mul_f32 v[48:49], v[0:1], v[48:49] op_sel_hi:[0,1]
	v_lshrrev_b32_e32 v46, 16, v46
	v_add3_u32 v47, v47, v52, s53
	v_and_or_b32 v46, v47, s45, v46
	v_bfe_u32 v47, v48, 16, 1
	v_add3_u32 v47, v48, v47, s53
	v_bfe_u32 v48, v49, 16, 1
	v_lshrrev_b32_e32 v47, 16, v47
	v_add3_u32 v48, v49, v48, s53
	v_and_or_b32 v47, v48, s45, v47
	v_pk_mul_f32 v[42:43], v[0:1], v[42:43] op_sel_hi:[0,1]
	global_store_dwordx2 v[50:51], v[46:47], off sc1
	v_bfe_u32 v46, v42, 16, 1
	v_add3_u32 v42, v42, v46, s53
	v_bfe_u32 v46, v43, 16, 1
	v_pk_mul_f32 v[44:45], v[0:1], v[44:45] op_sel_hi:[0,1]
	v_lshrrev_b32_e32 v42, 16, v42
	v_add3_u32 v43, v43, v46, s53
	v_and_or_b32 v42, v43, s45, v42
	v_bfe_u32 v43, v44, 16, 1
	v_add3_u32 v43, v44, v43, s53
	v_bfe_u32 v44, v45, 16, 1
	v_lshrrev_b32_e32 v43, 16, v43
	v_add3_u32 v44, v45, v44, s53
	v_and_or_b32 v43, v44, s45, v43
	v_pk_mul_f32 v[38:39], v[0:1], v[38:39] op_sel_hi:[0,1]
	v_pk_mul_f32 v[34:35], v[0:1], v[34:35] op_sel_hi:[0,1]
	global_store_dwordx2 v[50:51], v[42:43], off offset:512 sc1
	v_pk_mul_f32 v[40:41], v[0:1], v[40:41] op_sel_hi:[0,1]
	v_bfe_u32 v42, v38, 16, 1
	v_pk_mul_f32 v[36:37], v[0:1], v[36:37] op_sel_hi:[0,1]
	v_bfe_u32 v0, v34, 16, 1
	v_add3_u32 v38, v38, v42, s53
	v_bfe_u32 v42, v39, 16, 1
	v_add3_u32 v0, v34, v0, s53
	v_bfe_u32 v34, v35, 16, 1
	v_lshrrev_b32_e32 v38, 16, v38
	v_add3_u32 v39, v39, v42, s53
	v_lshrrev_b32_e32 v0, 16, v0
	v_add3_u32 v34, v35, v34, s53
	v_and_or_b32 v38, v39, s45, v38
	v_bfe_u32 v39, v40, 16, 1
	v_and_or_b32 v34, v34, s45, v0
	v_bfe_u32 v0, v36, 16, 1
	v_add3_u32 v39, v40, v39, s53
	v_bfe_u32 v40, v41, 16, 1
	v_add3_u32 v0, v36, v0, s53
	v_bfe_u32 v35, v37, 16, 1
	v_lshrrev_b32_e32 v39, 16, v39
	v_add3_u32 v40, v41, v40, s53
	v_lshrrev_b32_e32 v0, 16, v0
	v_add3_u32 v35, v37, v35, s53
	v_and_or_b32 v39, v40, s45, v39
	v_and_or_b32 v35, v35, s45, v0
	global_store_dwordx2 v[50:51], v[38:39], off offset:1024 sc1
	global_store_dwordx2 v[50:51], v[34:35], off offset:1536 sc1
	global_load_dword v0, v1, s[22:23] sc1
	v_lshl_add_u64 v[34:35], v[64:65], 0, s[16:17]
	s_lshl_b64 s[16:17], s[4:5], 2
	s_add_u32 s16, s40, s16
	s_addc_u32 s17, s41, s17
	s_lshl_b64 s[4:5], s[4:5], 11
	s_waitcnt vmcnt(0)
	v_mul_f32_e32 v0, 0x3db8aa3b, v0
	v_pk_mul_f32 v[30:31], v[0:1], v[30:31] op_sel_hi:[0,1]
	v_bfe_u32 v36, v30, 16, 1
	v_add3_u32 v30, v30, v36, s53
	v_bfe_u32 v36, v31, 16, 1
	v_pk_mul_f32 v[32:33], v[0:1], v[32:33] op_sel_hi:[0,1]
	v_lshrrev_b32_e32 v30, 16, v30
	v_add3_u32 v31, v31, v36, s53
	v_and_or_b32 v30, v31, s45, v30
	v_bfe_u32 v31, v32, 16, 1
	v_add3_u32 v31, v32, v31, s53
	v_bfe_u32 v32, v33, 16, 1
	v_lshrrev_b32_e32 v31, 16, v31
	v_add3_u32 v32, v33, v32, s53
	v_and_or_b32 v31, v32, s45, v31
	v_pk_mul_f32 v[26:27], v[0:1], v[26:27] op_sel_hi:[0,1]
	global_store_dwordx2 v[34:35], v[30:31], off sc1
	v_bfe_u32 v30, v26, 16, 1
	v_add3_u32 v26, v26, v30, s53
	v_bfe_u32 v30, v27, 16, 1
	v_pk_mul_f32 v[28:29], v[0:1], v[28:29] op_sel_hi:[0,1]
	v_lshrrev_b32_e32 v26, 16, v26
	v_add3_u32 v27, v27, v30, s53
	v_and_or_b32 v26, v27, s45, v26
	v_bfe_u32 v27, v28, 16, 1
	v_add3_u32 v27, v28, v27, s53
	v_bfe_u32 v28, v29, 16, 1
	v_lshrrev_b32_e32 v27, 16, v27
	v_add3_u32 v28, v29, v28, s53
	v_and_or_b32 v27, v28, s45, v27
	v_pk_mul_f32 v[22:23], v[0:1], v[22:23] op_sel_hi:[0,1]
	v_pk_mul_f32 v[18:19], v[0:1], v[18:19] op_sel_hi:[0,1]
	global_store_dwordx2 v[34:35], v[26:27], off offset:512 sc1
	v_pk_mul_f32 v[24:25], v[0:1], v[24:25] op_sel_hi:[0,1]
	v_bfe_u32 v26, v22, 16, 1
	v_pk_mul_f32 v[20:21], v[0:1], v[20:21] op_sel_hi:[0,1]
	v_bfe_u32 v0, v18, 16, 1
	v_add3_u32 v22, v22, v26, s53
	v_bfe_u32 v26, v23, 16, 1
	v_add3_u32 v0, v18, v0, s53
	v_bfe_u32 v18, v19, 16, 1
	v_lshrrev_b32_e32 v22, 16, v22
	v_add3_u32 v23, v23, v26, s53
	v_lshrrev_b32_e32 v0, 16, v0
	v_add3_u32 v18, v19, v18, s53
	v_and_or_b32 v22, v23, s45, v22
	v_bfe_u32 v23, v24, 16, 1
	v_and_or_b32 v18, v18, s45, v0
	v_bfe_u32 v0, v20, 16, 1
	v_add3_u32 v23, v24, v23, s53
	v_bfe_u32 v24, v25, 16, 1
	v_add3_u32 v0, v20, v0, s53
	v_bfe_u32 v19, v21, 16, 1
	v_lshrrev_b32_e32 v23, 16, v23
	v_add3_u32 v24, v25, v24, s53
	v_lshrrev_b32_e32 v0, 16, v0
	v_add3_u32 v19, v21, v19, s53
	v_and_or_b32 v23, v24, s45, v23
	v_and_or_b32 v19, v19, s45, v0
	global_store_dwordx2 v[34:35], v[22:23], off offset:1024 sc1
	global_store_dwordx2 v[34:35], v[18:19], off offset:1536 sc1
	global_load_dword v0, v1, s[16:17] sc1
	v_lshl_add_u64 v[18:19], v[64:65], 0, s[4:5]
	s_mov_b64 s[4:5], 0
	s_waitcnt vmcnt(0)
	v_mul_f32_e32 v0, 0x3db8aa3b, v0
	v_pk_mul_f32 v[14:15], v[0:1], v[14:15] op_sel_hi:[0,1]
	v_bfe_u32 v20, v14, 16, 1
	v_add3_u32 v14, v14, v20, s53
	v_bfe_u32 v20, v15, 16, 1
	v_pk_mul_f32 v[16:17], v[0:1], v[16:17] op_sel_hi:[0,1]
	v_lshrrev_b32_e32 v14, 16, v14
	v_add3_u32 v15, v15, v20, s53
	v_and_or_b32 v14, v15, s45, v14
	v_bfe_u32 v15, v16, 16, 1
	v_add3_u32 v15, v16, v15, s53
	v_bfe_u32 v16, v17, 16, 1
	v_lshrrev_b32_e32 v15, 16, v15
	v_add3_u32 v16, v17, v16, s53
	v_and_or_b32 v15, v16, s45, v15
	v_pk_mul_f32 v[10:11], v[0:1], v[10:11] op_sel_hi:[0,1]
	global_store_dwordx2 v[18:19], v[14:15], off sc1
	v_bfe_u32 v14, v10, 16, 1
	v_add3_u32 v10, v10, v14, s53
	v_bfe_u32 v14, v11, 16, 1
	v_pk_mul_f32 v[12:13], v[0:1], v[12:13] op_sel_hi:[0,1]
	v_lshrrev_b32_e32 v10, 16, v10
	v_add3_u32 v11, v11, v14, s53
	v_and_or_b32 v10, v11, s45, v10
	v_bfe_u32 v11, v12, 16, 1
	v_add3_u32 v11, v12, v11, s53
	v_bfe_u32 v12, v13, 16, 1
	v_lshrrev_b32_e32 v11, 16, v11
	v_add3_u32 v12, v13, v12, s53
	v_and_or_b32 v11, v12, s45, v11
	v_pk_mul_f32 v[6:7], v[0:1], v[6:7] op_sel_hi:[0,1]
	v_pk_mul_f32 v[2:3], v[0:1], v[2:3] op_sel_hi:[0,1]
	global_store_dwordx2 v[18:19], v[10:11], off offset:512 sc1
	v_pk_mul_f32 v[8:9], v[0:1], v[8:9] op_sel_hi:[0,1]
	v_bfe_u32 v10, v6, 16, 1
	v_pk_mul_f32 v[4:5], v[0:1], v[4:5] op_sel_hi:[0,1]
	v_bfe_u32 v0, v2, 16, 1
	v_add3_u32 v6, v6, v10, s53
	v_bfe_u32 v10, v7, 16, 1
	v_add3_u32 v0, v2, v0, s53
	v_bfe_u32 v2, v3, 16, 1
	v_lshrrev_b32_e32 v6, 16, v6
	v_add3_u32 v7, v7, v10, s53
	v_lshrrev_b32_e32 v0, 16, v0
	v_add3_u32 v2, v3, v2, s53
	v_and_or_b32 v6, v7, s45, v6
	v_bfe_u32 v7, v8, 16, 1
	v_and_or_b32 v2, v2, s45, v0
	v_bfe_u32 v0, v4, 16, 1
	v_add3_u32 v7, v8, v7, s53
	v_bfe_u32 v8, v9, 16, 1
	v_add3_u32 v0, v4, v0, s53
	v_bfe_u32 v3, v5, 16, 1
	v_lshrrev_b32_e32 v7, 16, v7
	v_add3_u32 v8, v9, v8, s53
	v_lshrrev_b32_e32 v0, 16, v0
	v_add3_u32 v3, v5, v3, s53
	v_and_or_b32 v7, v8, s45, v7
	v_and_or_b32 v3, v3, s45, v0
	global_store_dwordx2 v[18:19], v[6:7], off offset:1024 sc1
	global_store_dwordx2 v[18:19], v[2:3], off offset:1536 sc1
.LBB0_464:
	s_andn2_b64 vcc, exec, s[4:5]
	s_cbranch_vccnz .LBB0_466
	s_mov_b32 s4, 20
	s_ashr_i32 s5, s4, 31
	s_lshl_b64 s[4:5], s[4:5], 3
	s_add_u32 s4, s0, s4
	s_addc_u32 s5, s1, s5
	s_load_dwordx2 s[22:23], s[4:5], 0x0
	s_lshl_b32 s4, s25, 6
	s_and_b32 s5, s4, 0x3c0
	s_lshl_b32 s4, s25, 2
	s_and_b32 s4, s4, 0x3fc0
	s_add_i32 s26, s4, 0xffffd3c0
	s_add_u32 s16, s14, 0x4000000
	s_addc_u32 s17, s15, 0
	s_lshl_b64 s[40:41], s[26:27], 12
	s_waitcnt lgkmcnt(0)
	s_add_u32 s22, s22, s40
	s_addc_u32 s23, s23, s41
	s_lshl_b32 s40, s5, 2
	s_add_u32 s22, s22, s40
	s_addc_u32 s23, s23, 0
	v_lshlrev_b32_e32 v0, 2, v62
	v_lshl_add_u64 v[2:3], s[22:23], 0, v[0:1]
	s_mov_b32 s22, 0x401000
	v_add_co_u32_e32 v4, vcc, s22, v2
	s_mov_b32 s22, 0x403000
	s_nop 0
	v_addc_co_u32_e32 v5, vcc, 0, v3, vcc
	global_load_dword v6, v[4:5], off offset:-4096 sc1 nt
	global_load_dword v0, v[4:5], off sc1 nt
	v_add_co_u32_e32 v4, vcc, s22, v2
	s_mov_b32 s22, 0x405000
	s_nop 0
	v_addc_co_u32_e32 v5, vcc, 0, v3, vcc
	global_load_dword v7, v[4:5], off offset:-4096 sc1 nt
	global_load_dword v8, v[4:5], off sc1 nt
	v_add_co_u32_e32 v4, vcc, s22, v2
	s_mov_b32 s22, 0x407000
	s_nop 0
	v_addc_co_u32_e32 v5, vcc, 0, v3, vcc
	global_load_dword v9, v[4:5], off offset:-4096 sc1 nt
	global_load_dword v10, v[4:5], off sc1 nt
	v_add_co_u32_e32 v4, vcc, s22, v2
	s_mov_b32 s22, 0x409000
	s_nop 0
	v_addc_co_u32_e32 v5, vcc, 0, v3, vcc
	global_load_dword v11, v[4:5], off offset:-4096 sc1 nt
	global_load_dword v12, v[4:5], off sc1 nt
	v_add_co_u32_e32 v4, vcc, s22, v2
	s_mov_b32 s22, 0x40b000
	s_nop 0
	v_addc_co_u32_e32 v5, vcc, 0, v3, vcc
	global_load_dword v13, v[4:5], off offset:-4096 sc1 nt
	global_load_dword v14, v[4:5], off sc1 nt
	v_add_co_u32_e32 v4, vcc, s22, v2
	s_mov_b32 s22, 0x40d000
	s_nop 0
	v_addc_co_u32_e32 v5, vcc, 0, v3, vcc
	global_load_dword v15, v[4:5], off offset:-4096 sc1 nt
	global_load_dword v16, v[4:5], off sc1 nt
	v_add_co_u32_e32 v4, vcc, s22, v2
	s_mov_b32 s22, 0x40f000
	s_nop 0
	v_addc_co_u32_e32 v5, vcc, 0, v3, vcc
	global_load_dword v17, v[4:5], off offset:-4096 sc1 nt
	global_load_dword v18, v[4:5], off sc1 nt
	v_add_co_u32_e32 v4, vcc, s22, v2
	s_mov_b32 s22, 0x411000
	s_nop 0
	v_addc_co_u32_e32 v5, vcc, 0, v3, vcc
	global_load_dword v19, v[4:5], off offset:-4096 sc1 nt
	global_load_dword v20, v[4:5], off sc1 nt
	v_add_co_u32_e32 v4, vcc, s22, v2
	s_mov_b32 s22, 0x413000
	s_nop 0
	v_addc_co_u32_e32 v5, vcc, 0, v3, vcc
	global_load_dword v21, v[4:5], off offset:-4096 sc1 nt
	global_load_dword v22, v[4:5], off sc1 nt
	v_add_co_u32_e32 v4, vcc, s22, v2
	s_mov_b32 s22, 0x415000
	s_nop 0
	v_addc_co_u32_e32 v5, vcc, 0, v3, vcc
	global_load_dword v23, v[4:5], off offset:-4096 sc1 nt
	global_load_dword v24, v[4:5], off sc1 nt
	v_add_co_u32_e32 v4, vcc, s22, v2
	s_mov_b32 s22, 0x417000
	s_nop 0
	v_addc_co_u32_e32 v5, vcc, 0, v3, vcc
	global_load_dword v25, v[4:5], off offset:-4096 sc1 nt
	global_load_dword v26, v[4:5], off sc1 nt
	v_add_co_u32_e32 v4, vcc, s22, v2
	s_mov_b32 s22, 0x419000
	s_nop 0
	v_addc_co_u32_e32 v5, vcc, 0, v3, vcc
	global_load_dword v27, v[4:5], off offset:-4096 sc1 nt
	global_load_dword v28, v[4:5], off sc1 nt
	v_add_co_u32_e32 v4, vcc, s22, v2
	s_mov_b32 s22, 0x41b000
	s_nop 0
	v_addc_co_u32_e32 v5, vcc, 0, v3, vcc
	global_load_dword v29, v[4:5], off offset:-4096 sc1 nt
	global_load_dword v30, v[4:5], off sc1 nt
	v_add_co_u32_e32 v4, vcc, s22, v2
	s_mov_b32 s22, 0x41d000
	s_nop 0
	v_addc_co_u32_e32 v5, vcc, 0, v3, vcc
	global_load_dword v31, v[4:5], off offset:-4096 sc1 nt
	global_load_dword v32, v[4:5], off sc1 nt
	v_add_co_u32_e32 v4, vcc, s22, v2
	s_mov_b32 s22, 0x41f000
	s_nop 0
	v_addc_co_u32_e32 v5, vcc, 0, v3, vcc
	global_load_dword v33, v[4:5], off offset:-4096 sc1 nt
	global_load_dword v34, v[4:5], off sc1 nt
	v_add_co_u32_e32 v4, vcc, s22, v2
	s_mov_b32 s22, 0x421000
	s_nop 0
	v_addc_co_u32_e32 v5, vcc, 0, v3, vcc
	global_load_dword v35, v[4:5], off offset:-4096 sc1 nt
	global_load_dword v36, v[4:5], off sc1 nt
	v_add_co_u32_e32 v4, vcc, s22, v2
	s_mov_b32 s22, 0x423000
	s_nop 0
	v_addc_co_u32_e32 v5, vcc, 0, v3, vcc
	global_load_dword v37, v[4:5], off offset:-4096 sc1 nt
	global_load_dword v38, v[4:5], off sc1 nt
	v_add_co_u32_e32 v4, vcc, s22, v2
	s_mov_b32 s22, 0x425000
	s_nop 0
	v_addc_co_u32_e32 v5, vcc, 0, v3, vcc
	global_load_dword v39, v[4:5], off offset:-4096 sc1 nt
	global_load_dword v40, v[4:5], off sc1 nt
	v_add_co_u32_e32 v4, vcc, s22, v2
	s_mov_b32 s22, 0x427000
	s_nop 0
	v_addc_co_u32_e32 v5, vcc, 0, v3, vcc
	global_load_dword v41, v[4:5], off offset:-4096 sc1 nt
	global_load_dword v42, v[4:5], off sc1 nt
	v_add_co_u32_e32 v4, vcc, s22, v2
	s_mov_b32 s22, 0x429000
	s_nop 0
	v_addc_co_u32_e32 v5, vcc, 0, v3, vcc
	global_load_dword v43, v[4:5], off offset:-4096 sc1 nt
	global_load_dword v44, v[4:5], off sc1 nt
	v_add_co_u32_e32 v4, vcc, s22, v2
	s_mov_b32 s22, 0x42b000
	s_nop 0
	v_addc_co_u32_e32 v5, vcc, 0, v3, vcc
	global_load_dword v45, v[4:5], off offset:-4096 sc1 nt
	global_load_dword v46, v[4:5], off sc1 nt
	v_add_co_u32_e32 v4, vcc, s22, v2
	s_mov_b32 s22, 0x42d000
	s_nop 0
	v_addc_co_u32_e32 v5, vcc, 0, v3, vcc
	global_load_dword v47, v[4:5], off offset:-4096 sc1 nt
	global_load_dword v48, v[4:5], off sc1 nt
	v_add_co_u32_e32 v4, vcc, s22, v2
	s_mov_b32 s22, 0x42f000
	s_nop 0
	v_addc_co_u32_e32 v5, vcc, 0, v3, vcc
	global_load_dword v49, v[4:5], off offset:-4096 sc1 nt
	global_load_dword v50, v[4:5], off sc1 nt
	v_add_co_u32_e32 v4, vcc, s22, v2
	s_mov_b32 s22, 0x431000
	s_nop 0
	v_addc_co_u32_e32 v5, vcc, 0, v3, vcc
	global_load_dword v51, v[4:5], off offset:-4096 sc1 nt
	global_load_dword v52, v[4:5], off sc1 nt
	v_add_co_u32_e32 v4, vcc, s22, v2
	s_mov_b32 s22, 0x433000
	s_nop 0
	v_addc_co_u32_e32 v5, vcc, 0, v3, vcc
	global_load_dword v53, v[4:5], off offset:-4096 sc1 nt
	global_load_dword v54, v[4:5], off sc1 nt
	v_add_co_u32_e32 v4, vcc, s22, v2
	s_mov_b32 s22, 0x435000
	s_nop 0
	v_addc_co_u32_e32 v5, vcc, 0, v3, vcc
	global_load_dword v55, v[4:5], off offset:-4096 sc1 nt
	global_load_dword v56, v[4:5], off sc1 nt
	v_add_co_u32_e32 v4, vcc, s22, v2
	s_mov_b32 s22, 0x437000
	s_nop 0
	v_addc_co_u32_e32 v5, vcc, 0, v3, vcc
	global_load_dword v57, v[4:5], off offset:-4096 sc1 nt
	global_load_dword v58, v[4:5], off sc1 nt
	v_add_co_u32_e32 v4, vcc, s22, v2
	s_mov_b32 s22, 0x439000
	s_nop 0
	v_addc_co_u32_e32 v5, vcc, 0, v3, vcc
	global_load_dword v59, v[4:5], off offset:-4096 sc1 nt
	global_load_dword v60, v[4:5], off sc1 nt
	v_add_co_u32_e32 v4, vcc, s22, v2
	s_mov_b32 s22, 0x43b000
	s_nop 0
	v_addc_co_u32_e32 v5, vcc, 0, v3, vcc
	global_load_dword v61, v[4:5], off offset:-4096 sc1 nt
	global_load_dword v64, v[4:5], off sc1 nt
	v_add_co_u32_e32 v4, vcc, s22, v2
	s_mov_b32 s22, 0x43d000
	s_nop 0
	v_addc_co_u32_e32 v5, vcc, 0, v3, vcc
	global_load_dword v65, v[4:5], off offset:-4096 sc1 nt
	global_load_dword v66, v[4:5], off sc1 nt
	v_add_co_u32_e32 v4, vcc, s22, v2
	s_mov_b32 s22, 0x43f000
	s_nop 0
	v_addc_co_u32_e32 v5, vcc, 0, v3, vcc
	v_add_co_u32_e32 v2, vcc, s22, v2
	global_load_dword v67, v[4:5], off offset:-4096 sc1 nt
	global_load_dword v68, v[4:5], off sc1 nt
	v_addc_co_u32_e32 v3, vcc, 0, v3, vcc
	global_load_dword v69, v[2:3], off offset:-4096 sc1 nt
	global_load_dword v70, v[2:3], off sc1 nt
	s_waitcnt vmcnt(62)
	v_bfe_u32 v2, v6, 16, 1
	v_add3_u32 v2, v6, v2, s53
	v_bfe_u32 v3, v0, 16, 1
	v_lshrrev_b32_e32 v2, 16, v2
	v_add3_u32 v0, v0, v3, s53
	v_and_or_b32 v2, v0, s45, v2
	s_waitcnt vmcnt(61)
	v_bfe_u32 v0, v7, 16, 1
	v_add3_u32 v0, v7, v0, s53
	s_waitcnt vmcnt(60)
	v_bfe_u32 v3, v8, 16, 1
	v_lshrrev_b32_e32 v0, 16, v0
	v_add3_u32 v3, v8, v3, s53
	v_and_or_b32 v3, v3, s45, v0
	s_waitcnt vmcnt(59)
	v_bfe_u32 v0, v9, 16, 1
	v_add3_u32 v0, v9, v0, s53
	s_waitcnt vmcnt(58)
	v_bfe_u32 v4, v10, 16, 1
	v_lshrrev_b32_e32 v0, 16, v0
	v_add3_u32 v4, v10, v4, s53
	v_and_or_b32 v4, v4, s45, v0
	s_waitcnt vmcnt(57)
	v_bfe_u32 v0, v11, 16, 1
	v_add3_u32 v0, v11, v0, s53
	s_waitcnt vmcnt(56)
	v_bfe_u32 v5, v12, 16, 1
	v_lshrrev_b32_e32 v0, 16, v0
	v_add3_u32 v5, v12, v5, s53
	v_and_or_b32 v5, v5, s45, v0
	s_waitcnt vmcnt(55)
	v_bfe_u32 v0, v13, 16, 1
	ds_write_b128 v132, v[2:5]
	v_add3_u32 v0, v13, v0, s53
	s_waitcnt vmcnt(54)
	v_bfe_u32 v2, v14, 16, 1
	v_lshrrev_b32_e32 v0, 16, v0
	v_add3_u32 v2, v14, v2, s53
	v_and_or_b32 v2, v2, s45, v0
	s_waitcnt vmcnt(53)
	v_bfe_u32 v0, v15, 16, 1
	v_add3_u32 v0, v15, v0, s53
	s_waitcnt vmcnt(52)
	v_bfe_u32 v3, v16, 16, 1
	v_lshrrev_b32_e32 v0, 16, v0
	v_add3_u32 v3, v16, v3, s53
	v_and_or_b32 v3, v3, s45, v0
	s_waitcnt vmcnt(51)
	v_bfe_u32 v0, v17, 16, 1
	v_add3_u32 v0, v17, v0, s53
	s_waitcnt vmcnt(50)
	v_bfe_u32 v4, v18, 16, 1
	v_lshrrev_b32_e32 v0, 16, v0
	v_add3_u32 v4, v18, v4, s53
	v_and_or_b32 v4, v4, s45, v0
	s_waitcnt vmcnt(49)
	v_bfe_u32 v0, v19, 16, 1
	v_add3_u32 v0, v19, v0, s53
	s_waitcnt vmcnt(48)
	v_bfe_u32 v5, v20, 16, 1
	v_lshrrev_b32_e32 v0, 16, v0
	v_add3_u32 v5, v20, v5, s53
	v_and_or_b32 v5, v5, s45, v0
	s_waitcnt vmcnt(47)
	v_bfe_u32 v0, v21, 16, 1
	ds_write_b128 v133, v[2:5]
	v_add3_u32 v0, v21, v0, s53
	s_waitcnt vmcnt(46)
	v_bfe_u32 v2, v22, 16, 1
	v_lshrrev_b32_e32 v0, 16, v0
	v_add3_u32 v2, v22, v2, s53
	v_and_or_b32 v2, v2, s45, v0
	s_waitcnt vmcnt(45)
	v_bfe_u32 v0, v23, 16, 1
	v_add3_u32 v0, v23, v0, s53
	s_waitcnt vmcnt(44)
	v_bfe_u32 v3, v24, 16, 1
	v_lshrrev_b32_e32 v0, 16, v0
	v_add3_u32 v3, v24, v3, s53
	v_and_or_b32 v3, v3, s45, v0
	s_waitcnt vmcnt(43)
	v_bfe_u32 v0, v25, 16, 1
	v_add3_u32 v0, v25, v0, s53
	s_waitcnt vmcnt(42)
	v_bfe_u32 v4, v26, 16, 1
	v_lshrrev_b32_e32 v0, 16, v0
	v_add3_u32 v4, v26, v4, s53
	v_and_or_b32 v4, v4, s45, v0
	s_waitcnt vmcnt(41)
	v_bfe_u32 v0, v27, 16, 1
	v_add3_u32 v0, v27, v0, s53
	s_waitcnt vmcnt(40)
	v_bfe_u32 v5, v28, 16, 1
	v_lshrrev_b32_e32 v0, 16, v0
	v_add3_u32 v5, v28, v5, s53
	v_and_or_b32 v5, v5, s45, v0
	s_waitcnt vmcnt(39)
	v_bfe_u32 v0, v29, 16, 1
	ds_write_b128 v134, v[2:5]
	v_add3_u32 v0, v29, v0, s53
	s_waitcnt vmcnt(38)
	v_bfe_u32 v2, v30, 16, 1
	v_lshrrev_b32_e32 v0, 16, v0
	v_add3_u32 v2, v30, v2, s53
	v_and_or_b32 v2, v2, s45, v0
	s_waitcnt vmcnt(37)
	v_bfe_u32 v0, v31, 16, 1
	v_add3_u32 v0, v31, v0, s53
	s_waitcnt vmcnt(36)
	v_bfe_u32 v3, v32, 16, 1
	v_lshrrev_b32_e32 v0, 16, v0
	v_add3_u32 v3, v32, v3, s53
	v_and_or_b32 v3, v3, s45, v0
	s_waitcnt vmcnt(35)
	v_bfe_u32 v0, v33, 16, 1
	v_add3_u32 v0, v33, v0, s53
	s_waitcnt vmcnt(34)
	v_bfe_u32 v4, v34, 16, 1
	v_lshrrev_b32_e32 v0, 16, v0
	v_add3_u32 v4, v34, v4, s53
	v_and_or_b32 v4, v4, s45, v0
	s_waitcnt vmcnt(33)
	v_bfe_u32 v0, v35, 16, 1
	v_add3_u32 v0, v35, v0, s53
	s_waitcnt vmcnt(32)
	v_bfe_u32 v5, v36, 16, 1
	v_lshrrev_b32_e32 v0, 16, v0
	v_add3_u32 v5, v36, v5, s53
	v_and_or_b32 v5, v5, s45, v0
	s_waitcnt vmcnt(31)
	v_bfe_u32 v0, v37, 16, 1
	ds_write_b128 v135, v[2:5]
	v_add3_u32 v0, v37, v0, s53
	s_waitcnt vmcnt(30)
	v_bfe_u32 v2, v38, 16, 1
	v_lshrrev_b32_e32 v0, 16, v0
	v_add3_u32 v2, v38, v2, s53
	v_and_or_b32 v2, v2, s45, v0
	s_waitcnt vmcnt(29)
	v_bfe_u32 v0, v39, 16, 1
	v_add3_u32 v0, v39, v0, s53
	s_waitcnt vmcnt(28)
	v_bfe_u32 v3, v40, 16, 1
	v_lshrrev_b32_e32 v0, 16, v0
	v_add3_u32 v3, v40, v3, s53
	v_and_or_b32 v3, v3, s45, v0
	s_waitcnt vmcnt(27)
	v_bfe_u32 v0, v41, 16, 1
	v_add3_u32 v0, v41, v0, s53
	s_waitcnt vmcnt(26)
	v_bfe_u32 v4, v42, 16, 1
	v_lshrrev_b32_e32 v0, 16, v0
	v_add3_u32 v4, v42, v4, s53
	v_and_or_b32 v4, v4, s45, v0
	s_waitcnt vmcnt(25)
	v_bfe_u32 v0, v43, 16, 1
	v_add3_u32 v0, v43, v0, s53
	s_waitcnt vmcnt(24)
	v_bfe_u32 v5, v44, 16, 1
	v_lshrrev_b32_e32 v0, 16, v0
	v_add3_u32 v5, v44, v5, s53
	v_and_or_b32 v5, v5, s45, v0
	s_waitcnt vmcnt(23)
	v_bfe_u32 v0, v45, 16, 1
	ds_write_b128 v136, v[2:5]
	v_add3_u32 v0, v45, v0, s53
	s_waitcnt vmcnt(22)
	v_bfe_u32 v2, v46, 16, 1
	v_lshrrev_b32_e32 v0, 16, v0
	v_add3_u32 v2, v46, v2, s53
	v_and_or_b32 v2, v2, s45, v0
	s_waitcnt vmcnt(21)
	v_bfe_u32 v0, v47, 16, 1
	v_add3_u32 v0, v47, v0, s53
	s_waitcnt vmcnt(20)
	v_bfe_u32 v3, v48, 16, 1
	v_lshrrev_b32_e32 v0, 16, v0
	v_add3_u32 v3, v48, v3, s53
	v_and_or_b32 v3, v3, s45, v0
	s_waitcnt vmcnt(19)
	v_bfe_u32 v0, v49, 16, 1
	v_add3_u32 v0, v49, v0, s53
	s_waitcnt vmcnt(18)
	v_bfe_u32 v4, v50, 16, 1
	v_lshrrev_b32_e32 v0, 16, v0
	v_add3_u32 v4, v50, v4, s53
	v_and_or_b32 v4, v4, s45, v0
	s_waitcnt vmcnt(17)
	v_bfe_u32 v0, v51, 16, 1
	v_add3_u32 v0, v51, v0, s53
	s_waitcnt vmcnt(16)
	v_bfe_u32 v5, v52, 16, 1
	v_lshrrev_b32_e32 v0, 16, v0
	v_add3_u32 v5, v52, v5, s53
	v_and_or_b32 v5, v5, s45, v0
	s_waitcnt vmcnt(15)
	v_bfe_u32 v0, v53, 16, 1
	ds_write_b128 v137, v[2:5]
	v_add3_u32 v0, v53, v0, s53
	s_waitcnt vmcnt(14)
	v_bfe_u32 v2, v54, 16, 1
	v_lshrrev_b32_e32 v0, 16, v0
	v_add3_u32 v2, v54, v2, s53
	v_and_or_b32 v2, v2, s45, v0
	s_waitcnt vmcnt(13)
	v_bfe_u32 v0, v55, 16, 1
	v_add3_u32 v0, v55, v0, s53
	s_waitcnt vmcnt(12)
	v_bfe_u32 v3, v56, 16, 1
	v_lshrrev_b32_e32 v0, 16, v0
	v_add3_u32 v3, v56, v3, s53
	v_and_or_b32 v3, v3, s45, v0
	s_waitcnt vmcnt(11)
	v_bfe_u32 v0, v57, 16, 1
	v_add3_u32 v0, v57, v0, s53
	s_waitcnt vmcnt(10)
	v_bfe_u32 v4, v58, 16, 1
	v_lshrrev_b32_e32 v0, 16, v0
	v_add3_u32 v4, v58, v4, s53
	v_and_or_b32 v4, v4, s45, v0
	s_waitcnt vmcnt(9)
	v_bfe_u32 v0, v59, 16, 1
	v_add3_u32 v0, v59, v0, s53
	s_waitcnt vmcnt(8)
	v_bfe_u32 v5, v60, 16, 1
	v_lshrrev_b32_e32 v0, 16, v0
	v_add3_u32 v5, v60, v5, s53
	v_and_or_b32 v5, v5, s45, v0
	s_waitcnt vmcnt(7)
	v_bfe_u32 v0, v61, 16, 1
	ds_write_b128 v138, v[2:5]
	v_add3_u32 v0, v61, v0, s53
	s_waitcnt vmcnt(6)
	v_bfe_u32 v2, v64, 16, 1
	v_lshrrev_b32_e32 v0, 16, v0
	v_add3_u32 v2, v64, v2, s53
	v_and_or_b32 v2, v2, s45, v0
	s_waitcnt vmcnt(5)
	v_bfe_u32 v0, v65, 16, 1
	v_add3_u32 v0, v65, v0, s53
	s_waitcnt vmcnt(4)
	v_bfe_u32 v3, v66, 16, 1
	v_lshrrev_b32_e32 v0, 16, v0
	v_add3_u32 v3, v66, v3, s53
	v_and_or_b32 v3, v3, s45, v0
	s_waitcnt vmcnt(3)
	v_bfe_u32 v0, v67, 16, 1
	v_add3_u32 v0, v67, v0, s53
	s_waitcnt vmcnt(2)
	v_bfe_u32 v4, v68, 16, 1
	v_lshrrev_b32_e32 v0, 16, v0
	v_add3_u32 v4, v68, v4, s53
	v_and_or_b32 v4, v4, s45, v0
	s_waitcnt vmcnt(1)
	v_bfe_u32 v0, v69, 16, 1
	v_add3_u32 v0, v69, v0, s53
	s_waitcnt vmcnt(0)
	v_bfe_u32 v5, v70, 16, 1
	v_lshrrev_b32_e32 v0, 16, v0
	v_add3_u32 v5, v70, v5, s53
	v_and_or_b32 v5, v5, s45, v0
	ds_write_b128 v139, v[2:5]
	s_waitcnt lgkmcnt(0)
	v_add_u32_e32 v6, v63, v140
	ds_read_b128 v[2:5], v6
	v_or_b32_e32 v0, s5, v141
	v_lshlrev_b32_e32 v0, 11, v0
	v_lshl_add_u32 v7, s26, 1, v0
	s_and_b32 s17, s17, 0xffff
	v_or_b32_e32 v7, v7, v142
	s_waitcnt lgkmcnt(0)
	buffer_store_dwordx4 v[2:5], v7, s[16:19], 0 offen sc1
	ds_read_b128 v[2:5], v6 offset:1024
	s_lshl_b32 s4, s4, 1
	s_add_i32 s5, s4, 0xffffe780
	v_add_u32_e32 v7, s5, v0
	v_or_b32_e32 v7, v7, v142
	s_waitcnt lgkmcnt(0)
	buffer_store_dwordx4 v[2:5], v7, s[16:19], 0 offen sc1
	ds_read_b128 v[2:5], v6 offset:2048
	s_add_i32 s5, s4, 0x2780
	v_add_u32_e32 v7, s5, v0
	v_or_b32_e32 v7, v7, v142
	s_add_i32 s5, s4, 0x6780
	s_waitcnt lgkmcnt(0)
	buffer_store_dwordx4 v[2:5], v7, s[16:19], 0 offen sc1
	ds_read_b128 v[2:5], v6 offset:3072
	v_add_u32_e32 v7, s5, v0
	v_or_b32_e32 v7, v7, v142
	s_add_i32 s5, s4, 0xa780
	s_waitcnt lgkmcnt(0)
	buffer_store_dwordx4 v[2:5], v7, s[16:19], 0 offen sc1
	ds_read_b128 v[2:5], v6 offset:4096
	v_add_u32_e32 v7, s5, v0
	v_or_b32_e32 v7, v7, v142
	s_add_i32 s5, s4, 0xe780
	s_waitcnt lgkmcnt(0)
	buffer_store_dwordx4 v[2:5], v7, s[16:19], 0 offen sc1
	ds_read_b128 v[2:5], v6 offset:5120
	v_add_u32_e32 v7, s5, v0
	v_or_b32_e32 v7, v7, v142
	s_add_i32 s5, s4, 0x12780
	s_add_i32 s4, s4, 0x16780
	s_waitcnt lgkmcnt(0)
	buffer_store_dwordx4 v[2:5], v7, s[16:19], 0 offen sc1
	ds_read_b128 v[2:5], v6 offset:6144
	v_add_u32_e32 v7, s5, v0
	v_or_b32_e32 v7, v7, v142
	v_add_u32_e32 v0, s4, v0
	v_or_b32_e32 v0, v0, v142
	s_waitcnt lgkmcnt(0)
	buffer_store_dwordx4 v[2:5], v7, s[16:19], 0 offen sc1
	ds_read_b128 v[2:5], v6 offset:7168
	s_waitcnt lgkmcnt(0)
	buffer_store_dwordx4 v[2:5], v0, s[16:19], 0 offen sc1
	s_waitcnt lgkmcnt(0)

.LBB0_467:
	s_andn2_b64 vcc, exec, s[4:5]
	s_cbranch_vccnz .LBB0_469
	s_mov_b32 s4, 19
	s_ashr_i32 s5, s4, 31
	s_add_i32 s26, s25, 0xfffff6f0
	s_lshl_b64 s[4:5], s[4:5], 3
	s_add_u32 s4, s0, s4
	s_addc_u32 s5, s1, s5
	s_mov_b32 s16, 17
	s_load_dwordx2 s[4:5], s[4:5], 0x0
	s_ashr_i32 s17, s16, 31
	s_lshl_b64 s[16:17], s[16:17], 3
	s_add_u32 s16, s0, s16
	s_addc_u32 s17, s1, s17
	s_load_dwordx2 s[16:17], s[16:17], 0x0
	v_lshlrev_b32_e32 v0, 2, v62
	s_waitcnt lgkmcnt(0)
	s_add_u32 s23, s16, 0x1000
	s_addc_u32 s40, s17, 0
	s_lshl_b32 s16, s26, 6
	s_lshl_b32 s41, s26, 1
	s_and_b32 s22, s16, 0x7c0
	s_and_b32 s26, s41, 0x7fffffc0
	s_add_u32 s16, s14, 0x3c00000
	s_addc_u32 s17, s15, 0
	s_lshl_b64 s[42:43], s[26:27], 13
	s_add_u32 s4, s4, s42
	s_addc_u32 s5, s5, s43
	s_lshl_b32 s42, s22, 2
	s_add_u32 s4, s4, s42
	s_addc_u32 s5, s5, 0
	v_lshl_add_u64 v[30:31], s[4:5], 0, v[0:1]
	s_mov_b32 s4, 0x800000
	v_add_co_u32_e32 v2, vcc, s4, v30
	s_mov_b32 s4, 0x802000
	s_nop 0
	v_addc_co_u32_e32 v3, vcc, 0, v31, vcc
	v_add_co_u32_e32 v4, vcc, s4, v30
	s_mov_b32 s4, 0x804000
	s_nop 0
	v_addc_co_u32_e32 v5, vcc, 0, v31, vcc
	v_add_co_u32_e32 v6, vcc, s4, v30
	s_mov_b32 s4, 0x806000
	s_nop 0
	v_addc_co_u32_e32 v7, vcc, 0, v31, vcc
	global_load_dword v2, v[2:3], off sc1 nt
	s_mov_b32 s43, s27
	global_load_dword v4, v[4:5], off sc1 nt
	s_nop 0
	global_load_dword v3, v[6:7], off sc1 nt
	v_add_co_u32_e32 v6, vcc, s4, v30
	s_mov_b32 s4, 0x808000
	s_nop 0
	v_addc_co_u32_e32 v7, vcc, 0, v31, vcc
	global_load_dword v5, v[6:7], off sc1 nt
	v_add_co_u32_e32 v6, vcc, s4, v30
	s_mov_b32 s4, 0x80a000
	s_nop 0
	v_addc_co_u32_e32 v7, vcc, 0, v31, vcc
	v_add_co_u32_e32 v8, vcc, s4, v30
	s_mov_b32 s4, 0x80c000
	s_nop 0
	v_addc_co_u32_e32 v9, vcc, 0, v31, vcc
	v_add_co_u32_e32 v10, vcc, s4, v30
	s_mov_b32 s4, 0x80e000
	s_nop 0
	v_addc_co_u32_e32 v11, vcc, 0, v31, vcc
	global_load_dword v6, v[6:7], off sc1 nt
	s_nop 0
	global_load_dword v8, v[8:9], off sc1 nt
	s_nop 0
	global_load_dword v7, v[10:11], off sc1 nt
	v_add_co_u32_e32 v10, vcc, s4, v30
	s_mov_b32 s4, 0x810000
	s_nop 0
	v_addc_co_u32_e32 v11, vcc, 0, v31, vcc
	global_load_dword v9, v[10:11], off sc1 nt
	v_add_co_u32_e32 v10, vcc, s4, v30
	s_mov_b32 s4, 0x812000
	s_nop 0
	v_addc_co_u32_e32 v11, vcc, 0, v31, vcc
	v_add_co_u32_e32 v12, vcc, s4, v30
	s_mov_b32 s4, 0x814000
	s_nop 0
	v_addc_co_u32_e32 v13, vcc, 0, v31, vcc
	v_add_co_u32_e32 v14, vcc, s4, v30
	s_mov_b32 s4, 0x816000
	s_nop 0
	v_addc_co_u32_e32 v15, vcc, 0, v31, vcc
	global_load_dword v10, v[10:11], off sc1 nt
	s_nop 0
	global_load_dword v12, v[12:13], off sc1 nt
	s_nop 0
	global_load_dword v11, v[14:15], off sc1 nt
	v_add_co_u32_e32 v14, vcc, s4, v30
	s_mov_b32 s4, 0x818000
	s_nop 0
	v_addc_co_u32_e32 v15, vcc, 0, v31, vcc
	global_load_dword v13, v[14:15], off sc1 nt
	v_add_co_u32_e32 v14, vcc, s4, v30
	s_mov_b32 s4, 0x81a000
	s_nop 0
	v_addc_co_u32_e32 v15, vcc, 0, v31, vcc
	global_load_dword v68, v[14:15], off sc1 nt
	v_add_co_u32_e32 v14, vcc, s4, v30
	s_mov_b32 s4, 0x81c000
	s_nop 0
	v_addc_co_u32_e32 v15, vcc, 0, v31, vcc
	global_load_dword v70, v[14:15], off sc1 nt
	v_add_co_u32_e32 v14, vcc, s4, v30
	s_mov_b32 s4, 0x81e000
	s_nop 0
	v_addc_co_u32_e32 v15, vcc, 0, v31, vcc
	global_load_dword v69, v[14:15], off sc1 nt
	v_add_co_u32_e32 v14, vcc, s4, v30
	s_mov_b32 s4, 0x820000
	s_nop 0
	v_addc_co_u32_e32 v15, vcc, 0, v31, vcc
	global_load_dword v71, v[14:15], off sc1 nt
	v_add_co_u32_e32 v14, vcc, s4, v30
	s_mov_b32 s4, 0x822000
	s_nop 0
	v_addc_co_u32_e32 v15, vcc, 0, v31, vcc
	global_load_dword v50, v[14:15], off sc1 nt
	v_add_co_u32_e32 v14, vcc, s4, v30
	s_mov_b32 s4, 0x824000
	s_nop 0
	v_addc_co_u32_e32 v15, vcc, 0, v31, vcc
	global_load_dword v52, v[14:15], off sc1 nt
	v_add_co_u32_e32 v14, vcc, s4, v30
	s_mov_b32 s4, 0x826000
	s_nop 0
	v_addc_co_u32_e32 v15, vcc, 0, v31, vcc
	global_load_dword v51, v[14:15], off sc1 nt
	v_add_co_u32_e32 v14, vcc, s4, v30
	s_mov_b32 s4, 0x828000
	s_nop 0
	v_addc_co_u32_e32 v15, vcc, 0, v31, vcc
	global_load_dword v53, v[14:15], off sc1 nt
	v_add_co_u32_e32 v14, vcc, s4, v30
	s_mov_b32 s4, 0x82a000
	s_nop 0
	v_addc_co_u32_e32 v15, vcc, 0, v31, vcc
	global_load_dword v54, v[14:15], off sc1 nt
	v_add_co_u32_e32 v14, vcc, s4, v30
	s_mov_b32 s4, 0x82c000
	s_nop 0
	v_addc_co_u32_e32 v15, vcc, 0, v31, vcc
	global_load_dword v56, v[14:15], off sc1 nt
	v_add_co_u32_e32 v14, vcc, s4, v30
	s_mov_b32 s4, 0x82e000
	s_nop 0
	v_addc_co_u32_e32 v15, vcc, 0, v31, vcc
	global_load_dword v55, v[14:15], off sc1 nt
	v_add_co_u32_e32 v14, vcc, s4, v30
	s_mov_b32 s4, 0x830000
	s_nop 0
	v_addc_co_u32_e32 v15, vcc, 0, v31, vcc
	global_load_dword v57, v[14:15], off sc1 nt
	v_add_co_u32_e32 v14, vcc, s4, v30
	s_mov_b32 s4, 0x832000
	s_nop 0
	v_addc_co_u32_e32 v15, vcc, 0, v31, vcc
	global_load_dword v58, v[14:15], off sc1 nt
	v_add_co_u32_e32 v14, vcc, s4, v30
	s_mov_b32 s4, 0x834000
	s_nop 0
	v_addc_co_u32_e32 v15, vcc, 0, v31, vcc
	global_load_dword v60, v[14:15], off sc1 nt
	v_add_co_u32_e32 v14, vcc, s4, v30
	s_mov_b32 s4, 0x836000
	s_nop 0
	v_addc_co_u32_e32 v15, vcc, 0, v31, vcc
	global_load_dword v59, v[14:15], off sc1 nt
	v_add_co_u32_e32 v14, vcc, s4, v30
	s_mov_b32 s4, 0x838000
	s_nop 0
	v_addc_co_u32_e32 v15, vcc, 0, v31, vcc
	global_load_dword v61, v[14:15], off sc1 nt
	v_add_co_u32_e32 v14, vcc, s4, v30
	s_mov_b32 s4, 0x83a000
	s_nop 0
	v_addc_co_u32_e32 v15, vcc, 0, v31, vcc
	global_load_dword v64, v[14:15], off sc1 nt
	v_add_co_u32_e32 v14, vcc, s4, v30
	s_mov_b32 s4, 0x83c000
	s_nop 0
	v_addc_co_u32_e32 v15, vcc, 0, v31, vcc
	global_load_dword v66, v[14:15], off sc1 nt
	v_add_co_u32_e32 v14, vcc, s4, v30
	s_mov_b32 s4, 0x83e000
	s_nop 0
	v_addc_co_u32_e32 v15, vcc, 0, v31, vcc
	global_load_dword v65, v[14:15], off sc1 nt
	v_add_co_u32_e32 v14, vcc, s4, v30
	s_mov_b32 s4, 0x840000
	s_nop 0
	v_addc_co_u32_e32 v15, vcc, 0, v31, vcc
	global_load_dword v67, v[14:15], off sc1 nt
	v_add_co_u32_e32 v14, vcc, s4, v30
	s_mov_b32 s4, 0x842000
	s_nop 0
	v_addc_co_u32_e32 v15, vcc, 0, v31, vcc
	global_load_dword v34, v[14:15], off sc1 nt
	v_add_co_u32_e32 v14, vcc, s4, v30
	s_mov_b32 s4, 0x844000
	s_nop 0
	v_addc_co_u32_e32 v15, vcc, 0, v31, vcc
	global_load_dword v36, v[14:15], off sc1 nt
	v_add_co_u32_e32 v14, vcc, s4, v30
	s_mov_b32 s4, 0x846000
	s_nop 0
	v_addc_co_u32_e32 v15, vcc, 0, v31, vcc
	global_load_dword v35, v[14:15], off sc1 nt
	v_add_co_u32_e32 v14, vcc, s4, v30
	s_mov_b32 s4, 0x848000
	s_nop 0
	v_addc_co_u32_e32 v15, vcc, 0, v31, vcc
	global_load_dword v37, v[14:15], off sc1 nt
	v_add_co_u32_e32 v14, vcc, s4, v30
	s_mov_b32 s4, 0x84a000
	s_nop 0
	v_addc_co_u32_e32 v15, vcc, 0, v31, vcc
	global_load_dword v38, v[14:15], off sc1 nt
	v_add_co_u32_e32 v14, vcc, s4, v30
	s_mov_b32 s4, 0x84c000
	s_nop 0
	v_addc_co_u32_e32 v15, vcc, 0, v31, vcc
	global_load_dword v40, v[14:15], off sc1 nt
	v_add_co_u32_e32 v14, vcc, s4, v30
	s_mov_b32 s4, 0x84e000
	s_nop 0
	v_addc_co_u32_e32 v15, vcc, 0, v31, vcc
	global_load_dword v39, v[14:15], off sc1 nt
	v_add_co_u32_e32 v14, vcc, s4, v30
	s_mov_b32 s4, 0x850000
	s_nop 0
	v_addc_co_u32_e32 v15, vcc, 0, v31, vcc
	global_load_dword v41, v[14:15], off sc1 nt
	v_add_co_u32_e32 v14, vcc, s4, v30
	s_mov_b32 s4, 0x852000
	s_nop 0
	v_addc_co_u32_e32 v15, vcc, 0, v31, vcc
	global_load_dword v42, v[14:15], off sc1 nt
	v_add_co_u32_e32 v14, vcc, s4, v30
	s_mov_b32 s4, 0x854000
	s_nop 0
	v_addc_co_u32_e32 v15, vcc, 0, v31, vcc
	global_load_dword v44, v[14:15], off sc1 nt
	v_add_co_u32_e32 v14, vcc, s4, v30
	s_mov_b32 s4, 0x856000
	s_nop 0
	v_addc_co_u32_e32 v15, vcc, 0, v31, vcc
	global_load_dword v43, v[14:15], off sc1 nt
	v_add_co_u32_e32 v14, vcc, s4, v30
	s_mov_b32 s4, 0x858000
	s_nop 0
	v_addc_co_u32_e32 v15, vcc, 0, v31, vcc
	global_load_dword v45, v[14:15], off sc1 nt
	v_add_co_u32_e32 v14, vcc, s4, v30
	s_mov_b32 s4, 0x85a000
	s_nop 0
	v_addc_co_u32_e32 v15, vcc, 0, v31, vcc
	global_load_dword v46, v[14:15], off sc1 nt
	v_add_co_u32_e32 v14, vcc, s4, v30
	s_mov_b32 s4, 0x85c000
	s_nop 0
	v_addc_co_u32_e32 v15, vcc, 0, v31, vcc
	global_load_dword v48, v[14:15], off sc1 nt
	v_add_co_u32_e32 v14, vcc, s4, v30
	s_mov_b32 s4, 0x85e000
	s_nop 0
	v_addc_co_u32_e32 v15, vcc, 0, v31, vcc
	global_load_dword v47, v[14:15], off sc1 nt
	v_add_co_u32_e32 v14, vcc, s4, v30
	s_mov_b32 s4, 0x860000
	s_nop 0
	v_addc_co_u32_e32 v15, vcc, 0, v31, vcc
	global_load_dword v49, v[14:15], off sc1 nt
	v_add_co_u32_e32 v14, vcc, s4, v30
	s_mov_b32 s4, 0x862000
	s_nop 0
	v_addc_co_u32_e32 v15, vcc, 0, v31, vcc
	global_load_dword v18, v[14:15], off sc1 nt
	v_add_co_u32_e32 v14, vcc, s4, v30
	s_mov_b32 s4, 0x864000
	s_nop 0
	v_addc_co_u32_e32 v15, vcc, 0, v31, vcc
	global_load_dword v22, v[14:15], off sc1 nt
	v_add_co_u32_e32 v14, vcc, s4, v30
	s_mov_b32 s4, 0x866000
	s_nop 0
	v_addc_co_u32_e32 v15, vcc, 0, v31, vcc
	global_load_dword v19, v[14:15], off sc1 nt
	v_add_co_u32_e32 v14, vcc, s4, v30
	s_mov_b32 s4, 0x868000
	s_nop 0
	v_addc_co_u32_e32 v15, vcc, 0, v31, vcc
	global_load_dword v23, v[14:15], off sc1 nt
	v_add_co_u32_e32 v14, vcc, s4, v30
	s_mov_b32 s4, 0x86a000
	s_nop 0
	v_addc_co_u32_e32 v15, vcc, 0, v31, vcc
	global_load_dword v28, v[14:15], off sc1 nt
	v_add_co_u32_e32 v14, vcc, s4, v30
	s_mov_b32 s4, 0x86c000
	s_nop 0
	v_addc_co_u32_e32 v15, vcc, 0, v31, vcc
	global_load_dword v26, v[14:15], off sc1 nt
	v_add_co_u32_e32 v14, vcc, s4, v30
	s_mov_b32 s4, 0x86e000
	s_nop 0
	v_addc_co_u32_e32 v15, vcc, 0, v31, vcc
	global_load_dword v29, v[14:15], off sc1 nt
	v_add_co_u32_e32 v14, vcc, s4, v30
	s_mov_b32 s4, 0x870000
	s_nop 0
	v_addc_co_u32_e32 v15, vcc, 0, v31, vcc
	global_load_dword v27, v[14:15], off sc1 nt
	v_add_co_u32_e32 v14, vcc, s4, v30
	s_mov_b32 s4, 0x872000
	s_nop 0
	v_addc_co_u32_e32 v15, vcc, 0, v31, vcc
	global_load_dword v16, v[14:15], off sc1 nt
	v_add_co_u32_e32 v14, vcc, s4, v30
	s_mov_b32 s4, 0x874000
	s_nop 0
	v_addc_co_u32_e32 v15, vcc, 0, v31, vcc
	v_add_co_u32_e32 v20, vcc, s4, v30
	s_mov_b32 s4, 0x876000
	s_nop 0
	v_addc_co_u32_e32 v21, vcc, 0, v31, vcc
	global_load_dword v14, v[14:15], off sc1 nt
	s_nop 0
	global_load_dword v17, v[20:21], off sc1 nt
	v_add_co_u32_e32 v20, vcc, s4, v30
	s_mov_b32 s4, 0x878000
	s_nop 0
	v_addc_co_u32_e32 v21, vcc, 0, v31, vcc
	global_load_dword v15, v[20:21], off sc1 nt
	v_add_co_u32_e32 v20, vcc, s4, v30
	s_mov_b32 s4, 0x87a000
	s_nop 0
	v_addc_co_u32_e32 v21, vcc, 0, v31, vcc
	global_load_dword v24, v[20:21], off sc1 nt
	v_add_co_u32_e32 v20, vcc, s4, v30
	s_mov_b32 s4, 0x87c000
	s_nop 0
	v_addc_co_u32_e32 v21, vcc, 0, v31, vcc
	v_add_co_u32_e32 v32, vcc, s4, v30
	s_mov_b32 s4, 0x87e000
	s_nop 0
	v_addc_co_u32_e32 v33, vcc, 0, v31, vcc
	v_add_co_u32_e32 v30, vcc, s4, v30
	s_lshl_b64 s[4:5], s[26:27], 2
	s_add_u32 s4, s23, s4
	s_addc_u32 s5, s40, s5
	s_or_b32 s42, s41, 62
	s_lshl_b64 s[42:43], s[42:43], 2
	s_add_u32 s42, s23, s42
	s_addc_u32 s43, s40, s43
	global_load_dword v20, v[20:21], off sc1 nt
	v_addc_co_u32_e32 v31, vcc, 0, v31, vcc
	global_load_dword v25, v[32:33], off sc1 nt
	global_load_dword v21, v[30:31], off sc1 nt
	s_nop 0
	global_load_dword v33, v1, s[42:43] sc1
	s_or_b32 s42, s41, 63
	s_mov_b32 s43, s27
	s_lshl_b64 s[42:43], s[42:43], 2
	s_add_u32 s42, s23, s42
	s_addc_u32 s43, s40, s43
	global_load_dword v31, v1, s[42:43] sc1
	global_load_dwordx4 v[72:75], v1, s[4:5] offset:48 sc1
	global_load_dwordx4 v[76:79], v1, s[4:5] offset:32 sc1
	global_load_dwordx4 v[80:83], v1, s[4:5] offset:16 sc1
	global_load_dwordx4 v[84:87], v1, s[4:5] sc1
	s_and_b32 s17, s17, 0xffff
	s_waitcnt vmcnt(0)
	v_mov_b32_e32 v89, v86
	v_mov_b32_e32 v86, v85
	v_mov_b32_e32 v85, v82
	v_mov_b32_e32 v82, v81
	v_mov_b32_e32 v88, v84
	v_pk_mul_f32 v[4:5], v[4:5], v[86:87]
	v_mov_b32_e32 v84, v80
	v_pk_mul_f32 v[8:9], v[8:9], v[82:83]
	v_pk_mul_f32 v[2:3], v[2:3], v[88:89]
	v_pk_mul_f32 v[6:7], v[6:7], v[84:85]
	v_bfe_u32 v0, v9, 16, 1
	v_bfe_u32 v30, v8, 16, 1
	v_bfe_u32 v32, v5, 16, 1
	v_bfe_u32 v80, v4, 16, 1
	v_add3_u32 v80, v4, v80, s53
	v_add3_u32 v32, v5, v32, s53
	v_add3_u32 v4, v8, v30, s53
	v_add3_u32 v0, v9, v0, s53
	v_bfe_u32 v5, v2, 16, 1
	v_bfe_u32 v8, v3, 16, 1
	v_bfe_u32 v9, v6, 16, 1
	v_bfe_u32 v30, v7, 16, 1
	v_add3_u32 v7, v7, v30, s53
	v_add3_u32 v6, v6, v9, s53
	v_add3_u32 v3, v3, v8, s53
	v_add3_u32 v2, v2, v5, s53
	v_lshrrev_b32_e32 v2, 16, v2
	v_lshrrev_b32_e32 v3, 16, v3
	v_lshrrev_b32_e32 v6, 16, v6
	v_lshrrev_b32_e32 v5, 16, v7
	v_and_or_b32 v5, v0, s45, v5
	v_and_or_b32 v4, v4, s45, v6
	v_and_or_b32 v3, v32, s45, v3
	v_and_or_b32 v2, v80, s45, v2
	ds_write_b128 v132, v[2:5]
	v_mov_b32_e32 v3, v78
	v_mov_b32_e32 v78, v77
	v_mov_b32_e32 v7, v74
	v_mov_b32_e32 v74, v73
	v_mov_b32_e32 v2, v76
	v_pk_mul_f32 v[4:5], v[12:13], v[78:79]
	v_mov_b32_e32 v6, v72
	v_pk_mul_f32 v[8:9], v[70:71], v[74:75]
	v_pk_mul_f32 v[2:3], v[10:11], v[2:3]
	v_pk_mul_f32 v[6:7], v[68:69], v[6:7]
	v_bfe_u32 v0, v9, 16, 1
	v_bfe_u32 v10, v8, 16, 1
	v_bfe_u32 v11, v5, 16, 1
	v_bfe_u32 v12, v4, 16, 1
	v_add3_u32 v12, v4, v12, s53
	v_add3_u32 v11, v5, v11, s53
	v_add3_u32 v4, v8, v10, s53
	v_add3_u32 v0, v9, v0, s53
	v_bfe_u32 v5, v2, 16, 1
	v_bfe_u32 v8, v3, 16, 1
	v_bfe_u32 v9, v6, 16, 1
	v_bfe_u32 v10, v7, 16, 1
	v_add3_u32 v7, v7, v10, s53
	v_add3_u32 v6, v6, v9, s53
	v_add3_u32 v3, v3, v8, s53
	v_add3_u32 v2, v2, v5, s53
	v_lshrrev_b32_e32 v2, 16, v2
	v_lshrrev_b32_e32 v3, 16, v3
	v_lshrrev_b32_e32 v6, 16, v6
	v_lshrrev_b32_e32 v5, 16, v7
	v_and_or_b32 v5, v0, s45, v5
	v_and_or_b32 v4, v4, s45, v6
	v_and_or_b32 v3, v11, s45, v3
	v_and_or_b32 v2, v12, s45, v2
	ds_write_b128 v133, v[2:5]
	global_load_dwordx4 v[2:5], v1, s[4:5] offset:112 sc1
	global_load_dwordx4 v[6:9], v1, s[4:5] offset:96 sc1
	global_load_dwordx4 v[10:13], v1, s[4:5] offset:80 sc1
	global_load_dwordx4 v[68:71], v1, s[4:5] offset:64 sc1
	s_waitcnt vmcnt(0)
	v_mov_b32_e32 v73, v70
	v_mov_b32_e32 v70, v69
	v_mov_b32_e32 v69, v12
	v_mov_b32_e32 v12, v11
	v_mov_b32_e32 v72, v68
	v_pk_mul_f32 v[52:53], v[52:53], v[70:71]
	v_mov_b32_e32 v68, v10
	v_pk_mul_f32 v[10:11], v[56:57], v[12:13]
	v_pk_mul_f32 v[50:51], v[50:51], v[72:73]
	v_pk_mul_f32 v[54:55], v[54:55], v[68:69]
	v_bfe_u32 v0, v11, 16, 1
	v_bfe_u32 v12, v10, 16, 1
	v_bfe_u32 v13, v53, 16, 1
	v_bfe_u32 v30, v52, 16, 1
	v_add3_u32 v30, v52, v30, s53
	v_add3_u32 v32, v53, v13, s53
	v_add3_u32 v10, v10, v12, s53
	v_add3_u32 v0, v11, v0, s53
	v_bfe_u32 v11, v50, 16, 1
	v_bfe_u32 v12, v51, 16, 1
	v_bfe_u32 v13, v54, 16, 1
	v_bfe_u32 v52, v55, 16, 1
	v_add3_u32 v52, v55, v52, s53
	v_add3_u32 v13, v54, v13, s53
	v_add3_u32 v12, v51, v12, s53
	v_add3_u32 v11, v50, v11, s53
	v_lshrrev_b32_e32 v50, 16, v11
	v_lshrrev_b32_e32 v11, 16, v12
	v_lshrrev_b32_e32 v12, 16, v13
	v_lshrrev_b32_e32 v13, 16, v52
	v_and_or_b32 v13, v0, s45, v13
	v_and_or_b32 v12, v10, s45, v12
	v_and_or_b32 v11, v32, s45, v11
	v_and_or_b32 v10, v30, s45, v50
	ds_write_b128 v134, v[10:13]
	v_mov_b32_e32 v11, v8
	v_mov_b32_e32 v8, v7
	v_mov_b32_e32 v10, v6
	v_pk_mul_f32 v[6:7], v[60:61], v[8:9]
	v_mov_b32_e32 v9, v4
	v_mov_b32_e32 v4, v3
	v_mov_b32_e32 v8, v2
	v_pk_mul_f32 v[2:3], v[66:67], v[4:5]
	v_pk_mul_f32 v[10:11], v[58:59], v[10:11]
	v_pk_mul_f32 v[8:9], v[64:65], v[8:9]
	v_bfe_u32 v0, v3, 16, 1
	v_bfe_u32 v4, v2, 16, 1
	v_bfe_u32 v5, v7, 16, 1
	v_bfe_u32 v12, v6, 16, 1
	v_add3_u32 v6, v6, v12, s53
	v_add3_u32 v7, v7, v5, s53
	v_add3_u32 v2, v2, v4, s53
	v_add3_u32 v0, v3, v0, s53
	v_bfe_u32 v3, v10, 16, 1
	v_bfe_u32 v4, v11, 16, 1
	v_bfe_u32 v5, v8, 16, 1
	v_bfe_u32 v12, v9, 16, 1
	v_add3_u32 v9, v9, v12, s53
	v_add3_u32 v5, v8, v5, s53
	v_add3_u32 v4, v11, v4, s53
	v_add3_u32 v3, v10, v3, s53
	v_lshrrev_b32_e32 v8, 16, v3
	v_lshrrev_b32_e32 v3, 16, v4
	v_lshrrev_b32_e32 v4, 16, v5
	v_lshrrev_b32_e32 v5, 16, v9
	v_and_or_b32 v5, v0, s45, v5
	v_and_or_b32 v4, v2, s45, v4
	v_and_or_b32 v3, v7, s45, v3
	v_and_or_b32 v2, v6, s45, v8
	ds_write_b128 v135, v[2:5]
	global_load_dwordx4 v[2:5], v1, s[4:5] offset:176 sc1
	global_load_dwordx4 v[6:9], v1, s[4:5] offset:160 sc1
	global_load_dwordx4 v[10:13], v1, s[4:5] offset:144 sc1
	global_load_dwordx4 v[50:53], v1, s[4:5] offset:128 sc1
	s_waitcnt vmcnt(0)
	v_mov_b32_e32 v55, v52
	v_mov_b32_e32 v52, v51
	v_mov_b32_e32 v51, v12
	v_mov_b32_e32 v12, v11
	v_mov_b32_e32 v54, v50
	v_pk_mul_f32 v[36:37], v[36:37], v[52:53]
	v_mov_b32_e32 v50, v10
	v_pk_mul_f32 v[10:11], v[40:41], v[12:13]
	v_pk_mul_f32 v[34:35], v[34:35], v[54:55]
	v_pk_mul_f32 v[38:39], v[38:39], v[50:51]
	v_bfe_u32 v0, v11, 16, 1
	v_bfe_u32 v12, v10, 16, 1
	v_bfe_u32 v13, v37, 16, 1
	v_bfe_u32 v30, v36, 16, 1
	v_add3_u32 v30, v36, v30, s53
	v_add3_u32 v32, v37, v13, s53
	v_add3_u32 v10, v10, v12, s53
	v_add3_u32 v0, v11, v0, s53
	v_bfe_u32 v11, v34, 16, 1
	v_bfe_u32 v12, v35, 16, 1
	v_bfe_u32 v13, v38, 16, 1
	v_bfe_u32 v36, v39, 16, 1
	v_add3_u32 v36, v39, v36, s53
	v_add3_u32 v13, v38, v13, s53
	v_add3_u32 v12, v35, v12, s53
	v_add3_u32 v11, v34, v11, s53
	v_lshrrev_b32_e32 v34, 16, v11
	v_lshrrev_b32_e32 v11, 16, v12
	v_lshrrev_b32_e32 v12, 16, v13
	v_lshrrev_b32_e32 v13, 16, v36
	v_and_or_b32 v13, v0, s45, v13
	v_and_or_b32 v12, v10, s45, v12
	v_and_or_b32 v11, v32, s45, v11
	v_and_or_b32 v10, v30, s45, v34
	ds_write_b128 v136, v[10:13]
	v_mov_b32_e32 v11, v8
	v_mov_b32_e32 v8, v7
	v_mov_b32_e32 v10, v6
	v_pk_mul_f32 v[6:7], v[44:45], v[8:9]
	v_mov_b32_e32 v9, v4
	v_mov_b32_e32 v4, v3
	v_mov_b32_e32 v8, v2
	v_pk_mul_f32 v[2:3], v[48:49], v[4:5]
	v_pk_mul_f32 v[10:11], v[42:43], v[10:11]
	v_pk_mul_f32 v[8:9], v[46:47], v[8:9]
	v_bfe_u32 v0, v3, 16, 1
	v_bfe_u32 v4, v2, 16, 1
	v_bfe_u32 v5, v7, 16, 1
	v_bfe_u32 v12, v6, 16, 1
	v_add3_u32 v6, v6, v12, s53
	v_add3_u32 v7, v7, v5, s53
	v_add3_u32 v2, v2, v4, s53
	v_add3_u32 v0, v3, v0, s53
	v_bfe_u32 v3, v10, 16, 1
	v_bfe_u32 v4, v11, 16, 1
	v_bfe_u32 v5, v8, 16, 1
	v_bfe_u32 v12, v9, 16, 1
	v_add3_u32 v9, v9, v12, s53
	v_add3_u32 v5, v8, v5, s53
	v_add3_u32 v4, v11, v4, s53
	v_add3_u32 v3, v10, v3, s53
	v_lshrrev_b32_e32 v8, 16, v3
	v_lshrrev_b32_e32 v3, 16, v4
	v_lshrrev_b32_e32 v4, 16, v5
	v_lshrrev_b32_e32 v5, 16, v9
	v_and_or_b32 v5, v0, s45, v5
	v_and_or_b32 v4, v2, s45, v4
	v_and_or_b32 v3, v7, s45, v3
	v_and_or_b32 v2, v6, s45, v8
	ds_write_b128 v137, v[2:5]
	global_load_dwordx4 v[2:5], v1, s[4:5] offset:224 sc1
	global_load_dwordx4 v[6:9], v1, s[4:5] offset:208 sc1
	global_load_dwordx4 v[10:13], v1, s[4:5] offset:192 sc1
	global_load_dwordx2 v[34:35], v1, s[4:5] offset:240 sc1
	s_lshl_b32 s4, s26, 1
	s_add_i32 s5, s4, 0x4000
	s_waitcnt vmcnt(1)
	v_mov_b32_e32 v37, v12
	v_mov_b32_e32 v12, v11
	v_mov_b32_e32 v36, v10
	v_pk_mul_f32 v[10:11], v[22:23], v[12:13]
	v_mov_b32_e32 v13, v8
	v_mov_b32_e32 v8, v7
	v_mov_b32_e32 v12, v6
	v_pk_mul_f32 v[6:7], v[26:27], v[8:9]
	v_pk_mul_f32 v[18:19], v[18:19], v[36:37]
	v_pk_mul_f32 v[12:13], v[28:29], v[12:13]
	v_bfe_u32 v0, v7, 16, 1
	v_bfe_u32 v8, v6, 16, 1
	v_bfe_u32 v9, v11, 16, 1
	v_bfe_u32 v22, v10, 16, 1
	v_add3_u32 v10, v10, v22, s53
	v_add3_u32 v11, v11, v9, s53
	v_add3_u32 v6, v6, v8, s53
	v_add3_u32 v0, v7, v0, s53
	v_bfe_u32 v7, v18, 16, 1
	v_bfe_u32 v8, v19, 16, 1
	v_bfe_u32 v9, v12, 16, 1
	v_bfe_u32 v22, v13, 16, 1
	v_add3_u32 v13, v13, v22, s53
	v_add3_u32 v9, v12, v9, s53
	v_add3_u32 v8, v19, v8, s53
	v_add3_u32 v7, v18, v7, s53
	v_lshrrev_b32_e32 v12, 16, v7
	v_lshrrev_b32_e32 v7, 16, v8
	v_lshrrev_b32_e32 v8, 16, v9
	v_lshrrev_b32_e32 v9, 16, v13
	v_and_or_b32 v9, v0, s45, v9
	v_and_or_b32 v8, v6, s45, v8
	v_and_or_b32 v7, v11, s45, v7
	v_and_or_b32 v6, v10, s45, v12
	ds_write_b128 v138, v[6:9]
	v_mov_b32_e32 v7, v4
	v_mov_b32_e32 v4, v3
	s_waitcnt vmcnt(0)
	v_mov_b32_e32 v30, v35
	v_mov_b32_e32 v6, v2
	v_pk_mul_f32 v[2:3], v[14:15], v[4:5]
	v_mov_b32_e32 v32, v34
	v_pk_mul_f32 v[8:9], v[20:21], v[30:31]
	v_pk_mul_f32 v[6:7], v[16:17], v[6:7]
	v_pk_mul_f32 v[4:5], v[24:25], v[32:33]
	v_bfe_u32 v0, v3, 16, 1
	v_bfe_u32 v10, v2, 16, 1
	v_bfe_u32 v11, v9, 16, 1
	v_bfe_u32 v12, v8, 16, 1
	v_add3_u32 v8, v8, v12, s53
	v_add3_u32 v9, v9, v11, s53
	v_add3_u32 v2, v2, v10, s53
	v_add3_u32 v0, v3, v0, s53
	v_bfe_u32 v3, v4, 16, 1
	v_bfe_u32 v10, v5, 16, 1
	v_bfe_u32 v11, v6, 16, 1
	v_bfe_u32 v12, v7, 16, 1
	v_add3_u32 v7, v7, v12, s53
	v_add3_u32 v6, v6, v11, s53
	v_add3_u32 v5, v5, v10, s53
	v_add3_u32 v3, v4, v3, s53
	v_lshrrev_b32_e32 v4, 16, v3
	v_lshrrev_b32_e32 v5, 16, v5
	v_lshrrev_b32_e32 v6, 16, v6
	v_lshrrev_b32_e32 v3, 16, v7
	v_and_or_b32 v3, v0, s45, v3
	v_and_or_b32 v2, v2, s45, v6
	v_and_or_b32 v5, v9, s45, v5
	v_and_or_b32 v4, v8, s45, v4
	ds_write_b128 v139, v[2:5]
	s_waitcnt lgkmcnt(0)
	v_add_u32_e32 v6, v63, v140
	ds_read_b128 v[2:5], v6
	v_or_b32_e32 v0, s22, v141
	v_lshlrev_b32_e32 v0, 11, v0
	v_add_u32_e32 v7, s4, v0
	v_or_b32_e32 v7, v7, v142
	s_waitcnt lgkmcnt(0)
	buffer_store_dwordx4 v[2:5], v7, s[16:19], 0 offen sc1
	ds_read_b128 v[2:5], v6 offset:1024
	v_add_u32_e32 v7, s5, v0
	v_or_b32_e32 v7, v7, v142
	s_add_i32 s5, s4, 0x8000
	s_waitcnt lgkmcnt(0)
	buffer_store_dwordx4 v[2:5], v7, s[16:19], 0 offen sc1
	ds_read_b128 v[2:5], v6 offset:2048
	v_add_u32_e32 v7, s5, v0
	v_or_b32_e32 v7, v7, v142
	s_add_i32 s5, s4, 0xc000
	s_waitcnt lgkmcnt(0)
	buffer_store_dwordx4 v[2:5], v7, s[16:19], 0 offen sc1
	ds_read_b128 v[2:5], v6 offset:3072
	v_add_u32_e32 v7, s5, v0
	v_or_b32_e32 v7, v7, v142
	s_add_i32 s5, s4, 0x10000
	s_waitcnt lgkmcnt(0)
	buffer_store_dwordx4 v[2:5], v7, s[16:19], 0 offen sc1
	ds_read_b128 v[2:5], v6 offset:4096
	v_add_u32_e32 v7, s5, v0
	v_or_b32_e32 v7, v7, v142
	s_add_i32 s5, s4, 0x14000
	s_waitcnt lgkmcnt(0)
	buffer_store_dwordx4 v[2:5], v7, s[16:19], 0 offen sc1
	ds_read_b128 v[2:5], v6 offset:5120
	v_add_u32_e32 v7, s5, v0
	v_or_b32_e32 v7, v7, v142
	s_add_i32 s5, s4, 0x18000
	s_add_i32 s4, s4, 0x1c000
	s_waitcnt lgkmcnt(0)
	buffer_store_dwordx4 v[2:5], v7, s[16:19], 0 offen sc1
	ds_read_b128 v[2:5], v6 offset:6144
	v_add_u32_e32 v7, s5, v0
	v_or_b32_e32 v7, v7, v142
	v_add_u32_e32 v0, s4, v0
	v_or_b32_e32 v0, v0, v142
	s_waitcnt lgkmcnt(0)
	buffer_store_dwordx4 v[2:5], v7, s[16:19], 0 offen sc1
	ds_read_b128 v[2:5], v6 offset:7168
	s_waitcnt lgkmcnt(0)
	buffer_store_dwordx4 v[2:5], v0, s[16:19], 0 offen sc1
	s_waitcnt lgkmcnt(0)

.LBB0_470:
	s_andn2_b64 vcc, exec, s[4:5]
	s_cbranch_vccnz .LBB0_472
	s_mov_b32 s4, 15
	s_ashr_i32 s5, s4, 31
	s_lshl_b64 s[4:5], s[4:5], 3
	s_add_u32 s4, s0, s4
	s_addc_u32 s5, s1, s5
	s_load_dwordx2 s[42:43], s[4:5], 0x0
	s_lshl_b32 s4, s25, 6
	s_and_b32 s41, s4, 0x3c0
	s_lshl_b32 s4, s25, 2
	s_and_b32 s40, s4, 0x3fc0
	s_mov_b32 s4, 13
	s_ashr_i32 s5, s4, 31
	s_add_i32 s26, s40, 0xffffdfc0
	s_lshl_b64 s[4:5], s[4:5], 3
	s_add_u32 s4, s0, s4
	s_addc_u32 s5, s1, s5
	s_mov_b32 s16, 14
	s_load_dwordx2 s[4:5], s[4:5], 0x0
	s_ashr_i32 s17, s16, 31
	s_lshl_b64 s[16:17], s[16:17], 3
	s_add_u32 s16, s0, s16
	s_addc_u32 s17, s1, s17
	s_load_dwordx2 s[22:23], s[16:17], 0x0
	s_add_u32 s16, s14, 0x3800000
	s_addc_u32 s17, s15, 0
	s_lshl_b64 s[46:47], s[26:27], 12
	s_waitcnt lgkmcnt(0)
	s_add_u32 s42, s42, s46
	s_addc_u32 s43, s43, s47
	s_lshl_b32 s46, s41, 2
	s_add_u32 s42, s42, s46
	s_addc_u32 s43, s43, 0
	v_lshlrev_b32_e32 v0, 2, v62
	v_lshl_add_u64 v[68:69], s[42:43], 0, v[0:1]
	s_mov_b32 s42, 0x401000
	v_add_co_u32_e32 v2, vcc, s42, v68
	s_mov_b32 s42, 0x403000
	s_nop 0
	v_addc_co_u32_e32 v3, vcc, 0, v69, vcc
	v_add_co_u32_e32 v6, vcc, s42, v68
	s_mov_b32 s42, 0x405000
	s_nop 0
	v_addc_co_u32_e32 v7, vcc, 0, v69, vcc
	global_load_dword v4, v[2:3], off offset:-4096 sc1 nt
	s_nop 0
	global_load_dword v2, v[2:3], off sc1 nt
	s_nop 0
	global_load_dword v5, v[6:7], off offset:-4096 sc1 nt
	global_load_dword v3, v[6:7], off sc1 nt
	v_add_co_u32_e32 v6, vcc, s42, v68
	s_mov_b32 s42, 0x407000
	s_nop 0
	v_addc_co_u32_e32 v7, vcc, 0, v69, vcc
	global_load_dword v12, v[6:7], off offset:-4096 sc1 nt
	global_load_dword v8, v[6:7], off sc1 nt
	v_add_co_u32_e32 v6, vcc, s42, v68
	s_mov_b32 s42, 0x409000
	s_nop 0
	v_addc_co_u32_e32 v7, vcc, 0, v69, vcc
	global_load_dword v13, v[6:7], off offset:-4096 sc1 nt
	global_load_dword v9, v[6:7], off sc1 nt
	v_add_co_u32_e32 v6, vcc, s42, v68
	s_mov_b32 s42, 0x40b000
	s_nop 0
	v_addc_co_u32_e32 v7, vcc, 0, v69, vcc
	v_add_co_u32_e32 v14, vcc, s42, v68
	s_mov_b32 s42, 0x40d000
	s_nop 0
	v_addc_co_u32_e32 v15, vcc, 0, v69, vcc
	global_load_dword v10, v[6:7], off offset:-4096 sc1 nt
	s_nop 0
	global_load_dword v6, v[6:7], off sc1 nt
	s_nop 0
	global_load_dword v11, v[14:15], off offset:-4096 sc1 nt
	global_load_dword v7, v[14:15], off sc1 nt
	v_add_co_u32_e32 v14, vcc, s42, v68
	s_mov_b32 s42, 0x40f000
	s_nop 0
	v_addc_co_u32_e32 v15, vcc, 0, v69, vcc
	global_load_dword v20, v[14:15], off offset:-4096 sc1 nt
	global_load_dword v16, v[14:15], off sc1 nt
	v_add_co_u32_e32 v14, vcc, s42, v68
	s_mov_b32 s42, 0x411000
	s_nop 0
	v_addc_co_u32_e32 v15, vcc, 0, v69, vcc
	global_load_dword v21, v[14:15], off offset:-4096 sc1 nt
	global_load_dword v17, v[14:15], off sc1 nt
	v_add_co_u32_e32 v14, vcc, s42, v68
	s_mov_b32 s42, 0x413000
	s_nop 0
	v_addc_co_u32_e32 v15, vcc, 0, v69, vcc
	v_add_co_u32_e32 v22, vcc, s42, v68
	s_mov_b32 s42, 0x415000
	s_nop 0
	v_addc_co_u32_e32 v23, vcc, 0, v69, vcc
	global_load_dword v18, v[14:15], off offset:-4096 sc1 nt
	s_nop 0
	global_load_dword v14, v[14:15], off sc1 nt
	s_nop 0
	global_load_dword v19, v[22:23], off offset:-4096 sc1 nt
	global_load_dword v15, v[22:23], off sc1 nt
	v_add_co_u32_e32 v22, vcc, s42, v68
	s_mov_b32 s42, 0x417000
	s_nop 0
	v_addc_co_u32_e32 v23, vcc, 0, v69, vcc
	global_load_dword v28, v[22:23], off offset:-4096 sc1 nt
	global_load_dword v24, v[22:23], off sc1 nt
	v_add_co_u32_e32 v22, vcc, s42, v68
	s_mov_b32 s42, 0x419000
	s_nop 0
	v_addc_co_u32_e32 v23, vcc, 0, v69, vcc
	global_load_dword v29, v[22:23], off offset:-4096 sc1 nt
	global_load_dword v25, v[22:23], off sc1 nt
	v_add_co_u32_e32 v22, vcc, s42, v68
	s_mov_b32 s42, 0x41b000
	s_nop 0
	v_addc_co_u32_e32 v23, vcc, 0, v69, vcc
	v_add_co_u32_e32 v30, vcc, s42, v68
	s_mov_b32 s42, 0x41d000
	s_nop 0
	v_addc_co_u32_e32 v31, vcc, 0, v69, vcc
	global_load_dword v26, v[22:23], off offset:-4096 sc1 nt
	s_nop 0
	global_load_dword v22, v[22:23], off sc1 nt
	s_nop 0
	global_load_dword v27, v[30:31], off offset:-4096 sc1 nt
	global_load_dword v23, v[30:31], off sc1 nt
	v_add_co_u32_e32 v30, vcc, s42, v68
	s_mov_b32 s42, 0x41f000
	s_nop 0
	v_addc_co_u32_e32 v31, vcc, 0, v69, vcc
	global_load_dword v36, v[30:31], off offset:-4096 sc1 nt
	global_load_dword v32, v[30:31], off sc1 nt
	v_add_co_u32_e32 v30, vcc, s42, v68
	s_mov_b32 s42, 0x421000
	s_nop 0
	v_addc_co_u32_e32 v31, vcc, 0, v69, vcc
	global_load_dword v37, v[30:31], off offset:-4096 sc1 nt
	global_load_dword v33, v[30:31], off sc1 nt
	v_add_co_u32_e32 v30, vcc, s42, v68
	s_mov_b32 s42, 0x423000
	s_nop 0
	v_addc_co_u32_e32 v31, vcc, 0, v69, vcc
	v_add_co_u32_e32 v38, vcc, s42, v68
	s_mov_b32 s42, 0x425000
	s_nop 0
	v_addc_co_u32_e32 v39, vcc, 0, v69, vcc
	global_load_dword v34, v[30:31], off offset:-4096 sc1 nt
	s_nop 0
	global_load_dword v30, v[30:31], off sc1 nt
	s_nop 0
	global_load_dword v35, v[38:39], off offset:-4096 sc1 nt
	global_load_dword v31, v[38:39], off sc1 nt
	v_add_co_u32_e32 v38, vcc, s42, v68
	s_mov_b32 s42, 0x427000
	s_nop 0
	v_addc_co_u32_e32 v39, vcc, 0, v69, vcc
	global_load_dword v44, v[38:39], off offset:-4096 sc1 nt
	global_load_dword v40, v[38:39], off sc1 nt
	v_add_co_u32_e32 v38, vcc, s42, v68
	s_mov_b32 s42, 0x429000
	s_nop 0
	v_addc_co_u32_e32 v39, vcc, 0, v69, vcc
	global_load_dword v45, v[38:39], off offset:-4096 sc1 nt
	global_load_dword v41, v[38:39], off sc1 nt
	v_add_co_u32_e32 v38, vcc, s42, v68
	s_mov_b32 s42, 0x42b000
	s_nop 0
	v_addc_co_u32_e32 v39, vcc, 0, v69, vcc
	v_add_co_u32_e32 v46, vcc, s42, v68
	s_mov_b32 s42, 0x42d000
	s_nop 0
	v_addc_co_u32_e32 v47, vcc, 0, v69, vcc
	global_load_dword v42, v[38:39], off offset:-4096 sc1 nt
	s_nop 0
	global_load_dword v38, v[38:39], off sc1 nt
	s_nop 0
	global_load_dword v43, v[46:47], off offset:-4096 sc1 nt
	global_load_dword v39, v[46:47], off sc1 nt
	v_add_co_u32_e32 v46, vcc, s42, v68
	s_mov_b32 s42, 0x42f000
	s_nop 0
	v_addc_co_u32_e32 v47, vcc, 0, v69, vcc
	global_load_dword v52, v[46:47], off offset:-4096 sc1 nt
	global_load_dword v48, v[46:47], off sc1 nt
	v_add_co_u32_e32 v46, vcc, s42, v68
	s_mov_b32 s42, 0x431000
	s_nop 0
	v_addc_co_u32_e32 v47, vcc, 0, v69, vcc
	global_load_dword v53, v[46:47], off offset:-4096 sc1 nt
	global_load_dword v49, v[46:47], off sc1 nt
	v_add_co_u32_e32 v46, vcc, s42, v68
	s_mov_b32 s42, 0x433000
	s_nop 0
	v_addc_co_u32_e32 v47, vcc, 0, v69, vcc
	v_add_co_u32_e32 v54, vcc, s42, v68
	s_mov_b32 s42, 0x435000
	s_nop 0
	v_addc_co_u32_e32 v55, vcc, 0, v69, vcc
	global_load_dword v50, v[46:47], off offset:-4096 sc1 nt
	s_nop 0
	global_load_dword v46, v[46:47], off sc1 nt
	s_nop 0
	global_load_dword v51, v[54:55], off offset:-4096 sc1 nt
	global_load_dword v47, v[54:55], off sc1 nt
	v_add_co_u32_e32 v54, vcc, s42, v68
	s_mov_b32 s42, 0x437000
	s_nop 0
	v_addc_co_u32_e32 v55, vcc, 0, v69, vcc
	global_load_dword v60, v[54:55], off offset:-4096 sc1 nt
	global_load_dword v56, v[54:55], off sc1 nt
	v_add_co_u32_e32 v54, vcc, s42, v68
	s_mov_b32 s42, 0x439000
	s_nop 0
	v_addc_co_u32_e32 v55, vcc, 0, v69, vcc
	global_load_dword v61, v[54:55], off offset:-4096 sc1 nt
	global_load_dword v57, v[54:55], off sc1 nt
	v_add_co_u32_e32 v54, vcc, s42, v68
	s_mov_b32 s42, 0x43b000
	s_nop 0
	v_addc_co_u32_e32 v55, vcc, 0, v69, vcc
	v_add_co_u32_e32 v64, vcc, s42, v68
	s_mov_b32 s42, 0x43d000
	s_nop 0
	v_addc_co_u32_e32 v65, vcc, 0, v69, vcc
	global_load_dword v58, v[54:55], off offset:-4096 sc1 nt
	s_nop 0
	global_load_dword v54, v[54:55], off sc1 nt
	s_nop 0
	global_load_dword v59, v[64:65], off offset:-4096 sc1 nt
	global_load_dword v55, v[64:65], off sc1 nt
	v_add_co_u32_e32 v64, vcc, s42, v68
	s_mov_b32 s42, 0x43f000
	s_nop 0
	v_addc_co_u32_e32 v65, vcc, 0, v69, vcc
	v_add_co_u32_e32 v68, vcc, s42, v68
	s_lshl_b64 s[42:43], s[26:27], 2
	s_add_u32 s42, s4, s42
	s_addc_u32 s43, s5, s43
	s_add_u32 s42, s42, 0x800
	s_addc_u32 s43, s43, 0
	s_lshl_b32 s46, s40, 2
	s_add_u32 s22, s22, s46
	s_addc_u32 s23, s23, 0
	s_add_u32 s46, s22, 0xffff7f00
	s_addc_u32 s47, s23, -1
	s_cmpk_lt_u32 s26, 0x200
	v_addc_co_u32_e32 v69, vcc, 0, v69, vcc
	s_cselect_b32 s43, s43, s47
	s_cselect_b32 s42, s42, s46
	global_load_dword v66, v[64:65], off offset:-4096 sc1 nt
	s_nop 0
	global_load_dword v64, v[64:65], off sc1 nt
	s_nop 0
	global_load_dword v67, v[68:69], off offset:-4096 sc1 nt
	global_load_dword v65, v[68:69], off sc1 nt
	s_nop 0
	global_load_dword v68, v1, s[42:43] sc1
	s_add_i32 s42, s40, 0xffffdfc1
	s_mov_b32 s43, s27
	s_lshl_b64 s[46:47], s[42:43], 2
	s_add_u32 s43, s4, s46
	s_addc_u32 s46, s5, s47
	s_add_u32 s47, s43, 0x800
	s_addc_u32 s43, s46, 0
	s_add_u32 s46, s22, 0xffff7f04
	s_addc_u32 s48, s23, -1
	s_cmpk_lt_u32 s42, 0x200
	s_cselect_b32 s43, s43, s48
	s_cselect_b32 s42, s47, s46
	global_load_dword v70, v1, s[42:43] sc1
	s_add_i32 s42, s40, 0xffffdfc2
	s_mov_b32 s43, s27
	s_lshl_b64 s[46:47], s[42:43], 2
	s_add_u32 s43, s4, s46
	s_addc_u32 s46, s5, s47
	s_add_u32 s47, s43, 0x800
	s_addc_u32 s43, s46, 0
	s_add_u32 s46, s22, 0xffff7f08
	s_addc_u32 s48, s23, -1
	s_cmpk_lt_u32 s42, 0x200
	s_cselect_b32 s43, s43, s48
	s_cselect_b32 s42, s47, s46
	global_load_dword v69, v1, s[42:43] sc1
	s_add_i32 s42, s40, 0xffffdfc3
	s_mov_b32 s43, s27
	s_lshl_b64 s[46:47], s[42:43], 2
	s_add_u32 s43, s4, s46
	s_addc_u32 s46, s5, s47
	s_add_u32 s47, s43, 0x800
	s_addc_u32 s43, s46, 0
	s_add_u32 s46, s22, 0xffff7f0c
	s_addc_u32 s48, s23, -1
	s_cmpk_lt_u32 s42, 0x200
	s_cselect_b32 s43, s43, s48
	s_cselect_b32 s42, s47, s46
	global_load_dword v71, v1, s[42:43] sc1
	s_add_i32 s42, s40, 0xffffdfc4
	s_mov_b32 s43, s27
	s_lshl_b64 s[46:47], s[42:43], 2
	s_add_u32 s43, s4, s46
	s_addc_u32 s46, s5, s47
	s_add_u32 s47, s43, 0x800
	s_addc_u32 s43, s46, 0
	s_add_u32 s46, s22, 0xffff7f10
	s_addc_u32 s48, s23, -1
	s_cmpk_lt_u32 s42, 0x200
	s_cselect_b32 s43, s43, s48
	s_cselect_b32 s42, s47, s46
	global_load_dword v72, v1, s[42:43] sc1
	s_add_i32 s42, s40, 0xffffdfc5
	s_mov_b32 s43, s27
	s_lshl_b64 s[46:47], s[42:43], 2
	s_add_u32 s43, s4, s46
	s_addc_u32 s46, s5, s47
	s_add_u32 s47, s43, 0x800
	s_addc_u32 s43, s46, 0
	s_add_u32 s46, s22, 0xffff7f14
	s_addc_u32 s48, s23, -1
	s_cmpk_lt_u32 s42, 0x200
	s_cselect_b32 s43, s43, s48
	s_cselect_b32 s42, s47, s46
	global_load_dword v74, v1, s[42:43] sc1
	s_add_i32 s42, s40, 0xffffdfc6
	s_mov_b32 s43, s27
	s_lshl_b64 s[46:47], s[42:43], 2
	s_add_u32 s43, s4, s46
	s_addc_u32 s46, s5, s47
	s_add_u32 s47, s43, 0x800
	s_addc_u32 s43, s46, 0
	s_add_u32 s46, s22, 0xffff7f18
	s_addc_u32 s48, s23, -1
	s_cmpk_lt_u32 s42, 0x200
	s_cselect_b32 s43, s43, s48
	s_cselect_b32 s42, s47, s46
	global_load_dword v73, v1, s[42:43] sc1
	s_add_i32 s42, s40, 0xffffdfc7
	s_mov_b32 s43, s27
	s_lshl_b64 s[46:47], s[42:43], 2
	s_add_u32 s43, s4, s46
	s_addc_u32 s46, s5, s47
	s_add_u32 s47, s43, 0x800
	s_addc_u32 s43, s46, 0
	s_add_u32 s46, s22, 0xffff7f1c
	s_addc_u32 s48, s23, -1
	s_cmpk_lt_u32 s42, 0x200
	s_cselect_b32 s43, s43, s48
	s_cselect_b32 s42, s47, s46
	global_load_dword v75, v1, s[42:43] sc1
	s_add_i32 s42, s40, 0xffffdfc8
	s_mov_b32 s43, s27
	s_lshl_b64 s[46:47], s[42:43], 2
	s_add_u32 s43, s4, s46
	s_addc_u32 s46, s5, s47
	s_add_u32 s47, s43, 0x800
	s_addc_u32 s43, s46, 0
	s_add_u32 s46, s22, 0xffff7f20
	s_addc_u32 s48, s23, -1
	s_cmpk_lt_u32 s42, 0x200
	s_cselect_b32 s43, s43, s48
	s_cselect_b32 s42, s47, s46
	global_load_dword v76, v1, s[42:43] sc1
	s_add_i32 s42, s40, 0xffffdfc9
	s_mov_b32 s43, s27
	s_lshl_b64 s[46:47], s[42:43], 2
	s_add_u32 s43, s4, s46
	s_addc_u32 s46, s5, s47
	s_add_u32 s47, s43, 0x800
	s_addc_u32 s43, s46, 0
	s_add_u32 s46, s22, 0xffff7f24
	s_addc_u32 s48, s23, -1
	s_cmpk_lt_u32 s42, 0x200
	s_cselect_b32 s43, s43, s48
	s_cselect_b32 s42, s47, s46
	global_load_dword v78, v1, s[42:43] sc1
	s_add_i32 s42, s40, 0xffffdfca
	s_mov_b32 s43, s27
	s_lshl_b64 s[46:47], s[42:43], 2
	s_add_u32 s43, s4, s46
	s_addc_u32 s46, s5, s47
	s_add_u32 s47, s43, 0x800
	s_addc_u32 s43, s46, 0
	s_add_u32 s46, s22, 0xffff7f28
	s_addc_u32 s48, s23, -1
	s_cmpk_lt_u32 s42, 0x200
	s_cselect_b32 s43, s43, s48
	s_cselect_b32 s42, s47, s46
	global_load_dword v77, v1, s[42:43] sc1
	s_add_i32 s42, s40, 0xffffdfcb
	s_mov_b32 s43, s27
	s_lshl_b64 s[46:47], s[42:43], 2
	s_add_u32 s43, s4, s46
	s_addc_u32 s46, s5, s47
	s_add_u32 s47, s43, 0x800
	s_addc_u32 s43, s46, 0
	s_add_u32 s46, s22, 0xffff7f2c
	s_addc_u32 s48, s23, -1
	s_cmpk_lt_u32 s42, 0x200
	s_cselect_b32 s43, s43, s48
	s_cselect_b32 s42, s47, s46
	global_load_dword v79, v1, s[42:43] sc1
	s_add_i32 s42, s40, 0xffffdfcc
	s_mov_b32 s43, s27
	s_lshl_b64 s[46:47], s[42:43], 2
	s_add_u32 s43, s4, s46
	s_addc_u32 s46, s5, s47
	s_add_u32 s47, s43, 0x800
	s_addc_u32 s43, s46, 0
	s_add_u32 s46, s22, 0xffff7f30
	s_addc_u32 s48, s23, -1
	s_cmpk_lt_u32 s42, 0x200
	s_cselect_b32 s43, s43, s48
	s_cselect_b32 s42, s47, s46
	global_load_dword v80, v1, s[42:43] sc1
	s_add_i32 s42, s40, 0xffffdfcd
	s_mov_b32 s43, s27
	s_lshl_b64 s[46:47], s[42:43], 2
	s_add_u32 s43, s4, s46
	s_addc_u32 s46, s5, s47
	s_add_u32 s47, s43, 0x800
	s_addc_u32 s43, s46, 0
	s_add_u32 s46, s22, 0xffff7f34
	s_addc_u32 s48, s23, -1
	s_cmpk_lt_u32 s42, 0x200
	s_cselect_b32 s43, s43, s48
	s_cselect_b32 s42, s47, s46
	global_load_dword v82, v1, s[42:43] sc1
	s_add_i32 s42, s40, 0xffffdfce
	s_mov_b32 s43, s27
	s_lshl_b64 s[46:47], s[42:43], 2
	s_add_u32 s43, s4, s46
	s_addc_u32 s46, s5, s47
	s_add_u32 s47, s43, 0x800
	s_addc_u32 s43, s46, 0
	s_add_u32 s46, s22, 0xffff7f38
	s_addc_u32 s48, s23, -1
	s_cmpk_lt_u32 s42, 0x200
	s_cselect_b32 s43, s43, s48
	s_cselect_b32 s42, s47, s46
	global_load_dword v81, v1, s[42:43] sc1
	s_add_i32 s42, s40, 0xffffdfcf
	s_mov_b32 s43, s27
	s_lshl_b64 s[46:47], s[42:43], 2
	s_add_u32 s43, s4, s46
	s_addc_u32 s46, s5, s47
	s_add_u32 s47, s43, 0x800
	s_addc_u32 s43, s46, 0
	s_add_u32 s46, s22, 0xffff7f3c
	s_addc_u32 s48, s23, -1
	s_cmpk_lt_u32 s42, 0x200
	s_cselect_b32 s43, s43, s48
	s_cselect_b32 s42, s47, s46
	global_load_dword v83, v1, s[42:43] sc1
	s_add_i32 s42, s40, 0xffffdfd0
	s_mov_b32 s43, s27
	s_lshl_b64 s[46:47], s[42:43], 2
	s_add_u32 s43, s4, s46
	s_addc_u32 s46, s5, s47
	s_add_u32 s47, s43, 0x800
	s_addc_u32 s43, s46, 0
	s_add_u32 s46, s22, 0xffff7f40
	s_addc_u32 s48, s23, -1
	s_cmpk_lt_u32 s42, 0x200
	s_cselect_b32 s43, s43, s48
	s_cselect_b32 s42, s47, s46
	global_load_dword v84, v1, s[42:43] sc1
	s_add_i32 s42, s40, 0xffffdfd1
	s_mov_b32 s43, s27
	s_lshl_b64 s[46:47], s[42:43], 2
	s_add_u32 s43, s4, s46
	s_addc_u32 s46, s5, s47
	s_add_u32 s47, s43, 0x800
	s_addc_u32 s43, s46, 0
	s_add_u32 s46, s22, 0xffff7f44
	s_addc_u32 s48, s23, -1
	s_cmpk_lt_u32 s42, 0x200
	s_cselect_b32 s43, s43, s48
	s_cselect_b32 s42, s47, s46
	global_load_dword v86, v1, s[42:43] sc1
	s_add_i32 s42, s40, 0xffffdfd2
	s_mov_b32 s43, s27
	s_lshl_b64 s[46:47], s[42:43], 2
	s_add_u32 s43, s4, s46
	s_addc_u32 s46, s5, s47
	s_add_u32 s47, s43, 0x800
	s_addc_u32 s43, s46, 0
	s_add_u32 s46, s22, 0xffff7f48
	s_addc_u32 s48, s23, -1
	s_cmpk_lt_u32 s42, 0x200
	s_cselect_b32 s43, s43, s48
	s_cselect_b32 s42, s47, s46
	global_load_dword v85, v1, s[42:43] sc1
	s_add_i32 s42, s40, 0xffffdfd3
	s_mov_b32 s43, s27
	s_lshl_b64 s[46:47], s[42:43], 2
	s_add_u32 s43, s4, s46
	s_addc_u32 s46, s5, s47
	s_add_u32 s47, s43, 0x800
	s_addc_u32 s43, s46, 0
	s_add_u32 s46, s22, 0xffff7f4c
	s_addc_u32 s48, s23, -1
	s_cmpk_lt_u32 s42, 0x200
	s_cselect_b32 s43, s43, s48
	s_cselect_b32 s42, s47, s46
	global_load_dword v87, v1, s[42:43] sc1
	s_add_i32 s42, s40, 0xffffdfd4
	s_mov_b32 s43, s27
	s_lshl_b64 s[46:47], s[42:43], 2
	s_add_u32 s43, s4, s46
	s_addc_u32 s46, s5, s47
	s_add_u32 s47, s43, 0x800
	s_addc_u32 s43, s46, 0
	s_add_u32 s46, s22, 0xffff7f50
	s_addc_u32 s48, s23, -1
	s_cmpk_lt_u32 s42, 0x200
	s_cselect_b32 s43, s43, s48
	s_cselect_b32 s42, s47, s46
	global_load_dword v88, v1, s[42:43] sc1
	s_add_i32 s42, s40, 0xffffdfd5
	s_mov_b32 s43, s27
	s_lshl_b64 s[46:47], s[42:43], 2
	s_add_u32 s43, s4, s46
	s_addc_u32 s46, s5, s47
	s_add_u32 s47, s43, 0x800
	s_addc_u32 s43, s46, 0
	s_add_u32 s46, s22, 0xffff7f54
	s_addc_u32 s48, s23, -1
	s_cmpk_lt_u32 s42, 0x200
	s_cselect_b32 s43, s43, s48
	s_cselect_b32 s42, s47, s46
	global_load_dword v90, v1, s[42:43] sc1
	s_add_i32 s42, s40, 0xffffdfd6
	s_mov_b32 s43, s27
	s_lshl_b64 s[46:47], s[42:43], 2
	s_add_u32 s43, s4, s46
	s_addc_u32 s46, s5, s47
	s_add_u32 s47, s43, 0x800
	s_addc_u32 s43, s46, 0
	s_add_u32 s46, s22, 0xffff7f58
	s_addc_u32 s48, s23, -1
	s_cmpk_lt_u32 s42, 0x200
	s_cselect_b32 s43, s43, s48
	s_cselect_b32 s42, s47, s46
	global_load_dword v89, v1, s[42:43] sc1
	s_add_i32 s42, s40, 0xffffdfd7
	s_mov_b32 s43, s27
	s_lshl_b64 s[46:47], s[42:43], 2
	s_add_u32 s43, s4, s46
	s_addc_u32 s46, s5, s47
	s_add_u32 s47, s43, 0x800
	s_addc_u32 s43, s46, 0
	s_add_u32 s46, s22, 0xffff7f5c
	s_addc_u32 s48, s23, -1
	s_cmpk_lt_u32 s42, 0x200
	s_cselect_b32 s43, s43, s48
	s_cselect_b32 s42, s47, s46
	global_load_dword v91, v1, s[42:43] sc1
	s_add_i32 s42, s40, 0xffffdfd8
	s_mov_b32 s43, s27
	s_lshl_b64 s[46:47], s[42:43], 2
	s_add_u32 s43, s4, s46
	s_addc_u32 s46, s5, s47
	s_add_u32 s47, s43, 0x800
	s_addc_u32 s43, s46, 0
	s_add_u32 s46, s22, 0xffff7f60
	s_addc_u32 s48, s23, -1
	s_cmpk_lt_u32 s42, 0x200
	s_cselect_b32 s43, s43, s48
	s_cselect_b32 s42, s47, s46
	global_load_dword v92, v1, s[42:43] sc1
	s_add_i32 s42, s40, 0xffffdfd9
	s_mov_b32 s43, s27
	s_lshl_b64 s[46:47], s[42:43], 2
	s_add_u32 s43, s4, s46
	s_addc_u32 s46, s5, s47
	s_add_u32 s47, s43, 0x800
	s_addc_u32 s43, s46, 0
	s_add_u32 s46, s22, 0xffff7f64
	s_addc_u32 s48, s23, -1
	s_cmpk_lt_u32 s42, 0x200
	s_cselect_b32 s43, s43, s48
	s_cselect_b32 s42, s47, s46
	global_load_dword v94, v1, s[42:43] sc1
	s_add_i32 s42, s40, 0xffffdfda
	s_mov_b32 s43, s27
	s_lshl_b64 s[46:47], s[42:43], 2
	s_add_u32 s43, s4, s46
	s_addc_u32 s46, s5, s47
	s_add_u32 s47, s43, 0x800
	s_addc_u32 s43, s46, 0
	s_add_u32 s46, s22, 0xffff7f68
	s_addc_u32 s48, s23, -1
	s_cmpk_lt_u32 s42, 0x200
	s_cselect_b32 s43, s43, s48
	s_cselect_b32 s42, s47, s46
	global_load_dword v93, v1, s[42:43] sc1
	s_add_i32 s42, s40, 0xffffdfdb
	s_mov_b32 s43, s27
	s_lshl_b64 s[46:47], s[42:43], 2
	s_add_u32 s43, s4, s46
	s_addc_u32 s46, s5, s47
	s_add_u32 s47, s43, 0x800
	s_addc_u32 s43, s46, 0
	s_add_u32 s46, s22, 0xffff7f6c
	s_addc_u32 s48, s23, -1
	s_cmpk_lt_u32 s42, 0x200
	s_cselect_b32 s43, s43, s48
	s_cselect_b32 s42, s47, s46
	global_load_dword v95, v1, s[42:43] sc1
	s_add_i32 s42, s40, 0xffffdfdc
	s_mov_b32 s43, s27
	s_lshl_b64 s[46:47], s[42:43], 2
	s_add_u32 s43, s4, s46
	s_addc_u32 s46, s5, s47
	s_add_u32 s47, s43, 0x800
	s_addc_u32 s43, s46, 0
	s_add_u32 s46, s22, 0xffff7f70
	s_addc_u32 s48, s23, -1
	s_cmpk_lt_u32 s42, 0x200
	s_cselect_b32 s43, s43, s48
	s_cselect_b32 s42, s47, s46
	global_load_dword v96, v1, s[42:43] sc1
	s_add_i32 s42, s40, 0xffffdfdd
	s_mov_b32 s43, s27
	s_lshl_b64 s[46:47], s[42:43], 2
	s_add_u32 s43, s4, s46
	s_addc_u32 s46, s5, s47
	s_add_u32 s47, s43, 0x800
	s_addc_u32 s43, s46, 0
	s_add_u32 s46, s22, 0xffff7f74
	s_addc_u32 s48, s23, -1
	s_cmpk_lt_u32 s42, 0x200
	s_cselect_b32 s43, s43, s48
	s_cselect_b32 s42, s47, s46
	global_load_dword v98, v1, s[42:43] sc1
	s_add_i32 s42, s40, 0xffffdfde
	s_mov_b32 s43, s27
	s_lshl_b64 s[46:47], s[42:43], 2
	s_add_u32 s43, s4, s46
	s_addc_u32 s46, s5, s47
	s_add_u32 s47, s43, 0x800
	s_addc_u32 s43, s46, 0
	s_add_u32 s46, s22, 0xffff7f78
	s_addc_u32 s48, s23, -1
	s_cmpk_lt_u32 s42, 0x200
	s_cselect_b32 s43, s43, s48
	s_cselect_b32 s42, s47, s46
	global_load_dword v97, v1, s[42:43] sc1
	s_add_i32 s42, s40, 0xffffdfdf
	s_mov_b32 s43, s27
	s_lshl_b64 s[46:47], s[42:43], 2
	s_add_u32 s43, s4, s46
	s_addc_u32 s46, s5, s47
	s_add_u32 s47, s43, 0x800
	s_addc_u32 s43, s46, 0
	s_add_u32 s46, s22, 0xffff7f7c
	s_addc_u32 s48, s23, -1
	s_cmpk_lt_u32 s42, 0x200
	s_cselect_b32 s43, s43, s48
	s_cselect_b32 s42, s47, s46
	global_load_dword v99, v1, s[42:43] sc1
	s_add_i32 s42, s40, 0xffffdfe0
	s_mov_b32 s43, s27
	s_lshl_b64 s[46:47], s[42:43], 2
	s_add_u32 s43, s4, s46
	s_addc_u32 s46, s5, s47
	s_add_u32 s47, s43, 0x800
	s_addc_u32 s43, s46, 0
	s_add_u32 s46, s22, 0xffff7f80
	s_addc_u32 s48, s23, -1
	s_cmpk_lt_u32 s42, 0x200
	s_cselect_b32 s43, s43, s48
	s_cselect_b32 s42, s47, s46
	global_load_dword v100, v1, s[42:43] sc1
	s_add_i32 s42, s40, 0xffffdfe1
	s_mov_b32 s43, s27
	s_lshl_b64 s[46:47], s[42:43], 2
	s_add_u32 s43, s4, s46
	s_addc_u32 s46, s5, s47
	s_add_u32 s47, s43, 0x800
	s_addc_u32 s43, s46, 0
	s_add_u32 s46, s22, 0xffff7f84
	s_addc_u32 s48, s23, -1
	s_cmpk_lt_u32 s42, 0x200
	s_cselect_b32 s43, s43, s48
	s_cselect_b32 s42, s47, s46
	global_load_dword v102, v1, s[42:43] sc1
	s_add_i32 s42, s40, 0xffffdfe2
	s_mov_b32 s43, s27
	s_lshl_b64 s[46:47], s[42:43], 2
	s_add_u32 s43, s4, s46
	s_addc_u32 s46, s5, s47
	s_add_u32 s47, s43, 0x800
	s_addc_u32 s43, s46, 0
	s_add_u32 s46, s22, 0xffff7f88
	s_addc_u32 s48, s23, -1
	s_cmpk_lt_u32 s42, 0x200
	s_cselect_b32 s43, s43, s48
	s_cselect_b32 s42, s47, s46
	global_load_dword v101, v1, s[42:43] sc1
	s_add_i32 s42, s40, 0xffffdfe3
	s_mov_b32 s43, s27
	s_lshl_b64 s[46:47], s[42:43], 2
	s_add_u32 s43, s4, s46
	s_addc_u32 s46, s5, s47
	s_add_u32 s47, s43, 0x800
	s_addc_u32 s43, s46, 0
	s_add_u32 s46, s22, 0xffff7f8c
	s_addc_u32 s48, s23, -1
	s_cmpk_lt_u32 s42, 0x200
	s_cselect_b32 s43, s43, s48
	s_cselect_b32 s42, s47, s46
	global_load_dword v103, v1, s[42:43] sc1
	s_add_i32 s42, s40, 0xffffdfe4
	s_mov_b32 s43, s27
	s_lshl_b64 s[46:47], s[42:43], 2
	s_add_u32 s43, s4, s46
	s_addc_u32 s46, s5, s47
	s_add_u32 s47, s43, 0x800
	s_addc_u32 s43, s46, 0
	s_add_u32 s46, s22, 0xffff7f90
	s_addc_u32 s48, s23, -1
	s_cmpk_lt_u32 s42, 0x200
	s_cselect_b32 s43, s43, s48
	s_cselect_b32 s42, s47, s46
	global_load_dword v104, v1, s[42:43] sc1
	s_add_i32 s42, s40, 0xffffdfe5
	s_mov_b32 s43, s27
	s_lshl_b64 s[46:47], s[42:43], 2
	s_add_u32 s43, s4, s46
	s_addc_u32 s46, s5, s47
	s_add_u32 s47, s43, 0x800
	s_addc_u32 s43, s46, 0
	s_add_u32 s46, s22, 0xffff7f94
	s_addc_u32 s48, s23, -1
	s_cmpk_lt_u32 s42, 0x200
	s_cselect_b32 s43, s43, s48
	s_cselect_b32 s42, s47, s46
	global_load_dword v106, v1, s[42:43] sc1
	s_add_i32 s42, s40, 0xffffdfe6
	s_mov_b32 s43, s27
	s_lshl_b64 s[46:47], s[42:43], 2
	s_add_u32 s43, s4, s46
	s_addc_u32 s46, s5, s47
	s_add_u32 s47, s43, 0x800
	s_addc_u32 s43, s46, 0
	s_add_u32 s46, s22, 0xffff7f98
	s_addc_u32 s48, s23, -1
	s_cmpk_lt_u32 s42, 0x200
	s_cselect_b32 s43, s43, s48
	s_cselect_b32 s42, s47, s46
	global_load_dword v105, v1, s[42:43] sc1
	s_add_i32 s42, s40, 0xffffdfe7
	s_mov_b32 s43, s27
	s_lshl_b64 s[46:47], s[42:43], 2
	s_add_u32 s43, s4, s46
	s_addc_u32 s46, s5, s47
	s_add_u32 s47, s43, 0x800
	s_addc_u32 s43, s46, 0
	s_add_u32 s46, s22, 0xffff7f9c
	s_addc_u32 s48, s23, -1
	s_cmpk_lt_u32 s42, 0x200
	s_cselect_b32 s43, s43, s48
	s_cselect_b32 s42, s47, s46
	global_load_dword v107, v1, s[42:43] sc1
	s_add_i32 s42, s40, 0xffffdfe8
	s_mov_b32 s43, s27
	s_lshl_b64 s[46:47], s[42:43], 2
	s_add_u32 s43, s4, s46
	s_addc_u32 s46, s5, s47
	s_add_u32 s47, s43, 0x800
	s_addc_u32 s43, s46, 0
	s_add_u32 s46, s22, 0xffff7fa0
	s_addc_u32 s48, s23, -1
	s_cmpk_lt_u32 s42, 0x200
	s_cselect_b32 s43, s43, s48
	s_cselect_b32 s42, s47, s46
	global_load_dword v108, v1, s[42:43] sc1
	s_add_i32 s42, s40, 0xffffdfe9
	s_mov_b32 s43, s27
	s_lshl_b64 s[46:47], s[42:43], 2
	s_add_u32 s43, s4, s46
	s_addc_u32 s46, s5, s47
	s_add_u32 s47, s43, 0x800
	s_addc_u32 s43, s46, 0
	s_add_u32 s46, s22, 0xffff7fa4
	s_addc_u32 s48, s23, -1
	s_cmpk_lt_u32 s42, 0x200
	s_cselect_b32 s43, s43, s48
	s_cselect_b32 s42, s47, s46
	global_load_dword v110, v1, s[42:43] sc1
	s_add_i32 s42, s40, 0xffffdfea
	s_mov_b32 s43, s27
	s_lshl_b64 s[46:47], s[42:43], 2
	s_add_u32 s43, s4, s46
	s_addc_u32 s46, s5, s47
	s_add_u32 s47, s43, 0x800
	s_addc_u32 s43, s46, 0
	s_add_u32 s46, s22, 0xffff7fa8
	s_addc_u32 s48, s23, -1
	s_cmpk_lt_u32 s42, 0x200
	s_cselect_b32 s43, s43, s48
	s_cselect_b32 s42, s47, s46
	global_load_dword v109, v1, s[42:43] sc1
	s_add_i32 s42, s40, 0xffffdfeb
	s_mov_b32 s43, s27
	s_lshl_b64 s[46:47], s[42:43], 2
	s_add_u32 s43, s4, s46
	s_addc_u32 s46, s5, s47
	s_add_u32 s47, s43, 0x800
	s_addc_u32 s43, s46, 0
	s_add_u32 s46, s22, 0xffff7fac
	s_addc_u32 s48, s23, -1
	s_cmpk_lt_u32 s42, 0x200
	s_cselect_b32 s43, s43, s48
	s_cselect_b32 s42, s47, s46
	global_load_dword v111, v1, s[42:43] sc1
	s_add_i32 s42, s40, 0xffffdfec
	s_mov_b32 s43, s27
	s_lshl_b64 s[46:47], s[42:43], 2
	s_add_u32 s43, s4, s46
	s_addc_u32 s46, s5, s47
	s_add_u32 s47, s43, 0x800
	s_addc_u32 s43, s46, 0
	s_add_u32 s46, s22, 0xffff7fb0
	s_addc_u32 s48, s23, -1
	s_cmpk_lt_u32 s42, 0x200
	s_cselect_b32 s43, s43, s48
	s_cselect_b32 s42, s47, s46
	global_load_dword v112, v1, s[42:43] sc1
	s_add_i32 s42, s40, 0xffffdfed
	s_mov_b32 s43, s27
	s_lshl_b64 s[46:47], s[42:43], 2
	s_add_u32 s43, s4, s46
	s_addc_u32 s46, s5, s47
	s_add_u32 s47, s43, 0x800
	s_addc_u32 s43, s46, 0
	s_add_u32 s46, s22, 0xffff7fb4
	s_addc_u32 s48, s23, -1
	s_cmpk_lt_u32 s42, 0x200
	s_cselect_b32 s43, s43, s48
	s_cselect_b32 s42, s47, s46
	global_load_dword v114, v1, s[42:43] sc1
	s_add_i32 s42, s40, 0xffffdfee
	s_mov_b32 s43, s27
	s_lshl_b64 s[46:47], s[42:43], 2
	s_add_u32 s43, s4, s46
	s_addc_u32 s46, s5, s47
	s_add_u32 s47, s43, 0x800
	s_addc_u32 s43, s46, 0
	s_add_u32 s46, s22, 0xffff7fb8
	s_addc_u32 s48, s23, -1
	s_cmpk_lt_u32 s42, 0x200
	s_cselect_b32 s43, s43, s48
	s_cselect_b32 s42, s47, s46
	global_load_dword v113, v1, s[42:43] sc1
	s_add_i32 s42, s40, 0xffffdfef
	s_mov_b32 s43, s27
	s_lshl_b64 s[46:47], s[42:43], 2
	s_add_u32 s43, s4, s46
	s_addc_u32 s46, s5, s47
	s_add_u32 s47, s43, 0x800
	s_addc_u32 s43, s46, 0
	s_add_u32 s46, s22, 0xffff7fbc
	s_addc_u32 s48, s23, -1
	s_cmpk_lt_u32 s42, 0x200
	s_cselect_b32 s43, s43, s48
	s_cselect_b32 s42, s47, s46
	global_load_dword v115, v1, s[42:43] sc1
	s_add_i32 s42, s40, 0xffffdff0
	s_mov_b32 s43, s27
	s_lshl_b64 s[46:47], s[42:43], 2
	s_add_u32 s43, s4, s46
	s_addc_u32 s46, s5, s47
	s_add_u32 s47, s43, 0x800
	s_addc_u32 s43, s46, 0
	s_add_u32 s46, s22, 0xffff7fc0
	s_addc_u32 s48, s23, -1
	s_cmpk_lt_u32 s42, 0x200
	s_cselect_b32 s43, s43, s48
	s_cselect_b32 s42, s47, s46
	global_load_dword v116, v1, s[42:43] sc1
	s_add_i32 s42, s40, 0xffffdff1
	s_mov_b32 s43, s27
	s_lshl_b64 s[46:47], s[42:43], 2
	s_add_u32 s43, s4, s46
	s_addc_u32 s46, s5, s47
	s_add_u32 s47, s43, 0x800
	s_addc_u32 s43, s46, 0
	s_add_u32 s46, s22, 0xffff7fc4
	s_addc_u32 s48, s23, -1
	s_cmpk_lt_u32 s42, 0x200
	s_cselect_b32 s43, s43, s48
	s_cselect_b32 s42, s47, s46
	global_load_dword v118, v1, s[42:43] sc1
	s_add_i32 s42, s40, 0xffffdff2
	s_mov_b32 s43, s27
	s_lshl_b64 s[46:47], s[42:43], 2
	s_add_u32 s43, s4, s46
	s_addc_u32 s46, s5, s47
	s_add_u32 s47, s43, 0x800
	s_addc_u32 s43, s46, 0
	s_add_u32 s46, s22, 0xffff7fc8
	s_addc_u32 s48, s23, -1
	s_cmpk_lt_u32 s42, 0x200
	s_cselect_b32 s43, s43, s48
	s_cselect_b32 s42, s47, s46
	global_load_dword v117, v1, s[42:43] sc1
	s_add_i32 s42, s40, 0xffffdff3
	s_mov_b32 s43, s27
	s_lshl_b64 s[46:47], s[42:43], 2
	s_add_u32 s43, s4, s46
	s_addc_u32 s46, s5, s47
	s_add_u32 s47, s43, 0x800
	s_addc_u32 s43, s46, 0
	s_add_u32 s46, s22, 0xffff7fcc
	s_addc_u32 s48, s23, -1
	s_cmpk_lt_u32 s42, 0x200
	s_cselect_b32 s43, s43, s48
	s_cselect_b32 s42, s47, s46
	global_load_dword v119, v1, s[42:43] sc1
	s_add_i32 s42, s40, 0xffffdff4
	s_mov_b32 s43, s27
	s_lshl_b64 s[46:47], s[42:43], 2
	s_add_u32 s43, s4, s46
	s_addc_u32 s46, s5, s47
	s_add_u32 s47, s43, 0x800
	s_addc_u32 s43, s46, 0
	s_add_u32 s46, s22, 0xffff7fd0
	s_addc_u32 s48, s23, -1
	s_cmpk_lt_u32 s42, 0x200
	s_cselect_b32 s43, s43, s48
	s_cselect_b32 s42, s47, s46
	global_load_dword v120, v1, s[42:43] sc1
	s_add_i32 s42, s40, 0xffffdff5
	s_mov_b32 s43, s27
	s_lshl_b64 s[46:47], s[42:43], 2
	s_add_u32 s43, s4, s46
	s_addc_u32 s46, s5, s47
	s_add_u32 s47, s43, 0x800
	s_addc_u32 s43, s46, 0
	s_add_u32 s46, s22, 0xffff7fd4
	s_addc_u32 s48, s23, -1
	s_cmpk_lt_u32 s42, 0x200
	s_cselect_b32 s43, s43, s48
	s_cselect_b32 s42, s47, s46
	global_load_dword v122, v1, s[42:43] sc1
	s_add_i32 s42, s40, 0xffffdff6
	s_mov_b32 s43, s27
	s_lshl_b64 s[46:47], s[42:43], 2
	s_add_u32 s43, s4, s46
	s_addc_u32 s46, s5, s47
	s_add_u32 s47, s43, 0x800
	s_addc_u32 s43, s46, 0
	s_add_u32 s46, s22, 0xffff7fd8
	s_addc_u32 s48, s23, -1
	s_cmpk_lt_u32 s42, 0x200
	s_cselect_b32 s43, s43, s48
	s_cselect_b32 s42, s47, s46
	global_load_dword v121, v1, s[42:43] sc1
	s_add_i32 s42, s40, 0xffffdff7
	s_mov_b32 s43, s27
	s_lshl_b64 s[46:47], s[42:43], 2
	s_add_u32 s43, s4, s46
	s_addc_u32 s46, s5, s47
	s_add_u32 s47, s43, 0x800
	s_addc_u32 s43, s46, 0
	s_add_u32 s46, s22, 0xffff7fdc
	s_addc_u32 s48, s23, -1
	s_cmpk_lt_u32 s42, 0x200
	s_cselect_b32 s43, s43, s48
	s_cselect_b32 s42, s47, s46
	global_load_dword v123, v1, s[42:43] sc1
	s_add_i32 s42, s40, 0xffffdff8
	s_mov_b32 s43, s27
	s_lshl_b64 s[46:47], s[42:43], 2
	s_add_u32 s43, s4, s46
	s_addc_u32 s46, s5, s47
	s_add_u32 s47, s43, 0x800
	s_addc_u32 s43, s46, 0
	s_add_u32 s46, s22, 0xffff7fe0
	s_addc_u32 s48, s23, -1
	s_cmpk_lt_u32 s42, 0x200
	s_cselect_b32 s43, s43, s48
	s_cselect_b32 s42, s47, s46
	global_load_dword v124, v1, s[42:43] sc1
	s_add_i32 s42, s40, 0xffffdff9
	s_mov_b32 s43, s27
	s_lshl_b64 s[46:47], s[42:43], 2
	s_add_u32 s43, s4, s46
	s_addc_u32 s46, s5, s47
	s_add_u32 s47, s43, 0x800
	s_addc_u32 s43, s46, 0
	s_add_u32 s46, s22, 0xffff7fe4
	s_addc_u32 s48, s23, -1
	s_cmpk_lt_u32 s42, 0x200
	s_cselect_b32 s43, s43, s48
	s_cselect_b32 s42, s47, s46
	global_load_dword v126, v1, s[42:43] sc1
	s_add_i32 s42, s40, 0xffffdffa
	s_mov_b32 s43, s27
	s_lshl_b64 s[46:47], s[42:43], 2
	s_add_u32 s43, s4, s46
	s_addc_u32 s46, s5, s47
	s_add_u32 s47, s43, 0x800
	s_addc_u32 s43, s46, 0
	s_add_u32 s46, s22, 0xffff7fe8
	s_addc_u32 s48, s23, -1
	s_cmpk_lt_u32 s42, 0x200
	s_cselect_b32 s43, s43, s48
	s_cselect_b32 s42, s47, s46
	global_load_dword v125, v1, s[42:43] sc1
	s_add_i32 s42, s40, 0xffffdffb
	s_mov_b32 s43, s27
	s_lshl_b64 s[46:47], s[42:43], 2
	s_add_u32 s43, s4, s46
	s_addc_u32 s46, s5, s47
	s_add_u32 s47, s43, 0x800
	s_addc_u32 s43, s46, 0
	s_add_u32 s46, s22, 0xffff7fec
	s_addc_u32 s48, s23, -1
	s_cmpk_lt_u32 s42, 0x200
	s_cselect_b32 s43, s43, s48
	s_cselect_b32 s42, s47, s46
	global_load_dword v127, v1, s[42:43] sc1
	s_add_i32 s42, s40, 0xffffdffc
	s_mov_b32 s43, s27
	s_lshl_b64 s[46:47], s[42:43], 2
	s_add_u32 s43, s4, s46
	s_addc_u32 s46, s5, s47
	s_add_u32 s47, s43, 0x800
	s_addc_u32 s43, s46, 0
	s_add_u32 s46, s22, 0xffff7ff0
	s_addc_u32 s48, s23, -1
	s_cmpk_lt_u32 s42, 0x200
	s_cselect_b32 s43, s43, s48
	s_cselect_b32 s42, s47, s46
	global_load_dword v128, v1, s[42:43] sc1
	s_add_i32 s42, s40, 0xffffdffd
	s_mov_b32 s43, s27
	s_lshl_b64 s[46:47], s[42:43], 2
	s_add_u32 s43, s4, s46
	s_addc_u32 s46, s5, s47
	s_add_u32 s47, s43, 0x800
	s_addc_u32 s43, s46, 0
	s_add_u32 s46, s22, 0xffff7ff4
	s_addc_u32 s48, s23, -1
	s_cmpk_lt_u32 s42, 0x200
	s_cselect_b32 s43, s43, s48
	s_cselect_b32 s42, s47, s46
	global_load_dword v130, v1, s[42:43] sc1
	s_add_i32 s42, s40, 0xffffdffe
	s_mov_b32 s43, s27
	s_lshl_b64 s[46:47], s[42:43], 2
	s_add_u32 s43, s4, s46
	s_addc_u32 s46, s5, s47
	s_add_u32 s47, s43, 0x800
	s_addc_u32 s43, s46, 0
	s_add_u32 s46, s22, 0xffff7ff8
	s_addc_u32 s48, s23, -1
	s_cmpk_lt_u32 s42, 0x200
	s_cselect_b32 s43, s43, s48
	s_cselect_b32 s42, s47, s46
	global_load_dword v129, v1, s[42:43] sc1
	s_add_i32 s42, s40, 0xffffdfff
	s_mov_b32 s43, s27
	s_lshl_b64 s[46:47], s[42:43], 2
	s_add_u32 s4, s4, s46
	s_addc_u32 s5, s5, s47
	s_add_u32 s4, s4, 0x800
	s_addc_u32 s5, s5, 0
	s_add_u32 s22, s22, 0xffff7ffc
	s_addc_u32 s23, s23, -1
	s_cmpk_lt_u32 s42, 0x200
	s_cselect_b32 s5, s5, s23
	s_cselect_b32 s4, s4, s22
	global_load_dword v131, v1, s[4:5] sc1
	s_waitcnt vmcnt(60)
	v_pk_mul_f32 v[2:3], v[2:3], v[70:71]
	s_waitcnt vmcnt(56)
	v_pk_mul_f32 v[8:9], v[8:9], v[74:75]
	v_pk_mul_f32 v[4:5], v[4:5], v[68:69]
	v_pk_mul_f32 v[12:13], v[12:13], v[72:73]
	v_bfe_u32 v0, v9, 16, 1
	v_bfe_u32 v68, v8, 16, 1
	v_bfe_u32 v69, v3, 16, 1
	v_bfe_u32 v70, v2, 16, 1
	v_add3_u32 v2, v2, v70, s53
	v_add3_u32 v3, v3, v69, s53
	v_add3_u32 v8, v8, v68, s53
	v_add3_u32 v0, v9, v0, s53
	v_bfe_u32 v9, v4, 16, 1
	v_bfe_u32 v68, v5, 16, 1
	v_bfe_u32 v69, v12, 16, 1
	v_bfe_u32 v70, v13, 16, 1
	v_add3_u32 v13, v13, v70, s53
	v_add3_u32 v12, v12, v69, s53
	v_add3_u32 v5, v5, v68, s53
	v_add3_u32 v4, v4, v9, s53
	v_lshrrev_b32_e32 v9, 16, v4
	v_lshrrev_b32_e32 v68, 16, v5
	v_lshrrev_b32_e32 v4, 16, v12
	v_lshrrev_b32_e32 v5, 16, v13
	v_and_or_b32 v5, v0, s45, v5
	v_and_or_b32 v4, v8, s45, v4
	v_and_or_b32 v3, v3, s45, v68
	v_and_or_b32 v2, v2, s45, v9
	ds_write_b128 v132, v[2:5]
	s_waitcnt vmcnt(52)
	v_pk_mul_f32 v[4:5], v[6:7], v[78:79]
	s_waitcnt vmcnt(48)
	v_pk_mul_f32 v[8:9], v[16:17], v[82:83]
	v_pk_mul_f32 v[2:3], v[10:11], v[76:77]
	v_pk_mul_f32 v[6:7], v[20:21], v[80:81]
	v_bfe_u32 v0, v9, 16, 1
	v_bfe_u32 v10, v8, 16, 1
	v_bfe_u32 v11, v5, 16, 1
	v_bfe_u32 v12, v4, 16, 1
	v_add3_u32 v12, v4, v12, s53
	v_add3_u32 v11, v5, v11, s53
	v_add3_u32 v4, v8, v10, s53
	v_add3_u32 v0, v9, v0, s53
	v_bfe_u32 v5, v2, 16, 1
	v_bfe_u32 v8, v3, 16, 1
	v_bfe_u32 v9, v6, 16, 1
	v_bfe_u32 v10, v7, 16, 1
	v_add3_u32 v7, v7, v10, s53
	v_add3_u32 v6, v6, v9, s53
	v_add3_u32 v3, v3, v8, s53
	v_add3_u32 v2, v2, v5, s53
	v_lshrrev_b32_e32 v2, 16, v2
	v_lshrrev_b32_e32 v3, 16, v3
	v_lshrrev_b32_e32 v6, 16, v6
	v_lshrrev_b32_e32 v5, 16, v7
	v_and_or_b32 v5, v0, s45, v5
	v_and_or_b32 v4, v4, s45, v6
	v_and_or_b32 v3, v11, s45, v3
	v_and_or_b32 v2, v12, s45, v2
	ds_write_b128 v133, v[2:5]
	s_waitcnt vmcnt(44)
	v_pk_mul_f32 v[4:5], v[14:15], v[86:87]
	s_waitcnt vmcnt(40)
	v_pk_mul_f32 v[8:9], v[24:25], v[90:91]
	v_pk_mul_f32 v[2:3], v[18:19], v[84:85]
	v_pk_mul_f32 v[6:7], v[28:29], v[88:89]
	v_bfe_u32 v0, v9, 16, 1
	v_bfe_u32 v10, v8, 16, 1
	v_bfe_u32 v11, v5, 16, 1
	v_bfe_u32 v12, v4, 16, 1
	v_add3_u32 v12, v4, v12, s53
	v_add3_u32 v11, v5, v11, s53
	v_add3_u32 v4, v8, v10, s53
	v_add3_u32 v0, v9, v0, s53
	v_bfe_u32 v5, v2, 16, 1
	v_bfe_u32 v8, v3, 16, 1
	v_bfe_u32 v9, v6, 16, 1
	v_bfe_u32 v10, v7, 16, 1
	v_add3_u32 v7, v7, v10, s53
	v_add3_u32 v6, v6, v9, s53
	v_add3_u32 v3, v3, v8, s53
	v_add3_u32 v2, v2, v5, s53
	v_lshrrev_b32_e32 v2, 16, v2
	v_lshrrev_b32_e32 v3, 16, v3
	v_lshrrev_b32_e32 v6, 16, v6
	v_lshrrev_b32_e32 v5, 16, v7
	v_and_or_b32 v5, v0, s45, v5
	v_and_or_b32 v4, v4, s45, v6
	v_and_or_b32 v3, v11, s45, v3
	v_and_or_b32 v2, v12, s45, v2
	ds_write_b128 v134, v[2:5]
	s_waitcnt vmcnt(36)
	v_pk_mul_f32 v[4:5], v[22:23], v[94:95]
	s_waitcnt vmcnt(32)
	v_pk_mul_f32 v[8:9], v[32:33], v[98:99]
	v_pk_mul_f32 v[2:3], v[26:27], v[92:93]
	v_pk_mul_f32 v[6:7], v[36:37], v[96:97]
	v_bfe_u32 v0, v9, 16, 1
	v_bfe_u32 v10, v8, 16, 1
	v_bfe_u32 v11, v5, 16, 1
	v_bfe_u32 v12, v4, 16, 1
	v_add3_u32 v12, v4, v12, s53
	v_add3_u32 v11, v5, v11, s53
	v_add3_u32 v4, v8, v10, s53
	v_add3_u32 v0, v9, v0, s53
	v_bfe_u32 v5, v2, 16, 1
	v_bfe_u32 v8, v3, 16, 1
	v_bfe_u32 v9, v6, 16, 1
	v_bfe_u32 v10, v7, 16, 1
	v_add3_u32 v7, v7, v10, s53
	v_add3_u32 v6, v6, v9, s53
	v_add3_u32 v3, v3, v8, s53
	v_add3_u32 v2, v2, v5, s53
	v_lshrrev_b32_e32 v2, 16, v2
	v_lshrrev_b32_e32 v3, 16, v3
	v_lshrrev_b32_e32 v6, 16, v6
	v_lshrrev_b32_e32 v5, 16, v7
	v_and_or_b32 v5, v0, s45, v5
	v_and_or_b32 v4, v4, s45, v6
	v_and_or_b32 v3, v11, s45, v3
	v_and_or_b32 v2, v12, s45, v2
	ds_write_b128 v135, v[2:5]
	s_waitcnt vmcnt(28)
	v_pk_mul_f32 v[4:5], v[30:31], v[102:103]
	s_waitcnt vmcnt(24)
	v_pk_mul_f32 v[8:9], v[40:41], v[106:107]
	v_pk_mul_f32 v[2:3], v[34:35], v[100:101]
	v_pk_mul_f32 v[6:7], v[44:45], v[104:105]
	v_bfe_u32 v0, v9, 16, 1
	v_bfe_u32 v10, v8, 16, 1
	v_bfe_u32 v11, v5, 16, 1
	v_bfe_u32 v12, v4, 16, 1
	v_add3_u32 v12, v4, v12, s53
	v_add3_u32 v11, v5, v11, s53
	v_add3_u32 v4, v8, v10, s53
	v_add3_u32 v0, v9, v0, s53
	v_bfe_u32 v5, v2, 16, 1
	v_bfe_u32 v8, v3, 16, 1
	v_bfe_u32 v9, v6, 16, 1
	v_bfe_u32 v10, v7, 16, 1
	v_add3_u32 v7, v7, v10, s53
	v_add3_u32 v6, v6, v9, s53
	v_add3_u32 v3, v3, v8, s53
	v_add3_u32 v2, v2, v5, s53
	v_lshrrev_b32_e32 v2, 16, v2
	v_lshrrev_b32_e32 v3, 16, v3
	v_lshrrev_b32_e32 v6, 16, v6
	v_lshrrev_b32_e32 v5, 16, v7
	v_and_or_b32 v5, v0, s45, v5
	v_and_or_b32 v4, v4, s45, v6
	v_and_or_b32 v3, v11, s45, v3
	v_and_or_b32 v2, v12, s45, v2
	ds_write_b128 v136, v[2:5]
	s_waitcnt vmcnt(20)
	v_pk_mul_f32 v[4:5], v[38:39], v[110:111]
	s_waitcnt vmcnt(16)
	v_pk_mul_f32 v[8:9], v[48:49], v[114:115]
	v_pk_mul_f32 v[2:3], v[42:43], v[108:109]
	v_pk_mul_f32 v[6:7], v[52:53], v[112:113]
	v_bfe_u32 v0, v9, 16, 1
	v_bfe_u32 v10, v8, 16, 1
	v_bfe_u32 v11, v5, 16, 1
	v_bfe_u32 v12, v4, 16, 1
	v_add3_u32 v12, v4, v12, s53
	v_add3_u32 v11, v5, v11, s53
	v_add3_u32 v4, v8, v10, s53
	v_add3_u32 v0, v9, v0, s53
	v_bfe_u32 v5, v2, 16, 1
	v_bfe_u32 v8, v3, 16, 1
	v_bfe_u32 v9, v6, 16, 1
	v_bfe_u32 v10, v7, 16, 1
	v_add3_u32 v7, v7, v10, s53
	v_add3_u32 v6, v6, v9, s53
	v_add3_u32 v3, v3, v8, s53
	v_add3_u32 v2, v2, v5, s53
	v_lshrrev_b32_e32 v2, 16, v2
	v_lshrrev_b32_e32 v3, 16, v3
	v_lshrrev_b32_e32 v6, 16, v6
	v_lshrrev_b32_e32 v5, 16, v7
	v_and_or_b32 v5, v0, s45, v5
	v_and_or_b32 v4, v4, s45, v6
	v_and_or_b32 v3, v11, s45, v3
	v_and_or_b32 v2, v12, s45, v2
	ds_write_b128 v137, v[2:5]
	s_waitcnt vmcnt(12)
	v_pk_mul_f32 v[4:5], v[46:47], v[118:119]
	s_waitcnt vmcnt(8)
	v_pk_mul_f32 v[8:9], v[56:57], v[122:123]
	v_pk_mul_f32 v[2:3], v[50:51], v[116:117]
	v_pk_mul_f32 v[6:7], v[60:61], v[120:121]
	v_bfe_u32 v0, v9, 16, 1
	v_bfe_u32 v10, v8, 16, 1
	v_bfe_u32 v11, v5, 16, 1
	v_bfe_u32 v12, v4, 16, 1
	v_add3_u32 v12, v4, v12, s53
	v_add3_u32 v11, v5, v11, s53
	v_add3_u32 v4, v8, v10, s53
	v_add3_u32 v0, v9, v0, s53
	v_bfe_u32 v5, v2, 16, 1
	v_bfe_u32 v8, v3, 16, 1
	v_bfe_u32 v9, v6, 16, 1
	v_bfe_u32 v10, v7, 16, 1
	v_add3_u32 v7, v7, v10, s53
	v_add3_u32 v6, v6, v9, s53
	v_add3_u32 v3, v3, v8, s53
	v_add3_u32 v2, v2, v5, s53
	v_lshrrev_b32_e32 v2, 16, v2
	v_lshrrev_b32_e32 v3, 16, v3
	v_lshrrev_b32_e32 v6, 16, v6
	v_lshrrev_b32_e32 v5, 16, v7
	v_and_or_b32 v5, v0, s45, v5
	v_and_or_b32 v4, v4, s45, v6
	v_and_or_b32 v3, v11, s45, v3
	v_and_or_b32 v2, v12, s45, v2
	ds_write_b128 v138, v[2:5]
	s_waitcnt vmcnt(4)
	v_pk_mul_f32 v[4:5], v[54:55], v[126:127]
	s_waitcnt vmcnt(0)
	v_pk_mul_f32 v[8:9], v[64:65], v[130:131]
	v_pk_mul_f32 v[2:3], v[58:59], v[124:125]
	v_pk_mul_f32 v[6:7], v[66:67], v[128:129]
	v_bfe_u32 v0, v9, 16, 1
	v_bfe_u32 v10, v8, 16, 1
	v_bfe_u32 v11, v5, 16, 1
	v_bfe_u32 v12, v4, 16, 1
	v_add3_u32 v12, v4, v12, s53
	v_add3_u32 v11, v5, v11, s53
	v_add3_u32 v4, v8, v10, s53
	v_add3_u32 v0, v9, v0, s53
	v_bfe_u32 v5, v2, 16, 1
	v_bfe_u32 v8, v3, 16, 1
	v_bfe_u32 v9, v6, 16, 1
	v_bfe_u32 v10, v7, 16, 1
	v_add3_u32 v7, v7, v10, s53
	v_add3_u32 v6, v6, v9, s53
	v_add3_u32 v3, v3, v8, s53
	v_add3_u32 v2, v2, v5, s53
	v_lshrrev_b32_e32 v2, 16, v2
	v_lshrrev_b32_e32 v3, 16, v3
	v_lshrrev_b32_e32 v6, 16, v6
	v_lshrrev_b32_e32 v5, 16, v7
	v_and_or_b32 v5, v0, s45, v5
	v_and_or_b32 v4, v4, s45, v6
	v_and_or_b32 v3, v11, s45, v3
	v_and_or_b32 v2, v12, s45, v2
	ds_write_b128 v139, v[2:5]
	s_waitcnt lgkmcnt(0)
	v_add_u32_e32 v6, v63, v140
	ds_read_b128 v[2:5], v6
	v_or_b32_e32 v0, s41, v141
	v_lshlrev_b32_e32 v0, 11, v0
	v_lshl_add_u32 v7, s26, 1, v0
	s_and_b32 s17, s17, 0xffff
	v_or_b32_e32 v7, v7, v142
	s_waitcnt lgkmcnt(0)
	buffer_store_dwordx4 v[2:5], v7, s[16:19], 0 offen sc1
	ds_read_b128 v[2:5], v6 offset:1024
	s_lshl_b32 s4, s40, 1
	s_add_i32 s5, s4, 0xffffff80
	v_add_u32_e32 v7, s5, v0
	v_or_b32_e32 v7, v7, v142
	s_waitcnt lgkmcnt(0)
	buffer_store_dwordx4 v[2:5], v7, s[16:19], 0 offen sc1
	ds_read_b128 v[2:5], v6 offset:2048
	s_add_i32 s5, s4, 0x3f80
	v_add_u32_e32 v7, s5, v0
	v_or_b32_e32 v7, v7, v142
	s_add_i32 s5, s4, 0x7f80
	s_waitcnt lgkmcnt(0)
	buffer_store_dwordx4 v[2:5], v7, s[16:19], 0 offen sc1
	ds_read_b128 v[2:5], v6 offset:3072
	v_add_u32_e32 v7, s5, v0
	v_or_b32_e32 v7, v7, v142
	s_add_i32 s5, s4, 0xbf80
	s_waitcnt lgkmcnt(0)
	buffer_store_dwordx4 v[2:5], v7, s[16:19], 0 offen sc1
	ds_read_b128 v[2:5], v6 offset:4096
	v_add_u32_e32 v7, s5, v0
	v_or_b32_e32 v7, v7, v142
	s_add_i32 s5, s4, 0xff80
	s_waitcnt lgkmcnt(0)
	buffer_store_dwordx4 v[2:5], v7, s[16:19], 0 offen sc1
	ds_read_b128 v[2:5], v6 offset:5120
	v_add_u32_e32 v7, s5, v0
	v_or_b32_e32 v7, v7, v142
	s_add_i32 s5, s4, 0x13f80
	s_add_i32 s4, s4, 0x17f80
	s_waitcnt lgkmcnt(0)
	buffer_store_dwordx4 v[2:5], v7, s[16:19], 0 offen sc1
	ds_read_b128 v[2:5], v6 offset:6144
	v_add_u32_e32 v7, s5, v0
	v_or_b32_e32 v7, v7, v142
	v_add_u32_e32 v0, s4, v0
	v_or_b32_e32 v0, v0, v142
	s_waitcnt lgkmcnt(0)
	buffer_store_dwordx4 v[2:5], v7, s[16:19], 0 offen sc1
	ds_read_b128 v[2:5], v6 offset:7168
	s_waitcnt lgkmcnt(0)
	buffer_store_dwordx4 v[2:5], v0, s[16:19], 0 offen sc1
	s_waitcnt lgkmcnt(0)

.LBB0_483:
	s_mov_b32 s4, 7
	s_ashr_i32 s5, s4, 31
	s_and_b32 s41, 0xffff, s16
	s_lshl_b64 s[4:5], s[4:5], 3
	s_add_u32 s4, s0, s4
	s_addc_u32 s5, s1, s5
	s_load_dwordx2 s[4:5], s[4:5], 0x0
	s_mov_b32 s16, 6
	s_ashr_i32 s17, s16, 31
	s_lshl_b64 s[16:17], s[16:17], 3
	s_add_u32 s16, s0, s16
	s_addc_u32 s17, s1, s17
	s_mul_i32 s23, s41, 0xa0800
	s_waitcnt lgkmcnt(0)
	s_add_u32 s23, s4, s23
	s_addc_u32 s42, s5, 0
	s_lshl_b64 s[4:5], s[26:27], 2
	s_add_u32 s4, s23, s4
	s_addc_u32 s5, s42, s5
	v_lshlrev_b32_e32 v0, 2, v62
	v_lshl_add_u64 v[2:3], s[4:5], 0, v[0:1]
	s_mov_b64 s[4:5], 0xa08000
	v_lshl_add_u64 v[6:7], v[2:3], 0, s[4:5]
	v_cmp_gt_u32_e64 s[4:5], s22, v62
	v_mov_b32_e32 v4, 0
	v_mov_b32_e32 v2, 0
	s_and_saveexec_b64 s[22:23], s[4:5]
	s_cbranch_execz .LBB0_485
	global_load_dword v2, v[6:7], off sc1 nt
.LBB0_485:
	s_or_b64 exec, exec, s[22:23]
	s_load_dwordx2 s[22:23], s[16:17], 0x0
	s_and_saveexec_b64 s[16:17], s[4:5]
	s_cbranch_execz .LBB0_487
	v_add_co_u32_e32 v4, vcc, 0x2000, v6
	s_nop 1
	v_addc_co_u32_e32 v5, vcc, 0, v7, vcc
	global_load_dword v4, v[4:5], off offset:2080 sc1 nt
.LBB0_487:
	s_or_b64 exec, exec, s[16:17]
	v_mov_b32_e32 v5, 0
	v_mov_b32_e32 v3, 0
	s_and_saveexec_b64 s[16:17], s[4:5]
	s_cbranch_execz .LBB0_489
	v_add_co_u32_e32 v8, vcc, 0x5000, v6
	s_nop 1
	v_addc_co_u32_e32 v9, vcc, 0, v7, vcc
	global_load_dword v3, v[8:9], off offset:64 sc1 nt
.LBB0_489:
	s_or_b64 exec, exec, s[16:17]
	s_and_saveexec_b64 s[16:17], s[4:5]
	s_cbranch_execz .LBB0_491
	v_add_co_u32_e32 v8, vcc, 0x7000, v6
	s_nop 1
	v_addc_co_u32_e32 v9, vcc, 0, v7, vcc
	global_load_dword v5, v[8:9], off offset:2144 sc1 nt
.LBB0_491:
	s_or_b64 exec, exec, s[16:17]
	v_mov_b32_e32 v8, 0
	v_mov_b32_e32 v10, 0
	s_and_saveexec_b64 s[16:17], s[4:5]
	s_cbranch_execz .LBB0_493
	v_add_co_u32_e32 v10, vcc, 0xa000, v6
	s_nop 1
	v_addc_co_u32_e32 v11, vcc, 0, v7, vcc
	global_load_dword v10, v[10:11], off offset:128 sc1 nt
.LBB0_493:
	s_or_b64 exec, exec, s[16:17]
	s_and_saveexec_b64 s[16:17], s[4:5]
	s_cbranch_execz .LBB0_495
	v_add_co_u32_e32 v8, vcc, 0xc000, v6
	s_nop 1
	v_addc_co_u32_e32 v9, vcc, 0, v7, vcc
	global_load_dword v8, v[8:9], off offset:2208 sc1 nt
.LBB0_495:
	s_or_b64 exec, exec, s[16:17]
	v_mov_b32_e32 v9, 0
	v_mov_b32_e32 v11, 0
	s_and_saveexec_b64 s[16:17], s[4:5]
	s_cbranch_execz .LBB0_497
	v_add_co_u32_e32 v12, vcc, 0xf000, v6
	s_nop 1
	v_addc_co_u32_e32 v13, vcc, 0, v7, vcc
	global_load_dword v11, v[12:13], off offset:192 sc1 nt
.LBB0_497:
	s_or_b64 exec, exec, s[16:17]
	s_and_saveexec_b64 s[16:17], s[4:5]
	s_cbranch_execz .LBB0_499
	v_add_co_u32_e32 v12, vcc, 0x11000, v6
	s_nop 1
	v_addc_co_u32_e32 v13, vcc, 0, v7, vcc
	global_load_dword v9, v[12:13], off offset:2272 sc1 nt
.LBB0_499:
	s_or_b64 exec, exec, s[16:17]
	v_mov_b32_e32 v12, 0
	v_mov_b32_e32 v60, 0
	s_and_saveexec_b64 s[16:17], s[4:5]
	s_cbranch_execz .LBB0_501
	v_add_co_u32_e32 v14, vcc, 0x14000, v6
	s_nop 1
	v_addc_co_u32_e32 v15, vcc, 0, v7, vcc
	global_load_dword v60, v[14:15], off offset:256 sc1 nt
.LBB0_501:
	s_or_b64 exec, exec, s[16:17]
	s_and_saveexec_b64 s[16:17], s[4:5]
	s_cbranch_execz .LBB0_503
	v_add_co_u32_e32 v12, vcc, 0x16000, v6
	s_nop 1
	v_addc_co_u32_e32 v13, vcc, 0, v7, vcc
	global_load_dword v12, v[12:13], off offset:2336 sc1 nt
.LBB0_503:
	s_or_b64 exec, exec, s[16:17]
	v_mov_b32_e32 v13, 0
	v_mov_b32_e32 v61, 0
	s_and_saveexec_b64 s[16:17], s[4:5]
	s_cbranch_execz .LBB0_505
	v_add_co_u32_e32 v14, vcc, 0x19000, v6
	s_nop 1
	v_addc_co_u32_e32 v15, vcc, 0, v7, vcc
	global_load_dword v61, v[14:15], off offset:320 sc1 nt
.LBB0_505:
	s_or_b64 exec, exec, s[16:17]
	s_and_saveexec_b64 s[16:17], s[4:5]
	s_cbranch_execz .LBB0_507
	v_add_co_u32_e32 v14, vcc, 0x1b000, v6
	s_nop 1
	v_addc_co_u32_e32 v15, vcc, 0, v7, vcc
	global_load_dword v13, v[14:15], off offset:2400 sc1 nt
.LBB0_507:
	s_or_b64 exec, exec, s[16:17]
	v_mov_b32_e32 v66, 0
	v_mov_b32_e32 v68, 0
	s_and_saveexec_b64 s[16:17], s[4:5]
	s_cbranch_execz .LBB0_509
	v_add_co_u32_e32 v14, vcc, 0x1e000, v6
	s_nop 1
	v_addc_co_u32_e32 v15, vcc, 0, v7, vcc
	global_load_dword v68, v[14:15], off offset:384 sc1 nt
.LBB0_509:
	s_or_b64 exec, exec, s[16:17]
	s_and_saveexec_b64 s[16:17], s[4:5]
	s_cbranch_execz .LBB0_511
	v_add_co_u32_e32 v14, vcc, 0x20000, v6
	s_nop 1
	v_addc_co_u32_e32 v15, vcc, 0, v7, vcc
	global_load_dword v66, v[14:15], off offset:2464 sc1 nt
.LBB0_511:
	s_or_b64 exec, exec, s[16:17]
	v_mov_b32_e32 v67, 0
	v_mov_b32_e32 v69, 0
	s_and_saveexec_b64 s[16:17], s[4:5]
	s_cbranch_execz .LBB0_513
	v_add_co_u32_e32 v14, vcc, 0x23000, v6
	s_nop 1
	v_addc_co_u32_e32 v15, vcc, 0, v7, vcc
	global_load_dword v69, v[14:15], off offset:448 sc1 nt
.LBB0_513:
	s_or_b64 exec, exec, s[16:17]
	s_and_saveexec_b64 s[16:17], s[4:5]
	s_cbranch_execz .LBB0_515
	v_add_co_u32_e32 v14, vcc, 0x25000, v6
	s_nop 1
	v_addc_co_u32_e32 v15, vcc, 0, v7, vcc
	global_load_dword v67, v[14:15], off offset:2528 sc1 nt
.LBB0_515:
	s_or_b64 exec, exec, s[16:17]
	v_mov_b32_e32 v34, 0
	v_mov_b32_e32 v36, 0
	s_and_saveexec_b64 s[16:17], s[4:5]
	s_cbranch_execz .LBB0_517
	v_add_co_u32_e32 v14, vcc, 0x28000, v6
	s_nop 1
	v_addc_co_u32_e32 v15, vcc, 0, v7, vcc
	global_load_dword v36, v[14:15], off offset:512 sc1 nt
.LBB0_517:
	s_or_b64 exec, exec, s[16:17]
	s_and_saveexec_b64 s[16:17], s[4:5]
	s_cbranch_execz .LBB0_519
	v_add_co_u32_e32 v14, vcc, 0x2a000, v6
	s_nop 1
	v_addc_co_u32_e32 v15, vcc, 0, v7, vcc
	global_load_dword v34, v[14:15], off offset:2592 sc1 nt
.LBB0_519:
	s_or_b64 exec, exec, s[16:17]
	v_mov_b32_e32 v35, 0
	v_mov_b32_e32 v37, 0
	s_and_saveexec_b64 s[16:17], s[4:5]
	s_cbranch_execz .LBB0_521
	v_add_co_u32_e32 v14, vcc, 0x2d000, v6
	s_nop 1
	v_addc_co_u32_e32 v15, vcc, 0, v7, vcc
	global_load_dword v37, v[14:15], off offset:576 sc1 nt
.LBB0_521:
	s_or_b64 exec, exec, s[16:17]
	s_and_saveexec_b64 s[16:17], s[4:5]
	s_cbranch_execz .LBB0_523
	v_add_co_u32_e32 v14, vcc, 0x2f000, v6
	s_nop 1
	v_addc_co_u32_e32 v15, vcc, 0, v7, vcc
	global_load_dword v35, v[14:15], off offset:2656 sc1 nt
.LBB0_523:
	s_or_b64 exec, exec, s[16:17]
	v_mov_b32_e32 v46, 0
	v_mov_b32_e32 v48, 0
	s_and_saveexec_b64 s[16:17], s[4:5]
	s_cbranch_execz .LBB0_525
	v_add_co_u32_e32 v14, vcc, 0x32000, v6
	s_nop 1
	v_addc_co_u32_e32 v15, vcc, 0, v7, vcc
	global_load_dword v48, v[14:15], off offset:640 sc1 nt
.LBB0_525:
	s_or_b64 exec, exec, s[16:17]
	s_and_saveexec_b64 s[16:17], s[4:5]
	s_cbranch_execz .LBB0_527
	v_add_co_u32_e32 v14, vcc, 0x34000, v6
	s_nop 1
	v_addc_co_u32_e32 v15, vcc, 0, v7, vcc
	global_load_dword v46, v[14:15], off offset:2720 sc1 nt
.LBB0_527:
	s_or_b64 exec, exec, s[16:17]
	v_mov_b32_e32 v47, 0
	v_mov_b32_e32 v49, 0
	s_and_saveexec_b64 s[16:17], s[4:5]
	s_cbranch_execz .LBB0_529
	v_add_co_u32_e32 v14, vcc, 0x37000, v6
	s_nop 1
	v_addc_co_u32_e32 v15, vcc, 0, v7, vcc
	global_load_dword v49, v[14:15], off offset:704 sc1 nt
.LBB0_529:
	s_or_b64 exec, exec, s[16:17]
	s_and_saveexec_b64 s[16:17], s[4:5]
	s_cbranch_execz .LBB0_531
	v_add_co_u32_e32 v14, vcc, 0x39000, v6
	s_nop 1
	v_addc_co_u32_e32 v15, vcc, 0, v7, vcc
	global_load_dword v47, v[14:15], off offset:2784 sc1 nt
.LBB0_531:
	s_or_b64 exec, exec, s[16:17]
	v_mov_b32_e32 v50, 0
	v_mov_b32_e32 v52, 0
	s_and_saveexec_b64 s[16:17], s[4:5]
	s_cbranch_execz .LBB0_533
	v_add_co_u32_e32 v14, vcc, 0x3c000, v6
	s_nop 1
	v_addc_co_u32_e32 v15, vcc, 0, v7, vcc
	global_load_dword v52, v[14:15], off offset:768 sc1 nt
.LBB0_533:
	s_or_b64 exec, exec, s[16:17]
	s_and_saveexec_b64 s[16:17], s[4:5]
	s_cbranch_execz .LBB0_535
	v_add_co_u32_e32 v14, vcc, 0x3e000, v6
	s_nop 1
	v_addc_co_u32_e32 v15, vcc, 0, v7, vcc
	global_load_dword v50, v[14:15], off offset:2848 sc1 nt
.LBB0_535:
	s_or_b64 exec, exec, s[16:17]
	v_mov_b32_e32 v51, 0
	v_mov_b32_e32 v53, 0
	s_and_saveexec_b64 s[16:17], s[4:5]
	s_cbranch_execz .LBB0_537
	v_add_co_u32_e32 v14, vcc, 0x41000, v6
	s_nop 1
	v_addc_co_u32_e32 v15, vcc, 0, v7, vcc
	global_load_dword v53, v[14:15], off offset:832 sc1 nt
.LBB0_537:
	s_or_b64 exec, exec, s[16:17]
	s_and_saveexec_b64 s[16:17], s[4:5]
	s_cbranch_execz .LBB0_539
	v_add_co_u32_e32 v14, vcc, 0x43000, v6
	s_nop 1
	v_addc_co_u32_e32 v15, vcc, 0, v7, vcc
	global_load_dword v51, v[14:15], off offset:2912 sc1 nt
.LBB0_539:
	s_or_b64 exec, exec, s[16:17]
	v_mov_b32_e32 v58, 0
	v_mov_b32_e32 v64, 0
	s_and_saveexec_b64 s[16:17], s[4:5]
	s_cbranch_execz .LBB0_541
	v_add_co_u32_e32 v14, vcc, 0x46000, v6
	s_nop 1
	v_addc_co_u32_e32 v15, vcc, 0, v7, vcc
	global_load_dword v64, v[14:15], off offset:896 sc1 nt
.LBB0_541:
	s_or_b64 exec, exec, s[16:17]
	s_and_saveexec_b64 s[16:17], s[4:5]
	s_cbranch_execz .LBB0_543
	v_add_co_u32_e32 v14, vcc, 0x48000, v6
	s_nop 1
	v_addc_co_u32_e32 v15, vcc, 0, v7, vcc
	global_load_dword v58, v[14:15], off offset:2976 sc1 nt
.LBB0_543:
	s_or_b64 exec, exec, s[16:17]
	v_mov_b32_e32 v59, 0
	v_mov_b32_e32 v65, 0
	s_and_saveexec_b64 s[16:17], s[4:5]
	s_cbranch_execz .LBB0_545
	v_add_co_u32_e32 v14, vcc, 0x4b000, v6
	s_nop 1
	v_addc_co_u32_e32 v15, vcc, 0, v7, vcc
	global_load_dword v65, v[14:15], off offset:960 sc1 nt
.LBB0_545:
	s_or_b64 exec, exec, s[16:17]
	s_and_saveexec_b64 s[16:17], s[4:5]
	s_cbranch_execz .LBB0_547
	v_add_co_u32_e32 v14, vcc, 0x4d000, v6
	s_nop 1
	v_addc_co_u32_e32 v15, vcc, 0, v7, vcc
	global_load_dword v59, v[14:15], off offset:3040 sc1 nt
.LBB0_547:
	s_or_b64 exec, exec, s[16:17]
	v_mov_b32_e32 v14, 0
	v_mov_b32_e32 v16, 0
	s_and_saveexec_b64 s[16:17], s[4:5]
	s_cbranch_execz .LBB0_549
	v_add_co_u32_e32 v16, vcc, 0x50000, v6
	s_nop 1
	v_addc_co_u32_e32 v17, vcc, 0, v7, vcc
	global_load_dword v16, v[16:17], off offset:1024 sc1 nt
.LBB0_549:
	s_or_b64 exec, exec, s[16:17]
	s_and_saveexec_b64 s[16:17], s[4:5]
	s_cbranch_execz .LBB0_551
	v_add_co_u32_e32 v14, vcc, 0x52000, v6
	s_nop 1
	v_addc_co_u32_e32 v15, vcc, 0, v7, vcc
	global_load_dword v14, v[14:15], off offset:3104 sc1 nt
.LBB0_551:
	s_or_b64 exec, exec, s[16:17]
	v_mov_b32_e32 v15, 0
	v_mov_b32_e32 v17, 0
	s_and_saveexec_b64 s[16:17], s[4:5]
	s_cbranch_execz .LBB0_553
	v_add_co_u32_e32 v18, vcc, 0x55000, v6
	s_nop 1
	v_addc_co_u32_e32 v19, vcc, 0, v7, vcc
	global_load_dword v17, v[18:19], off offset:1088 sc1 nt
.LBB0_553:
	s_or_b64 exec, exec, s[16:17]
	s_and_saveexec_b64 s[16:17], s[4:5]
	s_cbranch_execz .LBB0_555
	v_add_co_u32_e32 v18, vcc, 0x57000, v6
	s_nop 1
	v_addc_co_u32_e32 v19, vcc, 0, v7, vcc
	global_load_dword v15, v[18:19], off offset:3168 sc1 nt
.LBB0_555:
	s_or_b64 exec, exec, s[16:17]
	v_mov_b32_e32 v38, 0
	v_mov_b32_e32 v40, 0
	s_and_saveexec_b64 s[16:17], s[4:5]
	s_cbranch_execz .LBB0_557
	v_add_co_u32_e32 v18, vcc, 0x5a000, v6
	s_nop 1
	v_addc_co_u32_e32 v19, vcc, 0, v7, vcc
	global_load_dword v40, v[18:19], off offset:1152 sc1 nt
.LBB0_557:
	s_or_b64 exec, exec, s[16:17]
	s_and_saveexec_b64 s[16:17], s[4:5]
	s_cbranch_execz .LBB0_559
	v_add_co_u32_e32 v18, vcc, 0x5c000, v6
	s_nop 1
	v_addc_co_u32_e32 v19, vcc, 0, v7, vcc
	global_load_dword v38, v[18:19], off offset:3232 sc1 nt
.LBB0_559:
	s_or_b64 exec, exec, s[16:17]
	v_mov_b32_e32 v39, 0
	v_mov_b32_e32 v41, 0
	s_and_saveexec_b64 s[16:17], s[4:5]
	s_cbranch_execz .LBB0_561
	v_add_co_u32_e32 v18, vcc, 0x5f000, v6
	s_nop 1
	v_addc_co_u32_e32 v19, vcc, 0, v7, vcc
	global_load_dword v41, v[18:19], off offset:1216 sc1 nt
.LBB0_561:
	s_or_b64 exec, exec, s[16:17]
	s_and_saveexec_b64 s[16:17], s[4:5]
	s_cbranch_execz .LBB0_563
	v_add_co_u32_e32 v18, vcc, 0x61000, v6
	s_nop 1
	v_addc_co_u32_e32 v19, vcc, 0, v7, vcc
	global_load_dword v39, v[18:19], off offset:3296 sc1 nt
.LBB0_563:
	s_or_b64 exec, exec, s[16:17]
	v_mov_b32_e32 v42, 0
	v_mov_b32_e32 v44, 0
	s_and_saveexec_b64 s[16:17], s[4:5]
	s_cbranch_execz .LBB0_565
	v_add_co_u32_e32 v18, vcc, 0x64000, v6
	s_nop 1
	v_addc_co_u32_e32 v19, vcc, 0, v7, vcc
	global_load_dword v44, v[18:19], off offset:1280 sc1 nt
.LBB0_565:
	s_or_b64 exec, exec, s[16:17]
	s_and_saveexec_b64 s[16:17], s[4:5]
	s_cbranch_execz .LBB0_567
	v_add_co_u32_e32 v18, vcc, 0x66000, v6
	s_nop 1
	v_addc_co_u32_e32 v19, vcc, 0, v7, vcc
	global_load_dword v42, v[18:19], off offset:3360 sc1 nt
.LBB0_567:
	s_or_b64 exec, exec, s[16:17]
	v_mov_b32_e32 v43, 0
	v_mov_b32_e32 v45, 0
	s_and_saveexec_b64 s[16:17], s[4:5]
	s_cbranch_execz .LBB0_569
	v_add_co_u32_e32 v18, vcc, 0x69000, v6
	s_nop 1
	v_addc_co_u32_e32 v19, vcc, 0, v7, vcc
	global_load_dword v45, v[18:19], off offset:1344 sc1 nt
.LBB0_569:
	s_or_b64 exec, exec, s[16:17]
	s_and_saveexec_b64 s[16:17], s[4:5]
	s_cbranch_execz .LBB0_571
	v_add_co_u32_e32 v18, vcc, 0x6b000, v6
	s_nop 1
	v_addc_co_u32_e32 v19, vcc, 0, v7, vcc
	global_load_dword v43, v[18:19], off offset:3424 sc1 nt
.LBB0_571:
	s_or_b64 exec, exec, s[16:17]
	v_mov_b32_e32 v54, 0
	v_mov_b32_e32 v56, 0
	s_and_saveexec_b64 s[16:17], s[4:5]
	s_cbranch_execz .LBB0_573
	v_add_co_u32_e32 v18, vcc, 0x6e000, v6
	s_nop 1
	v_addc_co_u32_e32 v19, vcc, 0, v7, vcc
	global_load_dword v56, v[18:19], off offset:1408 sc1 nt
.LBB0_573:
	s_or_b64 exec, exec, s[16:17]
	s_and_saveexec_b64 s[16:17], s[4:5]
	s_cbranch_execz .LBB0_575
	v_add_co_u32_e32 v18, vcc, 0x70000, v6
	s_nop 1
	v_addc_co_u32_e32 v19, vcc, 0, v7, vcc
	global_load_dword v54, v[18:19], off offset:3488 sc1 nt
.LBB0_575:
	s_or_b64 exec, exec, s[16:17]
	v_mov_b32_e32 v55, 0
	v_mov_b32_e32 v57, 0
	s_and_saveexec_b64 s[16:17], s[4:5]
	s_cbranch_execz .LBB0_577
	v_add_co_u32_e32 v18, vcc, 0x73000, v6
	s_nop 1
	v_addc_co_u32_e32 v19, vcc, 0, v7, vcc
	global_load_dword v57, v[18:19], off offset:1472 sc1 nt
.LBB0_577:
	s_or_b64 exec, exec, s[16:17]
	s_and_saveexec_b64 s[16:17], s[4:5]
	s_cbranch_execz .LBB0_579
	v_add_co_u32_e32 v18, vcc, 0x75000, v6
	s_nop 1
	v_addc_co_u32_e32 v19, vcc, 0, v7, vcc
	global_load_dword v55, v[18:19], off offset:3552 sc1 nt
.LBB0_579:
	s_or_b64 exec, exec, s[16:17]
	v_mov_b32_e32 v18, 0
	v_mov_b32_e32 v20, 0
	s_and_saveexec_b64 s[16:17], s[4:5]
	s_cbranch_execz .LBB0_581
	v_add_co_u32_e32 v20, vcc, 0x78000, v6
	s_nop 1
	v_addc_co_u32_e32 v21, vcc, 0, v7, vcc
	global_load_dword v20, v[20:21], off offset:1536 sc1 nt
.LBB0_581:
	s_or_b64 exec, exec, s[16:17]
	s_and_saveexec_b64 s[16:17], s[4:5]
	s_cbranch_execz .LBB0_583
	v_add_co_u32_e32 v18, vcc, 0x7a000, v6
	s_nop 1
	v_addc_co_u32_e32 v19, vcc, 0, v7, vcc
	global_load_dword v18, v[18:19], off offset:3616 sc1 nt
.LBB0_583:
	s_or_b64 exec, exec, s[16:17]
	v_mov_b32_e32 v19, 0
	v_mov_b32_e32 v21, 0
	s_and_saveexec_b64 s[16:17], s[4:5]
	s_cbranch_execz .LBB0_585
	v_add_co_u32_e32 v22, vcc, 0x7d000, v6
	s_nop 1
	v_addc_co_u32_e32 v23, vcc, 0, v7, vcc
	global_load_dword v21, v[22:23], off offset:1600 sc1 nt
.LBB0_585:
	s_or_b64 exec, exec, s[16:17]
	s_and_saveexec_b64 s[16:17], s[4:5]
	s_cbranch_execz .LBB0_587
	v_add_co_u32_e32 v22, vcc, 0x7f000, v6
	s_nop 1
	v_addc_co_u32_e32 v23, vcc, 0, v7, vcc
	global_load_dword v19, v[22:23], off offset:3680 sc1 nt
.LBB0_587:
	s_or_b64 exec, exec, s[16:17]
	v_mov_b32_e32 v22, 0
	v_mov_b32_e32 v24, 0
	s_and_saveexec_b64 s[16:17], s[4:5]
	s_cbranch_execz .LBB0_589
	v_add_co_u32_e32 v24, vcc, 0x82000, v6
	s_nop 1
	v_addc_co_u32_e32 v25, vcc, 0, v7, vcc
	global_load_dword v24, v[24:25], off offset:1664 sc1 nt
.LBB0_589:
	s_or_b64 exec, exec, s[16:17]
	s_and_saveexec_b64 s[16:17], s[4:5]
	s_cbranch_execz .LBB0_591
	v_add_co_u32_e32 v22, vcc, 0x84000, v6
	s_nop 1
	v_addc_co_u32_e32 v23, vcc, 0, v7, vcc
	global_load_dword v22, v[22:23], off offset:3744 sc1 nt
.LBB0_591:
	s_or_b64 exec, exec, s[16:17]
	v_mov_b32_e32 v23, 0
	v_mov_b32_e32 v25, 0
	s_and_saveexec_b64 s[16:17], s[4:5]
	s_cbranch_execz .LBB0_593
	v_add_co_u32_e32 v26, vcc, 0x87000, v6
	s_nop 1
	v_addc_co_u32_e32 v27, vcc, 0, v7, vcc
	global_load_dword v25, v[26:27], off offset:1728 sc1 nt
.LBB0_593:
	s_or_b64 exec, exec, s[16:17]
	s_and_saveexec_b64 s[16:17], s[4:5]
	s_cbranch_execz .LBB0_595
	v_add_co_u32_e32 v26, vcc, 0x89000, v6
	s_nop 1
	v_addc_co_u32_e32 v27, vcc, 0, v7, vcc
	global_load_dword v23, v[26:27], off offset:3808 sc1 nt
.LBB0_595:
	s_or_b64 exec, exec, s[16:17]
	v_mov_b32_e32 v26, 0
	v_mov_b32_e32 v28, 0
	s_and_saveexec_b64 s[16:17], s[4:5]
	s_cbranch_execz .LBB0_597
	v_add_co_u32_e32 v28, vcc, 0x8c000, v6
	s_nop 1
	v_addc_co_u32_e32 v29, vcc, 0, v7, vcc
	global_load_dword v28, v[28:29], off offset:1792 sc1 nt
.LBB0_597:
	s_or_b64 exec, exec, s[16:17]
	s_and_saveexec_b64 s[16:17], s[4:5]
	s_cbranch_execz .LBB0_599
	v_add_co_u32_e32 v26, vcc, 0x8e000, v6
	s_nop 1
	v_addc_co_u32_e32 v27, vcc, 0, v7, vcc
	global_load_dword v26, v[26:27], off offset:3872 sc1 nt
.LBB0_599:
	s_or_b64 exec, exec, s[16:17]
	v_mov_b32_e32 v27, 0
	v_mov_b32_e32 v29, 0
	s_and_saveexec_b64 s[16:17], s[4:5]
	s_cbranch_execz .LBB0_601
	v_add_co_u32_e32 v30, vcc, 0x91000, v6
	s_nop 1
	v_addc_co_u32_e32 v31, vcc, 0, v7, vcc
	global_load_dword v29, v[30:31], off offset:1856 sc1 nt
.LBB0_601:
	s_or_b64 exec, exec, s[16:17]
	s_and_saveexec_b64 s[16:17], s[4:5]
	s_cbranch_execz .LBB0_603
	v_add_co_u32_e32 v30, vcc, 0x93000, v6
	s_nop 1
	v_addc_co_u32_e32 v31, vcc, 0, v7, vcc
	global_load_dword v27, v[30:31], off offset:3936 sc1 nt
.LBB0_603:
	s_or_b64 exec, exec, s[16:17]
	v_mov_b32_e32 v30, 0
	v_mov_b32_e32 v32, 0
	s_and_saveexec_b64 s[16:17], s[4:5]
	s_cbranch_execz .LBB0_605
	v_add_co_u32_e32 v32, vcc, 0x96000, v6
	s_nop 1
	v_addc_co_u32_e32 v33, vcc, 0, v7, vcc
	global_load_dword v32, v[32:33], off offset:1920 sc1 nt
.LBB0_605:
	s_or_b64 exec, exec, s[16:17]
	s_and_saveexec_b64 s[16:17], s[4:5]
	s_cbranch_execz .LBB0_607
	v_add_co_u32_e32 v30, vcc, 0x98000, v6
	s_nop 1
	v_addc_co_u32_e32 v31, vcc, 0, v7, vcc
	global_load_dword v30, v[30:31], off offset:4000 sc1 nt
.LBB0_607:
	s_or_b64 exec, exec, s[16:17]
	v_mov_b32_e32 v31, 0
	v_mov_b32_e32 v33, 0
	s_and_saveexec_b64 s[16:17], s[4:5]
	s_cbranch_execz .LBB0_609
	v_add_co_u32_e32 v70, vcc, 0x9b000, v6
	s_nop 1
	v_addc_co_u32_e32 v71, vcc, 0, v7, vcc
	global_load_dword v33, v[70:71], off offset:1984 sc1 nt
.LBB0_609:
	s_or_b64 exec, exec, s[16:17]
	s_and_saveexec_b64 s[16:17], s[4:5]
	s_cbranch_execz .LBB0_611
	v_add_co_u32_e32 v6, vcc, 0x9d000, v6
	s_nop 1
	v_addc_co_u32_e32 v7, vcc, 0, v7, vcc
	global_load_dword v31, v[6:7], off offset:4064 sc1 nt
.LBB0_611:
	s_or_b64 exec, exec, s[16:17]
	s_lshl_b32 s4, s41, 6
	s_add_u32 s16, s14, 0x3280000
	s_addc_u32 s17, s15, 0
	s_lshl_b32 s4, s4, 2
	s_waitcnt lgkmcnt(0)
	s_add_u32 s22, s22, s4
	s_addc_u32 s23, s23, 0
	s_add_u32 s4, s22, 0x1000
	s_addc_u32 s5, s23, 0
	global_load_dwordx4 v[70:73], v1, s[4:5] offset:48 sc1
	global_load_dwordx4 v[74:77], v1, s[4:5] offset:32 sc1
	global_load_dwordx4 v[78:81], v1, s[4:5] offset:16 sc1
	global_load_dwordx4 v[82:85], v254, s[22:23] sc1
	s_and_b32 s17, s17, 0xffff
	s_waitcnt vmcnt(0)
	v_mov_b32_e32 v6, v82
	v_mov_b32_e32 v7, v84
	v_pk_mul_f32 v[2:3], v[2:3], v[6:7]
	v_mov_b32_e32 v84, v83
	v_mov_b32_e32 v7, v80
	v_mov_b32_e32 v80, v79
	v_pk_mul_f32 v[4:5], v[4:5], v[84:85]
	v_mov_b32_e32 v6, v78
	v_pk_mul_f32 v[8:9], v[8:9], v[80:81]
	v_pk_mul_f32 v[6:7], v[10:11], v[6:7]
	v_bfe_u32 v0, v5, 16, 1
	v_bfe_u32 v10, v4, 16, 1
	v_bfe_u32 v11, v9, 16, 1
	v_bfe_u32 v78, v8, 16, 1
	v_add3_u32 v8, v8, v78, s53
	v_add3_u32 v9, v9, v11, s53
	v_add3_u32 v4, v4, v10, s53
	v_add3_u32 v0, v5, v0, s53
	v_bfe_u32 v5, v6, 16, 1
	v_bfe_u32 v10, v7, 16, 1
	v_bfe_u32 v11, v2, 16, 1
	v_bfe_u32 v78, v3, 16, 1
	v_add3_u32 v3, v3, v78, s53
	v_add3_u32 v2, v2, v11, s53
	v_add3_u32 v7, v7, v10, s53
	v_add3_u32 v5, v6, v5, s53
	v_lshrrev_b32_e32 v6, 16, v5
	v_lshrrev_b32_e32 v5, 16, v7
	v_lshrrev_b32_e32 v2, 16, v2
	v_lshrrev_b32_e32 v3, 16, v3
	v_and_or_b32 v3, v0, s45, v3
	v_and_or_b32 v2, v4, s45, v2
	v_and_or_b32 v5, v9, s45, v5
	v_and_or_b32 v4, v8, s45, v6
	ds_write_b128 v132, v[2:5]
	v_mov_b32_e32 v3, v76
	v_mov_b32_e32 v76, v75
	v_mov_b32_e32 v7, v72
	v_mov_b32_e32 v72, v71
	v_mov_b32_e32 v2, v74
	v_pk_mul_f32 v[4:5], v[12:13], v[76:77]
	v_mov_b32_e32 v6, v70
	v_pk_mul_f32 v[8:9], v[66:67], v[72:73]
	v_pk_mul_f32 v[2:3], v[60:61], v[2:3]
	v_pk_mul_f32 v[6:7], v[68:69], v[6:7]
	v_bfe_u32 v0, v9, 16, 1
	v_bfe_u32 v10, v8, 16, 1
	v_bfe_u32 v11, v5, 16, 1
	v_bfe_u32 v12, v4, 16, 1
	v_add3_u32 v12, v4, v12, s53
	v_add3_u32 v11, v5, v11, s53
	v_add3_u32 v4, v8, v10, s53
	v_add3_u32 v0, v9, v0, s53
	v_bfe_u32 v5, v2, 16, 1
	v_bfe_u32 v8, v3, 16, 1
	v_bfe_u32 v9, v6, 16, 1
	v_bfe_u32 v10, v7, 16, 1
	v_add3_u32 v7, v7, v10, s53
	v_add3_u32 v6, v6, v9, s53
	v_add3_u32 v3, v3, v8, s53
	v_add3_u32 v2, v2, v5, s53
	v_lshrrev_b32_e32 v2, 16, v2
	v_lshrrev_b32_e32 v3, 16, v3
	v_lshrrev_b32_e32 v6, 16, v6
	v_lshrrev_b32_e32 v5, 16, v7
	v_and_or_b32 v5, v0, s45, v5
	v_and_or_b32 v4, v4, s45, v6
	v_and_or_b32 v3, v11, s45, v3
	v_and_or_b32 v2, v12, s45, v2
	ds_write_b128 v133, v[2:5]
	global_load_dwordx4 v[2:5], v1, s[4:5] offset:112 sc1
	global_load_dwordx4 v[6:9], v1, s[4:5] offset:96 sc1
	global_load_dwordx4 v[10:13], v1, s[4:5] offset:80 sc1
	global_load_dwordx4 v[66:69], v1, s[4:5] offset:64 sc1
	s_waitcnt vmcnt(0)
	v_mov_b32_e32 v60, v66
	v_mov_b32_e32 v61, v68
	v_pk_mul_f32 v[36:37], v[36:37], v[60:61]
	v_mov_b32_e32 v68, v67
	v_mov_b32_e32 v61, v12
	v_mov_b32_e32 v12, v11
	v_pk_mul_f32 v[34:35], v[34:35], v[68:69]
	v_mov_b32_e32 v60, v10
	v_pk_mul_f32 v[10:11], v[46:47], v[12:13]
	v_pk_mul_f32 v[48:49], v[48:49], v[60:61]
	v_bfe_u32 v0, v11, 16, 1
	v_bfe_u32 v12, v10, 16, 1
	v_bfe_u32 v13, v35, 16, 1
	v_bfe_u32 v46, v34, 16, 1
	v_add3_u32 v34, v34, v46, s53
	v_add3_u32 v35, v35, v13, s53
	v_add3_u32 v10, v10, v12, s53
	v_add3_u32 v0, v11, v0, s53
	v_bfe_u32 v11, v36, 16, 1
	v_bfe_u32 v12, v37, 16, 1
	v_bfe_u32 v13, v48, 16, 1
	v_bfe_u32 v46, v49, 16, 1
	v_add3_u32 v46, v49, v46, s53
	v_add3_u32 v13, v48, v13, s53
	v_add3_u32 v12, v37, v12, s53
	v_add3_u32 v11, v36, v11, s53
	v_lshrrev_b32_e32 v36, 16, v11
	v_lshrrev_b32_e32 v11, 16, v12
	v_lshrrev_b32_e32 v12, 16, v13
	v_lshrrev_b32_e32 v13, 16, v46
	v_and_or_b32 v13, v0, s45, v13
	v_and_or_b32 v12, v10, s45, v12
	v_and_or_b32 v11, v35, s45, v11
	v_and_or_b32 v10, v34, s45, v36
	ds_write_b128 v134, v[10:13]
	v_mov_b32_e32 v11, v8
	v_mov_b32_e32 v8, v7
	v_mov_b32_e32 v10, v6
	v_pk_mul_f32 v[6:7], v[50:51], v[8:9]
	v_mov_b32_e32 v9, v4
	v_mov_b32_e32 v4, v3
	v_mov_b32_e32 v8, v2
	v_pk_mul_f32 v[2:3], v[58:59], v[4:5]
	v_pk_mul_f32 v[10:11], v[52:53], v[10:11]
	v_pk_mul_f32 v[8:9], v[64:65], v[8:9]
	v_bfe_u32 v0, v3, 16, 1
	v_bfe_u32 v4, v2, 16, 1
	v_bfe_u32 v5, v7, 16, 1
	v_bfe_u32 v12, v6, 16, 1
	v_add3_u32 v6, v6, v12, s53
	v_add3_u32 v7, v7, v5, s53
	v_add3_u32 v2, v2, v4, s53
	v_add3_u32 v0, v3, v0, s53
	v_bfe_u32 v3, v10, 16, 1
	v_bfe_u32 v4, v11, 16, 1
	v_bfe_u32 v5, v8, 16, 1
	v_bfe_u32 v12, v9, 16, 1
	v_add3_u32 v9, v9, v12, s53
	v_add3_u32 v5, v8, v5, s53
	v_add3_u32 v4, v11, v4, s53
	v_add3_u32 v3, v10, v3, s53
	v_lshrrev_b32_e32 v8, 16, v3
	v_lshrrev_b32_e32 v3, 16, v4
	v_lshrrev_b32_e32 v4, 16, v5
	v_lshrrev_b32_e32 v5, 16, v9
	v_and_or_b32 v5, v0, s45, v5
	v_and_or_b32 v4, v2, s45, v4
	v_and_or_b32 v3, v7, s45, v3
	v_and_or_b32 v2, v6, s45, v8
	ds_write_b128 v135, v[2:5]
	global_load_dwordx4 v[2:5], v1, s[4:5] offset:176 sc1
	global_load_dwordx4 v[6:9], v1, s[4:5] offset:160 sc1
	global_load_dwordx4 v[10:13], v1, s[4:5] offset:144 sc1
	global_load_dwordx4 v[34:37], v1, s[4:5] offset:128 sc1
	s_waitcnt vmcnt(0)
	v_mov_b32_e32 v47, v36
	v_mov_b32_e32 v36, v35
	v_mov_b32_e32 v35, v12
	v_mov_b32_e32 v12, v11
	v_mov_b32_e32 v46, v34
	v_pk_mul_f32 v[14:15], v[14:15], v[36:37]
	v_mov_b32_e32 v34, v10
	v_pk_mul_f32 v[10:11], v[38:39], v[12:13]
	v_pk_mul_f32 v[16:17], v[16:17], v[46:47]
	v_pk_mul_f32 v[34:35], v[40:41], v[34:35]
	v_bfe_u32 v0, v11, 16, 1
	v_bfe_u32 v12, v10, 16, 1
	v_bfe_u32 v13, v15, 16, 1
	v_bfe_u32 v36, v14, 16, 1
	v_add3_u32 v14, v14, v36, s53
	v_add3_u32 v15, v15, v13, s53
	v_add3_u32 v10, v10, v12, s53
	v_add3_u32 v0, v11, v0, s53
	v_bfe_u32 v11, v16, 16, 1
	v_bfe_u32 v12, v17, 16, 1
	v_bfe_u32 v13, v34, 16, 1
	v_bfe_u32 v36, v35, 16, 1
	v_add3_u32 v35, v35, v36, s53
	v_add3_u32 v13, v34, v13, s53
	v_add3_u32 v12, v17, v12, s53
	v_add3_u32 v11, v16, v11, s53
	v_lshrrev_b32_e32 v16, 16, v11
	v_lshrrev_b32_e32 v11, 16, v12
	v_lshrrev_b32_e32 v12, 16, v13
	v_lshrrev_b32_e32 v13, 16, v35
	v_and_or_b32 v13, v0, s45, v13
	v_and_or_b32 v12, v10, s45, v12
	v_and_or_b32 v11, v15, s45, v11
	v_and_or_b32 v10, v14, s45, v16
	ds_write_b128 v136, v[10:13]
	v_mov_b32_e32 v11, v8
	v_mov_b32_e32 v8, v7
	v_mov_b32_e32 v10, v6
	v_pk_mul_f32 v[6:7], v[42:43], v[8:9]
	v_mov_b32_e32 v9, v4
	v_mov_b32_e32 v4, v3
	v_mov_b32_e32 v8, v2
	v_pk_mul_f32 v[2:3], v[54:55], v[4:5]
	v_pk_mul_f32 v[10:11], v[44:45], v[10:11]
	v_pk_mul_f32 v[8:9], v[56:57], v[8:9]
	v_bfe_u32 v0, v3, 16, 1
	v_bfe_u32 v4, v2, 16, 1
	v_bfe_u32 v5, v7, 16, 1
	v_bfe_u32 v12, v6, 16, 1
	v_add3_u32 v6, v6, v12, s53
	v_add3_u32 v7, v7, v5, s53
	v_add3_u32 v2, v2, v4, s53
	v_add3_u32 v0, v3, v0, s53
	v_bfe_u32 v3, v10, 16, 1
	v_bfe_u32 v4, v11, 16, 1
	v_bfe_u32 v5, v8, 16, 1
	v_bfe_u32 v12, v9, 16, 1
	v_add3_u32 v9, v9, v12, s53
	v_add3_u32 v5, v8, v5, s53
	v_add3_u32 v4, v11, v4, s53
	v_add3_u32 v3, v10, v3, s53
	v_lshrrev_b32_e32 v8, 16, v3
	v_lshrrev_b32_e32 v3, 16, v4
	v_lshrrev_b32_e32 v4, 16, v5
	v_lshrrev_b32_e32 v5, 16, v9
	v_and_or_b32 v5, v0, s45, v5
	v_and_or_b32 v4, v2, s45, v4
	v_and_or_b32 v3, v7, s45, v3
	v_and_or_b32 v2, v6, s45, v8
	ds_write_b128 v137, v[2:5]
	global_load_dwordx4 v[2:5], v1, s[4:5] offset:240 sc1
	global_load_dwordx4 v[6:9], v1, s[4:5] offset:224 sc1
	global_load_dwordx4 v[10:13], v1, s[4:5] offset:208 sc1
	global_load_dwordx4 v[14:17], v1, s[4:5] offset:192 sc1
	s_lshl_b32 s4, s41, 7
	s_waitcnt vmcnt(0)
	v_mov_b32_e32 v35, v16
	v_mov_b32_e32 v16, v15
	v_mov_b32_e32 v34, v14
	v_pk_mul_f32 v[14:15], v[18:19], v[16:17]
	v_mov_b32_e32 v17, v12
	v_mov_b32_e32 v12, v11
	v_mov_b32_e32 v16, v10
	v_pk_mul_f32 v[10:11], v[22:23], v[12:13]
	v_pk_mul_f32 v[20:21], v[20:21], v[34:35]
	v_pk_mul_f32 v[16:17], v[24:25], v[16:17]
	v_bfe_u32 v0, v11, 16, 1
	v_bfe_u32 v12, v10, 16, 1
	v_bfe_u32 v13, v15, 16, 1
	v_bfe_u32 v18, v14, 16, 1
	v_add3_u32 v14, v14, v18, s53
	v_add3_u32 v15, v15, v13, s53
	v_add3_u32 v10, v10, v12, s53
	v_add3_u32 v0, v11, v0, s53
	v_bfe_u32 v11, v20, 16, 1
	v_bfe_u32 v12, v21, 16, 1
	v_bfe_u32 v13, v16, 16, 1
	v_bfe_u32 v18, v17, 16, 1
	v_add3_u32 v17, v17, v18, s53
	v_add3_u32 v13, v16, v13, s53
	v_add3_u32 v12, v21, v12, s53
	v_add3_u32 v11, v20, v11, s53
	v_lshrrev_b32_e32 v16, 16, v11
	v_lshrrev_b32_e32 v11, 16, v12
	v_lshrrev_b32_e32 v12, 16, v13
	v_lshrrev_b32_e32 v13, 16, v17
	v_and_or_b32 v13, v0, s45, v13
	v_and_or_b32 v12, v10, s45, v12
	v_and_or_b32 v11, v15, s45, v11
	v_and_or_b32 v10, v14, s45, v16
	ds_write_b128 v138, v[10:13]
	v_mov_b32_e32 v11, v8
	v_mov_b32_e32 v8, v7
	v_mov_b32_e32 v10, v6
	v_pk_mul_f32 v[6:7], v[26:27], v[8:9]
	v_mov_b32_e32 v9, v4
	v_mov_b32_e32 v4, v3
	v_mov_b32_e32 v8, v2
	v_pk_mul_f32 v[2:3], v[30:31], v[4:5]
	v_pk_mul_f32 v[10:11], v[28:29], v[10:11]
	v_pk_mul_f32 v[8:9], v[32:33], v[8:9]
	v_bfe_u32 v0, v3, 16, 1
	v_bfe_u32 v4, v2, 16, 1
	v_bfe_u32 v5, v7, 16, 1
	v_bfe_u32 v12, v6, 16, 1
	v_add3_u32 v6, v6, v12, s53
	v_add3_u32 v7, v7, v5, s53
	v_add3_u32 v2, v2, v4, s53
	v_add3_u32 v0, v3, v0, s53
	v_bfe_u32 v3, v10, 16, 1
	v_bfe_u32 v4, v11, 16, 1
	v_bfe_u32 v5, v8, 16, 1
	v_bfe_u32 v12, v9, 16, 1
	v_add3_u32 v9, v9, v12, s53
	v_add3_u32 v5, v8, v5, s53
	v_add3_u32 v4, v11, v4, s53
	v_add3_u32 v3, v10, v3, s53
	v_lshrrev_b32_e32 v8, 16, v3
	v_lshrrev_b32_e32 v3, 16, v4
	v_lshrrev_b32_e32 v4, 16, v5
	v_lshrrev_b32_e32 v5, 16, v9
	v_and_or_b32 v5, v0, s45, v5
	v_and_or_b32 v4, v2, s45, v4
	v_and_or_b32 v3, v7, s45, v3
	v_and_or_b32 v2, v6, s45, v8
	ds_write_b128 v139, v[2:5]
	s_waitcnt lgkmcnt(0)
	v_add_u32_e32 v6, v63, v140
	ds_read_b128 v[2:5], v6
	v_add_u32_e32 v0, s40, v141
	v_lshl_add_u32 v0, v0, 11, s4
	v_or_b32_e32 v0, v0, v142
	v_add_u32_e32 v7, 0x4000, v0
	s_waitcnt lgkmcnt(0)
	buffer_store_dwordx4 v[2:5], v0, s[16:19], 0 offen sc1
	ds_read_b128 v[2:5], v6 offset:1024
	s_waitcnt lgkmcnt(0)
	buffer_store_dwordx4 v[2:5], v7, s[16:19], 0 offen sc1
	ds_read_b128 v[2:5], v6 offset:2048
	v_add_u32_e32 v7, 0x8000, v0
	s_waitcnt lgkmcnt(0)
	buffer_store_dwordx4 v[2:5], v7, s[16:19], 0 offen sc1
	ds_read_b128 v[2:5], v6 offset:3072
	v_add_u32_e32 v7, 0xc000, v0
	s_waitcnt lgkmcnt(0)
	buffer_store_dwordx4 v[2:5], v7, s[16:19], 0 offen sc1
	ds_read_b128 v[2:5], v6 offset:4096
	v_add_u32_e32 v7, 0x10000, v0
	s_waitcnt lgkmcnt(0)
	buffer_store_dwordx4 v[2:5], v7, s[16:19], 0 offen sc1
	ds_read_b128 v[2:5], v6 offset:5120
	v_add_u32_e32 v7, 0x14000, v0
	s_waitcnt lgkmcnt(0)
	buffer_store_dwordx4 v[2:5], v7, s[16:19], 0 offen sc1
	ds_read_b128 v[2:5], v6 offset:6144
	v_add_u32_e32 v7, 0x18000, v0
	v_add_u32_e32 v0, 0x1c000, v0
	s_waitcnt lgkmcnt(0)
	buffer_store_dwordx4 v[2:5], v7, s[16:19], 0 offen sc1
	ds_read_b128 v[2:5], v6 offset:7168
	s_waitcnt lgkmcnt(0)
	buffer_store_dwordx4 v[2:5], v0, s[16:19], 0 offen sc1
	s_waitcnt lgkmcnt(0)

.LBB0_614:
	s_mul_hi_i32 s4, s25, 0x2e8ba2e9
	s_lshr_b32 s5, s4, 31
	s_lshr_b32 s4, s4, 7
	s_add_i32 s4, s4, s5
	s_mulk_i32 s4, 0x2c0
	s_sub_i32 s4, s25, s4
	s_sext_i32_i16 s5, s4
	s_bfe_u32 s5, s5, 0x4001b
	s_add_i32 s5, s4, s5
	s_sext_i32_i16 s23, s5
	s_and_b32 s5, s5, 0xfff0
	s_sub_i32 s4, s4, s5
	s_addk_i32 s25, 0x2bf
	s_cmpk_lt_u32 s25, 0x57f
	s_cselect_b64 s[16:17], -1, 0
	s_sext_i32_i16 s22, s4
	s_and_b64 s[4:5], s[16:17], exec
	s_cselect_b32 s4, 5, 24
	s_ashr_i32 s5, s4, 31
	s_lshl_b64 s[4:5], s[4:5], 3
	s_add_u32 s4, s0, s4
	s_addc_u32 s5, s1, s5
	s_load_dwordx2 s[40:41], s[4:5], 0x0
	s_lshl_b32 s4, s23, 2
	s_lshl_b32 s22, s22, 6
	s_andn2_b32 s4, s4, 63
	s_and_b64 s[16:17], s[16:17], exec
	s_mov_b32 s5, 0x580000
	s_cselect_b32 s5, s5, 0x2000000
	s_add_u32 s5, s14, s5
	s_addc_u32 s14, s15, 0
	s_add_u32 s16, s5, 0x2780000
	s_addc_u32 s14, s14, 0
	s_ashr_i32 s5, s4, 31
	s_lshl_b64 s[42:43], s[4:5], 12
	s_waitcnt lgkmcnt(0)
	s_add_u32 s5, s40, s42
	s_addc_u32 s15, s41, s43
	s_ashr_i32 s23, s22, 31
	s_lshl_b64 s[40:41], s[22:23], 2
	s_add_u32 s40, s5, s40
	s_addc_u32 s41, s15, s41
	v_lshlrev_b32_e32 v0, 2, v62
	v_lshl_add_u64 v[2:3], s[40:41], 0, v[0:1]
	s_mov_b32 s5, 0xb01000
	v_add_co_u32_e32 v4, vcc, s5, v2
	s_mov_b32 s5, 0xb03000
	s_nop 0
	v_addc_co_u32_e32 v5, vcc, 0, v3, vcc
	global_load_dword v6, v[4:5], off offset:-4096 sc1 nt
	global_load_dword v0, v[4:5], off sc1 nt
	v_add_co_u32_e32 v4, vcc, s5, v2
	s_mov_b32 s5, 0xb05000
	s_nop 0
	v_addc_co_u32_e32 v5, vcc, 0, v3, vcc
	global_load_dword v7, v[4:5], off offset:-4096 sc1 nt
	global_load_dword v8, v[4:5], off sc1 nt
	v_add_co_u32_e32 v4, vcc, s5, v2
	s_mov_b32 s5, 0xb07000
	s_nop 0
	v_addc_co_u32_e32 v5, vcc, 0, v3, vcc
	global_load_dword v9, v[4:5], off offset:-4096 sc1 nt
	global_load_dword v10, v[4:5], off sc1 nt
	v_add_co_u32_e32 v4, vcc, s5, v2
	s_mov_b32 s5, 0xb09000
	s_nop 0
	v_addc_co_u32_e32 v5, vcc, 0, v3, vcc
	global_load_dword v11, v[4:5], off offset:-4096 sc1 nt
	global_load_dword v12, v[4:5], off sc1 nt
	v_add_co_u32_e32 v4, vcc, s5, v2
	s_mov_b32 s5, 0xb0b000
	s_nop 0
	v_addc_co_u32_e32 v5, vcc, 0, v3, vcc
	global_load_dword v13, v[4:5], off offset:-4096 sc1 nt
	global_load_dword v14, v[4:5], off sc1 nt
	v_add_co_u32_e32 v4, vcc, s5, v2
	s_mov_b32 s5, 0xb0d000
	s_nop 0
	v_addc_co_u32_e32 v5, vcc, 0, v3, vcc
	global_load_dword v15, v[4:5], off offset:-4096 sc1 nt
	global_load_dword v16, v[4:5], off sc1 nt
	v_add_co_u32_e32 v4, vcc, s5, v2
	s_mov_b32 s5, 0xb0f000
	s_nop 0
	v_addc_co_u32_e32 v5, vcc, 0, v3, vcc
	global_load_dword v17, v[4:5], off offset:-4096 sc1 nt
	global_load_dword v18, v[4:5], off sc1 nt
	v_add_co_u32_e32 v4, vcc, s5, v2
	s_mov_b32 s5, 0xb11000
	s_nop 0
	v_addc_co_u32_e32 v5, vcc, 0, v3, vcc
	global_load_dword v19, v[4:5], off offset:-4096 sc1 nt
	global_load_dword v20, v[4:5], off sc1 nt
	v_add_co_u32_e32 v4, vcc, s5, v2
	s_mov_b32 s5, 0xb13000
	s_nop 0
	v_addc_co_u32_e32 v5, vcc, 0, v3, vcc
	global_load_dword v21, v[4:5], off offset:-4096 sc1 nt
	global_load_dword v22, v[4:5], off sc1 nt
	v_add_co_u32_e32 v4, vcc, s5, v2
	s_mov_b32 s5, 0xb15000
	s_nop 0
	v_addc_co_u32_e32 v5, vcc, 0, v3, vcc
	global_load_dword v23, v[4:5], off offset:-4096 sc1 nt
	global_load_dword v24, v[4:5], off sc1 nt
	v_add_co_u32_e32 v4, vcc, s5, v2
	s_mov_b32 s5, 0xb17000
	s_nop 0
	v_addc_co_u32_e32 v5, vcc, 0, v3, vcc
	global_load_dword v25, v[4:5], off offset:-4096 sc1 nt
	global_load_dword v26, v[4:5], off sc1 nt
	v_add_co_u32_e32 v4, vcc, s5, v2
	s_mov_b32 s5, 0xb19000
	s_nop 0
	v_addc_co_u32_e32 v5, vcc, 0, v3, vcc
	global_load_dword v27, v[4:5], off offset:-4096 sc1 nt
	global_load_dword v28, v[4:5], off sc1 nt
	v_add_co_u32_e32 v4, vcc, s5, v2
	s_mov_b32 s5, 0xb1b000
	s_nop 0
	v_addc_co_u32_e32 v5, vcc, 0, v3, vcc
	global_load_dword v29, v[4:5], off offset:-4096 sc1 nt
	global_load_dword v30, v[4:5], off sc1 nt
	v_add_co_u32_e32 v4, vcc, s5, v2
	s_mov_b32 s5, 0xb1d000
	s_nop 0
	v_addc_co_u32_e32 v5, vcc, 0, v3, vcc
	global_load_dword v31, v[4:5], off offset:-4096 sc1 nt
	global_load_dword v32, v[4:5], off sc1 nt
	v_add_co_u32_e32 v4, vcc, s5, v2
	s_mov_b32 s5, 0xb1f000
	s_nop 0
	v_addc_co_u32_e32 v5, vcc, 0, v3, vcc
	global_load_dword v33, v[4:5], off offset:-4096 sc1 nt
	global_load_dword v34, v[4:5], off sc1 nt
	v_add_co_u32_e32 v4, vcc, s5, v2
	s_mov_b32 s5, 0xb21000
	s_nop 0
	v_addc_co_u32_e32 v5, vcc, 0, v3, vcc
	global_load_dword v35, v[4:5], off offset:-4096 sc1 nt
	global_load_dword v36, v[4:5], off sc1 nt
	v_add_co_u32_e32 v4, vcc, s5, v2
	s_mov_b32 s5, 0xb23000
	s_nop 0
	v_addc_co_u32_e32 v5, vcc, 0, v3, vcc
	global_load_dword v37, v[4:5], off offset:-4096 sc1 nt
	global_load_dword v38, v[4:5], off sc1 nt
	v_add_co_u32_e32 v4, vcc, s5, v2
	s_mov_b32 s5, 0xb25000
	s_nop 0
	v_addc_co_u32_e32 v5, vcc, 0, v3, vcc
	global_load_dword v39, v[4:5], off offset:-4096 sc1 nt
	global_load_dword v40, v[4:5], off sc1 nt
	v_add_co_u32_e32 v4, vcc, s5, v2
	s_mov_b32 s5, 0xb27000
	s_nop 0
	v_addc_co_u32_e32 v5, vcc, 0, v3, vcc
	global_load_dword v41, v[4:5], off offset:-4096 sc1 nt
	global_load_dword v42, v[4:5], off sc1 nt
	v_add_co_u32_e32 v4, vcc, s5, v2
	s_mov_b32 s5, 0xb29000
	s_nop 0
	v_addc_co_u32_e32 v5, vcc, 0, v3, vcc
	global_load_dword v43, v[4:5], off offset:-4096 sc1 nt
	global_load_dword v44, v[4:5], off sc1 nt
	v_add_co_u32_e32 v4, vcc, s5, v2
	s_mov_b32 s5, 0xb2b000
	s_nop 0
	v_addc_co_u32_e32 v5, vcc, 0, v3, vcc
	global_load_dword v45, v[4:5], off offset:-4096 sc1 nt
	global_load_dword v46, v[4:5], off sc1 nt
	v_add_co_u32_e32 v4, vcc, s5, v2
	s_mov_b32 s5, 0xb2d000
	s_nop 0
	v_addc_co_u32_e32 v5, vcc, 0, v3, vcc
	global_load_dword v47, v[4:5], off offset:-4096 sc1 nt
	global_load_dword v48, v[4:5], off sc1 nt
	v_add_co_u32_e32 v4, vcc, s5, v2
	s_mov_b32 s5, 0xb2f000
	s_nop 0
	v_addc_co_u32_e32 v5, vcc, 0, v3, vcc
	global_load_dword v49, v[4:5], off offset:-4096 sc1 nt
	global_load_dword v50, v[4:5], off sc1 nt
	v_add_co_u32_e32 v4, vcc, s5, v2
	s_mov_b32 s5, 0xb31000
	s_nop 0
	v_addc_co_u32_e32 v5, vcc, 0, v3, vcc
	global_load_dword v51, v[4:5], off offset:-4096 sc1 nt
	global_load_dword v52, v[4:5], off sc1 nt
	v_add_co_u32_e32 v4, vcc, s5, v2
	s_mov_b32 s5, 0xb33000
	s_nop 0
	v_addc_co_u32_e32 v5, vcc, 0, v3, vcc
	global_load_dword v53, v[4:5], off offset:-4096 sc1 nt
	global_load_dword v54, v[4:5], off sc1 nt
	v_add_co_u32_e32 v4, vcc, s5, v2
	s_mov_b32 s5, 0xb35000
	s_nop 0
	v_addc_co_u32_e32 v5, vcc, 0, v3, vcc
	global_load_dword v55, v[4:5], off offset:-4096 sc1 nt
	global_load_dword v56, v[4:5], off sc1 nt
	v_add_co_u32_e32 v4, vcc, s5, v2
	s_mov_b32 s5, 0xb37000
	s_nop 0
	v_addc_co_u32_e32 v5, vcc, 0, v3, vcc
	global_load_dword v57, v[4:5], off offset:-4096 sc1 nt
	global_load_dword v58, v[4:5], off sc1 nt
	v_add_co_u32_e32 v4, vcc, s5, v2
	s_mov_b32 s5, 0xb39000
	s_nop 0
	v_addc_co_u32_e32 v5, vcc, 0, v3, vcc
	global_load_dword v59, v[4:5], off offset:-4096 sc1 nt
	global_load_dword v60, v[4:5], off sc1 nt
	v_add_co_u32_e32 v4, vcc, s5, v2
	s_mov_b32 s5, 0xb3b000
	s_nop 0
	v_addc_co_u32_e32 v5, vcc, 0, v3, vcc
	global_load_dword v61, v[4:5], off offset:-4096 sc1 nt
	global_load_dword v64, v[4:5], off sc1 nt
	v_add_co_u32_e32 v4, vcc, s5, v2
	s_mov_b32 s5, 0xb3d000
	s_nop 0
	v_addc_co_u32_e32 v5, vcc, 0, v3, vcc
	global_load_dword v65, v[4:5], off offset:-4096 sc1 nt
	global_load_dword v66, v[4:5], off sc1 nt
	v_add_co_u32_e32 v4, vcc, s5, v2
	s_mov_b32 s5, 0xb3f000
	s_nop 0
	v_addc_co_u32_e32 v5, vcc, 0, v3, vcc
	v_add_co_u32_e32 v2, vcc, s5, v2
	global_load_dword v67, v[4:5], off offset:-4096 sc1 nt
	global_load_dword v68, v[4:5], off sc1 nt
	v_addc_co_u32_e32 v3, vcc, 0, v3, vcc
	global_load_dword v69, v[2:3], off offset:-4096 sc1 nt
	global_load_dword v70, v[2:3], off sc1 nt
	s_waitcnt vmcnt(62)
	v_bfe_u32 v2, v6, 16, 1
	v_add3_u32 v2, v6, v2, s53
	v_bfe_u32 v3, v0, 16, 1
	v_lshrrev_b32_e32 v2, 16, v2
	v_add3_u32 v0, v0, v3, s53
	v_and_or_b32 v2, v0, s45, v2
	s_waitcnt vmcnt(61)
	v_bfe_u32 v0, v7, 16, 1
	v_add3_u32 v0, v7, v0, s53
	s_waitcnt vmcnt(60)
	v_bfe_u32 v3, v8, 16, 1
	v_lshrrev_b32_e32 v0, 16, v0
	v_add3_u32 v3, v8, v3, s53
	v_and_or_b32 v3, v3, s45, v0
	s_waitcnt vmcnt(59)
	v_bfe_u32 v0, v9, 16, 1
	v_add3_u32 v0, v9, v0, s53
	s_waitcnt vmcnt(58)
	v_bfe_u32 v4, v10, 16, 1
	v_lshrrev_b32_e32 v0, 16, v0
	v_add3_u32 v4, v10, v4, s53
	v_and_or_b32 v4, v4, s45, v0
	s_waitcnt vmcnt(57)
	v_bfe_u32 v0, v11, 16, 1
	v_add3_u32 v0, v11, v0, s53
	s_waitcnt vmcnt(56)
	v_bfe_u32 v5, v12, 16, 1
	v_lshrrev_b32_e32 v0, 16, v0
	v_add3_u32 v5, v12, v5, s53
	v_and_or_b32 v5, v5, s45, v0
	s_waitcnt vmcnt(55)
	v_bfe_u32 v0, v13, 16, 1
	ds_write_b128 v132, v[2:5]
	v_add3_u32 v0, v13, v0, s53
	s_waitcnt vmcnt(54)
	v_bfe_u32 v2, v14, 16, 1
	v_lshrrev_b32_e32 v0, 16, v0
	v_add3_u32 v2, v14, v2, s53
	v_and_or_b32 v2, v2, s45, v0
	s_waitcnt vmcnt(53)
	v_bfe_u32 v0, v15, 16, 1
	v_add3_u32 v0, v15, v0, s53
	s_waitcnt vmcnt(52)
	v_bfe_u32 v3, v16, 16, 1
	v_lshrrev_b32_e32 v0, 16, v0
	v_add3_u32 v3, v16, v3, s53
	v_and_or_b32 v3, v3, s45, v0
	s_waitcnt vmcnt(51)
	v_bfe_u32 v0, v17, 16, 1
	v_add3_u32 v0, v17, v0, s53
	s_waitcnt vmcnt(50)
	v_bfe_u32 v4, v18, 16, 1
	v_lshrrev_b32_e32 v0, 16, v0
	v_add3_u32 v4, v18, v4, s53
	v_and_or_b32 v4, v4, s45, v0
	s_waitcnt vmcnt(49)
	v_bfe_u32 v0, v19, 16, 1
	v_add3_u32 v0, v19, v0, s53
	s_waitcnt vmcnt(48)
	v_bfe_u32 v5, v20, 16, 1
	v_lshrrev_b32_e32 v0, 16, v0
	v_add3_u32 v5, v20, v5, s53
	v_and_or_b32 v5, v5, s45, v0
	s_waitcnt vmcnt(47)
	v_bfe_u32 v0, v21, 16, 1
	ds_write_b128 v133, v[2:5]
	v_add3_u32 v0, v21, v0, s53
	s_waitcnt vmcnt(46)
	v_bfe_u32 v2, v22, 16, 1
	v_lshrrev_b32_e32 v0, 16, v0
	v_add3_u32 v2, v22, v2, s53
	v_and_or_b32 v2, v2, s45, v0
	s_waitcnt vmcnt(45)
	v_bfe_u32 v0, v23, 16, 1
	v_add3_u32 v0, v23, v0, s53
	s_waitcnt vmcnt(44)
	v_bfe_u32 v3, v24, 16, 1
	v_lshrrev_b32_e32 v0, 16, v0
	v_add3_u32 v3, v24, v3, s53
	v_and_or_b32 v3, v3, s45, v0
	s_waitcnt vmcnt(43)
	v_bfe_u32 v0, v25, 16, 1
	v_add3_u32 v0, v25, v0, s53
	s_waitcnt vmcnt(42)
	v_bfe_u32 v4, v26, 16, 1
	v_lshrrev_b32_e32 v0, 16, v0
	v_add3_u32 v4, v26, v4, s53
	v_and_or_b32 v4, v4, s45, v0
	s_waitcnt vmcnt(41)
	v_bfe_u32 v0, v27, 16, 1
	v_add3_u32 v0, v27, v0, s53
	s_waitcnt vmcnt(40)
	v_bfe_u32 v5, v28, 16, 1
	v_lshrrev_b32_e32 v0, 16, v0
	v_add3_u32 v5, v28, v5, s53
	v_and_or_b32 v5, v5, s45, v0
	s_waitcnt vmcnt(39)
	v_bfe_u32 v0, v29, 16, 1
	ds_write_b128 v134, v[2:5]
	v_add3_u32 v0, v29, v0, s53
	s_waitcnt vmcnt(38)
	v_bfe_u32 v2, v30, 16, 1
	v_lshrrev_b32_e32 v0, 16, v0
	v_add3_u32 v2, v30, v2, s53
	v_and_or_b32 v2, v2, s45, v0
	s_waitcnt vmcnt(37)
	v_bfe_u32 v0, v31, 16, 1
	v_add3_u32 v0, v31, v0, s53
	s_waitcnt vmcnt(36)
	v_bfe_u32 v3, v32, 16, 1
	v_lshrrev_b32_e32 v0, 16, v0
	v_add3_u32 v3, v32, v3, s53
	v_and_or_b32 v3, v3, s45, v0
	s_waitcnt vmcnt(35)
	v_bfe_u32 v0, v33, 16, 1
	v_add3_u32 v0, v33, v0, s53
	s_waitcnt vmcnt(34)
	v_bfe_u32 v4, v34, 16, 1
	v_lshrrev_b32_e32 v0, 16, v0
	v_add3_u32 v4, v34, v4, s53
	v_and_or_b32 v4, v4, s45, v0
	s_waitcnt vmcnt(33)
	v_bfe_u32 v0, v35, 16, 1
	v_add3_u32 v0, v35, v0, s53
	s_waitcnt vmcnt(32)
	v_bfe_u32 v5, v36, 16, 1
	v_lshrrev_b32_e32 v0, 16, v0
	v_add3_u32 v5, v36, v5, s53
	v_and_or_b32 v5, v5, s45, v0
	s_waitcnt vmcnt(31)
	v_bfe_u32 v0, v37, 16, 1
	ds_write_b128 v135, v[2:5]
	v_add3_u32 v0, v37, v0, s53
	s_waitcnt vmcnt(30)
	v_bfe_u32 v2, v38, 16, 1
	v_lshrrev_b32_e32 v0, 16, v0
	v_add3_u32 v2, v38, v2, s53
	v_and_or_b32 v2, v2, s45, v0
	s_waitcnt vmcnt(29)
	v_bfe_u32 v0, v39, 16, 1
	v_add3_u32 v0, v39, v0, s53
	s_waitcnt vmcnt(28)
	v_bfe_u32 v3, v40, 16, 1
	v_lshrrev_b32_e32 v0, 16, v0
	v_add3_u32 v3, v40, v3, s53
	v_and_or_b32 v3, v3, s45, v0
	s_waitcnt vmcnt(27)
	v_bfe_u32 v0, v41, 16, 1
	v_add3_u32 v0, v41, v0, s53
	s_waitcnt vmcnt(26)
	v_bfe_u32 v4, v42, 16, 1
	v_lshrrev_b32_e32 v0, 16, v0
	v_add3_u32 v4, v42, v4, s53
	v_and_or_b32 v4, v4, s45, v0
	s_waitcnt vmcnt(25)
	v_bfe_u32 v0, v43, 16, 1
	v_add3_u32 v0, v43, v0, s53
	s_waitcnt vmcnt(24)
	v_bfe_u32 v5, v44, 16, 1
	v_lshrrev_b32_e32 v0, 16, v0
	v_add3_u32 v5, v44, v5, s53
	v_and_or_b32 v5, v5, s45, v0
	s_waitcnt vmcnt(23)
	v_bfe_u32 v0, v45, 16, 1
	ds_write_b128 v136, v[2:5]
	v_add3_u32 v0, v45, v0, s53
	s_waitcnt vmcnt(22)
	v_bfe_u32 v2, v46, 16, 1
	v_lshrrev_b32_e32 v0, 16, v0
	v_add3_u32 v2, v46, v2, s53
	v_and_or_b32 v2, v2, s45, v0
	s_waitcnt vmcnt(21)
	v_bfe_u32 v0, v47, 16, 1
	v_add3_u32 v0, v47, v0, s53
	s_waitcnt vmcnt(20)
	v_bfe_u32 v3, v48, 16, 1
	v_lshrrev_b32_e32 v0, 16, v0
	v_add3_u32 v3, v48, v3, s53
	v_and_or_b32 v3, v3, s45, v0
	s_waitcnt vmcnt(19)
	v_bfe_u32 v0, v49, 16, 1
	v_add3_u32 v0, v49, v0, s53
	s_waitcnt vmcnt(18)
	v_bfe_u32 v4, v50, 16, 1
	v_lshrrev_b32_e32 v0, 16, v0
	v_add3_u32 v4, v50, v4, s53
	v_and_or_b32 v4, v4, s45, v0
	s_waitcnt vmcnt(17)
	v_bfe_u32 v0, v51, 16, 1
	v_add3_u32 v0, v51, v0, s53
	s_waitcnt vmcnt(16)
	v_bfe_u32 v5, v52, 16, 1
	v_lshrrev_b32_e32 v0, 16, v0
	v_add3_u32 v5, v52, v5, s53
	v_and_or_b32 v5, v5, s45, v0
	s_waitcnt vmcnt(15)
	v_bfe_u32 v0, v53, 16, 1
	ds_write_b128 v137, v[2:5]
	v_add3_u32 v0, v53, v0, s53
	s_waitcnt vmcnt(14)
	v_bfe_u32 v2, v54, 16, 1
	v_lshrrev_b32_e32 v0, 16, v0
	v_add3_u32 v2, v54, v2, s53
	v_and_or_b32 v2, v2, s45, v0
	s_waitcnt vmcnt(13)
	v_bfe_u32 v0, v55, 16, 1
	v_add3_u32 v0, v55, v0, s53
	s_waitcnt vmcnt(12)
	v_bfe_u32 v3, v56, 16, 1
	v_lshrrev_b32_e32 v0, 16, v0
	v_add3_u32 v3, v56, v3, s53
	v_and_or_b32 v3, v3, s45, v0
	s_waitcnt vmcnt(11)
	v_bfe_u32 v0, v57, 16, 1
	v_add3_u32 v0, v57, v0, s53
	s_waitcnt vmcnt(10)
	v_bfe_u32 v4, v58, 16, 1
	v_lshrrev_b32_e32 v0, 16, v0
	v_add3_u32 v4, v58, v4, s53
	v_and_or_b32 v4, v4, s45, v0
	s_waitcnt vmcnt(9)
	v_bfe_u32 v0, v59, 16, 1
	v_add3_u32 v0, v59, v0, s53
	s_waitcnt vmcnt(8)
	v_bfe_u32 v5, v60, 16, 1
	v_lshrrev_b32_e32 v0, 16, v0
	v_add3_u32 v5, v60, v5, s53
	v_and_or_b32 v5, v5, s45, v0
	s_waitcnt vmcnt(7)
	v_bfe_u32 v0, v61, 16, 1
	ds_write_b128 v138, v[2:5]
	v_add3_u32 v0, v61, v0, s53
	s_waitcnt vmcnt(6)
	v_bfe_u32 v2, v64, 16, 1
	v_lshrrev_b32_e32 v0, 16, v0
	v_add3_u32 v2, v64, v2, s53
	v_and_or_b32 v2, v2, s45, v0
	s_waitcnt vmcnt(5)
	v_bfe_u32 v0, v65, 16, 1
	v_add3_u32 v0, v65, v0, s53
	s_waitcnt vmcnt(4)
	v_bfe_u32 v3, v66, 16, 1
	v_lshrrev_b32_e32 v0, 16, v0
	v_add3_u32 v3, v66, v3, s53
	v_and_or_b32 v3, v3, s45, v0
	s_waitcnt vmcnt(3)
	v_bfe_u32 v0, v67, 16, 1
	v_add3_u32 v0, v67, v0, s53
	s_waitcnt vmcnt(2)
	v_bfe_u32 v4, v68, 16, 1
	v_lshrrev_b32_e32 v0, 16, v0
	v_add3_u32 v4, v68, v4, s53
	v_and_or_b32 v4, v4, s45, v0
	s_waitcnt vmcnt(1)
	v_bfe_u32 v0, v69, 16, 1
	v_add3_u32 v0, v69, v0, s53
	s_waitcnt vmcnt(0)
	v_bfe_u32 v5, v70, 16, 1
	v_lshrrev_b32_e32 v0, 16, v0
	v_add3_u32 v5, v70, v5, s53
	v_and_or_b32 v5, v5, s45, v0
	ds_write_b128 v139, v[2:5]
	s_waitcnt lgkmcnt(0)
	v_add_u32_e32 v6, v63, v140
	ds_read_b128 v[2:5], v6
	v_or_b32_e32 v0, s22, v141
	v_mov_b32_e32 v7, s4
	v_mad_i32_i24 v7, v0, s80, v7
	s_and_b32 s17, s14, 0xffff
	v_lshl_or_b32 v7, v7, 1, v142
	s_waitcnt lgkmcnt(0)
	buffer_store_dwordx4 v[2:5], v7, s[16:19], 0 offen sc1
	ds_read_b128 v[2:5], v6 offset:1024
	s_add_i32 s5, s4, 0x5800
	v_mov_b32_e32 v7, s5
	v_mad_i32_i24 v7, v0, s80, v7
	v_lshl_or_b32 v7, v7, 1, v142
	s_waitcnt lgkmcnt(0)
	buffer_store_dwordx4 v[2:5], v7, s[16:19], 0 offen sc1
	ds_read_b128 v[2:5], v6 offset:2048
	s_add_i32 s5, s4, 0xb000
	v_mov_b32_e32 v7, s5
	v_mad_i32_i24 v7, v0, s80, v7
	v_lshl_or_b32 v7, v7, 1, v142
	s_waitcnt lgkmcnt(0)
	buffer_store_dwordx4 v[2:5], v7, s[16:19], 0 offen sc1
	ds_read_b128 v[2:5], v6 offset:3072
	s_add_i32 s5, s4, 0x10800
	v_mov_b32_e32 v7, s5
	v_mad_i32_i24 v7, v0, s80, v7
	v_lshl_or_b32 v7, v7, 1, v142
	s_waitcnt lgkmcnt(0)
	buffer_store_dwordx4 v[2:5], v7, s[16:19], 0 offen sc1
	ds_read_b128 v[2:5], v6 offset:4096
	s_add_i32 s5, s4, 0x16000
	v_mov_b32_e32 v7, s5
	v_mad_i32_i24 v7, v0, s80, v7
	v_lshl_or_b32 v7, v7, 1, v142
	s_waitcnt lgkmcnt(0)
	buffer_store_dwordx4 v[2:5], v7, s[16:19], 0 offen sc1
	ds_read_b128 v[2:5], v6 offset:5120
	s_add_i32 s5, s4, 0x1b800
	v_mov_b32_e32 v7, s5
	v_mad_i32_i24 v7, v0, s80, v7
	v_lshl_or_b32 v7, v7, 1, v142
	s_waitcnt lgkmcnt(0)
	buffer_store_dwordx4 v[2:5], v7, s[16:19], 0 offen sc1
	ds_read_b128 v[2:5], v6 offset:6144
	s_add_i32 s5, s4, 0x21000
	v_mov_b32_e32 v7, s5
	v_mad_i32_i24 v7, v0, s80, v7
	v_lshl_or_b32 v7, v7, 1, v142
	s_waitcnt lgkmcnt(0)
	buffer_store_dwordx4 v[2:5], v7, s[16:19], 0 offen sc1
	ds_read_b128 v[2:5], v6 offset:7168
	s_add_i32 s4, s4, 0x26800
	v_mov_b32_e32 v6, s4
	v_mad_i32_i24 v0, v0, s80, v6
	v_lshl_or_b32 v0, v0, 1, v142
	s_waitcnt lgkmcnt(0)
	buffer_store_dwordx4 v[2:5], v0, s[16:19], 0 offen sc1
	s_waitcnt lgkmcnt(0)
	s_branch .LBB0_457

.LBB0_645:
	s_or_b64 exec, exec, s[42:43]
	s_waitcnt vmcnt(0)
	v_readfirstlane_b32 s2, v2
	s_nop 1
	v_add_u32_e32 v0, s2, v0
	v_and_b32_e32 v2, -4, v0
	v_and_b32_e32 v0, 3, v0
	v_cmp_eq_u32_e64 s[2:3], 3, v0
	v_add_u32_e32 v2, 4, v2
	s_and_b64 s[2:3], s[2:3], exec

.LBB0_661:
	s_lshl_b64 s[4:5], s[26:27], 23
	s_add_u32 s4, s14, s4
	s_mov_b32 s17, s27
	s_addc_u32 s5, s15, s5
	s_lshl_b64 s[16:17], s[16:17], 2
	s_add_u32 s14, s14, s16
	s_addc_u32 s15, s15, s17
	s_lshl_b32 s16, s64, 5
	s_lshl_b32 s17, s42, 8
	s_or_b32 s16, s17, s16
	v_cvt_f32_i32_e32 v127, v127
	v_lshl_add_u32 v142, v143, 3, s16
	s_or_b32 s16, s41, s64
	s_lshl_b32 s16, s16, 2
	s_add_u32 s14, s14, s16
	s_addc_u32 s15, s15, 0
	s_add_u32 s16, s14, 0x6101000
	v_add_u32_e32 v130, s43, v140
	s_addc_u32 s17, s15, 0
	global_load_dword v140, v236, s[14:15] sc1
	global_load_dword v0, v1, s[16:17] offset:16 sc1
	v_ashrrev_i32_e32 v131, 31, v130
	v_cvt_f32_i32_e32 v126, v126
	v_lshlrev_b64 v[130:131], 12, v[130:131]
	v_cvt_f32_i32_e32 v123, v123
	v_cvt_f32_i32_e32 v122, v122
	v_cvt_f32_i32_e32 v125, v125
	v_cvt_f32_i32_e32 v124, v124
	v_ashrrev_i32_e32 v143, 31, v142
	v_lshl_add_u64 v[130:131], s[4:5], 0, v[130:131]
	v_lshl_add_u64 v[130:131], v[142:143], 1, v[130:131]
	s_mov_b64 s[4:5], 0x8400000
	v_cvt_f32_i32_e32 v129, v129
	v_cvt_f32_i32_e32 v128, v128
	v_lshl_add_u64 v[142:143], v[130:131], 0, s[4:5]
	s_mov_b32 s4, 0x8400000
	v_cvt_f32_i32_e32 v115, v115
	v_cvt_f32_i32_e32 v114, v114
	v_cvt_f32_i32_e32 v117, v117
	v_cvt_f32_i32_e32 v116, v116
	v_cvt_f32_i32_e32 v119, v119
	v_cvt_f32_i32_e32 v118, v118
	v_cvt_f32_i32_e32 v121, v121
	v_cvt_f32_i32_e32 v120, v120
	v_cvt_f32_i32_e32 v111, v111
	v_cvt_f32_i32_e32 v110, v110
	v_cvt_f32_i32_e32 v107, v107
	v_cvt_f32_i32_e32 v106, v106
	v_cvt_f32_i32_e32 v109, v109
	v_cvt_f32_i32_e32 v108, v108
	v_cvt_f32_i32_e32 v113, v113
	v_cvt_f32_i32_e32 v112, v112
	v_cvt_f32_i32_e32 v103, v103
	v_cvt_f32_i32_e32 v102, v102
	v_cvt_f32_i32_e32 v99, v99
	v_cvt_f32_i32_e32 v98, v98
	v_cvt_f32_i32_e32 v101, v101
	v_cvt_f32_i32_e32 v100, v100
	v_cvt_f32_i32_e32 v105, v105
	v_cvt_f32_i32_e32 v104, v104
	v_cvt_f32_i32_e32 v95, v95
	v_cvt_f32_i32_e32 v94, v94
	v_cvt_f32_i32_e32 v91, v91
	v_cvt_f32_i32_e32 v90, v90
	v_cvt_f32_i32_e32 v93, v93
	v_cvt_f32_i32_e32 v92, v92
	v_cvt_f32_i32_e32 v97, v97
	v_cvt_f32_i32_e32 v96, v96
	v_cvt_f32_i32_e32 v87, v87
	v_cvt_f32_i32_e32 v86, v86
	v_cvt_f32_i32_e32 v83, v83
	v_cvt_f32_i32_e32 v82, v82
	v_cvt_f32_i32_e32 v85, v85
	v_cvt_f32_i32_e32 v84, v84
	v_cvt_f32_i32_e32 v89, v89
	v_cvt_f32_i32_e32 v88, v88
	v_cvt_f32_i32_e32 v79, v79
	v_cvt_f32_i32_e32 v78, v78
	v_cvt_f32_i32_e32 v75, v75
	v_cvt_f32_i32_e32 v74, v74
	v_cvt_f32_i32_e32 v77, v77
	v_cvt_f32_i32_e32 v76, v76
	v_cvt_f32_i32_e32 v81, v81
	v_cvt_f32_i32_e32 v80, v80
	v_cvt_f32_i32_e32 v71, v71
	v_cvt_f32_i32_e32 v70, v70
	v_cvt_f32_i32_e32 v67, v67
	v_cvt_f32_i32_e32 v66, v66
	v_cvt_f32_i32_e32 v69, v69
	v_cvt_f32_i32_e32 v68, v68
	v_cvt_f32_i32_e32 v73, v73
	v_cvt_f32_i32_e32 v72, v72
	v_cvt_f32_i32_e32 v63, v63
	v_cvt_f32_i32_e32 v62, v62
	v_cvt_f32_i32_e32 v59, v59
	v_cvt_f32_i32_e32 v58, v58
	v_cvt_f32_i32_e32 v61, v61
	v_cvt_f32_i32_e32 v60, v60
	v_cvt_f32_i32_e32 v65, v65
	s_waitcnt vmcnt(0)
	v_mul_f32_e32 v144, v139, v140
	v_pk_mul_f32 v[126:127], v[144:145], v[126:127] op_sel_hi:[0,1]
	v_pk_mul_f32 v[146:147], v[144:145], v[124:125] op_sel_hi:[0,1]
	v_pk_mul_f32 v[124:125], v[144:145], v[122:123] op_sel_hi:[0,1]
	v_cvt_pk_bf16_f32 v122, v126, v127
	v_add_co_u32_e32 v126, vcc, s4, v130
	v_pk_mul_f32 v[128:129], v[144:145], v[128:129] op_sel_hi:[0,1]
	s_nop 0
	v_addc_co_u32_e32 v127, vcc, 0, v131, vcc
	v_cvt_pk_bf16_f32 v123, v128, v129
	v_cvt_pk_bf16_f32 v124, v124, v125
	v_cvt_pk_bf16_f32 v125, v146, v147
	global_store_dwordx4 v[126:127], v[122:125], off
	s_mov_b64 s[4:5], 0x8410000
	v_cvt_f32_i32_e32 v64, v64
	v_mul_f32_e32 v122, v139, v0
	v_pk_mul_f32 v[124:125], v[122:123], v[116:117] op_sel_hi:[0,1]
	v_pk_mul_f32 v[116:117], v[122:123], v[114:115] op_sel_hi:[0,1]
	v_pk_mul_f32 v[120:121], v[122:123], v[120:121] op_sel_hi:[0,1]
	v_pk_mul_f32 v[118:119], v[122:123], v[118:119] op_sel_hi:[0,1]
	v_cvt_pk_bf16_f32 v114, v118, v119
	v_cvt_pk_bf16_f32 v115, v120, v121
	v_cvt_pk_bf16_f32 v116, v116, v117
	v_cvt_pk_bf16_f32 v117, v124, v125
	global_store_dwordx4 v[142:143], v[114:117], off offset:256
	v_cvt_f32_i32_e32 v55, v55
	v_cvt_f32_i32_e32 v54, v54
	v_mul_f32_e32 v116, v138, v140
	v_lshl_add_u64 v[114:115], v[130:131], 0, s[4:5]
	v_pk_mul_f32 v[110:111], v[116:117], v[110:111] op_sel_hi:[0,1]
	s_mov_b32 s4, 0x8410000
	v_pk_mul_f32 v[118:119], v[116:117], v[108:109] op_sel_hi:[0,1]
	v_pk_mul_f32 v[108:109], v[116:117], v[106:107] op_sel_hi:[0,1]
	v_cvt_pk_bf16_f32 v106, v110, v111
	v_add_co_u32_e32 v110, vcc, s4, v130
	v_pk_mul_f32 v[112:113], v[116:117], v[112:113] op_sel_hi:[0,1]
	s_nop 0
	v_addc_co_u32_e32 v111, vcc, 0, v131, vcc
	v_cvt_pk_bf16_f32 v107, v112, v113
	v_cvt_pk_bf16_f32 v108, v108, v109
	v_cvt_pk_bf16_f32 v109, v118, v119
	global_store_dwordx4 v[110:111], v[106:109], off
	s_mov_b64 s[4:5], 0x8420000
	v_cvt_f32_i32_e32 v51, v51
	v_mul_f32_e32 v106, v138, v0
	v_pk_mul_f32 v[102:103], v[106:107], v[102:103] op_sel_hi:[0,1]
	v_pk_mul_f32 v[108:109], v[106:107], v[100:101] op_sel_hi:[0,1]
	v_pk_mul_f32 v[100:101], v[106:107], v[98:99] op_sel_hi:[0,1]
	v_cvt_pk_bf16_f32 v98, v102, v103
	v_pk_mul_f32 v[104:105], v[106:107], v[104:105] op_sel_hi:[0,1]
	v_cvt_pk_bf16_f32 v99, v104, v105
	v_cvt_pk_bf16_f32 v100, v100, v101
	v_cvt_pk_bf16_f32 v101, v108, v109
	global_store_dwordx4 v[114:115], v[98:101], off offset:256
	v_cvt_f32_i32_e32 v50, v50
	v_cvt_f32_i32_e32 v53, v53
	v_mul_f32_e32 v98, v137, v140
	v_lshl_add_u64 v[100:101], v[130:131], 0, s[4:5]
	v_pk_mul_f32 v[94:95], v[98:99], v[94:95] op_sel_hi:[0,1]
	s_mov_b32 s4, 0x8420000
	v_pk_mul_f32 v[102:103], v[98:99], v[92:93] op_sel_hi:[0,1]
	v_pk_mul_f32 v[92:93], v[98:99], v[90:91] op_sel_hi:[0,1]
	v_cvt_pk_bf16_f32 v90, v94, v95
	v_add_co_u32_e32 v94, vcc, s4, v130
	v_pk_mul_f32 v[96:97], v[98:99], v[96:97] op_sel_hi:[0,1]
	s_nop 0
	v_addc_co_u32_e32 v95, vcc, 0, v131, vcc
	v_cvt_pk_bf16_f32 v91, v96, v97
	v_cvt_pk_bf16_f32 v92, v92, v93
	v_cvt_pk_bf16_f32 v93, v102, v103
	global_store_dwordx4 v[94:95], v[90:93], off
	s_mov_b64 s[4:5], 0x8430000
	v_cvt_f32_i32_e32 v52, v52
	v_mul_f32_e32 v90, v137, v0
	v_pk_mul_f32 v[86:87], v[90:91], v[86:87] op_sel_hi:[0,1]
	v_pk_mul_f32 v[92:93], v[90:91], v[84:85] op_sel_hi:[0,1]
	v_pk_mul_f32 v[84:85], v[90:91], v[82:83] op_sel_hi:[0,1]
	v_cvt_pk_bf16_f32 v82, v86, v87
	v_pk_mul_f32 v[88:89], v[90:91], v[88:89] op_sel_hi:[0,1]
	v_cvt_pk_bf16_f32 v83, v88, v89
	v_cvt_pk_bf16_f32 v84, v84, v85
	v_cvt_pk_bf16_f32 v85, v92, v93
	global_store_dwordx4 v[100:101], v[82:85], off offset:256
	v_cvt_f32_i32_e32 v57, v57
	v_cvt_f32_i32_e32 v56, v56
	v_mul_f32_e32 v82, v136, v140
	v_lshl_add_u64 v[84:85], v[130:131], 0, s[4:5]
	v_pk_mul_f32 v[78:79], v[82:83], v[78:79] op_sel_hi:[0,1]
	s_mov_b32 s4, 0x8430000
	v_pk_mul_f32 v[86:87], v[82:83], v[76:77] op_sel_hi:[0,1]
	v_pk_mul_f32 v[76:77], v[82:83], v[74:75] op_sel_hi:[0,1]
	v_cvt_pk_bf16_f32 v74, v78, v79
	v_add_co_u32_e32 v78, vcc, s4, v130
	v_pk_mul_f32 v[80:81], v[82:83], v[80:81] op_sel_hi:[0,1]
	s_nop 0
	v_addc_co_u32_e32 v79, vcc, 0, v131, vcc
	v_cvt_pk_bf16_f32 v75, v80, v81
	v_cvt_pk_bf16_f32 v76, v76, v77
	v_cvt_pk_bf16_f32 v77, v86, v87
	global_store_dwordx4 v[78:79], v[74:77], off
	s_mov_b64 s[4:5], 0x8480000
	v_cvt_f32_i32_e32 v47, v47
	v_mul_f32_e32 v74, v136, v0
	v_pk_mul_f32 v[70:71], v[74:75], v[70:71] op_sel_hi:[0,1]
	v_pk_mul_f32 v[76:77], v[74:75], v[68:69] op_sel_hi:[0,1]
	v_pk_mul_f32 v[68:69], v[74:75], v[66:67] op_sel_hi:[0,1]
	v_cvt_pk_bf16_f32 v66, v70, v71
	v_pk_mul_f32 v[72:73], v[74:75], v[72:73] op_sel_hi:[0,1]
	v_cvt_pk_bf16_f32 v67, v72, v73
	v_cvt_pk_bf16_f32 v68, v68, v69
	v_cvt_pk_bf16_f32 v69, v76, v77
	global_store_dwordx4 v[84:85], v[66:69], off offset:256
	v_cvt_f32_i32_e32 v46, v46
	v_cvt_f32_i32_e32 v43, v43
	v_mul_f32_e32 v66, v135, v140
	v_lshl_add_u64 v[68:69], v[130:131], 0, s[4:5]
	v_pk_mul_f32 v[62:63], v[66:67], v[62:63] op_sel_hi:[0,1]
	s_mov_b32 s4, 0x8480000
	v_pk_mul_f32 v[70:71], v[66:67], v[60:61] op_sel_hi:[0,1]
	v_pk_mul_f32 v[60:61], v[66:67], v[58:59] op_sel_hi:[0,1]
	v_cvt_pk_bf16_f32 v58, v62, v63
	v_add_co_u32_e32 v62, vcc, s4, v130
	v_pk_mul_f32 v[64:65], v[66:67], v[64:65] op_sel_hi:[0,1]
	s_nop 0
	v_addc_co_u32_e32 v63, vcc, 0, v131, vcc
	v_cvt_pk_bf16_f32 v59, v64, v65
	v_cvt_pk_bf16_f32 v60, v60, v61
	v_cvt_pk_bf16_f32 v61, v70, v71
	global_store_dwordx4 v[62:63], v[58:61], off
	v_cvt_f32_i32_e32 v42, v42
	v_cvt_f32_i32_e32 v45, v45
	v_mul_f32_e32 v58, v135, v0
	v_cvt_f32_i32_e32 v44, v44
	v_pk_mul_f32 v[54:55], v[58:59], v[54:55] op_sel_hi:[0,1]
	v_pk_mul_f32 v[60:61], v[58:59], v[52:53] op_sel_hi:[0,1]
	v_pk_mul_f32 v[52:53], v[58:59], v[50:51] op_sel_hi:[0,1]
	v_cvt_pk_bf16_f32 v50, v54, v55
	v_pk_mul_f32 v[56:57], v[58:59], v[56:57] op_sel_hi:[0,1]
	v_cvt_pk_bf16_f32 v51, v56, v57
	v_cvt_pk_bf16_f32 v52, v52, v53
	v_cvt_pk_bf16_f32 v53, v60, v61
	global_store_dwordx4 v[68:69], v[50:53], off offset:256
	s_mov_b64 s[4:5], 0x8490000
	v_cvt_f32_i32_e32 v49, v49
	v_mul_f32_e32 v50, v134, v140
	v_cvt_f32_i32_e32 v48, v48
	v_lshl_add_u64 v[52:53], v[130:131], 0, s[4:5]
	v_pk_mul_f32 v[46:47], v[50:51], v[46:47] op_sel_hi:[0,1]
	s_mov_b32 s4, 0x8490000
	v_cvt_f32_i32_e32 v39, v39
	v_cvt_f32_i32_e32 v38, v38
	v_cvt_f32_i32_e32 v35, v35
	v_cvt_f32_i32_e32 v34, v34
	v_cvt_f32_i32_e32 v37, v37
	v_cvt_f32_i32_e32 v36, v36
	v_pk_mul_f32 v[54:55], v[50:51], v[44:45] op_sel_hi:[0,1]
	v_pk_mul_f32 v[44:45], v[50:51], v[42:43] op_sel_hi:[0,1]
	v_cvt_pk_bf16_f32 v42, v46, v47
	v_add_co_u32_e32 v46, vcc, s4, v130
	v_cvt_f32_i32_e32 v41, v41
	v_cvt_f32_i32_e32 v40, v40
	v_addc_co_u32_e32 v47, vcc, 0, v131, vcc
	v_cvt_f32_i32_e32 v31, v31
	v_cvt_f32_i32_e32 v30, v30
	v_pk_mul_f32 v[48:49], v[50:51], v[48:49] op_sel_hi:[0,1]
	v_cvt_pk_bf16_f32 v43, v48, v49
	v_cvt_pk_bf16_f32 v44, v44, v45
	v_cvt_pk_bf16_f32 v45, v54, v55
	global_store_dwordx4 v[46:47], v[42:45], off
	v_cvt_f32_i32_e32 v27, v27
	v_cvt_f32_i32_e32 v26, v26
	v_mul_f32_e32 v42, v134, v0
	v_cvt_f32_i32_e32 v29, v29
	v_cvt_f32_i32_e32 v28, v28
	v_pk_mul_f32 v[38:39], v[42:43], v[38:39] op_sel_hi:[0,1]
	v_pk_mul_f32 v[44:45], v[42:43], v[36:37] op_sel_hi:[0,1]
	v_pk_mul_f32 v[36:37], v[42:43], v[34:35] op_sel_hi:[0,1]
	v_cvt_pk_bf16_f32 v34, v38, v39
	v_pk_mul_f32 v[40:41], v[42:43], v[40:41] op_sel_hi:[0,1]
	v_cvt_pk_bf16_f32 v35, v40, v41
	v_cvt_pk_bf16_f32 v36, v36, v37
	v_cvt_pk_bf16_f32 v37, v44, v45
	global_store_dwordx4 v[52:53], v[34:37], off offset:256
	s_mov_b64 s[4:5], 0x84a0000
	v_cvt_f32_i32_e32 v33, v33
	v_mul_f32_e32 v34, v133, v140
	v_cvt_f32_i32_e32 v32, v32
	v_lshl_add_u64 v[36:37], v[130:131], 0, s[4:5]
	v_pk_mul_f32 v[30:31], v[34:35], v[30:31] op_sel_hi:[0,1]
	s_mov_b32 s4, 0x84a0000
	v_cvt_f32_i32_e32 v23, v23
	v_cvt_f32_i32_e32 v22, v22
	v_cvt_f32_i32_e32 v19, v19
	v_cvt_f32_i32_e32 v18, v18
	v_cvt_f32_i32_e32 v21, v21
	v_cvt_f32_i32_e32 v20, v20
	v_pk_mul_f32 v[38:39], v[34:35], v[28:29] op_sel_hi:[0,1]
	v_pk_mul_f32 v[28:29], v[34:35], v[26:27] op_sel_hi:[0,1]
	v_cvt_pk_bf16_f32 v26, v30, v31
	v_add_co_u32_e32 v30, vcc, s4, v130
	v_cvt_f32_i32_e32 v25, v25
	v_cvt_f32_i32_e32 v24, v24
	v_addc_co_u32_e32 v31, vcc, 0, v131, vcc
	v_cvt_f32_i32_e32 v15, v15
	v_cvt_f32_i32_e32 v14, v14
	v_pk_mul_f32 v[32:33], v[34:35], v[32:33] op_sel_hi:[0,1]
	v_cvt_pk_bf16_f32 v27, v32, v33
	v_cvt_pk_bf16_f32 v28, v28, v29
	v_cvt_pk_bf16_f32 v29, v38, v39
	global_store_dwordx4 v[30:31], v[26:29], off
	v_cvt_f32_i32_e32 v11, v11
	v_cvt_f32_i32_e32 v10, v10
	v_mul_f32_e32 v26, v133, v0
	v_cvt_f32_i32_e32 v13, v13
	v_cvt_f32_i32_e32 v12, v12
	v_pk_mul_f32 v[22:23], v[26:27], v[22:23] op_sel_hi:[0,1]
	v_pk_mul_f32 v[28:29], v[26:27], v[20:21] op_sel_hi:[0,1]
	v_pk_mul_f32 v[20:21], v[26:27], v[18:19] op_sel_hi:[0,1]
	v_cvt_pk_bf16_f32 v18, v22, v23
	v_cvt_f32_i32_e32 v17, v17
	v_cvt_f32_i32_e32 v16, v16
	v_pk_mul_f32 v[24:25], v[26:27], v[24:25] op_sel_hi:[0,1]
	v_cvt_pk_bf16_f32 v19, v24, v25
	v_cvt_pk_bf16_f32 v20, v20, v21
	v_cvt_pk_bf16_f32 v21, v28, v29
	global_store_dwordx4 v[36:37], v[18:21], off offset:256
	s_mov_b64 s[4:5], 0x84b0000
	v_cvt_f32_i32_e32 v3, v3
	v_mul_f32_e32 v18, v132, v140
	v_cvt_f32_i32_e32 v2, v2
	v_cvt_f32_i32_e32 v5, v5
	v_cvt_f32_i32_e32 v4, v4
	v_lshl_add_u64 v[20:21], v[130:131], 0, s[4:5]
	v_pk_mul_f32 v[14:15], v[18:19], v[14:15] op_sel_hi:[0,1]
	s_mov_b32 s4, 0x84b0000
	v_cvt_f32_i32_e32 v7, v7
	v_cvt_f32_i32_e32 v6, v6
	v_cvt_f32_i32_e32 v9, v9
	v_cvt_f32_i32_e32 v8, v8
	v_pk_mul_f32 v[22:23], v[18:19], v[12:13] op_sel_hi:[0,1]
	v_pk_mul_f32 v[12:13], v[18:19], v[10:11] op_sel_hi:[0,1]
	v_cvt_pk_bf16_f32 v10, v14, v15
	v_add_co_u32_e32 v14, vcc, s4, v130
	v_pk_mul_f32 v[16:17], v[18:19], v[16:17] op_sel_hi:[0,1]
	v_cvt_pk_bf16_f32 v11, v16, v17
	s_nop 0
	v_addc_co_u32_e32 v15, vcc, 0, v131, vcc
	v_mul_f32_e32 v0, v132, v0
	v_cvt_pk_bf16_f32 v12, v12, v13
	v_cvt_pk_bf16_f32 v13, v22, v23
	global_store_dwordx4 v[14:15], v[10:13], off
	v_pk_mul_f32 v[8:9], v[0:1], v[8:9] op_sel_hi:[0,1]
	v_pk_mul_f32 v[6:7], v[0:1], v[6:7] op_sel_hi:[0,1]
	v_pk_mul_f32 v[10:11], v[0:1], v[4:5] op_sel_hi:[0,1]
	v_pk_mul_f32 v[4:5], v[0:1], v[2:3] op_sel_hi:[0,1]
	v_cvt_pk_bf16_f32 v2, v6, v7
	v_cvt_pk_bf16_f32 v3, v8, v9
	v_cvt_pk_bf16_f32 v4, v4, v5
	v_cvt_pk_bf16_f32 v5, v10, v11
	global_store_dwordx4 v[20:21], v[2:5], off offset:256
	s_waitcnt vmcnt(0)
	s_barrier

.LBB0_663:
	s_mov_b64 s[14:15], s[20:21]
	s_mov_b32 s5, s33
	s_mov_b32 s17, -1
	s_lshl_b32 s16, s26, 6
	v_mbcnt_lo_u32_b32 v0, s17, 0
	v_mbcnt_hi_u32_b32 v0, s17, v0
	s_sub_i32 s4, s24, s16
	v_lshl_or_b32 v0, s5, 6, v0
	s_cmp_gt_u32 s4, 63
	v_readfirstlane_b32 s17, v0
	s_cbranch_scc1 .LBB0_662
	s_waitcnt vmcnt(0)
	v_bfe_i32 v4, v0, 27, 1
	v_lshlrev_b32_e32 v2, 4, v0
	v_lshrrev_b32_e32 v4, 22, v4
	v_add_u32_e32 v4, v2, v4
	v_and_b32_e32 v4, 0xfffffc00, v4
	v_sub_u32_e32 v4, v2, v4
	v_ashrrev_i32_e32 v3, 31, v0
	v_lshrrev_b32_e32 v5, 4, v4
	v_lshrrev_b32_e32 v3, 26, v3
	v_bitop3_b32 v4, v5, v4, 32 bitop3:0x6c
	v_add_u32_e32 v3, v0, v3
	v_ashrrev_i32_e32 v6, 31, v4
	v_ashrrev_i32_e32 v3, 6, v3
	v_lshrrev_b32_e32 v6, 26, v6
	v_lshlrev_b32_e32 v5, 3, v3
	v_add_u32_e32 v6, v4, v6
	v_and_b32_e32 v5, -16, v5
	v_ashrrev_i32_e32 v7, 6, v6
	v_and_b32_e32 v6, 0xc0, v6
	v_add_u32_e32 v5, v7, v5
	v_sub_u32_e32 v4, v4, v6
	v_lshlrev_b32_e32 v3, 5, v3
	v_ashrrev_i16_sdwa v4, v230, sext(v4) dst_sel:DWORD dst_unused:UNUSED_PAD src0_sel:DWORD src1_sel:BYTE_0
	v_lshlrev_b32_e32 v6, 1, v5
	v_lshrrev_b32_e32 v8, 2, v5
	v_and_b32_e32 v7, 3, v7
	v_and_b32_e32 v3, 32, v3
	v_bfe_i32 v4, v4, 0, 16
	v_and_b32_e32 v6, 24, v6
	v_and_b32_e32 v8, 4, v8
	v_and_or_b32 v7, v5, s72, v7
	v_or3_b32 v6, v7, v8, v6
	v_add_lshl_u32 v3, v3, v4, 1
	v_add_u32_e32 v2, 0x2000, v2
	v_lshl_add_u32 v130, v5, 10, v3
	v_lshl_add_u32 v131, v6, 10, v3
	v_ashrrev_i32_e32 v3, 31, v2
	v_lshrrev_b32_e32 v3, 22, v3
	v_add_u32_e32 v3, v2, v3
	v_ashrrev_i32_e32 v3, 10, v3
	s_mul_i32 s46, s26, 0x2580000
	v_mul_i32_i24_e32 v4, 0x400, v3
	s_add_u32 s43, s14, s46
	v_sub_u32_e32 v2, v2, v4
	s_addc_u32 s48, s15, 0
	s_ashr_i32 s5, s17, 6
	v_lshrrev_b32_e32 v4, 4, v2
	s_ashr_i32 s47, s17, 8
	s_lshr_b32 s42, s4, 3
	v_bitop3_b32 v2, v4, v2, 32 bitop3:0x6c
	s_lshl_b32 s60, s5, 10
	s_lshl_b32 s50, s47, 6
	s_lshl_b32 s4, s42, 18
	v_ashrrev_i32_e32 v5, 31, v2
	s_add_u32 s51, s14, s25
	v_lshrrev_b32_e32 v5, 26, v5
	s_addc_u32 s64, s15, 0
	v_lshlrev_b32_e32 v4, 3, v3
	v_add_u32_e32 v5, v2, v5
	s_add_u32 s22, s51, 0x9400000
	v_and_b32_e32 v4, -16, v4
	v_ashrrev_i32_e32 v6, 6, v5
	v_and_b32_e32 v5, 0xc0, v5
	s_addc_u32 s23, s64, 0
	v_add_u32_e32 v4, v6, v4
	v_sub_u32_e32 v2, v2, v5
	s_add_u32 s58, s43, s4
	v_lshlrev_b32_e32 v3, 5, v3
	v_ashrrev_i16_sdwa v2, v230, sext(v2) dst_sel:DWORD dst_unused:UNUSED_PAD src0_sel:DWORD src1_sel:BYTE_0
	v_lshlrev_b32_e32 v5, 1, v4
	v_lshrrev_b32_e32 v7, 2, v4
	v_and_b32_e32 v6, 3, v6
	s_addc_u32 s59, s48, 0
	v_and_b32_e32 v3, 32, v3
	v_bfe_i32 v2, v2, 0, 16
	v_and_b32_e32 v5, 24, v5
	v_and_b32_e32 v7, 4, v7
	v_and_or_b32 v6, v4, s72, v6
	s_add_u32 s48, s58, 0x1680000
	v_or3_b32 v5, v6, v7, v5
	v_add_lshl_u32 v2, v3, v2, 1
	v_and_b32_e32 v140, 15, v0
	s_addc_u32 s49, s59, 0
	s_add_i32 s43, s50, s40
	v_lshl_add_u32 v141, v4, 10, v2
	v_lshl_add_u32 v142, v5, 10, v2
	v_or_b32_e32 v2, s43, v140
	v_ashrrev_i32_e32 v3, 31, v2
	v_lshl_add_u64 v[2:3], v[2:3], 2, s[14:15]
	s_mov_b64 s[66:67], 0x40000
	s_mov_b32 s61, 0x40000
	v_lshl_add_u64 v[4:5], v[2:3], 0, s[66:67]
	v_add_co_u32_e32 v2, vcc, s61, v2
	s_add_i32 s61, s60, 0
	s_nop 0
	v_addc_co_u32_e32 v3, vcc, 0, v3, vcc
	global_load_dword v139, v[2:3], off sc1
	global_load_dword v138, v[4:5], off offset:64 sc1
	global_load_dword v137, v[4:5], off offset:128 sc1
	global_load_dword v136, v[4:5], off offset:192 sc1
	global_load_dword v135, v[4:5], off offset:512 sc1
	global_load_dword v134, v[4:5], off offset:576 sc1
	global_load_dword v133, v[4:5], off offset:640 sc1
	global_load_dword v132, v[4:5], off offset:704 sc1
	v_mov_b32_e32 v2, v131
	s_add_i32 m0, s61, 0x10000
	s_nop 0
	global_load_lds_dwordx4 v2, s[48:49]
	v_mov_b32_e32 v2, v142
	s_add_i32 m0, s61, 0x12000
	s_add_u32 s58, s58, 0x16a0000
	global_load_lds_dwordx4 v2, s[48:49]
	v_mov_b32_e32 v2, v131
	s_addc_u32 s59, s59, 0
	s_add_i32 m0, s61, 0x14000
	s_add_i32 s65, s61, 0x2000
	global_load_lds_dwordx4 v2, s[58:59]
	v_mov_b32_e32 v2, v142
	s_add_i32 m0, s61, 0x16000
	s_nop 0
	global_load_lds_dwordx4 v2, s[58:59]
	v_mov_b32_e32 v2, v130
	s_mov_b32 m0, s61
	s_add_u32 s58, s51, 0x9420000
	global_load_lds_dwordx4 v2, s[22:23]
	v_mov_b32_e32 v2, v141
	s_mov_b32 m0, s65
	s_addc_u32 s59, s64, 0
	global_load_lds_dwordx4 v2, s[22:23]
	s_add_i32 s66, s61, 0x4000
	v_mov_b32_e32 v2, v130
	s_mov_b32 m0, s66
	s_add_i32 s67, s61, 0x6000
	global_load_lds_dwordx4 v2, s[58:59]
	v_mov_b32_e32 v2, v141
	s_mov_b32 m0, s67
	s_cmp_lg_u32 s47, 1
	global_load_lds_dwordx4 v2, s[58:59]
	s_cbranch_scc1 .LBB0_666
	s_barrier

.LBB0_738:
	s_or_b64 exec, exec, s[42:43]
	s_waitcnt vmcnt(0)
	v_readfirstlane_b32 s2, v2
	s_nop 1
	v_add_u32_e32 v0, s2, v0
	v_and_b32_e32 v2, 0xffffffe0, v0
	v_and_b32_e32 v0, 31, v0
	v_cmp_eq_u32_e64 s[2:3], 31, v0
	v_add_u32_e32 v2, 32, v2
	s_and_b64 s[2:3], s[2:3], exec

.LBB0_824:
	s_lshl_b32 s4, s25, 8
	s_add_u32 s48, s12, 0x6300000
	s_addc_u32 s49, s13, 0
	s_add_i32 s4, s4, s74
	s_lshl_b32 s5, s41, 5
	s_lshl_b32 s46, s61, 2
	v_add_u32_e32 v160, s4, v196
	s_lshl_b32 s4, s61, 8
	s_or_b32 s4, s4, s5
	v_lshl_add_u32 v178, v197, 3, s4
	v_ashrrev_i32_e32 v179, 31, v178
	v_lshl_add_u64 v[130:131], v[178:179], 1, s[12:13]
	s_mov_b64 s[4:5], 0x6400000
	v_ashrrev_i32_e32 v161, 31, v160
	v_lshl_add_u64 v[180:181], v[130:131], 0, s[4:5]
	v_lshlrev_b64 v[130:131], 11, v[160:161]
	v_lshl_add_u64 v[130:131], v[180:181], 0, v[130:131]
	global_load_dwordx4 v[162:165], v[130:131], off sc1
	global_load_dwordx4 v[166:169], v[130:131], off offset:256 sc1
	v_add_u32_e32 v158, 16, v160
	v_ashrrev_i32_e32 v159, 31, v158
	v_lshlrev_b64 v[130:131], 11, v[158:159]
	v_add_u32_e32 v156, 32, v160
	v_lshl_add_u64 v[130:131], v[180:181], 0, v[130:131]
	v_ashrrev_i32_e32 v157, 31, v156
	global_load_dwordx4 v[150:153], v[130:131], off sc1
	global_load_dwordx4 v[146:149], v[130:131], off offset:256 sc1
	v_lshlrev_b64 v[130:131], 11, v[156:157]
	v_add_u32_e32 v154, 48, v160
	v_lshl_add_u64 v[130:131], v[180:181], 0, v[130:131]
	v_ashrrev_i32_e32 v155, 31, v154
	global_load_dwordx4 v[142:145], v[130:131], off sc1
	global_load_dwordx4 v[134:137], v[130:131], off offset:256 sc1
	v_lshlrev_b64 v[130:131], 11, v[154:155]
	v_lshl_add_u64 v[130:131], v[180:181], 0, v[130:131]
	global_load_dwordx4 v[138:141], v[130:131], off sc1
	s_nop 0
	global_load_dwordx4 v[130:133], v[130:131], off offset:256 sc1
	v_cmp_eq_u32_e32 vcc, 0, v197
	s_waitcnt vmcnt(0)
	v_lshlrev_b32_e32 v170, 16, v162
	v_and_b32_e32 v171, 0xffff0000, v162
	v_lshlrev_b32_e32 v162, 16, v163
	v_and_b32_e32 v163, 0xffff0000, v163
	v_pk_fma_f32 v[128:129], v[128:129], 0.5, v[162:163] op_sel_hi:[1,0,1]
	v_pk_fma_f32 v[126:127], v[126:127], 0.5, v[170:171] op_sel_hi:[1,0,1]
	v_lshlrev_b32_e32 v172, 16, v164
	v_and_b32_e32 v173, 0xffff0000, v164
	v_mul_f32_e32 v0, v127, v127
	v_mul_f32_e32 v162, v129, v129
	v_pk_fma_f32 v[122:123], v[122:123], 0.5, v[172:173] op_sel_hi:[1,0,1]
	v_fmac_f32_e32 v0, v126, v126
	v_fmac_f32_e32 v162, v128, v128
	v_lshlrev_b32_e32 v164, 16, v165
	v_and_b32_e32 v165, 0xffff0000, v165
	v_add_f32_e32 v0, v0, v162
	v_mul_f32_e32 v162, v123, v123
	v_pk_fma_f32 v[124:125], v[124:125], 0.5, v[164:165] op_sel_hi:[1,0,1]
	v_fmac_f32_e32 v162, v122, v122
	v_add_f32_e32 v0, v162, v0
	v_mul_f32_e32 v162, v125, v125
	v_fmac_f32_e32 v162, v124, v124
	v_add_f32_e32 v0, v162, v0
	v_lshlrev_b32_e32 v162, 16, v166
	v_and_b32_e32 v163, 0xffff0000, v166
	v_lshlrev_b32_e32 v164, 16, v167
	v_and_b32_e32 v165, 0xffff0000, v167
	v_pk_fma_f32 v[120:121], v[120:121], 0.5, v[164:165] op_sel_hi:[1,0,1]
	v_pk_fma_f32 v[118:119], v[118:119], 0.5, v[162:163] op_sel_hi:[1,0,1]
	v_lshlrev_b32_e32 v166, 16, v168
	v_and_b32_e32 v167, 0xffff0000, v168
	v_mul_f32_e32 v162, v119, v119
	v_mul_f32_e32 v163, v121, v121
	v_pk_fma_f32 v[114:115], v[114:115], 0.5, v[166:167] op_sel_hi:[1,0,1]
	v_fmac_f32_e32 v162, v118, v118
	v_fmac_f32_e32 v163, v120, v120
	v_lshlrev_b32_e32 v168, 16, v169
	v_and_b32_e32 v169, 0xffff0000, v169
	v_add_f32_e32 v162, v162, v163
	v_mul_f32_e32 v163, v115, v115
	v_pk_fma_f32 v[116:117], v[116:117], 0.5, v[168:169] op_sel_hi:[1,0,1]
	v_fmac_f32_e32 v163, v114, v114
	v_add_f32_e32 v162, v163, v162
	v_mul_f32_e32 v163, v117, v117
	v_fmac_f32_e32 v163, v116, v116
	v_add_f32_e32 v162, v163, v162
	v_add_f32_e32 v0, v0, v162
	ds_swizzle_b32 v162, v0 offset:swizzle(SWAP,16)
	v_lshlrev_b64 v[164:165], 6, v[160:161]
	v_lshl_add_u64 v[194:195], s[48:49], 0, v[164:165]
	s_waitcnt lgkmcnt(0)
	v_add_f32_e32 v0, v0, v162
	v_mov_b32_e32 v162, v0
	s_nop 1
	v_permlane32_swap_b32_e32 v0, v162
	s_and_saveexec_b64 s[24:25], vcc
	s_mov_b64 s[84:85], s[92:93]
	s_cbranch_execz .LBB0_826
	s_lshl_b32 s26, s46, 2
	v_lshl_add_u64 v[164:165], v[194:195], 0, s[26:27]
	s_lshl_b32 s26, s41, 2
	v_lshl_add_u64 v[164:165], v[164:165], 0, s[26:27]
	v_add_f32_e32 v0, v0, v162
	global_store_dword v[164:165], v0, off

.LBB0_832:
	s_or_b64 exec, exec, s[24:25]
	v_add_u32_e32 v96, 0x80, v160
	v_ashrrev_i32_e32 v97, 31, v96
	v_lshlrev_b64 v[66:67], 11, v[96:97]
	v_lshl_add_u64 v[66:67], v[180:181], 0, v[66:67]
	global_load_dwordx4 v[98:101], v[66:67], off sc1
	global_load_dwordx4 v[102:105], v[66:67], off offset:256 sc1
	v_add_u32_e32 v94, 0x90, v160
	v_ashrrev_i32_e32 v95, 31, v94
	v_lshlrev_b64 v[66:67], 11, v[94:95]
	v_add_u32_e32 v92, 0xa0, v160
	v_lshl_add_u64 v[66:67], v[180:181], 0, v[66:67]
	v_ashrrev_i32_e32 v93, 31, v92
	global_load_dwordx4 v[86:89], v[66:67], off sc1
	global_load_dwordx4 v[82:85], v[66:67], off offset:256 sc1
	v_lshlrev_b64 v[66:67], 11, v[92:93]
	v_add_u32_e32 v90, 0xb0, v160
	v_lshl_add_u64 v[66:67], v[180:181], 0, v[66:67]
	v_ashrrev_i32_e32 v91, 31, v90
	global_load_dwordx4 v[78:81], v[66:67], off sc1
	global_load_dwordx4 v[70:73], v[66:67], off offset:256 sc1
	v_lshlrev_b64 v[66:67], 11, v[90:91]
	v_lshl_add_u64 v[66:67], v[180:181], 0, v[66:67]
	global_load_dwordx4 v[74:77], v[66:67], off sc1
	s_nop 0
	global_load_dwordx4 v[66:69], v[66:67], off offset:256 sc1
	s_waitcnt vmcnt(7)
	v_lshlrev_b32_e32 v180, 16, v98
	v_and_b32_e32 v181, 0xffff0000, v98
	v_lshlrev_b32_e32 v98, 16, v99
	v_and_b32_e32 v99, 0xffff0000, v99
	v_pk_fma_f32 v[64:65], v[64:65], 0.5, v[98:99] op_sel_hi:[1,0,1]
	v_pk_fma_f32 v[62:63], v[62:63], 0.5, v[180:181] op_sel_hi:[1,0,1]
	v_lshlrev_b32_e32 v182, 16, v100
	v_and_b32_e32 v183, 0xffff0000, v100
	v_mul_f32_e32 v0, v63, v63
	v_mul_f32_e32 v98, v65, v65
	v_pk_fma_f32 v[58:59], v[58:59], 0.5, v[182:183] op_sel_hi:[1,0,1]
	v_fmac_f32_e32 v0, v62, v62
	v_fmac_f32_e32 v98, v64, v64
	v_lshlrev_b32_e32 v100, 16, v101
	v_and_b32_e32 v101, 0xffff0000, v101
	v_add_f32_e32 v0, v0, v98
	v_mul_f32_e32 v98, v59, v59
	v_pk_fma_f32 v[60:61], v[60:61], 0.5, v[100:101] op_sel_hi:[1,0,1]
	v_fmac_f32_e32 v98, v58, v58
	v_add_f32_e32 v0, v98, v0
	v_mul_f32_e32 v98, v61, v61
	v_fmac_f32_e32 v98, v60, v60
	v_add_f32_e32 v0, v98, v0
	s_waitcnt vmcnt(6)
	v_lshlrev_b32_e32 v98, 16, v102
	v_and_b32_e32 v99, 0xffff0000, v102
	v_lshlrev_b32_e32 v100, 16, v103
	v_and_b32_e32 v101, 0xffff0000, v103
	v_pk_fma_f32 v[56:57], v[56:57], 0.5, v[100:101] op_sel_hi:[1,0,1]
	v_pk_fma_f32 v[54:55], v[54:55], 0.5, v[98:99] op_sel_hi:[1,0,1]
	v_lshlrev_b32_e32 v102, 16, v104
	v_and_b32_e32 v103, 0xffff0000, v104
	v_mul_f32_e32 v98, v55, v55
	v_mul_f32_e32 v99, v57, v57
	v_pk_fma_f32 v[50:51], v[50:51], 0.5, v[102:103] op_sel_hi:[1,0,1]
	v_fmac_f32_e32 v98, v54, v54
	v_fmac_f32_e32 v99, v56, v56
	v_lshlrev_b32_e32 v104, 16, v105
	v_and_b32_e32 v105, 0xffff0000, v105
	v_add_f32_e32 v98, v98, v99
	v_mul_f32_e32 v99, v51, v51
	v_pk_fma_f32 v[52:53], v[52:53], 0.5, v[104:105] op_sel_hi:[1,0,1]
	v_fmac_f32_e32 v99, v50, v50
	v_add_f32_e32 v98, v99, v98
	v_mul_f32_e32 v99, v53, v53
	v_fmac_f32_e32 v99, v52, v52
	v_add_f32_e32 v98, v99, v98
	v_add_f32_e32 v0, v0, v98
	ds_swizzle_b32 v98, v0 offset:swizzle(SWAP,16)
	v_lshlrev_b64 v[100:101], 6, v[96:97]
	v_lshl_add_u64 v[186:187], s[48:49], 0, v[100:101]
	s_waitcnt lgkmcnt(0)
	v_add_f32_e32 v0, v0, v98
	v_mov_b32_e32 v98, v0
	s_nop 1
	v_permlane32_swap_b32_e32 v0, v98
	s_and_saveexec_b64 s[24:25], vcc
	s_cbranch_execz .LBB0_834
	s_lshl_b32 s26, s46, 2
	v_lshl_add_u64 v[100:101], v[186:187], 0, s[26:27]
	s_lshl_b32 s26, s41, 2
	v_lshl_add_u64 v[100:101], v[100:101], 0, s[26:27]
	v_add_f32_e32 v0, v0, v98
	global_store_dword v[100:101], v0, off

.LBB0_843:
	s_or_b64 exec, exec, s[42:43]
	s_waitcnt vmcnt(0)
	v_readfirstlane_b32 s4, v2
	s_nop 1
	v_add_u32_e32 v0, s4, v0
	v_and_b32_e32 v2, 3, v0
	v_cmp_ne_u32_e32 vcc, 3, v2
	s_and_saveexec_b64 s[40:41], vcc
	s_cbranch_execz .LBB0_858
	global_load_dword v2, v1, s[24:25] sc1
	v_bitop3_b32 v0, v0, -4, v0 bitop3:0xc
	s_waitcnt vmcnt(0)
	v_add_u32_e32 v2, v2, v0
	v_cmp_gt_i32_e32 vcc, 0, v2
	s_and_b64 exec, exec, vcc
	s_cbranch_execz .LBB0_858
	s_add_u32 s22, s22, 0x4200
	s_addc_u32 s23, s23, 0
	s_mov_b32 s4, 1
	s_mov_b64 s[42:43], 0
	s_branch .LBB0_847

.LBB0_859:
	s_or_b64 exec, exec, s[46:47]
	v_lshlrev_b64 v[178:179], 2, v[178:179]
	s_waitcnt lgkmcnt(0)
	s_barrier
	v_lshl_add_u64 v[6:7], s[16:17], 0, v[178:179]
	global_load_dwordx4 v[10:13], v[6:7], off offset:16 sc1
	global_load_dwordx4 v[14:17], v[6:7], off sc1
	global_load_dwordx4 v[2:5], v[6:7], off offset:528 sc1
	s_nop 0
	global_load_dwordx4 v[6:9], v[6:7], off offset:512 sc1
	s_nop 0
	global_load_dwordx4 v[18:21], v[194:195], off offset:16 sc1
	global_load_dwordx4 v[22:25], v[194:195], off offset:48 sc1
	global_load_dwordx4 v[26:29], v[194:195], off sc1
	global_load_dwordx4 v[30:33], v[194:195], off offset:32 sc1
	s_waitcnt vmcnt(1)
	v_mov_b32_e32 v194, v26
	s_waitcnt vmcnt(0)
	v_mov_b32_e32 v195, v30
	v_mov_b32_e32 v30, v27
	v_pk_add_f32 v[26:27], v[194:195], v[30:31]
	v_mov_b32_e32 v30, v28
	v_mov_b32_e32 v31, v32
	v_mov_b32_e32 v32, v29
	v_pk_add_f32 v[28:29], v[30:31], v[32:33]
	s_nop 0
	v_pk_add_f32 v[26:27], v[26:27], v[28:29]
	v_mov_b32_e32 v28, v18
	v_mov_b32_e32 v29, v22
	v_mov_b32_e32 v22, v19
	v_pk_add_f32 v[18:19], v[28:29], v[22:23]
	v_mov_b32_e32 v22, v20
	v_mov_b32_e32 v23, v24
	v_mov_b32_e32 v24, v21
	v_pk_add_f32 v[20:21], v[22:23], v[24:25]
	s_nop 0
	v_pk_add_f32 v[18:19], v[18:19], v[20:21]
	s_nop 0
	v_pk_add_f32 v[18:19], v[26:27], v[18:19]
	s_nop 0
	v_add_f32_e32 v0, v18, v19
	global_load_dwordx4 v[18:21], v[192:193], off offset:16 sc1
	global_load_dwordx4 v[22:25], v[192:193], off offset:48 sc1
	global_load_dwordx4 v[26:29], v[192:193], off sc1
	global_load_dwordx4 v[30:33], v[192:193], off offset:32 sc1
	v_fmamk_f32 v0, v0, 0x3a800000, v231
	v_rsq_f32_e32 v0, v0
	s_waitcnt vmcnt(1)
	v_mov_b32_e32 v192, v26
	s_waitcnt vmcnt(0)
	v_mov_b32_e32 v193, v30
	v_mov_b32_e32 v30, v27
	v_pk_add_f32 v[26:27], v[192:193], v[30:31]
	v_mov_b32_e32 v30, v28
	v_mov_b32_e32 v31, v32
	v_mov_b32_e32 v32, v29
	v_pk_add_f32 v[28:29], v[30:31], v[32:33]
	s_nop 0
	v_pk_add_f32 v[26:27], v[26:27], v[28:29]
	v_mov_b32_e32 v28, v18
	v_mov_b32_e32 v29, v22
	v_mov_b32_e32 v22, v19
	v_pk_add_f32 v[18:19], v[28:29], v[22:23]
	v_mov_b32_e32 v22, v20
	v_mov_b32_e32 v23, v24
	v_mov_b32_e32 v24, v21
	v_pk_add_f32 v[20:21], v[22:23], v[24:25]
	s_nop 0
	v_pk_add_f32 v[18:19], v[18:19], v[20:21]
	s_nop 0
	v_pk_add_f32 v[18:19], v[26:27], v[18:19]
	s_nop 0
	v_add_f32_e32 v18, v18, v19
	v_fmamk_f32 v18, v18, 0x3a800000, v231
	v_rsq_f32_e32 v192, v18
	global_load_dwordx4 v[18:21], v[190:191], off offset:16 sc1
	global_load_dwordx4 v[22:25], v[190:191], off offset:48 sc1
	global_load_dwordx4 v[26:29], v[190:191], off sc1
	global_load_dwordx4 v[30:33], v[190:191], off offset:32 sc1
	s_waitcnt vmcnt(1)
	v_mov_b32_e32 v190, v26
	s_waitcnt vmcnt(0)
	v_mov_b32_e32 v191, v30
	v_mov_b32_e32 v30, v27
	v_pk_add_f32 v[26:27], v[190:191], v[30:31]
	v_mov_b32_e32 v30, v28
	v_mov_b32_e32 v31, v32
	v_mov_b32_e32 v32, v29
	v_pk_add_f32 v[28:29], v[30:31], v[32:33]
	s_nop 0
	v_pk_add_f32 v[26:27], v[26:27], v[28:29]
	v_mov_b32_e32 v28, v18
	v_mov_b32_e32 v29, v22
	v_mov_b32_e32 v22, v19
	v_pk_add_f32 v[18:19], v[28:29], v[22:23]
	v_mov_b32_e32 v22, v20
	v_mov_b32_e32 v23, v24
	v_mov_b32_e32 v24, v21
	v_pk_add_f32 v[20:21], v[22:23], v[24:25]
	s_nop 0
	v_pk_add_f32 v[18:19], v[18:19], v[20:21]
	s_nop 0
	v_pk_add_f32 v[18:19], v[26:27], v[18:19]
	s_nop 0
	v_add_f32_e32 v18, v18, v19
	v_fmamk_f32 v18, v18, 0x3a800000, v231
	v_rsq_f32_e32 v190, v18
	global_load_dwordx4 v[22:25], v[188:189], off offset:16 sc1
	global_load_dwordx4 v[18:21], v[188:189], off offset:48 sc1
	global_load_dwordx4 v[30:33], v[188:189], off sc1
	global_load_dwordx4 v[26:29], v[188:189], off offset:32 sc1
	s_waitcnt vmcnt(1)
	v_mov_b32_e32 v188, v30
	s_waitcnt vmcnt(0)
	v_mov_b32_e32 v189, v26
	v_mov_b32_e32 v26, v31
	v_mov_b32_e32 v30, v32
	v_mov_b32_e32 v31, v28
	v_mov_b32_e32 v28, v33
	v_pk_add_f32 v[26:27], v[188:189], v[26:27]
	v_pk_add_f32 v[28:29], v[30:31], v[28:29]
	s_nop 0
	v_pk_add_f32 v[26:27], v[26:27], v[28:29]
	v_mov_b32_e32 v28, v22
	v_mov_b32_e32 v29, v18
	v_mov_b32_e32 v18, v23
	v_mov_b32_e32 v22, v24
	v_mov_b32_e32 v23, v20
	v_mov_b32_e32 v20, v25
	v_pk_add_f32 v[18:19], v[28:29], v[18:19]
	v_pk_add_f32 v[20:21], v[22:23], v[20:21]
	v_lshlrev_b64 v[24:25], 12, v[160:161]
	v_pk_add_f32 v[18:19], v[18:19], v[20:21]
	v_pk_mul_f32 v[20:21], v[128:129], v[0:1] op_sel_hi:[1,0]
	v_pk_add_f32 v[18:19], v[26:27], v[18:19]
	v_lshl_add_u64 v[24:25], s[2:3], 0, v[24:25]
	v_add_f32_e32 v18, v18, v19
	v_fmamk_f32 v18, v18, 0x3a800000, v231
	v_rsq_f32_e32 v22, v18
	v_pk_mul_f32 v[18:19], v[126:127], v[0:1] op_sel_hi:[1,0]
	v_pk_mul_f32 v[20:21], v[16:17], v[20:21]
	v_pk_mul_f32 v[18:19], v[14:15], v[18:19]
	v_lshl_add_u64 v[24:25], v[24:25], 0, v[178:179]
	global_store_dwordx4 v[24:25], v[18:21], off nt
	s_nop 1
	v_pk_mul_f32 v[18:19], v[122:123], v[0:1] op_sel_hi:[1,0]
	v_pk_mul_f32 v[20:21], v[124:125], v[0:1] op_sel_hi:[1,0]
	v_pk_mul_f32 v[18:19], v[10:11], v[18:19]
	v_pk_mul_f32 v[20:21], v[12:13], v[20:21]
	global_store_dwordx4 v[24:25], v[18:21], off offset:16 nt
	s_nop 1
	v_pk_mul_f32 v[18:19], v[118:119], v[0:1] op_sel_hi:[1,0]
	v_pk_mul_f32 v[20:21], v[120:121], v[0:1] op_sel_hi:[1,0]
	v_pk_mul_f32 v[18:19], v[6:7], v[18:19]
	v_pk_mul_f32 v[20:21], v[8:9], v[20:21]
	global_store_dwordx4 v[24:25], v[18:21], off offset:512 nt
	s_nop 1
	v_pk_mul_f32 v[18:19], v[114:115], v[0:1] op_sel_hi:[1,0]
	v_pk_mul_f32 v[20:21], v[116:117], v[0:1] op_sel_hi:[1,0]
	v_pk_mul_f32 v[18:19], v[2:3], v[18:19]
	v_pk_mul_f32 v[20:21], v[4:5], v[20:21]
	global_store_dwordx4 v[24:25], v[18:21], off offset:528 nt
	v_lshlrev_b64 v[24:25], 12, v[158:159]
	v_lshl_add_u64 v[24:25], s[2:3], 0, v[24:25]
	v_pk_mul_f32 v[18:19], v[110:111], v[192:193] op_sel_hi:[1,0]
	v_pk_mul_f32 v[20:21], v[112:113], v[192:193] op_sel_hi:[1,0]
	v_pk_mul_f32 v[18:19], v[14:15], v[18:19]
	v_pk_mul_f32 v[20:21], v[16:17], v[20:21]
	v_lshl_add_u64 v[24:25], v[24:25], 0, v[178:179]
	global_store_dwordx4 v[24:25], v[18:21], off nt
	s_nop 1
	v_pk_mul_f32 v[18:19], v[106:107], v[192:193] op_sel_hi:[1,0]
	v_pk_mul_f32 v[20:21], v[108:109], v[192:193] op_sel_hi:[1,0]
	v_pk_mul_f32 v[18:19], v[10:11], v[18:19]
	v_pk_mul_f32 v[20:21], v[12:13], v[20:21]
	global_store_dwordx4 v[24:25], v[18:21], off offset:16 nt
	s_nop 1
	v_pk_mul_f32 v[18:19], v[152:153], v[192:193] op_sel_hi:[1,0]
	v_pk_mul_f32 v[20:21], v[148:149], v[192:193] op_sel_hi:[1,0]
	v_pk_mul_f32 v[18:19], v[6:7], v[18:19]
	v_pk_mul_f32 v[20:21], v[8:9], v[20:21]
	global_store_dwordx4 v[24:25], v[18:21], off offset:512 nt
	s_nop 1
	v_pk_mul_f32 v[18:19], v[150:151], v[192:193] op_sel_hi:[1,0]
	v_pk_mul_f32 v[20:21], v[146:147], v[192:193] op_sel_hi:[1,0]
	v_pk_mul_f32 v[18:19], v[2:3], v[18:19]
	v_pk_mul_f32 v[20:21], v[4:5], v[20:21]
	global_store_dwordx4 v[24:25], v[18:21], off offset:528 nt
	v_lshlrev_b64 v[24:25], 12, v[156:157]
	v_lshl_add_u64 v[24:25], s[2:3], 0, v[24:25]
	v_pk_mul_f32 v[18:19], v[164:165], v[190:191] op_sel_hi:[1,0]
	v_pk_mul_f32 v[20:21], v[144:145], v[190:191] op_sel_hi:[1,0]
	v_pk_mul_f32 v[18:19], v[14:15], v[18:19]
	v_pk_mul_f32 v[20:21], v[16:17], v[20:21]
	v_lshl_add_u64 v[24:25], v[24:25], 0, v[178:179]
	global_store_dwordx4 v[24:25], v[18:21], off nt
	s_nop 1
	v_pk_mul_f32 v[18:19], v[162:163], v[190:191] op_sel_hi:[1,0]
	v_pk_mul_f32 v[20:21], v[142:143], v[190:191] op_sel_hi:[1,0]
	v_pk_mul_f32 v[18:19], v[10:11], v[18:19]
	v_pk_mul_f32 v[20:21], v[12:13], v[20:21]
	global_store_dwordx4 v[24:25], v[18:21], off offset:16 nt
	s_nop 1
	v_pk_mul_f32 v[18:19], v[168:169], v[190:191] op_sel_hi:[1,0]
	v_pk_mul_f32 v[20:21], v[136:137], v[190:191] op_sel_hi:[1,0]
	v_pk_mul_f32 v[18:19], v[6:7], v[18:19]
	v_pk_mul_f32 v[20:21], v[8:9], v[20:21]
	global_store_dwordx4 v[24:25], v[18:21], off offset:512 nt
	s_nop 1
	v_pk_mul_f32 v[18:19], v[166:167], v[190:191] op_sel_hi:[1,0]
	v_pk_mul_f32 v[20:21], v[134:135], v[190:191] op_sel_hi:[1,0]
	v_pk_mul_f32 v[18:19], v[2:3], v[18:19]
	v_pk_mul_f32 v[20:21], v[4:5], v[20:21]
	global_store_dwordx4 v[24:25], v[18:21], off offset:528 nt
	v_lshlrev_b64 v[24:25], 12, v[154:155]
	v_lshl_add_u64 v[24:25], s[2:3], 0, v[24:25]
	v_pk_mul_f32 v[18:19], v[172:173], v[22:23] op_sel_hi:[1,0]
	v_pk_mul_f32 v[20:21], v[140:141], v[22:23] op_sel_hi:[1,0]
	v_pk_mul_f32 v[18:19], v[14:15], v[18:19]
	v_pk_mul_f32 v[20:21], v[16:17], v[20:21]
	v_lshl_add_u64 v[24:25], v[24:25], 0, v[178:179]
	global_store_dwordx4 v[24:25], v[18:21], off nt
	s_nop 1
	v_pk_mul_f32 v[18:19], v[170:171], v[22:23] op_sel_hi:[1,0]
	v_pk_mul_f32 v[20:21], v[138:139], v[22:23] op_sel_hi:[1,0]
	v_pk_mul_f32 v[18:19], v[10:11], v[18:19]
	v_pk_mul_f32 v[20:21], v[12:13], v[20:21]
	global_store_dwordx4 v[24:25], v[18:21], off offset:16 nt
	s_nop 1
	v_pk_mul_f32 v[18:19], v[176:177], v[22:23] op_sel_hi:[1,0]
	v_pk_mul_f32 v[20:21], v[132:133], v[22:23] op_sel_hi:[1,0]
	v_pk_mul_f32 v[18:19], v[6:7], v[18:19]
	v_pk_mul_f32 v[20:21], v[8:9], v[20:21]
	global_store_dwordx4 v[24:25], v[18:21], off offset:512 nt
	s_nop 1
	v_pk_mul_f32 v[18:19], v[174:175], v[22:23] op_sel_hi:[1,0]
	v_pk_mul_f32 v[20:21], v[130:131], v[22:23] op_sel_hi:[1,0]
	v_pk_mul_f32 v[18:19], v[2:3], v[18:19]
	v_pk_mul_f32 v[20:21], v[4:5], v[20:21]
	global_store_dwordx4 v[24:25], v[18:21], off offset:528 nt
	global_load_dwordx4 v[18:21], v[186:187], off offset:16 sc1
	s_nop 0
	global_load_dwordx4 v[22:25], v[186:187], off offset:48 sc1
	global_load_dwordx4 v[26:29], v[186:187], off sc1
	global_load_dwordx4 v[30:33], v[186:187], off offset:32 sc1
	s_waitcnt vmcnt(1)
	v_mov_b32_e32 v106, v26
	s_waitcnt vmcnt(0)
	v_mov_b32_e32 v107, v30
	v_mov_b32_e32 v30, v27
	v_pk_add_f32 v[26:27], v[106:107], v[30:31]
	v_mov_b32_e32 v30, v28
	v_mov_b32_e32 v31, v32
	v_mov_b32_e32 v32, v29
	v_pk_add_f32 v[28:29], v[30:31], v[32:33]
	s_nop 0
	v_pk_add_f32 v[26:27], v[26:27], v[28:29]
	v_mov_b32_e32 v28, v18
	v_mov_b32_e32 v29, v22
	v_mov_b32_e32 v22, v19
	v_pk_add_f32 v[18:19], v[28:29], v[22:23]
	v_mov_b32_e32 v22, v20
	v_mov_b32_e32 v23, v24
	v_mov_b32_e32 v24, v21
	v_pk_add_f32 v[20:21], v[22:23], v[24:25]
	s_nop 0
	v_pk_add_f32 v[18:19], v[18:19], v[20:21]
	s_nop 0
	v_pk_add_f32 v[18:19], v[26:27], v[18:19]
	s_nop 0
	v_add_f32_e32 v0, v18, v19
	global_load_dwordx4 v[18:21], v[184:185], off offset:16 sc1
	global_load_dwordx4 v[22:25], v[184:185], off offset:48 sc1
	global_load_dwordx4 v[26:29], v[184:185], off sc1
	global_load_dwordx4 v[30:33], v[184:185], off offset:32 sc1
	v_fmamk_f32 v0, v0, 0x3a800000, v231
	v_rsq_f32_e32 v0, v0
	s_waitcnt vmcnt(1)
	v_mov_b32_e32 v106, v26
	s_waitcnt vmcnt(0)
	v_mov_b32_e32 v107, v30
	v_mov_b32_e32 v30, v27
	v_pk_add_f32 v[26:27], v[106:107], v[30:31]
	v_mov_b32_e32 v30, v28
	v_mov_b32_e32 v31, v32
	v_mov_b32_e32 v32, v29
	v_pk_add_f32 v[28:29], v[30:31], v[32:33]
	s_nop 0
	v_pk_add_f32 v[26:27], v[26:27], v[28:29]
	v_mov_b32_e32 v28, v18
	v_mov_b32_e32 v29, v22
	v_mov_b32_e32 v22, v19
	v_pk_add_f32 v[18:19], v[28:29], v[22:23]
	v_mov_b32_e32 v22, v20
	v_mov_b32_e32 v23, v24
	v_mov_b32_e32 v24, v21
	v_pk_add_f32 v[20:21], v[22:23], v[24:25]
	s_nop 0
	v_pk_add_f32 v[18:19], v[18:19], v[20:21]
	s_nop 0
	v_pk_add_f32 v[18:19], v[26:27], v[18:19]
	s_nop 0
	v_add_f32_e32 v18, v18, v19
	v_fmamk_f32 v18, v18, 0x3a800000, v231
	v_rsq_f32_e32 v106, v18
	global_load_dwordx4 v[18:21], v[182:183], off offset:16 sc1
	global_load_dwordx4 v[22:25], v[182:183], off offset:48 sc1
	global_load_dwordx4 v[26:29], v[182:183], off sc1
	global_load_dwordx4 v[30:33], v[182:183], off offset:32 sc1
	s_waitcnt vmcnt(1)
	v_mov_b32_e32 v108, v26
	s_waitcnt vmcnt(0)
	v_mov_b32_e32 v109, v30
	v_mov_b32_e32 v30, v27
	v_pk_add_f32 v[26:27], v[108:109], v[30:31]
	v_mov_b32_e32 v30, v28
	v_mov_b32_e32 v31, v32
	v_mov_b32_e32 v32, v29
	v_pk_add_f32 v[28:29], v[30:31], v[32:33]
	s_nop 0
	v_pk_add_f32 v[26:27], v[26:27], v[28:29]
	v_mov_b32_e32 v28, v18
	v_mov_b32_e32 v29, v22
	v_mov_b32_e32 v22, v19
	v_pk_add_f32 v[18:19], v[28:29], v[22:23]
	v_mov_b32_e32 v22, v20
	v_mov_b32_e32 v23, v24
	v_mov_b32_e32 v24, v21
	v_pk_add_f32 v[20:21], v[22:23], v[24:25]
	s_nop 0
	v_pk_add_f32 v[18:19], v[18:19], v[20:21]
	s_nop 0
	v_pk_add_f32 v[18:19], v[26:27], v[18:19]
	s_nop 0
	v_add_f32_e32 v18, v18, v19
	v_fmamk_f32 v18, v18, 0x3a800000, v231
	v_rsq_f32_e32 v108, v18
	global_load_dwordx4 v[22:25], v[180:181], off offset:16 sc1
	global_load_dwordx4 v[18:21], v[180:181], off offset:48 sc1
	global_load_dwordx4 v[30:33], v[180:181], off sc1
	global_load_dwordx4 v[26:29], v[180:181], off offset:32 sc1
	s_waitcnt vmcnt(1)
	v_mov_b32_e32 v110, v30
	s_waitcnt vmcnt(0)
	v_mov_b32_e32 v111, v26
	v_mov_b32_e32 v26, v31
	v_mov_b32_e32 v30, v32
	v_mov_b32_e32 v31, v28
	v_mov_b32_e32 v28, v33
	v_pk_add_f32 v[26:27], v[110:111], v[26:27]
	v_pk_add_f32 v[28:29], v[30:31], v[28:29]
	s_nop 0
	v_pk_add_f32 v[26:27], v[26:27], v[28:29]
	v_mov_b32_e32 v28, v22
	v_mov_b32_e32 v29, v18
	v_mov_b32_e32 v18, v23
	v_mov_b32_e32 v22, v24
	v_mov_b32_e32 v23, v20
	v_mov_b32_e32 v20, v25
	v_pk_add_f32 v[18:19], v[28:29], v[18:19]
	v_pk_add_f32 v[20:21], v[22:23], v[20:21]
	v_lshlrev_b64 v[24:25], 12, v[96:97]
	v_pk_add_f32 v[18:19], v[18:19], v[20:21]
	v_pk_mul_f32 v[20:21], v[64:65], v[0:1] op_sel_hi:[1,0]
	v_pk_add_f32 v[18:19], v[26:27], v[18:19]
	v_lshl_add_u64 v[24:25], s[2:3], 0, v[24:25]
	v_add_f32_e32 v18, v18, v19
	v_fmamk_f32 v18, v18, 0x3a800000, v231
	v_rsq_f32_e32 v22, v18
	v_pk_mul_f32 v[18:19], v[62:63], v[0:1] op_sel_hi:[1,0]
	v_pk_mul_f32 v[20:21], v[16:17], v[20:21]
	v_pk_mul_f32 v[18:19], v[14:15], v[18:19]
	v_lshl_add_u64 v[24:25], v[24:25], 0, v[178:179]
	global_store_dwordx4 v[24:25], v[18:21], off nt
	s_nop 1
	v_pk_mul_f32 v[18:19], v[58:59], v[0:1] op_sel_hi:[1,0]
	v_pk_mul_f32 v[20:21], v[60:61], v[0:1] op_sel_hi:[1,0]
	v_pk_mul_f32 v[18:19], v[10:11], v[18:19]
	v_pk_mul_f32 v[20:21], v[12:13], v[20:21]
	global_store_dwordx4 v[24:25], v[18:21], off offset:16 nt
	s_nop 1
	v_pk_mul_f32 v[18:19], v[54:55], v[0:1] op_sel_hi:[1,0]
	v_pk_mul_f32 v[20:21], v[56:57], v[0:1] op_sel_hi:[1,0]
	v_pk_mul_f32 v[18:19], v[6:7], v[18:19]
	v_pk_mul_f32 v[20:21], v[8:9], v[20:21]
	global_store_dwordx4 v[24:25], v[18:21], off offset:512 nt
	s_nop 1
	v_pk_mul_f32 v[18:19], v[50:51], v[0:1] op_sel_hi:[1,0]
	v_pk_mul_f32 v[20:21], v[52:53], v[0:1] op_sel_hi:[1,0]
	v_pk_mul_f32 v[18:19], v[2:3], v[18:19]
	v_pk_mul_f32 v[20:21], v[4:5], v[20:21]
	global_store_dwordx4 v[24:25], v[18:21], off offset:528 nt
	v_lshlrev_b64 v[24:25], 12, v[94:95]
	v_lshl_add_u64 v[24:25], s[2:3], 0, v[24:25]
	v_pk_mul_f32 v[18:19], v[46:47], v[106:107] op_sel_hi:[1,0]
	v_pk_mul_f32 v[20:21], v[48:49], v[106:107] op_sel_hi:[1,0]
	v_pk_mul_f32 v[18:19], v[14:15], v[18:19]
	v_pk_mul_f32 v[20:21], v[16:17], v[20:21]
	v_lshl_add_u64 v[24:25], v[24:25], 0, v[178:179]
	global_store_dwordx4 v[24:25], v[18:21], off nt
	s_nop 1
	v_pk_mul_f32 v[18:19], v[42:43], v[106:107] op_sel_hi:[1,0]
	v_pk_mul_f32 v[20:21], v[44:45], v[106:107] op_sel_hi:[1,0]
	v_pk_mul_f32 v[18:19], v[10:11], v[18:19]
	v_pk_mul_f32 v[20:21], v[12:13], v[20:21]
	global_store_dwordx4 v[24:25], v[18:21], off offset:16 nt
	s_nop 1
	v_pk_mul_f32 v[18:19], v[38:39], v[106:107] op_sel_hi:[1,0]
	v_pk_mul_f32 v[20:21], v[40:41], v[106:107] op_sel_hi:[1,0]
	v_pk_mul_f32 v[18:19], v[6:7], v[18:19]
	v_pk_mul_f32 v[20:21], v[8:9], v[20:21]
	global_store_dwordx4 v[24:25], v[18:21], off offset:512 nt
	s_nop 1
	v_pk_mul_f32 v[18:19], v[34:35], v[106:107] op_sel_hi:[1,0]
	v_pk_mul_f32 v[20:21], v[36:37], v[106:107] op_sel_hi:[1,0]
	v_pk_mul_f32 v[18:19], v[2:3], v[18:19]
	v_pk_mul_f32 v[20:21], v[4:5], v[20:21]
	global_store_dwordx4 v[24:25], v[18:21], off offset:528 nt
	v_lshlrev_b64 v[24:25], 12, v[92:93]
	v_lshl_add_u64 v[24:25], s[2:3], 0, v[24:25]
	v_pk_mul_f32 v[18:19], v[84:85], v[108:109] op_sel_hi:[1,0]
	v_pk_mul_f32 v[20:21], v[80:81], v[108:109] op_sel_hi:[1,0]
	v_pk_mul_f32 v[18:19], v[14:15], v[18:19]
	v_pk_mul_f32 v[20:21], v[16:17], v[20:21]
	v_lshl_add_u64 v[24:25], v[24:25], 0, v[178:179]
	global_store_dwordx4 v[24:25], v[18:21], off nt
	s_nop 1
	v_pk_mul_f32 v[18:19], v[82:83], v[108:109] op_sel_hi:[1,0]
	v_pk_mul_f32 v[20:21], v[78:79], v[108:109] op_sel_hi:[1,0]
	v_pk_mul_f32 v[18:19], v[10:11], v[18:19]
	v_pk_mul_f32 v[20:21], v[12:13], v[20:21]
	global_store_dwordx4 v[24:25], v[18:21], off offset:16 nt
	s_nop 1
	v_pk_mul_f32 v[18:19], v[88:89], v[108:109] op_sel_hi:[1,0]
	v_pk_mul_f32 v[20:21], v[72:73], v[108:109] op_sel_hi:[1,0]
	v_pk_mul_f32 v[18:19], v[6:7], v[18:19]
	v_pk_mul_f32 v[20:21], v[8:9], v[20:21]
	global_store_dwordx4 v[24:25], v[18:21], off offset:512 nt
	s_nop 1
	v_pk_mul_f32 v[18:19], v[86:87], v[108:109] op_sel_hi:[1,0]
	v_pk_mul_f32 v[20:21], v[70:71], v[108:109] op_sel_hi:[1,0]
	v_pk_mul_f32 v[18:19], v[2:3], v[18:19]
	v_pk_mul_f32 v[20:21], v[4:5], v[20:21]
	global_store_dwordx4 v[24:25], v[18:21], off offset:528 nt
	s_nop 1
	v_pk_mul_f32 v[18:19], v[100:101], v[22:23] op_sel_hi:[1,0]
	v_pk_mul_f32 v[20:21], v[76:77], v[22:23] op_sel_hi:[1,0]
	v_pk_mul_f32 v[14:15], v[14:15], v[18:19]
	v_lshlrev_b64 v[18:19], 12, v[90:91]
	v_lshl_add_u64 v[18:19], s[2:3], 0, v[18:19]
	v_pk_mul_f32 v[16:17], v[16:17], v[20:21]
	v_lshl_add_u64 v[18:19], v[18:19], 0, v[178:179]
	global_store_dwordx4 v[18:19], v[14:17], off nt
	s_nop 1
	v_pk_mul_f32 v[14:15], v[98:99], v[22:23] op_sel_hi:[1,0]
	v_pk_mul_f32 v[16:17], v[74:75], v[22:23] op_sel_hi:[1,0]
	v_pk_mul_f32 v[10:11], v[10:11], v[14:15]
	v_pk_mul_f32 v[12:13], v[12:13], v[16:17]
	global_store_dwordx4 v[18:19], v[10:13], off offset:16 nt
	s_nop 1
	v_pk_mul_f32 v[10:11], v[104:105], v[22:23] op_sel_hi:[1,0]
	v_pk_mul_f32 v[12:13], v[68:69], v[22:23] op_sel_hi:[1,0]
	v_pk_mul_f32 v[6:7], v[6:7], v[10:11]
	v_pk_mul_f32 v[8:9], v[8:9], v[12:13]
	global_store_dwordx4 v[18:19], v[6:9], off offset:512 nt
	s_nop 1
	v_pk_mul_f32 v[6:7], v[102:103], v[22:23] op_sel_hi:[1,0]
	v_pk_mul_f32 v[8:9], v[66:67], v[22:23] op_sel_hi:[1,0]
	v_pk_mul_f32 v[2:3], v[2:3], v[6:7]
	v_pk_mul_f32 v[4:5], v[4:5], v[8:9]
	global_store_dwordx4 v[18:19], v[2:5], off offset:528 nt
	s_waitcnt vmcnt(0)
	s_barrier

.LBB0_872:
	s_add_u32 s22, s12, 0x6400000
	s_addc_u32 s23, s13, 0
	s_add_u32 s10, s12, 0x6300000
	s_addc_u32 s11, s13, 0
	s_add_u32 s16, s12, 0xfa00000
	s_addc_u32 s17, s13, 0
	s_add_i32 s3, s24, s51
	s_lshl_b32 s2, s61, 5
	s_nop 0
	v_add_u32_e32 v166, s3, v159
	s_lshl_b32 s3, s60, 8
	s_or_b32 s2, s3, s2
	v_lshl_add_u32 v168, v158, 3, s2
	v_ashrrev_i32_e32 v169, 31, v168
	v_lshlrev_b64 v[180:181], 1, v[168:169]
	v_ashrrev_i32_e32 v167, 31, v166
	v_lshl_add_u64 v[184:185], s[22:23], 0, v[180:181]
	v_lshlrev_b64 v[182:183], 11, v[166:167]
	v_lshl_add_u64 v[122:123], v[184:185], 0, v[182:183]
	global_load_dwordx4 v[176:179], v[122:123], off sc1
	global_load_dwordx4 v[154:157], v[122:123], off offset:256 sc1
	v_add_u32_e32 v164, 16, v166
	v_ashrrev_i32_e32 v165, 31, v164
	v_add_u32_e32 v162, 32, v166
	v_lshlrev_b64 v[172:173], 11, v[164:165]
	v_ashrrev_i32_e32 v163, 31, v162
	v_add_u32_e32 v160, 48, v166
	v_lshl_add_u64 v[122:123], v[184:185], 0, v[172:173]
	v_lshlrev_b64 v[170:171], 11, v[162:163]
	v_ashrrev_i32_e32 v161, 31, v160
	global_load_dwordx4 v[150:153], v[122:123], off sc1
	global_load_dwordx4 v[146:149], v[122:123], off offset:256 sc1
	v_lshl_add_u64 v[122:123], v[184:185], 0, v[170:171]
	v_lshlrev_b64 v[174:175], 11, v[160:161]
	global_load_dwordx4 v[142:145], v[122:123], off sc1
	global_load_dwordx4 v[130:133], v[122:123], off offset:256 sc1
	v_lshl_add_u64 v[122:123], v[184:185], 0, v[174:175]
	global_load_dwordx4 v[126:129], v[122:123], off sc1
	s_nop 0
	global_load_dwordx4 v[122:125], v[122:123], off offset:256 sc1
	v_cmp_eq_u32_e64 s[2:3], 0, v158
	s_waitcnt vmcnt(0)
	v_lshlrev_b32_e32 v186, 16, v176
	v_and_b32_e32 v187, 0xffff0000, v176
	v_lshlrev_b32_e32 v176, 16, v177
	v_and_b32_e32 v177, 0xffff0000, v177
	v_pk_fma_f32 v[140:141], v[140:141], 0.5, v[176:177] op_sel_hi:[1,0,1]
	v_lshl_add_u64 v[176:177], s[22:23], 0, v[182:183]
	v_lshlrev_b32_e32 v188, 16, v178
	v_and_b32_e32 v189, 0xffff0000, v178
	v_lshlrev_b32_e32 v178, 16, v179
	v_and_b32_e32 v179, 0xffff0000, v179
	v_pk_fma_f32 v[138:139], v[138:139], 0.5, v[186:187] op_sel_hi:[1,0,1]
	v_lshl_add_u64 v[180:181], v[176:177], 0, v[180:181]
	v_cvt_pk_bf16_f32 v176, v138, v139
	v_pk_fma_f32 v[136:137], v[136:137], 0.5, v[178:179] op_sel_hi:[1,0,1]
	v_pk_fma_f32 v[134:135], v[134:135], 0.5, v[188:189] op_sel_hi:[1,0,1]
	v_cvt_pk_bf16_f32 v177, v140, v141
	v_mul_f32_e32 v0, v139, v139
	v_cvt_pk_bf16_f32 v178, v134, v135
	v_cvt_pk_bf16_f32 v179, v136, v137
	global_store_dwordx4 v[180:181], v[176:179], off
	v_fmac_f32_e32 v0, v138, v138
	s_nop 0
	v_mul_f32_e32 v176, v141, v141
	v_fmac_f32_e32 v176, v140, v140
	v_add_f32_e32 v0, v0, v176
	v_mul_f32_e32 v176, v135, v135
	v_fmac_f32_e32 v176, v134, v134
	v_add_f32_e32 v0, v176, v0
	v_mul_f32_e32 v176, v137, v137
	v_fmac_f32_e32 v176, v136, v136
	v_add_f32_e32 v0, v176, v0
	v_max_f32_e64 v176, |v138|, |v139|
	v_max_f32_e64 v177, |v140|, |v141|
	v_max3_f32 v182, v176, 0, v177
	v_max_f32_e64 v176, |v136|, |v137|
	v_max3_f32 v183, |v134|, |v135|, v176
	v_lshlrev_b32_e32 v176, 16, v154
	v_and_b32_e32 v177, 0xffff0000, v154
	v_lshlrev_b32_e32 v154, 16, v155
	v_and_b32_e32 v155, 0xffff0000, v155
	v_lshlrev_b32_e32 v178, 16, v156
	v_and_b32_e32 v179, 0xffff0000, v156
	v_lshlrev_b32_e32 v156, 16, v157
	v_and_b32_e32 v157, 0xffff0000, v157
	v_pk_fma_f32 v[120:121], v[120:121], 0.5, v[154:155] op_sel_hi:[1,0,1]
	v_pk_fma_f32 v[118:119], v[118:119], 0.5, v[176:177] op_sel_hi:[1,0,1]
	v_pk_fma_f32 v[116:117], v[116:117], 0.5, v[156:157] op_sel_hi:[1,0,1]
	v_cvt_pk_bf16_f32 v154, v118, v119
	v_cvt_pk_bf16_f32 v155, v120, v121
	v_pk_fma_f32 v[114:115], v[114:115], 0.5, v[178:179] op_sel_hi:[1,0,1]
	v_lshlrev_b64 v[178:179], 6, v[166:167]
	v_cvt_pk_bf16_f32 v156, v114, v115
	v_cvt_pk_bf16_f32 v157, v116, v117
	global_store_dwordx4 v[180:181], v[154:157], off offset:256
	s_nop 1
	v_mul_f32_e32 v154, v119, v119
	v_mul_f32_e32 v155, v121, v121
	v_fmac_f32_e32 v154, v118, v118
	v_fmac_f32_e32 v155, v120, v120
	v_add_f32_e32 v154, v154, v155
	v_mul_f32_e32 v155, v115, v115
	v_fmac_f32_e32 v155, v114, v114
	v_add_f32_e32 v154, v155, v154
	v_mul_f32_e32 v155, v117, v117
	v_fmac_f32_e32 v155, v116, v116
	v_add_f32_e32 v154, v155, v154
	v_add_f32_e32 v0, v0, v154
	v_max_f32_e64 v154, |v118|, |v119|
	v_max_f32_e64 v156, |v116|, |v117|
	v_max3_f32 v154, v182, v183, v154
	v_max_f32_e64 v155, |v120|, |v121|
	v_max3_f32 v156, |v114|, |v115|, v156
	v_max3_f32 v155, v154, v155, v156
	ds_swizzle_b32 v156, v155 offset:swizzle(SWAP,16)
	ds_swizzle_b32 v154, v0 offset:swizzle(SWAP,16)
	s_waitcnt lgkmcnt(1)
	v_max_f32_e32 v156, v156, v156
	s_waitcnt lgkmcnt(0)
	v_add_f32_e32 v0, v0, v154
	v_max_f32_e32 v155, v155, v156
	v_mov_b32_e32 v154, v0
	v_mov_b32_e32 v156, v155
	s_nop 0
	v_permlane32_swap_b32_e32 v0, v154
	v_permlane32_swap_b32_e32 v155, v156
	s_and_saveexec_b64 s[24:25], s[2:3]
	s_cbranch_execz .LBB0_874
	s_lshl_b32 s4, s60, 2
	v_max_f32_e32 v155, v155, v155
	v_max_f32_e32 v156, v156, v156
	s_ashr_i32 s5, s4, 31
	v_max_f32_e32 v156, v155, v156
	v_add_f32_e32 v0, v0, v154
	v_lshl_add_u64 v[154:155], s[10:11], 0, v[178:179]
	s_lshl_b64 s[4:5], s[4:5], 2
	v_lshl_add_u64 v[154:155], v[154:155], 0, s[4:5]
	s_lshl_b32 s26, s61, 2
	v_lshl_add_u64 v[154:155], v[154:155], 0, s[26:27]
	global_store_dword v[154:155], v0, off
	v_lshl_add_u64 v[154:155], s[16:17], 0, v[178:179]
	v_lshl_add_u64 v[154:155], v[154:155], 0, s[4:5]
	v_lshl_add_u64 v[154:155], v[154:155], 0, s[26:27]
	global_store_dword v[154:155], v156, off

.LBB0_880:
	s_or_b64 exec, exec, s[24:25]
	v_add_u32_e32 v100, 0x80, v166
	v_ashrrev_i32_e32 v101, 31, v100
	v_lshlrev_b64 v[190:191], 11, v[100:101]
	v_lshl_add_u64 v[66:67], v[184:185], 0, v[190:191]
	global_load_dwordx4 v[196:199], v[66:67], off sc1
	global_load_dwordx4 v[90:93], v[66:67], off offset:256 sc1
	v_add_u32_e32 v98, 0x90, v166
	v_ashrrev_i32_e32 v99, 31, v98
	v_add_u32_e32 v96, 0xa0, v166
	v_lshlrev_b64 v[192:193], 11, v[98:99]
	v_ashrrev_i32_e32 v97, 31, v96
	v_add_u32_e32 v94, 0xb0, v166
	v_lshl_add_u64 v[66:67], v[184:185], 0, v[192:193]
	v_lshlrev_b64 v[194:195], 11, v[96:97]
	v_ashrrev_i32_e32 v95, 31, v94
	global_load_dwordx4 v[86:89], v[66:67], off sc1
	global_load_dwordx4 v[82:85], v[66:67], off offset:256 sc1
	v_lshl_add_u64 v[66:67], v[184:185], 0, v[194:195]
	v_lshlrev_b64 v[186:187], 11, v[94:95]
	global_load_dwordx4 v[78:81], v[66:67], off sc1
	global_load_dwordx4 v[74:77], v[66:67], off offset:256 sc1
	v_lshl_add_u64 v[66:67], v[184:185], 0, v[186:187]
	global_load_dwordx4 v[70:73], v[66:67], off sc1
	s_nop 0
	global_load_dwordx4 v[66:69], v[66:67], off offset:256 sc1
	s_waitcnt vmcnt(7)
	v_lshlrev_b32_e32 v184, 16, v196
	v_and_b32_e32 v185, 0xffff0000, v196
	v_lshlrev_b32_e32 v196, 16, v197
	v_and_b32_e32 v197, 0xffff0000, v197
	v_pk_fma_f32 v[64:65], v[64:65], 0.5, v[196:197] op_sel_hi:[1,0,1]
	v_pk_fma_f32 v[62:63], v[62:63], 0.5, v[184:185] op_sel_hi:[1,0,1]
	v_lshlrev_b32_e32 v200, 16, v198
	v_and_b32_e32 v201, 0xffff0000, v198
	v_lshl_add_u64 v[184:185], s[22:23], 0, v[190:191]
	v_mul_f32_e32 v0, v63, v63
	v_mul_f32_e32 v190, v65, v65
	v_pk_fma_f32 v[58:59], v[58:59], 0.5, v[200:201] op_sel_hi:[1,0,1]
	v_fmac_f32_e32 v0, v62, v62
	v_fmac_f32_e32 v190, v64, v64
	v_lshlrev_b32_e32 v198, 16, v199
	v_and_b32_e32 v199, 0xffff0000, v199
	v_add_f32_e32 v0, v0, v190
	v_mul_f32_e32 v190, v59, v59
	v_pk_fma_f32 v[60:61], v[60:61], 0.5, v[198:199] op_sel_hi:[1,0,1]
	v_fmac_f32_e32 v190, v58, v58
	v_add_f32_e32 v0, v190, v0
	v_mul_f32_e32 v190, v61, v61
	v_fmac_f32_e32 v190, v60, v60
	v_lshl_add_u64 v[184:185], v[168:169], 1, v[184:185]
	v_cvt_pk_bf16_f32 v196, v62, v63
	v_cvt_pk_bf16_f32 v197, v64, v65
	v_cvt_pk_bf16_f32 v198, v58, v59
	v_add_f32_e32 v0, v190, v0
	v_max_f32_e64 v190, |v62|, |v63|
	v_max_f32_e64 v191, |v64|, |v65|
	v_cvt_pk_bf16_f32 v199, v60, v61
	global_store_dwordx4 v[184:185], v[196:199], off
	s_nop 1
	v_max3_f32 v198, v190, 0, v191
	v_max_f32_e64 v190, |v60|, |v61|
	v_max3_f32 v199, |v58|, |v59|, v190
	s_waitcnt vmcnt(7)
	v_lshlrev_b32_e32 v190, 16, v90
	v_and_b32_e32 v191, 0xffff0000, v90
	v_lshlrev_b32_e32 v90, 16, v91
	v_and_b32_e32 v91, 0xffff0000, v91
	v_lshlrev_b32_e32 v196, 16, v92
	v_and_b32_e32 v197, 0xffff0000, v92
	v_lshlrev_b32_e32 v92, 16, v93
	v_and_b32_e32 v93, 0xffff0000, v93
	v_pk_fma_f32 v[56:57], v[56:57], 0.5, v[90:91] op_sel_hi:[1,0,1]
	v_pk_fma_f32 v[54:55], v[54:55], 0.5, v[190:191] op_sel_hi:[1,0,1]
	v_pk_fma_f32 v[52:53], v[52:53], 0.5, v[92:93] op_sel_hi:[1,0,1]
	v_cvt_pk_bf16_f32 v90, v54, v55
	v_cvt_pk_bf16_f32 v91, v56, v57
	v_pk_fma_f32 v[50:51], v[50:51], 0.5, v[196:197] op_sel_hi:[1,0,1]
	v_lshlrev_b64 v[190:191], 6, v[100:101]
	v_cvt_pk_bf16_f32 v92, v50, v51
	v_cvt_pk_bf16_f32 v93, v52, v53
	global_store_dwordx4 v[184:185], v[90:93], off offset:256
	s_nop 1
	v_mul_f32_e32 v90, v55, v55
	v_mul_f32_e32 v91, v57, v57
	v_fmac_f32_e32 v90, v54, v54
	v_fmac_f32_e32 v91, v56, v56
	v_add_f32_e32 v90, v90, v91
	v_mul_f32_e32 v91, v51, v51
	v_fmac_f32_e32 v91, v50, v50
	v_add_f32_e32 v90, v91, v90
	v_mul_f32_e32 v91, v53, v53
	v_fmac_f32_e32 v91, v52, v52
	v_add_f32_e32 v90, v91, v90
	v_add_f32_e32 v0, v0, v90
	v_max_f32_e64 v90, |v54|, |v55|
	v_max_f32_e64 v92, |v52|, |v53|
	v_max3_f32 v90, v198, v199, v90
	v_max_f32_e64 v91, |v56|, |v57|
	v_max3_f32 v92, |v50|, |v51|, v92
	v_max3_f32 v91, v90, v91, v92
	ds_swizzle_b32 v92, v91 offset:swizzle(SWAP,16)
	ds_swizzle_b32 v90, v0 offset:swizzle(SWAP,16)
	s_waitcnt lgkmcnt(1)
	v_max_f32_e32 v92, v92, v92
	s_waitcnt lgkmcnt(0)
	v_add_f32_e32 v0, v0, v90
	v_max_f32_e32 v91, v91, v92
	v_mov_b32_e32 v90, v0
	v_mov_b32_e32 v92, v91
	s_nop 0
	v_permlane32_swap_b32_e32 v0, v90
	v_permlane32_swap_b32_e32 v91, v92
	s_and_saveexec_b64 s[24:25], s[2:3]
	s_cbranch_execz .LBB0_882
	s_lshl_b32 s4, s60, 2
	v_max_f32_e32 v91, v91, v91
	v_max_f32_e32 v92, v92, v92
	s_ashr_i32 s5, s4, 31
	v_max_f32_e32 v92, v91, v92
	v_add_f32_e32 v0, v0, v90
	v_lshl_add_u64 v[90:91], s[10:11], 0, v[190:191]
	s_lshl_b64 s[4:5], s[4:5], 2
	v_lshl_add_u64 v[90:91], v[90:91], 0, s[4:5]
	s_lshl_b32 s26, s61, 2
	v_lshl_add_u64 v[90:91], v[90:91], 0, s[26:27]
	global_store_dword v[90:91], v0, off
	v_lshl_add_u64 v[90:91], s[16:17], 0, v[190:191]
	v_lshl_add_u64 v[90:91], v[90:91], 0, s[4:5]
	v_lshl_add_u64 v[90:91], v[90:91], 0, s[26:27]
	global_store_dword v[90:91], v92, off

.LBB0_891:
	s_or_b64 exec, exec, s[42:43]
	s_waitcnt vmcnt(0)
	v_readfirstlane_b32 s4, v2
	s_nop 1
	v_add_u32_e32 v0, s4, v0
	v_and_b32_e32 v2, 3, v0
	v_cmp_ne_u32_e32 vcc, 3, v2
	s_and_saveexec_b64 s[40:41], vcc
	s_cbranch_execz .LBB0_906
	global_load_dword v2, v1, s[24:25] sc1
	v_bitop3_b32 v0, v0, -4, v0 bitop3:0xc
	s_waitcnt vmcnt(0)
	v_add_u32_e32 v2, v2, v0
	v_cmp_gt_i32_e32 vcc, 0, v2
	s_and_b64 exec, exec, vcc
	s_cbranch_execz .LBB0_906
	s_add_u32 s6, s6, 0x4200
	s_addc_u32 s7, s7, 0
	s_mov_b32 s4, 1
	s_mov_b64 s[42:43], 0
	s_branch .LBB0_895

.LBB0_907:
	s_or_b64 exec, exec, s[22:23]
	v_ashrrev_i32_e32 v159, 31, v158
	v_lshlrev_b64 v[2:3], 4, v[158:159]
	v_lshl_add_u64 v[200:201], s[16:17], 0, v[2:3]
	s_waitcnt lgkmcnt(0)
	s_barrier
	v_lshl_add_u64 v[4:5], v[200:201], 0, v[178:179]
	v_lshl_add_u64 v[6:7], v[200:201], 0, v[180:181]
	global_load_dwordx4 v[30:33], v[4:5], off sc1
	global_load_dwordx4 v[26:29], v[6:7], off sc1
	v_lshl_add_u64 v[4:5], v[200:201], 0, v[182:183]
	v_lshl_add_u64 v[6:7], v[200:201], 0, v[188:189]
	global_load_dwordx4 v[22:25], v[4:5], off sc1
	global_load_dwordx4 v[18:21], v[6:7], off sc1
	s_or_b32 s4, s60, s61
	s_cmp_eq_u32 s4, 0
	s_cselect_b64 s[16:17], -1, 0
	s_cmp_lg_u32 s4, 0
	v_lshl_add_u64 v[198:199], s[10:11], 0, v[2:3]
	v_mov_b32_e32 v14, 0
	v_mov_b32_e32 v15, 0
	v_mov_b32_e32 v16, 0
	v_mov_b32_e32 v17, 0
	v_mov_b32_e32 v10, 0
	v_mov_b32_e32 v11, 0
	v_mov_b32_e32 v12, 0
	v_mov_b32_e32 v13, 0
	v_mov_b32_e32 v6, 0
	v_mov_b32_e32 v7, 0
	v_mov_b32_e32 v8, 0
	v_mov_b32_e32 v9, 0
	v_mov_b32_e32 v2, 0
	v_mov_b32_e32 v3, 0
	v_mov_b32_e32 v4, 0
	v_mov_b32_e32 v5, 0
	s_cbranch_scc1 .LBB0_909
	v_lshl_add_u64 v[2:3], v[198:199], 0, v[178:179]
	v_lshl_add_u64 v[4:5], v[198:199], 0, v[180:181]
	global_load_dwordx4 v[14:17], v[2:3], off sc1
	global_load_dwordx4 v[10:13], v[4:5], off sc1
	v_lshl_add_u64 v[2:3], v[198:199], 0, v[182:183]
	v_lshl_add_u64 v[4:5], v[198:199], 0, v[188:189]
	global_load_dwordx4 v[6:9], v[2:3], off sc1
	s_nop 0
	global_load_dwordx4 v[2:5], v[4:5], off sc1

.LBB0_925:
	v_lshl_add_u64 v[18:19], v[200:201], 0, v[190:191]
	v_lshl_add_u64 v[20:21], v[200:201], 0, v[192:193]
	global_load_dwordx4 v[30:33], v[18:19], off sc1
	global_load_dwordx4 v[26:29], v[20:21], off sc1
	v_lshl_add_u64 v[18:19], v[200:201], 0, v[194:195]
	v_lshl_add_u64 v[20:21], v[200:201], 0, v[196:197]
	global_load_dwordx4 v[22:25], v[18:19], off sc1
	s_nop 0
	global_load_dwordx4 v[18:21], v[20:21], off sc1
	s_and_b64 vcc, exec, s[6:7]
	s_cbranch_vccnz .LBB0_927
	v_lshl_add_u64 v[2:3], v[198:199], 0, v[190:191]
	v_lshl_add_u64 v[4:5], v[198:199], 0, v[192:193]
	global_load_dwordx4 v[14:17], v[2:3], off sc1
	global_load_dwordx4 v[10:13], v[4:5], off sc1
	v_lshl_add_u64 v[2:3], v[198:199], 0, v[194:195]
	v_lshl_add_u64 v[4:5], v[198:199], 0, v[196:197]
	global_load_dwordx4 v[6:9], v[2:3], off sc1
	s_nop 0
	global_load_dwordx4 v[2:5], v[4:5], off sc1

.LBB0_956:
	s_add_u32 s4, s12, 0x6400000
	s_addc_u32 s5, s13, 0
	s_add_u32 s2, s12, 0x6300000
	s_addc_u32 s3, s13, 0
	s_add_i32 s7, s24, s47
	s_lshl_b32 s6, s23, 5
	s_lshl_b32 s12, s22, 8
	s_or_b32 s6, s12, s6
	v_add_u32_e32 v202, s7, v132
	v_ashrrev_i32_e32 v203, 31, v202
	v_lshl_add_u32 v194, v240, 3, s6
	v_lshlrev_b64 v[186:187], 11, v[202:203]
	s_cmp_eq_u64 s[10:11], 0
	v_ashrrev_i32_e32 v195, 31, v194
	v_cmp_eq_u32_e64 s[6:7], 0, v240
	v_add_u32_e32 v200, 16, v202
	v_add_u32_e32 v198, 32, v202
	v_add_u32_e32 v196, 48, v202
	v_lshl_add_u64 v[206:207], s[4:5], 0, v[186:187]
	s_cbranch_scc1 .LBB0_987
	v_lshl_add_u64 v[188:189], v[194:195], 2, s[10:11]
	v_lshlrev_b64 v[130:131], 12, v[202:203]
	v_lshl_add_u64 v[130:131], v[188:189], 0, v[130:131]
	global_load_dwordx4 v[190:193], v[130:131], off offset:16 sc1 nt
	global_load_dwordx4 v[208:211], v[130:131], off sc1 nt
	global_load_dwordx4 v[178:181], v[130:131], off offset:528 sc1 nt
	global_load_dwordx4 v[182:185], v[130:131], off offset:512 sc1 nt
	v_ashrrev_i32_e32 v201, 31, v200
	v_lshlrev_b64 v[130:131], 12, v[200:201]
	v_lshl_add_u64 v[130:131], v[188:189], 0, v[130:131]
	v_ashrrev_i32_e32 v199, 31, v198
	global_load_dwordx4 v[170:173], v[130:131], off offset:16 sc1 nt
	global_load_dwordx4 v[174:177], v[130:131], off sc1 nt
	global_load_dwordx4 v[162:165], v[130:131], off offset:528 sc1 nt
	global_load_dwordx4 v[166:169], v[130:131], off offset:512 sc1 nt
	v_lshlrev_b64 v[130:131], 12, v[198:199]
	v_lshl_add_u64 v[130:131], v[188:189], 0, v[130:131]
	v_ashrrev_i32_e32 v197, 31, v196
	global_load_dwordx4 v[154:157], v[130:131], off offset:16 sc1 nt
	global_load_dwordx4 v[158:161], v[130:131], off sc1 nt
	global_load_dwordx4 v[142:145], v[130:131], off offset:528 sc1 nt
	global_load_dwordx4 v[150:153], v[130:131], off offset:512 sc1 nt
	v_lshlrev_b64 v[130:131], 12, v[196:197]
	v_lshl_add_u64 v[134:135], v[188:189], 0, v[130:131]
	global_load_dwordx4 v[138:141], v[134:135], off offset:16 sc1 nt
	global_load_dwordx4 v[146:149], v[134:135], off sc1 nt
	global_load_dwordx4 v[130:133], v[134:135], off offset:528 sc1 nt
	s_nop 0
	global_load_dwordx4 v[134:137], v[134:135], off offset:512 sc1 nt
	v_lshl_add_u64 v[214:215], v[194:195], 1, v[206:207]
	s_waitcnt vmcnt(0)
	v_pk_fma_f32 v[212:213], v[122:123], 0.5, v[190:191] op_sel_hi:[1,0,1]
	v_pk_fma_f32 v[204:205], v[128:129], 0.5, v[210:211] op_sel_hi:[1,0,1]
	v_pk_fma_f32 v[208:209], v[126:127], 0.5, v[208:209] op_sel_hi:[1,0,1]
	v_pk_fma_f32 v[210:211], v[124:125], 0.5, v[192:193] op_sel_hi:[1,0,1]
	v_cvt_pk_bf16_f32 v190, v208, v209
	v_cvt_pk_bf16_f32 v191, v204, v205
	v_cvt_pk_bf16_f32 v192, v212, v213
	v_mul_f32_e32 v0, v209, v209
	v_cvt_pk_bf16_f32 v193, v210, v211
	global_store_dwordx4 v[214:215], v[190:193], off
	v_fmac_f32_e32 v0, v208, v208
	v_pk_fma_f32 v[184:185], v[120:121], 0.5, v[184:185] op_sel_hi:[1,0,1]
	v_mul_f32_e32 v190, v205, v205
	v_fmac_f32_e32 v190, v204, v204
	v_add_f32_e32 v0, v0, v190
	v_mul_f32_e32 v190, v213, v213
	v_fmac_f32_e32 v190, v212, v212
	v_add_f32_e32 v0, v190, v0
	v_mul_f32_e32 v190, v211, v211
	v_fmac_f32_e32 v190, v210, v210
	v_pk_fma_f32 v[182:183], v[118:119], 0.5, v[182:183] op_sel_hi:[1,0,1]
	v_pk_fma_f32 v[192:193], v[114:115], 0.5, v[178:179] op_sel_hi:[1,0,1]
	v_cvt_pk_bf16_f32 v178, v182, v183
	v_cvt_pk_bf16_f32 v179, v184, v185
	v_add_f32_e32 v0, v190, v0
	v_pk_fma_f32 v[190:191], v[116:117], 0.5, v[180:181] op_sel_hi:[1,0,1]
	v_cvt_pk_bf16_f32 v180, v192, v193
	s_nop 0
	v_cvt_pk_bf16_f32 v181, v190, v191
	global_store_dwordx4 v[214:215], v[178:181], off offset:256
	s_nop 1
	v_mul_f32_e32 v178, v183, v183
	v_mul_f32_e32 v179, v185, v185
	v_fmac_f32_e32 v178, v182, v182
	v_fmac_f32_e32 v179, v184, v184
	v_add_f32_e32 v178, v178, v179
	v_mul_f32_e32 v179, v193, v193
	v_fmac_f32_e32 v179, v192, v192
	v_add_f32_e32 v178, v179, v178
	v_mul_f32_e32 v179, v191, v191
	v_fmac_f32_e32 v179, v190, v190
	v_add_f32_e32 v178, v179, v178
	v_add_f32_e32 v0, v0, v178
	ds_swizzle_b32 v178, v0 offset:swizzle(SWAP,16)
	s_waitcnt lgkmcnt(0)
	v_add_f32_e32 v0, v0, v178
	v_mov_b32_e32 v178, v0
	s_nop 1
	v_permlane32_swap_b32_e32 v0, v178
	s_and_saveexec_b64 s[10:11], s[6:7]
	s_cbranch_execz .LBB0_959
	v_add_f32_e32 v0, v0, v178
	s_lshl_b32 s12, s22, 2
	v_lshlrev_b64 v[178:179], 6, v[202:203]
	s_ashr_i32 s13, s12, 31
	v_lshl_add_u64 v[178:179], s[2:3], 0, v[178:179]
	v_lshl_add_u64 v[178:179], s[12:13], 2, v[178:179]
	s_lshl_b32 s26, s23, 2
	v_lshl_add_u64 v[178:179], v[178:179], 0, s[26:27]
	global_store_dword v[178:179], v0, off

.LBB0_965:
	s_or_b64 exec, exec, s[10:11]
	v_add_u32_e32 v208, 0x80, v202
	v_ashrrev_i32_e32 v209, 31, v208
	v_lshlrev_b64 v[130:131], 12, v[208:209]
	v_lshl_add_u64 v[130:131], v[188:189], 0, v[130:131]
	global_load_dwordx4 v[210:213], v[130:131], off offset:16 sc1 nt
	global_load_dwordx4 v[214:217], v[130:131], off sc1 nt
	global_load_dwordx4 v[178:181], v[130:131], off offset:528 sc1 nt
	global_load_dwordx4 v[182:185], v[130:131], off offset:512 sc1 nt
	v_add_u32_e32 v192, 0x90, v202
	v_ashrrev_i32_e32 v193, 31, v192
	v_lshlrev_b64 v[130:131], 12, v[192:193]
	v_add_u32_e32 v190, 0xa0, v202
	v_lshl_add_u64 v[130:131], v[188:189], 0, v[130:131]
	v_ashrrev_i32_e32 v191, 31, v190
	global_load_dwordx4 v[170:173], v[130:131], off offset:16 sc1 nt
	global_load_dwordx4 v[174:177], v[130:131], off sc1 nt
	global_load_dwordx4 v[162:165], v[130:131], off offset:528 sc1 nt
	global_load_dwordx4 v[166:169], v[130:131], off offset:512 sc1 nt
	v_lshlrev_b64 v[130:131], 12, v[190:191]
	v_add_u32_e32 v204, 0xb0, v202
	v_lshl_add_u64 v[130:131], v[188:189], 0, v[130:131]
	v_ashrrev_i32_e32 v205, 31, v204
	global_load_dwordx4 v[154:157], v[130:131], off offset:16 sc1 nt
	global_load_dwordx4 v[158:161], v[130:131], off sc1 nt
	global_load_dwordx4 v[138:141], v[130:131], off offset:528 sc1 nt
	global_load_dwordx4 v[142:145], v[130:131], off offset:512 sc1 nt
	v_lshlrev_b64 v[130:131], 12, v[204:205]
	v_lshl_add_u64 v[134:135], v[188:189], 0, v[130:131]
	global_load_dwordx4 v[146:149], v[134:135], off offset:16 sc1 nt
	global_load_dwordx4 v[150:153], v[134:135], off sc1 nt
	global_load_dwordx4 v[130:133], v[134:135], off offset:528 sc1 nt
	s_nop 0
	global_load_dwordx4 v[134:137], v[134:135], off offset:512 sc1 nt
	v_lshlrev_b64 v[188:189], 11, v[208:209]
	v_lshl_add_u64 v[188:189], s[4:5], 0, v[188:189]
	v_lshl_add_u64 v[188:189], v[194:195], 1, v[188:189]
	s_waitcnt vmcnt(15)
	v_pk_fma_f32 v[218:219], v[60:61], 0.5, v[212:213] op_sel_hi:[1,0,1]
	s_waitcnt vmcnt(14)
	v_pk_fma_f32 v[216:217], v[64:65], 0.5, v[216:217] op_sel_hi:[1,0,1]
	v_pk_fma_f32 v[214:215], v[62:63], 0.5, v[214:215] op_sel_hi:[1,0,1]
	v_pk_fma_f32 v[220:221], v[58:59], 0.5, v[210:211] op_sel_hi:[1,0,1]
	v_cvt_pk_bf16_f32 v210, v214, v215
	v_cvt_pk_bf16_f32 v211, v216, v217
	s_waitcnt vmcnt(12)
	v_pk_fma_f32 v[184:185], v[56:57], 0.5, v[184:185] op_sel_hi:[1,0,1]
	v_cvt_pk_bf16_f32 v212, v220, v221
	v_cvt_pk_bf16_f32 v213, v218, v219
	global_store_dwordx4 v[188:189], v[210:213], off
	v_pk_fma_f32 v[182:183], v[54:55], 0.5, v[182:183] op_sel_hi:[1,0,1]
	v_mul_f32_e32 v0, v215, v215
	v_pk_fma_f32 v[212:213], v[50:51], 0.5, v[178:179] op_sel_hi:[1,0,1]
	v_cvt_pk_bf16_f32 v178, v182, v183
	v_cvt_pk_bf16_f32 v179, v184, v185
	v_mul_f32_e32 v197, v217, v217
	v_pk_fma_f32 v[210:211], v[52:53], 0.5, v[180:181] op_sel_hi:[1,0,1]
	v_cvt_pk_bf16_f32 v180, v212, v213
	v_fmac_f32_e32 v0, v214, v214
	v_cvt_pk_bf16_f32 v181, v210, v211
	global_store_dwordx4 v[188:189], v[178:181], off offset:256
	v_fmac_f32_e32 v197, v216, v216
	v_add_f32_e32 v0, v0, v197
	v_mul_f32_e32 v178, v183, v183
	v_mul_f32_e32 v179, v185, v185
	v_fmac_f32_e32 v178, v182, v182
	v_fmac_f32_e32 v179, v184, v184
	v_mul_f32_e32 v197, v221, v221
	v_add_f32_e32 v178, v178, v179
	v_mul_f32_e32 v179, v213, v213
	v_fmac_f32_e32 v197, v220, v220
	v_fmac_f32_e32 v179, v212, v212
	v_add_f32_e32 v0, v197, v0
	v_mul_f32_e32 v197, v219, v219
	v_add_f32_e32 v178, v179, v178
	v_mul_f32_e32 v179, v211, v211
	v_fmac_f32_e32 v197, v218, v218
	v_fmac_f32_e32 v179, v210, v210
	v_add_f32_e32 v0, v197, v0
	v_add_f32_e32 v178, v179, v178
	v_add_f32_e32 v0, v0, v178
	ds_swizzle_b32 v178, v0 offset:swizzle(SWAP,16)
	s_waitcnt lgkmcnt(0)
	v_add_f32_e32 v0, v0, v178
	v_mov_b32_e32 v178, v0
	s_nop 1
	v_permlane32_swap_b32_e32 v0, v178
	s_and_saveexec_b64 s[10:11], s[6:7]
	s_cbranch_execz .LBB0_967
	v_add_f32_e32 v0, v0, v178
	s_lshl_b32 s12, s22, 2
	v_lshlrev_b64 v[178:179], 6, v[208:209]
	s_ashr_i32 s13, s12, 31
	v_lshl_add_u64 v[178:179], s[2:3], 0, v[178:179]
	v_lshl_add_u64 v[178:179], s[12:13], 2, v[178:179]
	s_lshl_b32 s26, s23, 2
	v_lshl_add_u64 v[178:179], v[178:179], 0, s[26:27]
	global_store_dword v[178:179], v0, off

.LBB0_972:
	v_lshlrev_b64 v[228:229], 1, v[194:195]
	v_lshl_add_u64 v[134:135], s[4:5], 0, v[228:229]
	v_lshl_add_u64 v[130:131], v[134:135], 0, v[186:187]
	global_load_dwordx4 v[190:193], v[130:131], off sc1
	global_load_dwordx4 v[186:189], v[130:131], off offset:256 sc1
	v_ashrrev_i32_e32 v201, 31, v200
	v_lshlrev_b64 v[226:227], 11, v[200:201]
	v_ashrrev_i32_e32 v199, 31, v198
	v_lshl_add_u64 v[130:131], v[134:135], 0, v[226:227]
	v_lshlrev_b64 v[224:225], 11, v[198:199]
	v_ashrrev_i32_e32 v197, 31, v196
	v_add_u32_e32 v218, 0x80, v202
	global_load_dwordx4 v[182:185], v[130:131], off sc1
	global_load_dwordx4 v[178:181], v[130:131], off offset:256 sc1
	v_lshl_add_u64 v[130:131], v[134:135], 0, v[224:225]
	v_lshlrev_b64 v[222:223], 11, v[196:197]
	v_ashrrev_i32_e32 v219, 31, v218
	v_add_u32_e32 v214, 0x90, v202
	global_load_dwordx4 v[174:177], v[130:131], off sc1
	global_load_dwordx4 v[170:173], v[130:131], off offset:256 sc1
	v_lshl_add_u64 v[130:131], v[134:135], 0, v[222:223]
	v_lshlrev_b64 v[220:221], 11, v[218:219]
	v_ashrrev_i32_e32 v215, 31, v214
	v_add_u32_e32 v208, 0xa0, v202
	v_add_u32_e32 v204, 0xb0, v202
	global_load_dwordx4 v[166:169], v[130:131], off sc1
	global_load_dwordx4 v[162:165], v[130:131], off offset:256 sc1
	v_lshl_add_u64 v[130:131], v[134:135], 0, v[220:221]
	v_lshlrev_b64 v[216:217], 11, v[214:215]
	v_ashrrev_i32_e32 v209, 31, v208
	v_ashrrev_i32_e32 v205, 31, v204
	global_load_dwordx4 v[158:161], v[130:131], off sc1
	global_load_dwordx4 v[154:157], v[130:131], off offset:256 sc1
	v_lshl_add_u64 v[130:131], v[134:135], 0, v[216:217]
	v_lshlrev_b64 v[212:213], 11, v[208:209]
	v_lshlrev_b64 v[210:211], 11, v[204:205]
	global_load_dwordx4 v[150:153], v[130:131], off sc1
	global_load_dwordx4 v[146:149], v[130:131], off offset:256 sc1
	v_lshl_add_u64 v[130:131], v[134:135], 0, v[212:213]
	v_lshl_add_u64 v[134:135], v[134:135], 0, v[210:211]
	global_load_dwordx4 v[142:145], v[130:131], off sc1
	s_nop 0
	global_load_dwordx4 v[130:133], v[130:131], off offset:256 sc1
	s_nop 0
	global_load_dwordx4 v[138:141], v[134:135], off sc1
	s_nop 0
	global_load_dwordx4 v[134:137], v[134:135], off offset:256 sc1
	v_lshl_add_u64 v[206:207], v[206:207], 0, v[228:229]
	v_cmp_eq_u32_e64 s[6:7], 0, v240
	s_waitcnt vmcnt(0)
	v_lshlrev_b32_e32 v232, 16, v190
	v_and_b32_e32 v233, 0xffff0000, v190
	v_lshlrev_b32_e32 v190, 16, v191
	v_and_b32_e32 v191, 0xffff0000, v191
	v_lshlrev_b32_e32 v234, 16, v192
	v_and_b32_e32 v235, 0xffff0000, v192
	v_lshlrev_b32_e32 v192, 16, v193
	v_and_b32_e32 v193, 0xffff0000, v193
	v_pk_fma_f32 v[128:129], v[128:129], 0.5, v[190:191] op_sel_hi:[1,0,1]
	v_pk_fma_f32 v[126:127], v[126:127], 0.5, v[232:233] op_sel_hi:[1,0,1]
	v_pk_fma_f32 v[190:191], v[124:125], 0.5, v[192:193] op_sel_hi:[1,0,1]
	v_pk_fma_f32 v[192:193], v[122:123], 0.5, v[234:235] op_sel_hi:[1,0,1]
	v_cvt_pk_bf16_f32 v122, v126, v127
	v_cvt_pk_bf16_f32 v123, v128, v129
	v_mul_f32_e32 v0, v127, v127
	v_cvt_pk_bf16_f32 v124, v192, v193
	v_cvt_pk_bf16_f32 v125, v190, v191
	global_store_dwordx4 v[206:207], v[122:125], off
	v_fmac_f32_e32 v0, v126, v126
	v_lshlrev_b32_e32 v126, 16, v188
	v_mul_f32_e32 v122, v129, v129
	v_fmac_f32_e32 v122, v128, v128
	v_add_f32_e32 v0, v0, v122
	v_mul_f32_e32 v122, v193, v193
	v_fmac_f32_e32 v122, v192, v192
	v_add_f32_e32 v0, v122, v0
	v_mul_f32_e32 v122, v191, v191
	v_fmac_f32_e32 v122, v190, v190
	v_add_f32_e32 v0, v122, v0
	v_lshlrev_b32_e32 v122, 16, v186
	v_and_b32_e32 v123, 0xffff0000, v186
	v_lshlrev_b32_e32 v124, 16, v187
	v_and_b32_e32 v125, 0xffff0000, v187
	v_and_b32_e32 v127, 0xffff0000, v188
	v_lshlrev_b32_e32 v128, 16, v189
	v_and_b32_e32 v129, 0xffff0000, v189
	v_pk_fma_f32 v[120:121], v[120:121], 0.5, v[124:125] op_sel_hi:[1,0,1]
	v_pk_fma_f32 v[118:119], v[118:119], 0.5, v[122:123] op_sel_hi:[1,0,1]
	v_pk_fma_f32 v[124:125], v[114:115], 0.5, v[126:127] op_sel_hi:[1,0,1]
	v_cvt_pk_bf16_f32 v114, v118, v119
	v_cvt_pk_bf16_f32 v115, v120, v121
	v_pk_fma_f32 v[122:123], v[116:117], 0.5, v[128:129] op_sel_hi:[1,0,1]
	v_cvt_pk_bf16_f32 v116, v124, v125
	s_nop 0
	v_cvt_pk_bf16_f32 v117, v122, v123
	global_store_dwordx4 v[206:207], v[114:117], off offset:256
	s_nop 1
	v_mul_f32_e32 v114, v119, v119
	v_mul_f32_e32 v115, v121, v121
	v_fmac_f32_e32 v114, v118, v118
	v_fmac_f32_e32 v115, v120, v120
	v_add_f32_e32 v114, v114, v115
	v_mul_f32_e32 v115, v125, v125
	v_fmac_f32_e32 v115, v124, v124
	v_add_f32_e32 v114, v115, v114
	v_mul_f32_e32 v115, v123, v123
	v_fmac_f32_e32 v115, v122, v122
	v_add_f32_e32 v114, v115, v114
	v_add_f32_e32 v0, v0, v114
	ds_swizzle_b32 v114, v0 offset:swizzle(SWAP,16)
	s_waitcnt lgkmcnt(0)
	v_add_f32_e32 v0, v0, v114
	v_mov_b32_e32 v114, v0
	s_nop 1
	v_permlane32_swap_b32_e32 v0, v114
	s_and_saveexec_b64 s[10:11], s[6:7]
	s_cbranch_execz .LBB0_974
	v_add_f32_e32 v0, v0, v114
	s_lshl_b32 s12, s22, 2
	v_lshlrev_b64 v[114:115], 6, v[202:203]
	s_ashr_i32 s13, s12, 31
	v_lshl_add_u64 v[114:115], s[2:3], 0, v[114:115]
	v_lshl_add_u64 v[114:115], s[12:13], 2, v[114:115]
	s_lshl_b32 s26, s23, 2
	v_lshl_add_u64 v[114:115], v[114:115], 0, s[26:27]
	global_store_dword v[114:115], v0, off

.LBB0_998:
	s_or_b64 exec, exec, s[16:17]
	s_waitcnt vmcnt(0)
	v_readfirstlane_b32 s2, v2
	s_nop 1
	v_add_u32_e32 v0, s2, v0
	v_and_b32_e32 v2, -4, v0
	v_and_b32_e32 v0, 3, v0
	v_cmp_eq_u32_e64 s[2:3], 3, v0
	v_add_u32_e32 v2, 4, v2
	s_and_b64 s[2:3], s[2:3], exec

.LBB0_1080:
	v_bfe_i32 v3, v141, 27, 1
	v_lshlrev_b32_e32 v0, 4, v141
	v_lshrrev_b32_e32 v3, 22, v3
	v_add_u32_e32 v3, v0, v3
	v_and_b32_e32 v3, 0xfffffc00, v3
	v_sub_u32_e32 v3, v0, v3
	v_ashrrev_i32_e32 v2, 31, v141
	v_lshrrev_b32_e32 v4, 4, v3
	v_lshrrev_b32_e32 v2, 26, v2
	v_bitop3_b32 v3, v4, v3, 32 bitop3:0x6c
	v_add_u32_e32 v2, v141, v2
	v_ashrrev_i32_e32 v5, 31, v3
	v_ashrrev_i32_e32 v2, 6, v2
	v_lshrrev_b32_e32 v5, 26, v5
	v_lshlrev_b32_e32 v4, 3, v2
	v_add_u32_e32 v5, v3, v5
	v_and_b32_e32 v4, -16, v4
	v_ashrrev_i32_e32 v139, 6, v5
	v_add_u32_e32 v137, v139, v4
	v_and_b32_e32 v4, 0xc0, v5
	v_sub_u32_e32 v3, v3, v4
	v_lshlrev_b32_e32 v2, 5, v2
	v_ashrrev_i16_sdwa v3, v230, sext(v3) dst_sel:DWORD dst_unused:UNUSED_PAD src0_sel:DWORD src1_sel:BYTE_0
	v_and_b32_e32 v2, 32, v2
	v_bfe_i32 v3, v3, 0, 16
	v_add_u32_e32 v0, 0x2000, v0
	v_add_lshl_u32 v143, v2, v3, 1
	v_ashrrev_i32_e32 v2, 31, v0
	v_lshrrev_b32_e32 v2, 22, v2
	v_add_u32_e32 v2, v0, v2
	v_ashrrev_i32_e32 v2, 10, v2
	v_mul_i32_i24_e32 v3, 0x400, v2
	v_sub_u32_e32 v0, v0, v3
	v_lshrrev_b32_e32 v3, 4, v0
	v_bitop3_b32 v0, v3, v0, 32 bitop3:0x6c
	v_ashrrev_i32_e32 v4, 31, v0
	v_lshrrev_b32_e32 v4, 26, v4
	v_lshlrev_b32_e32 v3, 3, v2
	v_add_u32_e32 v4, v0, v4
	v_and_b32_e32 v3, -16, v3
	v_ashrrev_i32_e32 v146, 6, v4
	s_add_u32 s10, s4, 0x6300000
	v_add_u32_e32 v145, v146, v3
	v_and_b32_e32 v3, 0xc0, v4
	s_addc_u32 s11, s5, 0
	v_sub_u32_e32 v0, v0, v3
	s_ashr_i32 s3, s16, 8
	v_lshlrev_b32_e32 v2, 5, v2
	v_ashrrev_i16_sdwa v0, v230, sext(v0) dst_sel:DWORD dst_unused:UNUSED_PAD src0_sel:DWORD src1_sel:BYTE_0
	s_lshl_b32 s43, s3, 6
	s_lshl_b32 s12, s84, 8
	v_and_b32_e32 v2, 32, v2
	v_bfe_i32 v0, v0, 0, 16
	v_and_b32_e32 v135, 15, v141
	s_add_i32 s12, s12, s43
	v_add_lshl_u32 v147, v2, v0, 1
	v_or_b32_e32 v2, s12, v135
	v_or_b32_e32 v6, 16, v2
	v_ashrrev_i32_e32 v3, 31, v2
	v_ashrrev_i32_e32 v7, 31, v6
	v_lshlrev_b64 v[4:5], 6, v[2:3]
	v_lshlrev_b64 v[6:7], 6, v[6:7]
	v_lshl_add_u64 v[4:5], s[10:11], 0, v[4:5]
	v_lshl_add_u64 v[6:7], s[10:11], 0, v[6:7]
	global_load_dwordx4 v[102:105], v[4:5], off offset:48 sc1
	global_load_dwordx4 v[114:117], v[4:5], off offset:32 sc1
	global_load_dwordx4 v[122:125], v[4:5], off offset:16 sc1
	global_load_dwordx4 v[126:129], v[4:5], off sc1
	global_load_dwordx4 v[86:89], v[6:7], off offset:48 sc1
	global_load_dwordx4 v[98:101], v[6:7], off offset:32 sc1
	global_load_dwordx4 v[110:113], v[6:7], off offset:16 sc1
	global_load_dwordx4 v[118:121], v[6:7], off sc1
	v_or_b32_e32 v6, 32, v2
	v_or_b32_e32 v2, 48, v2
	v_ashrrev_i32_e32 v7, 31, v6
	v_ashrrev_i32_e32 v3, 31, v2
	v_lshlrev_b64 v[6:7], 6, v[6:7]
	v_lshlrev_b64 v[2:3], 6, v[2:3]
	v_lshl_add_u64 v[6:7], s[10:11], 0, v[6:7]
	v_lshl_add_u64 v[2:3], s[10:11], 0, v[2:3]
	s_mov_b64 s[12:13], 0x2000
	global_load_dwordx4 v[74:77], v[6:7], off offset:48 sc1
	global_load_dwordx4 v[82:85], v[6:7], off offset:32 sc1
	global_load_dwordx4 v[94:97], v[6:7], off offset:16 sc1
	global_load_dwordx4 v[106:109], v[6:7], off sc1
	global_load_dwordx4 v[46:49], v[2:3], off offset:48 sc1
	global_load_dwordx4 v[58:61], v[2:3], off offset:32 sc1
	global_load_dwordx4 v[78:81], v[2:3], off offset:16 sc1
	global_load_dwordx4 v[90:93], v[2:3], off sc1
	v_lshl_add_u64 v[2:3], v[4:5], 0, s[12:13]
	s_movk_i32 s12, 0x2000
	v_add_co_u32_e32 v6, vcc, s12, v4
	s_mov_b64 s[12:13], 0x2400
	s_nop 0
	v_addc_co_u32_e32 v7, vcc, 0, v5, vcc
	s_ashr_i32 s2, s16, 6
	global_load_dwordx4 v[62:65], v[6:7], off sc1
	global_load_dwordx4 v[42:45], v[2:3], off offset:48 sc1
	global_load_dwordx4 v[50:53], v[2:3], off offset:32 sc1
	global_load_dwordx4 v[66:69], v[2:3], off offset:16 sc1
	v_lshl_add_u64 v[2:3], v[4:5], 0, s[12:13]
	s_mov_b64 s[12:13], 0x2800
	v_lshl_add_u32 v131, v137, 11, v143
	s_lshl_b32 s42, s2, 10
	v_lshl_add_u64 v[14:15], v[4:5], 0, s[12:13]
	s_mov_b64 s[12:13], 0x2c00
	v_lshl_add_u64 v[16:17], v[4:5], 0, s[12:13]
	s_add_i32 s60, s42, 0
	v_mov_b32_e32 v0, v131
	v_lshl_add_u32 v133, v145, 11, v147
	global_load_dwordx4 v[30:33], v[2:3], off offset:48 sc1
	global_load_dwordx4 v[38:41], v[2:3], off offset:32 sc1
	global_load_dwordx4 v[54:57], v[6:7], off offset:1024 sc1
	global_load_dwordx4 v[34:37], v[6:7], off offset:2048 sc1
	global_load_dwordx4 v[18:21], v[14:15], off offset:32 sc1
	global_load_dwordx4 v[26:29], v[14:15], off offset:16 sc1
	global_load_dwordx4 v[70:73], v[2:3], off offset:16 sc1
	global_load_dwordx4 v[10:13], v[6:7], off offset:3072 sc1
	s_nop 0
	global_load_dwordx4 v[2:5], v[16:17], off offset:48 sc1
	global_load_dwordx4 v[6:9], v[16:17], off offset:32 sc1
	global_load_dwordx4 v[22:25], v[14:15], off offset:48 sc1
	s_nop 0
	global_load_dwordx4 v[14:17], v[16:17], off offset:16 sc1
	s_mov_b32 m0, s60
	s_add_i32 s61, s60, 0x2000
	global_load_lds_dwordx4 v0, s[6:7]
	v_mov_b32_e32 v0, v133
	s_mov_b32 m0, s61
	s_add_u32 s12, s6, 0x40000
	global_load_lds_dwordx4 v0, s[6:7]
	s_addc_u32 s13, s7, 0
	s_add_i32 s66, s60, 0x4000
	v_mov_b32_e32 v0, v131
	s_mov_b32 m0, s66
	s_add_i32 s67, s60, 0x6000
	global_load_lds_dwordx4 v0, s[12:13]
	v_mov_b32_e32 v0, v133
	s_mov_b32 m0, s67
	s_cmp_eq_u32 s3, 1
	global_load_lds_dwordx4 v0, s[12:13]
	s_cselect_b64 s[12:13], -1, 0
	s_cmp_lg_u32 s3, 1
	s_cbranch_scc1 .LBB0_1082
	s_barrier

.LBB0_1091:
	s_cmp_gt_i32 s24, 9
	v_mov_b32_e32 v147, v141
	v_mov_b32_e32 v146, v135
	s_cselect_b64 s[4:5], -1, 0
	s_cmp_lt_i32 s24, 10
	v_mov_b32_e32 v156, 0
	v_mov_b32_e32 v157, 0
	s_cbranch_scc1 .LBB0_1099
	global_load_dword v157, v1, s[14:15] sc1
	v_cndmask_b32_e64 v0, 0, 1, s[4:5]
	v_cmp_ne_u32_e64 s[2:3], 1, v0
	s_andn2_b64 vcc, exec, s[4:5]
	s_cbranch_vccz .LBB0_1100

.LBB0_1094:
	global_load_dword v155, v1, s[14:15] offset:8 sc1
	s_and_b64 vcc, exec, s[2:3]
	s_cbranch_vccz .LBB0_1102

.LBB0_1096:
	global_load_dword v153, v1, s[14:15] offset:16 sc1
	s_and_b64 vcc, exec, s[2:3]
	s_cbranch_vccz .LBB0_1104

.LBB0_1098:
	global_load_dword v151, v1, s[14:15] offset:24 sc1
	s_and_b64 vcc, exec, s[2:3]
	s_cbranch_vccz .LBB0_1106
	s_branch .LBB0_1107

.LBB0_1100:
	global_load_dword v156, v1, s[14:15] offset:4 sc1
	v_mov_b32_e32 v154, 0
	s_and_b64 vcc, exec, s[2:3]
	v_mov_b32_e32 v155, 0
	s_cbranch_vccz .LBB0_1094

.LBB0_1102:
	global_load_dword v154, v1, s[14:15] offset:12 sc1
	v_mov_b32_e32 v152, 0
	s_and_b64 vcc, exec, s[2:3]
	v_mov_b32_e32 v153, 0
	s_cbranch_vccz .LBB0_1096

.LBB0_1104:
	global_load_dword v152, v1, s[14:15] offset:20 sc1
	v_mov_b32_e32 v0, 0
	s_and_b64 vcc, exec, s[2:3]
	v_mov_b32_e32 v151, 0
	s_cbranch_vccz .LBB0_1098

.LBB0_1106:
	global_load_dword v0, v1, s[14:15] offset:28 sc1

.LBB0_1188:
	s_cmp_eq_u32 s83, s84
	s_cbranch_scc1 .LBB0_1190
	v_lshl_add_u32 v4, s83, 8, v143
	v_ashrrev_i32_e32 v5, 31, v4
	v_lshlrev_b64 v[2:3], 6, v[4:5]
	v_lshl_add_u64 v[2:3], s[10:11], 0, v[2:3]
	global_load_dwordx4 v[6:9], v[2:3], off offset:16 sc1
	global_load_dwordx4 v[10:13], v[2:3], off offset:48 sc1
	global_load_dwordx4 v[14:17], v[2:3], off sc1
	global_load_dwordx4 v[18:21], v[2:3], off offset:32 sc1
	s_mov_b64 s[2:3], 0x2000
	s_waitcnt vmcnt(0)
	v_mov_b32_e32 v22, v14
	v_mov_b32_e32 v23, v18
	v_mov_b32_e32 v18, v15
	v_pk_add_f32 v[14:15], v[22:23], v[18:19]
	v_mov_b32_e32 v18, v16
	v_mov_b32_e32 v19, v20
	v_mov_b32_e32 v20, v17
	v_pk_add_f32 v[16:17], v[18:19], v[20:21]
	s_nop 0
	v_pk_add_f32 v[14:15], v[14:15], v[16:17]
	v_mov_b32_e32 v16, v6
	v_mov_b32_e32 v17, v10
	v_mov_b32_e32 v10, v7
	v_pk_add_f32 v[6:7], v[16:17], v[10:11]
	v_mov_b32_e32 v10, v8
	v_mov_b32_e32 v11, v12
	v_mov_b32_e32 v12, v9
	v_pk_add_f32 v[8:9], v[10:11], v[12:13]
	s_nop 0
	v_pk_add_f32 v[6:7], v[6:7], v[8:9]
	s_nop 0
	v_pk_add_f32 v[6:7], v[14:15], v[6:7]
	s_nop 0
	v_add_f32_e32 v0, v6, v7
	v_or_b32_e32 v6, 16, v4
	v_ashrrev_i32_e32 v7, 31, v6
	v_lshlrev_b64 v[6:7], 6, v[6:7]
	v_lshl_add_u64 v[18:19], s[10:11], 0, v[6:7]
	global_load_dwordx4 v[6:9], v[18:19], off offset:16 sc1
	global_load_dwordx4 v[10:13], v[18:19], off offset:48 sc1
	global_load_dwordx4 v[14:17], v[18:19], off sc1
	s_nop 0
	global_load_dwordx4 v[18:21], v[18:19], off offset:32 sc1
	v_fmamk_f32 v0, v0, 0x3a800000, v231
	v_rsq_f32_e32 v130, v0
	s_waitcnt vmcnt(1)
	v_mov_b32_e32 v22, v14
	s_waitcnt vmcnt(0)
	v_mov_b32_e32 v23, v18
	v_mov_b32_e32 v18, v15
	v_pk_add_f32 v[14:15], v[22:23], v[18:19]
	v_mov_b32_e32 v18, v16
	v_mov_b32_e32 v19, v20
	v_mov_b32_e32 v20, v17
	v_pk_add_f32 v[16:17], v[18:19], v[20:21]
	s_nop 0
	v_pk_add_f32 v[14:15], v[14:15], v[16:17]
	v_mov_b32_e32 v16, v6
	v_mov_b32_e32 v17, v10
	v_mov_b32_e32 v10, v7
	v_pk_add_f32 v[6:7], v[16:17], v[10:11]
	v_mov_b32_e32 v10, v8
	v_mov_b32_e32 v11, v12
	v_mov_b32_e32 v12, v9
	v_pk_add_f32 v[8:9], v[10:11], v[12:13]
	s_nop 0
	v_pk_add_f32 v[6:7], v[6:7], v[8:9]
	s_nop 0
	v_pk_add_f32 v[6:7], v[14:15], v[6:7]
	s_nop 0
	v_add_f32_e32 v0, v6, v7
	v_or_b32_e32 v6, 32, v4
	v_ashrrev_i32_e32 v7, 31, v6
	v_lshlrev_b64 v[6:7], 6, v[6:7]
	v_lshl_add_u64 v[18:19], s[10:11], 0, v[6:7]
	global_load_dwordx4 v[6:9], v[18:19], off offset:16 sc1
	global_load_dwordx4 v[10:13], v[18:19], off offset:48 sc1
	global_load_dwordx4 v[14:17], v[18:19], off sc1
	s_nop 0
	global_load_dwordx4 v[18:21], v[18:19], off offset:32 sc1
	v_or_b32_e32 v4, 48, v4
	v_ashrrev_i32_e32 v5, 31, v4
	v_lshlrev_b64 v[4:5], 6, v[4:5]
	v_fmamk_f32 v0, v0, 0x3a800000, v231
	v_rsq_f32_e32 v132, v0
	s_waitcnt vmcnt(1)
	v_mov_b32_e32 v22, v14
	s_waitcnt vmcnt(0)
	v_mov_b32_e32 v23, v18
	v_mov_b32_e32 v18, v15
	v_pk_add_f32 v[14:15], v[22:23], v[18:19]
	v_mov_b32_e32 v18, v16
	v_mov_b32_e32 v19, v20
	v_mov_b32_e32 v20, v17
	v_pk_add_f32 v[16:17], v[18:19], v[20:21]
	s_nop 0
	v_pk_add_f32 v[14:15], v[14:15], v[16:17]
	v_mov_b32_e32 v16, v6
	v_mov_b32_e32 v17, v10
	v_mov_b32_e32 v10, v7
	v_pk_add_f32 v[6:7], v[16:17], v[10:11]
	v_mov_b32_e32 v10, v8
	v_mov_b32_e32 v11, v12
	v_mov_b32_e32 v12, v9
	v_pk_add_f32 v[8:9], v[10:11], v[12:13]
	v_lshl_add_u64 v[16:17], s[10:11], 0, v[4:5]
	v_pk_add_f32 v[6:7], v[6:7], v[8:9]
	s_nop 0
	v_pk_add_f32 v[6:7], v[14:15], v[6:7]
	s_nop 0
	v_add_f32_e32 v0, v6, v7
	global_load_dwordx4 v[4:7], v[16:17], off offset:16 sc1
	global_load_dwordx4 v[8:11], v[16:17], off offset:48 sc1
	global_load_dwordx4 v[12:15], v[16:17], off sc1
	s_nop 0
	global_load_dwordx4 v[16:19], v[16:17], off offset:32 sc1
	v_fmamk_f32 v0, v0, 0x3a800000, v231
	v_rsq_f32_e32 v134, v0
	s_waitcnt vmcnt(1)
	v_mov_b32_e32 v20, v12
	s_waitcnt vmcnt(0)
	v_mov_b32_e32 v21, v16
	v_mov_b32_e32 v16, v13
	v_pk_add_f32 v[12:13], v[20:21], v[16:17]
	v_mov_b32_e32 v16, v14
	v_mov_b32_e32 v17, v18
	v_mov_b32_e32 v18, v15
	v_pk_add_f32 v[14:15], v[16:17], v[18:19]
	v_lshl_add_u64 v[18:19], v[2:3], 0, s[2:3]
	v_pk_add_f32 v[12:13], v[12:13], v[14:15]
	v_mov_b32_e32 v14, v4
	v_mov_b32_e32 v15, v8
	v_mov_b32_e32 v8, v5
	v_pk_add_f32 v[4:5], v[14:15], v[8:9]
	v_mov_b32_e32 v8, v6
	v_mov_b32_e32 v9, v10
	v_mov_b32_e32 v10, v7
	v_pk_add_f32 v[6:7], v[8:9], v[10:11]
	s_movk_i32 s2, 0x2000
	v_pk_add_f32 v[4:5], v[4:5], v[6:7]
	s_nop 0
	v_pk_add_f32 v[4:5], v[12:13], v[4:5]
	s_nop 0
	v_add_f32_e32 v0, v4, v5
	v_add_co_u32_e32 v4, vcc, s2, v2
	s_mov_b64 s[2:3], 0x2400
	s_nop 0
	v_addc_co_u32_e32 v5, vcc, 0, v3, vcc
	global_load_dwordx4 v[6:9], v[4:5], off sc1
	global_load_dwordx4 v[10:13], v[18:19], off offset:16 sc1
	global_load_dwordx4 v[14:17], v[18:19], off offset:48 sc1
	s_nop 0
	global_load_dwordx4 v[18:21], v[18:19], off offset:32 sc1
	v_fmamk_f32 v0, v0, 0x3a800000, v231
	v_rsq_f32_e32 v136, v0
	s_waitcnt vmcnt(3)
	v_mov_b32_e32 v22, v6
	s_waitcnt vmcnt(0)
	v_mov_b32_e32 v23, v18
	v_mov_b32_e32 v18, v7
	v_pk_add_f32 v[6:7], v[22:23], v[18:19]
	v_mov_b32_e32 v18, v8
	v_mov_b32_e32 v19, v20
	v_mov_b32_e32 v20, v9
	v_pk_add_f32 v[8:9], v[18:19], v[20:21]
	v_lshl_add_u64 v[18:19], v[2:3], 0, s[2:3]
	v_pk_add_f32 v[6:7], v[6:7], v[8:9]
	v_mov_b32_e32 v8, v10
	v_mov_b32_e32 v9, v14
	v_mov_b32_e32 v14, v11
	v_mov_b32_e32 v10, v12
	v_mov_b32_e32 v11, v16
	v_mov_b32_e32 v16, v13
	v_pk_add_f32 v[8:9], v[8:9], v[14:15]
	v_pk_add_f32 v[10:11], v[10:11], v[16:17]
	s_mov_b64 s[2:3], 0x2800
	v_pk_add_f32 v[8:9], v[8:9], v[10:11]
	s_nop 0
	v_pk_add_f32 v[6:7], v[6:7], v[8:9]
	s_nop 0
	v_add_f32_e32 v0, v6, v7
	global_load_dwordx4 v[6:9], v[4:5], off offset:1024 sc1
	global_load_dwordx4 v[10:13], v[18:19], off offset:16 sc1
	global_load_dwordx4 v[14:17], v[18:19], off offset:48 sc1
	s_nop 0
	global_load_dwordx4 v[18:21], v[18:19], off offset:32 sc1
	v_fmamk_f32 v0, v0, 0x3a800000, v231
	v_rsq_f32_e32 v138, v0
	s_waitcnt vmcnt(3)
	v_mov_b32_e32 v22, v6
	s_waitcnt vmcnt(0)
	v_mov_b32_e32 v23, v18
	v_mov_b32_e32 v18, v7
	v_pk_add_f32 v[6:7], v[22:23], v[18:19]
	v_mov_b32_e32 v18, v8
	v_mov_b32_e32 v19, v20
	v_mov_b32_e32 v20, v9
	v_pk_add_f32 v[8:9], v[18:19], v[20:21]
	v_lshl_add_u64 v[18:19], v[2:3], 0, s[2:3]
	v_pk_add_f32 v[6:7], v[6:7], v[8:9]
	v_mov_b32_e32 v8, v10
	v_mov_b32_e32 v9, v14
	v_mov_b32_e32 v14, v11
	v_mov_b32_e32 v10, v12
	v_mov_b32_e32 v11, v16
	v_mov_b32_e32 v16, v13
	v_pk_add_f32 v[8:9], v[8:9], v[14:15]
	v_pk_add_f32 v[10:11], v[10:11], v[16:17]
	s_mov_b64 s[2:3], 0x2c00
	v_pk_add_f32 v[8:9], v[8:9], v[10:11]
	s_nop 0
	v_pk_add_f32 v[6:7], v[6:7], v[8:9]
	s_nop 0
	v_add_f32_e32 v0, v6, v7
	global_load_dwordx4 v[6:9], v[4:5], off offset:2048 sc1
	global_load_dwordx4 v[10:13], v[18:19], off offset:16 sc1
	global_load_dwordx4 v[14:17], v[18:19], off offset:48 sc1
	s_nop 0
	global_load_dwordx4 v[18:21], v[18:19], off offset:32 sc1
	v_fmamk_f32 v0, v0, 0x3a800000, v231
	v_rsq_f32_e32 v140, v0
	s_waitcnt vmcnt(3)
	v_mov_b32_e32 v22, v6
	s_waitcnt vmcnt(0)
	v_mov_b32_e32 v23, v18
	v_mov_b32_e32 v18, v7
	v_pk_add_f32 v[6:7], v[22:23], v[18:19]
	v_mov_b32_e32 v18, v8
	v_mov_b32_e32 v19, v20
	v_mov_b32_e32 v20, v9
	v_pk_add_f32 v[8:9], v[18:19], v[20:21]
	s_nop 0
	v_pk_add_f32 v[6:7], v[6:7], v[8:9]
	v_mov_b32_e32 v8, v10
	v_mov_b32_e32 v9, v14
	v_mov_b32_e32 v14, v11
	v_mov_b32_e32 v10, v12
	v_mov_b32_e32 v11, v16
	v_mov_b32_e32 v16, v13
	v_pk_add_f32 v[8:9], v[8:9], v[14:15]
	v_pk_add_f32 v[10:11], v[10:11], v[16:17]
	v_lshl_add_u64 v[14:15], v[2:3], 0, s[2:3]
	v_pk_add_f32 v[8:9], v[8:9], v[10:11]
	s_nop 0
	v_pk_add_f32 v[6:7], v[6:7], v[8:9]
	s_nop 0
	v_add_f32_e32 v0, v6, v7
	global_load_dwordx4 v[10:13], v[4:5], off offset:3072 sc1
	s_nop 0
	global_load_dwordx4 v[2:5], v[14:15], off offset:16 sc1
	global_load_dwordx4 v[6:9], v[14:15], off offset:48 sc1
	s_nop 0
	global_load_dwordx4 v[14:17], v[14:15], off offset:32 sc1
	v_fmamk_f32 v0, v0, 0x3a800000, v231
	v_rsq_f32_e32 v142, v0
	s_waitcnt vmcnt(3)
	v_mov_b32_e32 v18, v10
	s_waitcnt vmcnt(0)
	v_mov_b32_e32 v19, v14
	v_mov_b32_e32 v14, v11
	v_pk_add_f32 v[10:11], v[18:19], v[14:15]
	v_mov_b32_e32 v14, v12
	v_mov_b32_e32 v15, v16
	v_mov_b32_e32 v16, v13
	v_pk_add_f32 v[12:13], v[14:15], v[16:17]
	s_nop 0
	v_pk_add_f32 v[10:11], v[10:11], v[12:13]
	v_mov_b32_e32 v12, v2
	v_mov_b32_e32 v13, v6
	v_mov_b32_e32 v6, v3
	v_pk_add_f32 v[2:3], v[12:13], v[6:7]
	v_mov_b32_e32 v6, v4
	v_mov_b32_e32 v7, v8
	v_mov_b32_e32 v8, v5
	v_pk_add_f32 v[4:5], v[6:7], v[8:9]
	s_nop 0
	v_pk_add_f32 v[2:3], v[2:3], v[4:5]
	s_nop 0
	v_pk_add_f32 v[2:3], v[10:11], v[2:3]
	s_nop 0
	v_add_f32_e32 v0, v2, v3
	v_fmamk_f32 v0, v0, 0x3a800000, v231
	v_rsq_f32_e32 v144, v0

.LBB0_1197:
	s_mul_hi_u32 s8, s14, 0xba2e8ba3
	s_lshr_b32 s16, s8, 6
	s_lshr_b32 s8, s8, 7
	s_mulk_i32 s8, 0xff50
	s_mul_i32 s9, s16, 0xb00
	s_add_i32 s17, s12, s8
	s_sub_i32 s26, s15, s9
	s_addk_i32 s17, 0xf0
	s_cmpk_lt_u32 s17, 0x58
	s_mov_b64 s[8:9], s[20:21]
	s_cselect_b32 s10, 22, 23
	s_ashr_i32 s11, s10, 31
	s_lshl_b64 s[10:11], s[10:11], 3
	s_add_u32 s10, s0, s10
	s_addc_u32 s11, s1, s11
	s_load_dwordx2 s[22:23], s[10:11], 0x0
	s_mov_b32 s10, 21
	s_ashr_i32 s11, s10, 31
	s_lshl_b64 s[10:11], s[10:11], 3
	s_add_u32 s10, s0, s10
	s_addc_u32 s11, s1, s11
	s_load_dwordx2 s[10:11], s[10:11], 0x0
	s_lshl_b64 s[24:25], s[26:27], 2
	s_waitcnt lgkmcnt(0)
	s_add_u32 s22, s22, s24
	s_addc_u32 s23, s23, s25
	v_lshl_add_u64 v[2:3], s[22:23], 0, v[0:1]
	s_mov_b64 s[22:23], 0xb00000
	v_lshl_add_u64 v[84:85], v[50:51], 2, s[10:11]
	s_mov_b64 s[10:11], 0x1000
	v_lshl_add_u64 v[2:3], v[2:3], 0, s[22:23]
	v_lshl_add_u64 v[104:105], v[84:85], 0, s[10:11]
	v_add_co_u32_e32 v84, vcc, s81, v84
	v_lshl_add_u64 v[4:5], v[2:3], 0, v[52:53]
	s_nop 0
	v_addc_co_u32_e32 v85, vcc, 0, v85, vcc
	global_load_dwordx4 v[86:89], v[4:5], off sc1 nt
	global_load_dwordx4 v[116:119], v[84:85], off sc1
	v_lshl_add_u64 v[4:5], v[2:3], 0, v[54:55]
	global_load_dwordx4 v[94:97], v[4:5], off sc1 nt
	v_lshl_add_u64 v[4:5], v[2:3], 0, v[56:57]
	global_load_dwordx4 v[98:101], v[4:5], off sc1 nt
	v_lshl_add_u64 v[4:5], v[2:3], 0, v[58:59]
	global_load_dwordx4 v[112:115], v[4:5], off sc1 nt
	v_lshl_add_u64 v[4:5], v[2:3], 0, v[60:61]
	global_load_dwordx4 v[46:49], v[4:5], off sc1 nt
	v_lshl_add_u64 v[4:5], v[2:3], 0, v[62:63]
	global_load_dwordx4 v[42:45], v[4:5], off sc1 nt
	v_lshl_add_u64 v[4:5], v[2:3], 0, v[64:65]
	global_load_dwordx4 v[38:41], v[4:5], off sc1 nt
	v_lshl_add_u64 v[4:5], v[2:3], 0, v[66:67]
	global_load_dwordx4 v[34:37], v[4:5], off sc1 nt
	v_lshl_add_u64 v[4:5], v[2:3], 0, v[68:69]
	global_load_dwordx4 v[30:33], v[4:5], off sc1 nt
	v_lshl_add_u64 v[4:5], v[2:3], 0, v[70:71]
	global_load_dwordx4 v[26:29], v[4:5], off sc1 nt
	v_lshl_add_u64 v[4:5], v[2:3], 0, v[72:73]
	global_load_dwordx4 v[22:25], v[4:5], off sc1 nt
	v_lshl_add_u64 v[4:5], v[2:3], 0, v[74:75]
	global_load_dwordx4 v[18:21], v[4:5], off sc1 nt
	v_lshl_add_u64 v[4:5], v[2:3], 0, v[76:77]
	global_load_dwordx4 v[14:17], v[4:5], off sc1 nt
	v_lshl_add_u64 v[4:5], v[2:3], 0, v[78:79]
	global_load_dwordx4 v[10:13], v[4:5], off sc1 nt
	v_lshl_add_u64 v[4:5], v[2:3], 0, v[80:81]
	global_load_dwordx4 v[6:9], v[4:5], off sc1 nt
	v_lshl_add_u64 v[2:3], v[2:3], 0, v[82:83]
	global_load_dwordx4 v[2:5], v[2:3], off sc1 nt
	s_waitcnt vmcnt(15)
	v_pk_mul_f32 v[84:85], v[88:89], v[116:117] op_sel_hi:[1,0]
	v_pk_mul_f32 v[92:93], v[86:87], v[116:117] op_sel_hi:[1,0]
	v_max_f32_e64 v87, |v84|, |v85|
	v_max_f32_e64 v86, |v92|, |v93|
	v_max3_f32 v88, v86, 0, v87
	s_waitcnt vmcnt(14)
	v_pk_mul_f32 v[86:87], v[96:97], v[116:117] op_sel:[0,1]
	v_pk_mul_f32 v[94:95], v[94:95], v[116:117] op_sel:[0,1]
	v_max_f32_e64 v90, |v86|, |v87|
	v_max_f32_e64 v89, |v94|, |v95|
	v_max3_f32 v90, v88, v89, v90
	s_waitcnt vmcnt(13)
	v_pk_mul_f32 v[88:89], v[100:101], v[118:119] op_sel_hi:[1,0]
	v_pk_mul_f32 v[96:97], v[98:99], v[118:119] op_sel_hi:[1,0]
	v_max_f32_e64 v98, |v88|, |v89|
	v_max_f32_e64 v91, |v96|, |v97|
	v_max3_f32 v100, v90, v91, v98
	v_mov_b32_e32 v98, v119
	s_waitcnt vmcnt(12)
	v_pk_mul_f32 v[90:91], v[114:115], v[98:99] op_sel_hi:[1,0]
	v_pk_mul_f32 v[98:99], v[112:113], v[98:99] op_sel_hi:[1,0]
	v_max_f32_e64 v102, |v90|, |v91|
	v_max_f32_e64 v101, |v98|, |v99|
	v_max3_f32 v111, v100, v101, v102
	global_load_dwordx4 v[100:103], v[104:105], off offset:1024 sc1
	s_waitcnt vmcnt(0)
	v_pk_mul_f32 v[48:49], v[48:49], v[100:101] op_sel_hi:[1,0]
	v_pk_mul_f32 v[46:47], v[46:47], v[100:101] op_sel_hi:[1,0]
	v_max_f32_e64 v113, |v48|, |v49|
	v_max_f32_e64 v112, |v46|, |v47|
	v_pk_mul_f32 v[44:45], v[44:45], v[100:101] op_sel:[0,1]
	v_pk_mul_f32 v[42:43], v[42:43], v[100:101] op_sel:[0,1]
	v_max3_f32 v111, v111, v112, v113
	v_max_f32_e64 v100, |v42|, |v43|
	v_max_f32_e64 v101, |v44|, |v45|
	v_pk_mul_f32 v[40:41], v[40:41], v[102:103] op_sel_hi:[1,0]
	v_pk_mul_f32 v[38:39], v[38:39], v[102:103] op_sel_hi:[1,0]
	v_max3_f32 v100, v111, v100, v101
	v_max_f32_e64 v101, |v38|, |v39|
	v_max_f32_e64 v102, |v40|, |v41|
	v_max3_f32 v101, v100, v101, v102
	v_mov_b32_e32 v100, v103
	v_pk_mul_f32 v[36:37], v[36:37], v[100:101] op_sel_hi:[1,0]
	v_pk_mul_f32 v[34:35], v[34:35], v[100:101] op_sel_hi:[1,0]
	v_max_f32_e64 v102, |v36|, |v37|
	v_max_f32_e64 v100, |v34|, |v35|
	v_max3_f32 v111, v101, v100, v102
	global_load_dwordx4 v[100:103], v[104:105], off offset:2048 sc1
	s_waitcnt vmcnt(0)
	v_pk_mul_f32 v[32:33], v[32:33], v[100:101] op_sel_hi:[1,0]
	v_pk_mul_f32 v[30:31], v[30:31], v[100:101] op_sel_hi:[1,0]
	v_max_f32_e64 v113, |v32|, |v33|
	v_max_f32_e64 v112, |v30|, |v31|
	v_pk_mul_f32 v[28:29], v[28:29], v[100:101] op_sel:[0,1]
	v_pk_mul_f32 v[26:27], v[26:27], v[100:101] op_sel:[0,1]
	v_max3_f32 v111, v111, v112, v113
	v_max_f32_e64 v100, |v26|, |v27|
	v_max_f32_e64 v101, |v28|, |v29|
	v_max3_f32 v111, v111, v100, v101
	v_pk_mul_f32 v[24:25], v[24:25], v[102:103] op_sel_hi:[1,0]
	v_pk_mul_f32 v[100:101], v[22:23], v[102:103] op_sel_hi:[1,0]
	v_max_f32_e64 v23, |v24|, |v25|
	v_max_f32_e64 v22, |v100|, |v101|
	v_mov_b32_e32 v102, v103
	v_max3_f32 v111, v111, v22, v23
	v_pk_mul_f32 v[22:23], v[20:21], v[102:103] op_sel_hi:[1,0]
	v_pk_mul_f32 v[102:103], v[18:19], v[102:103] op_sel_hi:[1,0]
	v_max_f32_e64 v19, |v22|, |v23|
	v_max_f32_e64 v18, |v102|, |v103|
	v_max3_f32 v111, v111, v18, v19
	global_load_dwordx4 v[18:21], v[104:105], off offset:3072 sc1
	s_waitcnt vmcnt(0)
	v_pk_mul_f32 v[16:17], v[16:17], v[18:19] op_sel_hi:[1,0]
	v_pk_mul_f32 v[14:15], v[14:15], v[18:19] op_sel_hi:[1,0]
	v_max_f32_e64 v105, |v16|, |v17|
	v_max_f32_e64 v104, |v14|, |v15|
	v_pk_mul_f32 v[12:13], v[12:13], v[18:19] op_sel:[0,1]
	v_pk_mul_f32 v[10:11], v[10:11], v[18:19] op_sel:[0,1]
	v_max3_f32 v104, v111, v104, v105
	v_max_f32_e64 v18, |v10|, |v11|
	v_max_f32_e64 v19, |v12|, |v13|
	v_pk_mul_f32 v[8:9], v[8:9], v[20:21] op_sel_hi:[1,0]
	v_pk_mul_f32 v[6:7], v[6:7], v[20:21] op_sel_hi:[1,0]
	v_max3_f32 v18, v104, v18, v19
	v_max_f32_e64 v19, |v6|, |v7|
	v_max_f32_e64 v20, |v8|, |v9|
	v_max3_f32 v19, v18, v19, v20
	v_mov_b32_e32 v18, v21
	v_pk_mul_f32 v[4:5], v[4:5], v[18:19] op_sel_hi:[1,0]
	v_pk_mul_f32 v[2:3], v[2:3], v[18:19] op_sel_hi:[1,0]
	v_max_f32_e64 v20, |v4|, |v5|
	v_max_f32_e64 v18, |v2|, |v3|
	v_max3_f32 v18, v19, v18, v20
	ds_swizzle_b32 v19, v18 offset:swizzle(SWAP,1)
	s_waitcnt lgkmcnt(0)
	v_max_f32_e32 v19, v19, v19
	v_max_f32_e32 v18, v18, v19
	ds_swizzle_b32 v19, v18 offset:swizzle(SWAP,2)
	s_waitcnt lgkmcnt(0)
	v_max_f32_e32 v19, v19, v19
	v_max_f32_e32 v18, v18, v19
	ds_swizzle_b32 v19, v18 offset:swizzle(SWAP,4)
	s_waitcnt lgkmcnt(0)
	v_max_f32_e32 v19, v19, v19
	v_max_f32_e32 v18, v18, v19
	ds_swizzle_b32 v19, v18 offset:swizzle(SWAP,8)
	s_waitcnt lgkmcnt(0)
	v_max_f32_e32 v19, v19, v19
	v_max_f32_e32 v18, v18, v19
	ds_swizzle_b32 v19, v18 offset:swizzle(SWAP,16)
	s_waitcnt lgkmcnt(0)
	v_max_f32_e32 v19, v19, v19
	v_max_f32_e32 v18, v18, v19
	v_mov_b32_e32 v19, v18
	s_nop 1
	v_permlane32_swap_b32_e32 v18, v19
	s_and_saveexec_b64 s[10:11], s[4:5]
	v_max_f32_e32 v18, v18, v18
	v_max_f32_e32 v19, v19, v19
	v_max_f32_e32 v18, v18, v19
	v_add_u32_e32 v19, 0, v107
	ds_write_b32 v19, v18 offset:33280
	s_or_b64 exec, exec, s[10:11]
	s_waitcnt lgkmcnt(0)
	s_barrier
	ds_read_b128 v[18:21], v1 offset:33280
	ds_read_b128 v[112:115], v1 offset:33296
	s_mulk_i32 s16, 0x1600
	s_sub_i32 s10, s13, s16
	s_and_b32 s10, s10, 0x1f00
	s_waitcnt lgkmcnt(1)
	v_max_f32_e32 v19, v19, v19
	v_max_f32_e32 v18, v18, v18
	v_max_f32_e32 v18, v18, v19
	v_max_f32_e32 v19, v21, v21
	v_max_f32_e32 v20, v20, v20
	v_max_f32_e32 v19, v20, v19
	s_waitcnt lgkmcnt(0)
	v_max_f32_e32 v20, v115, v115
	v_max_f32_e32 v21, v114, v114
	v_max_f32_e32 v20, v21, v20
	s_cmpk_gt_u32 s17, 0x57
	v_max3_f32 v20, v112, v113, v20
	s_cselect_b32 s11, 0x80, 0
	v_max3_f32 v18, v18, v19, v20
	s_or_b32 s16, s10, s11
	v_div_scale_f32 v19, s[10:11], v18, v18, s34
	v_rcp_f32_e32 v20, v19
	s_and_b32 s17, s26, 0x60
	s_or_b32 s22, s16, s17
	s_add_u32 s16, s8, 0x4200000
	v_fma_f32 v21, -v19, v20, 1.0
	v_fmac_f32_e32 v20, v21, v20
	v_div_scale_f32 v21, vcc, s34, v18, s34
	v_mul_f32_e32 v104, v21, v20
	v_fma_f32 v105, -v19, v104, v21
	v_fmac_f32_e32 v104, v105, v20
	v_fma_f32 v19, -v19, v104, v21
	v_div_fmas_f32 v19, v19, v20, v104
	v_div_fixup_f32 v19, v19, v18, s34
	v_cmp_lt_f32_e32 vcc, 0, v18
	s_addc_u32 s10, s9, 0
	s_and_b32 s17, s10, 0xffff
	v_cndmask_b32_e32 v19, 0, v19, vcc
	v_mul_f32_e32 v21, v94, v19
	v_mul_f32_e32 v42, v42, v19
	v_mul_f32_e32 v20, v92, v19
	v_mul_f32_e32 v92, v96, v19
	v_mul_f32_e32 v94, v98, v19
	v_rndne_f32_e32 v21, v21
	v_mul_f32_e32 v46, v46, v19
	v_mul_f32_e32 v38, v38, v19
	v_mul_f32_e32 v34, v34, v19
	v_rndne_f32_e32 v42, v42
	v_rndne_f32_e32 v20, v20
	v_cvt_i32_f32_e32 v21, v21
	v_rndne_f32_e32 v92, v92
	v_rndne_f32_e32 v94, v94
	v_rndne_f32_e32 v46, v46
	v_cvt_i32_f32_e32 v42, v42
	v_rndne_f32_e32 v38, v38
	v_rndne_f32_e32 v34, v34
	v_cvt_i32_f32_e32 v20, v20
	v_cvt_i32_f32_sdwa v92, v92 dst_sel:WORD_1 dst_unused:UNUSED_PAD src0_sel:DWORD
	v_cvt_i32_f32_e32 v94, v94
	v_cvt_i32_f32_e32 v46, v46
	v_cvt_i32_f32_sdwa v38, v38 dst_sel:WORD_1 dst_unused:UNUSED_PAD src0_sel:DWORD
	v_cvt_i32_f32_e32 v34, v34
	v_lshlrev_b32_e32 v21, 8, v21
	v_lshlrev_b32_e32 v42, 8, v42
	v_and_b32_e32 v21, 0xff00, v21
	v_and_b32_e32 v92, 0xff0000, v92
	v_perm_b32 v20, v94, v20, s35
	v_and_b32_e32 v42, 0xff00, v42
	v_and_b32_e32 v38, 0xff0000, v38
	v_perm_b32 v34, v34, v46, s35
	v_or3_b32 v20, v20, v21, v92
	v_or3_b32 v34, v34, v42, v38
	v_mul_f32_e32 v92, v95, v19
	ds_write2st64_b32 v109, v20, v34 offset1:1
	v_mul_f32_e32 v34, v43, v19
	v_mul_f32_e32 v21, v93, v19
	v_mul_f32_e32 v93, v97, v19
	v_mul_f32_e32 v94, v99, v19
	v_rndne_f32_e32 v92, v92
	v_mul_f32_e32 v20, v47, v19
	v_mul_f32_e32 v38, v39, v19
	v_mul_f32_e32 v35, v35, v19
	v_rndne_f32_e32 v34, v34
	v_rndne_f32_e32 v21, v21
	v_cvt_i32_f32_e32 v92, v92
	v_rndne_f32_e32 v93, v93
	v_rndne_f32_e32 v94, v94
	v_rndne_f32_e32 v20, v20
	v_cvt_i32_f32_e32 v34, v34
	v_rndne_f32_e32 v38, v38
	v_rndne_f32_e32 v35, v35
	v_cvt_i32_f32_e32 v21, v21
	v_cvt_i32_f32_sdwa v93, v93 dst_sel:WORD_1 dst_unused:UNUSED_PAD src0_sel:DWORD
	v_cvt_i32_f32_e32 v94, v94
	v_cvt_i32_f32_e32 v20, v20
	v_cvt_i32_f32_sdwa v38, v38 dst_sel:WORD_1 dst_unused:UNUSED_PAD src0_sel:DWORD
	v_cvt_i32_f32_e32 v35, v35
	v_lshlrev_b32_e32 v92, 8, v92
	v_lshlrev_b32_e32 v34, 8, v34
	v_and_b32_e32 v92, 0xff00, v92
	v_and_b32_e32 v93, 0xff0000, v93
	v_perm_b32 v21, v94, v21, s35
	v_and_b32_e32 v34, 0xff00, v34
	v_and_b32_e32 v38, 0xff0000, v38
	v_perm_b32 v20, v35, v20, s35
	v_or3_b32 v21, v21, v92, v93
	v_or3_b32 v20, v20, v34, v38
	v_add_u32_e32 v34, 16, v109
	v_mul_f32_e32 v86, v86, v19
	ds_write2st64_b32 v34, v21, v20 offset0:4 offset1:5
	v_mul_f32_e32 v21, v44, v19
	v_mul_f32_e32 v84, v84, v19
	v_mul_f32_e32 v88, v88, v19
	v_mul_f32_e32 v90, v90, v19
	v_rndne_f32_e32 v86, v86
	v_mul_f32_e32 v20, v48, v19
	v_mul_f32_e32 v35, v40, v19
	v_mul_f32_e32 v36, v36, v19
	v_rndne_f32_e32 v21, v21
	v_rndne_f32_e32 v84, v84
	v_cvt_i32_f32_e32 v86, v86
	v_rndne_f32_e32 v88, v88
	v_rndne_f32_e32 v90, v90
	v_rndne_f32_e32 v20, v20
	v_cvt_i32_f32_e32 v21, v21
	v_rndne_f32_e32 v35, v35
	v_rndne_f32_e32 v36, v36
	v_cvt_i32_f32_e32 v84, v84
	v_cvt_i32_f32_sdwa v88, v88 dst_sel:WORD_1 dst_unused:UNUSED_PAD src0_sel:DWORD
	v_cvt_i32_f32_e32 v90, v90
	v_cvt_i32_f32_e32 v20, v20
	v_cvt_i32_f32_sdwa v35, v35 dst_sel:WORD_1 dst_unused:UNUSED_PAD src0_sel:DWORD
	v_cvt_i32_f32_e32 v36, v36
	v_lshlrev_b32_e32 v86, 8, v86
	v_lshlrev_b32_e32 v21, 8, v21
	v_and_b32_e32 v86, 0xff00, v86
	v_and_b32_e32 v88, 0xff0000, v88
	v_perm_b32 v84, v90, v84, s35
	v_and_b32_e32 v21, 0xff00, v21
	v_and_b32_e32 v35, 0xff0000, v35
	v_perm_b32 v20, v36, v20, s35
	v_or3_b32 v84, v84, v86, v88
	v_mul_f32_e32 v86, v87, v19
	v_or3_b32 v20, v20, v21, v35
	v_add_u32_e32 v21, 32, v109
	v_mul_f32_e32 v35, v45, v19
	v_mul_f32_e32 v85, v85, v19
	v_mul_f32_e32 v87, v89, v19
	v_mul_f32_e32 v88, v91, v19
	v_rndne_f32_e32 v86, v86
	ds_write2st64_b32 v21, v84, v20 offset0:8 offset1:9
	v_mul_f32_e32 v20, v49, v19
	v_mul_f32_e32 v36, v41, v19
	v_mul_f32_e32 v37, v37, v19
	v_rndne_f32_e32 v35, v35
	v_rndne_f32_e32 v85, v85
	v_cvt_i32_f32_e32 v86, v86
	v_rndne_f32_e32 v87, v87
	v_rndne_f32_e32 v88, v88
	v_rndne_f32_e32 v20, v20
	v_cvt_i32_f32_e32 v35, v35
	v_rndne_f32_e32 v36, v36
	v_rndne_f32_e32 v37, v37
	v_cvt_i32_f32_e32 v85, v85
	v_cvt_i32_f32_sdwa v87, v87 dst_sel:WORD_1 dst_unused:UNUSED_PAD src0_sel:DWORD
	v_cvt_i32_f32_e32 v88, v88
	v_cvt_i32_f32_e32 v20, v20
	v_cvt_i32_f32_sdwa v36, v36 dst_sel:WORD_1 dst_unused:UNUSED_PAD src0_sel:DWORD
	v_cvt_i32_f32_e32 v37, v37
	v_lshlrev_b32_e32 v86, 8, v86
	v_lshlrev_b32_e32 v35, 8, v35
	v_and_b32_e32 v86, 0xff00, v86
	v_and_b32_e32 v87, 0xff0000, v87
	v_perm_b32 v85, v88, v85, s35
	v_and_b32_e32 v35, 0xff00, v35
	v_and_b32_e32 v36, 0xff0000, v36
	v_perm_b32 v20, v37, v20, s35
	v_or3_b32 v85, v85, v86, v87
	v_or3_b32 v20, v20, v35, v36
	v_add_u32_e32 v35, 48, v109
	v_mul_f32_e32 v26, v26, v19
	v_mul_f32_e32 v10, v10, v19
	ds_write2st64_b32 v35, v85, v20 offset0:12 offset1:13
	v_mul_f32_e32 v20, v30, v19
	v_mul_f32_e32 v30, v100, v19
	v_mul_f32_e32 v36, v102, v19
	v_rndne_f32_e32 v26, v26
	v_mul_f32_e32 v14, v14, v19
	v_mul_f32_e32 v6, v6, v19
	v_mul_f32_e32 v2, v2, v19
	v_rndne_f32_e32 v10, v10
	v_rndne_f32_e32 v20, v20
	v_cvt_i32_f32_e32 v26, v26
	v_rndne_f32_e32 v30, v30
	v_rndne_f32_e32 v36, v36
	v_rndne_f32_e32 v14, v14
	v_cvt_i32_f32_e32 v10, v10
	v_rndne_f32_e32 v6, v6
	v_rndne_f32_e32 v2, v2
	v_cvt_i32_f32_e32 v20, v20
	v_cvt_i32_f32_sdwa v30, v30 dst_sel:WORD_1 dst_unused:UNUSED_PAD src0_sel:DWORD
	v_cvt_i32_f32_e32 v36, v36
	v_cvt_i32_f32_e32 v14, v14
	v_cvt_i32_f32_sdwa v6, v6 dst_sel:WORD_1 dst_unused:UNUSED_PAD src0_sel:DWORD
	v_cvt_i32_f32_e32 v2, v2
	v_lshlrev_b32_e32 v26, 8, v26
	v_lshlrev_b32_e32 v10, 8, v10
	v_and_b32_e32 v26, 0xff00, v26
	v_and_b32_e32 v30, 0xff0000, v30
	v_perm_b32 v20, v36, v20, s35
	v_and_b32_e32 v10, 0xff00, v10
	v_and_b32_e32 v6, 0xff0000, v6
	v_perm_b32 v2, v2, v14, s35
	v_or3_b32 v20, v20, v26, v30
	v_mul_f32_e32 v27, v27, v19
	v_or3_b32 v2, v2, v10, v6
	v_mul_f32_e32 v6, v11, v19
	v_mul_f32_e32 v26, v31, v19
	v_mul_f32_e32 v30, v101, v19
	v_mul_f32_e32 v31, v103, v19
	v_rndne_f32_e32 v27, v27
	ds_write2st64_b32 v109, v20, v2 offset0:2 offset1:3
	v_mul_f32_e32 v2, v15, v19
	v_mul_f32_e32 v7, v7, v19
	v_mul_f32_e32 v3, v3, v19
	v_rndne_f32_e32 v6, v6
	v_rndne_f32_e32 v26, v26
	v_cvt_i32_f32_e32 v27, v27
	v_rndne_f32_e32 v30, v30
	v_rndne_f32_e32 v31, v31
	v_rndne_f32_e32 v2, v2
	v_cvt_i32_f32_e32 v6, v6
	v_rndne_f32_e32 v7, v7
	v_rndne_f32_e32 v3, v3
	v_cvt_i32_f32_e32 v26, v26
	v_cvt_i32_f32_sdwa v30, v30 dst_sel:WORD_1 dst_unused:UNUSED_PAD src0_sel:DWORD
	v_cvt_i32_f32_e32 v31, v31
	v_cvt_i32_f32_e32 v2, v2
	v_cvt_i32_f32_sdwa v7, v7 dst_sel:WORD_1 dst_unused:UNUSED_PAD src0_sel:DWORD
	v_cvt_i32_f32_e32 v3, v3
	v_lshlrev_b32_e32 v27, 8, v27
	v_lshlrev_b32_e32 v6, 8, v6
	v_and_b32_e32 v27, 0xff00, v27
	v_and_b32_e32 v30, 0xff0000, v30
	v_perm_b32 v26, v31, v26, s35
	v_and_b32_e32 v6, 0xff00, v6
	v_and_b32_e32 v7, 0xff0000, v7
	v_perm_b32 v2, v3, v2, s35
	v_or3_b32 v26, v26, v27, v30
	v_mul_f32_e32 v28, v28, v19
	v_or3_b32 v2, v2, v6, v7
	v_mul_f32_e32 v3, v12, v19
	v_mul_f32_e32 v27, v32, v19
	v_mul_f32_e32 v24, v24, v19
	v_mul_f32_e32 v22, v22, v19
	v_rndne_f32_e32 v28, v28
	ds_write2st64_b32 v34, v26, v2 offset0:6 offset1:7
	v_mul_f32_e32 v2, v16, v19
	v_mul_f32_e32 v6, v8, v19
	v_mul_f32_e32 v4, v4, v19
	v_rndne_f32_e32 v3, v3
	v_rndne_f32_e32 v27, v27
	v_cvt_i32_f32_e32 v28, v28
	v_rndne_f32_e32 v24, v24
	v_rndne_f32_e32 v22, v22
	v_rndne_f32_e32 v2, v2
	v_cvt_i32_f32_e32 v3, v3
	v_rndne_f32_e32 v6, v6
	v_rndne_f32_e32 v4, v4
	v_cvt_i32_f32_e32 v27, v27
	v_cvt_i32_f32_sdwa v24, v24 dst_sel:WORD_1 dst_unused:UNUSED_PAD src0_sel:DWORD
	v_cvt_i32_f32_e32 v22, v22
	v_cvt_i32_f32_e32 v2, v2
	v_cvt_i32_f32_sdwa v6, v6 dst_sel:WORD_1 dst_unused:UNUSED_PAD src0_sel:DWORD
	v_cvt_i32_f32_e32 v4, v4
	v_lshlrev_b32_e32 v28, 8, v28
	v_lshlrev_b32_e32 v3, 8, v3
	v_and_b32_e32 v28, 0xff00, v28
	v_and_b32_e32 v24, 0xff0000, v24
	v_perm_b32 v22, v22, v27, s35
	v_and_b32_e32 v3, 0xff00, v3
	v_and_b32_e32 v6, 0xff0000, v6
	v_perm_b32 v2, v4, v2, s35
	v_or3_b32 v22, v22, v28, v24
	v_mul_f32_e32 v27, v29, v19
	v_or3_b32 v2, v2, v3, v6
	v_mul_f32_e32 v3, v13, v19
	v_mul_f32_e32 v24, v33, v19
	v_mul_f32_e32 v25, v25, v19
	v_mul_f32_e32 v23, v23, v19
	v_rndne_f32_e32 v27, v27
	ds_write2st64_b32 v21, v22, v2 offset0:10 offset1:11
	v_mul_f32_e32 v2, v17, v19
	v_mul_f32_e32 v4, v9, v19
	v_mul_f32_e32 v5, v5, v19
	v_rndne_f32_e32 v3, v3
	v_rndne_f32_e32 v24, v24
	v_cvt_i32_f32_e32 v27, v27
	v_rndne_f32_e32 v25, v25
	v_rndne_f32_e32 v23, v23
	v_rndne_f32_e32 v2, v2
	v_cvt_i32_f32_e32 v3, v3
	v_rndne_f32_e32 v4, v4
	v_rndne_f32_e32 v5, v5
	v_cvt_i32_f32_e32 v24, v24
	v_cvt_i32_f32_sdwa v25, v25 dst_sel:WORD_1 dst_unused:UNUSED_PAD src0_sel:DWORD
	v_cvt_i32_f32_e32 v23, v23
	v_cvt_i32_f32_e32 v2, v2
	v_cvt_i32_f32_sdwa v4, v4 dst_sel:WORD_1 dst_unused:UNUSED_PAD src0_sel:DWORD
	v_cvt_i32_f32_e32 v5, v5
	v_lshlrev_b32_e32 v27, 8, v27
	v_lshlrev_b32_e32 v3, 8, v3
	v_and_b32_e32 v27, 0xff00, v27
	v_and_b32_e32 v25, 0xff0000, v25
	v_perm_b32 v23, v23, v24, s35
	v_and_b32_e32 v3, 0xff00, v3
	v_and_b32_e32 v4, 0xff0000, v4
	v_perm_b32 v2, v5, v2, s35
	v_or3_b32 v23, v23, v27, v25
	v_or3_b32 v2, v2, v3, v4
	ds_write2st64_b32 v35, v23, v2 offset0:14 offset1:15
	s_waitcnt lgkmcnt(0)
	s_barrier
	ds_read_b128 v[2:5], v110
	ds_read_b128 v[6:9], v110 offset:256
	ds_read_b128 v[10:13], v110 offset:512
	ds_read_b128 v[14:17], v110 offset:768
	v_add_u32_e32 v19, s22, v107
	v_lshl_or_b32 v19, v19, 10, v108
	s_waitcnt lgkmcnt(3)
	buffer_store_dwordx4 v[2:5], v19, s[16:19], 0 offen sc1
	s_waitcnt lgkmcnt(2)
	buffer_store_dwordx4 v[6:9], v19, s[16:19], 0 offen offset:256 sc1
	s_waitcnt lgkmcnt(1)
	buffer_store_dwordx4 v[10:13], v19, s[16:19], 0 offen offset:512 sc1
	s_waitcnt lgkmcnt(0)
	buffer_store_dwordx4 v[14:17], v19, s[16:19], 0 offen offset:768 sc1
	s_and_saveexec_b64 s[10:11], s[6:7]
	s_cbranch_execz .LBB0_1196
	s_lshr_b32 s16, s22, 3
	s_add_u32 s8, s8, s16
	v_mul_f32_e32 v2, 0x3c010204, v18
	s_addc_u32 s9, s9, 0
	v_cndmask_b32_e32 v2, 1.0, v2, vcc
	global_store_dword v237, v2, s[8:9] offset:2112 sc1
	s_branch .LBB0_1196

.LBB0_1208:
	s_mul_hi_u32 s8, s14, 0xba2e8ba3
	s_lshr_b32 s16, s8, 6
	s_lshr_b32 s8, s8, 7
	s_mulk_i32 s8, 0xff50
	s_mul_i32 s9, s16, 0xb00
	s_add_i32 s17, s12, s8
	s_sub_i32 s26, s15, s9
	s_addk_i32 s17, 0xf0
	s_cmpk_lt_u32 s17, 0x58
	s_mov_b64 s[8:9], s[20:21]
	s_cselect_b32 s10, 22, 23
	s_ashr_i32 s11, s10, 31
	s_lshl_b64 s[10:11], s[10:11], 3
	s_add_u32 s10, s0, s10
	s_addc_u32 s11, s1, s11
	s_load_dwordx2 s[22:23], s[10:11], 0x0
	s_mov_b32 s10, 21
	s_ashr_i32 s11, s10, 31
	s_lshl_b64 s[10:11], s[10:11], 3
	s_add_u32 s10, s0, s10
	s_addc_u32 s11, s1, s11
	s_load_dwordx2 s[10:11], s[10:11], 0x0
	s_lshl_b64 s[24:25], s[26:27], 2
	s_waitcnt lgkmcnt(0)
	s_add_u32 s22, s22, s24
	s_addc_u32 s23, s23, s25
	v_lshl_add_u64 v[2:3], s[22:23], 0, v[0:1]
	v_lshl_add_u64 v[4:5], v[2:3], 0, v[52:53]
	v_lshl_add_u64 v[104:105], v[50:51], 2, s[10:11]
	global_load_dwordx4 v[86:89], v[4:5], off sc1 nt
	global_load_dwordx4 v[114:117], v[104:105], off sc1
	v_lshl_add_u64 v[4:5], v[2:3], 0, v[54:55]
	global_load_dwordx4 v[94:97], v[4:5], off sc1 nt
	v_lshl_add_u64 v[4:5], v[2:3], 0, v[56:57]
	global_load_dwordx4 v[98:101], v[4:5], off sc1 nt
	v_lshl_add_u64 v[4:5], v[2:3], 0, v[58:59]
	global_load_dwordx4 v[110:113], v[4:5], off sc1 nt
	v_lshl_add_u64 v[4:5], v[2:3], 0, v[60:61]
	global_load_dwordx4 v[46:49], v[4:5], off sc1 nt
	v_lshl_add_u64 v[4:5], v[2:3], 0, v[62:63]
	global_load_dwordx4 v[42:45], v[4:5], off sc1 nt
	v_lshl_add_u64 v[4:5], v[2:3], 0, v[64:65]
	global_load_dwordx4 v[38:41], v[4:5], off sc1 nt
	v_lshl_add_u64 v[4:5], v[2:3], 0, v[66:67]
	global_load_dwordx4 v[34:37], v[4:5], off sc1 nt
	v_lshl_add_u64 v[4:5], v[2:3], 0, v[68:69]
	global_load_dwordx4 v[30:33], v[4:5], off sc1 nt
	v_lshl_add_u64 v[4:5], v[2:3], 0, v[70:71]
	global_load_dwordx4 v[26:29], v[4:5], off sc1 nt
	v_lshl_add_u64 v[4:5], v[2:3], 0, v[72:73]
	global_load_dwordx4 v[22:25], v[4:5], off sc1 nt
	v_lshl_add_u64 v[4:5], v[2:3], 0, v[74:75]
	global_load_dwordx4 v[18:21], v[4:5], off sc1 nt
	v_lshl_add_u64 v[4:5], v[2:3], 0, v[76:77]
	global_load_dwordx4 v[14:17], v[4:5], off sc1 nt
	v_lshl_add_u64 v[4:5], v[2:3], 0, v[78:79]
	global_load_dwordx4 v[10:13], v[4:5], off sc1 nt
	v_lshl_add_u64 v[4:5], v[2:3], 0, v[80:81]
	global_load_dwordx4 v[6:9], v[4:5], off sc1 nt
	v_lshl_add_u64 v[2:3], v[2:3], 0, v[82:83]
	global_load_dwordx4 v[2:5], v[2:3], off sc1 nt
	s_waitcnt vmcnt(15)
	v_pk_mul_f32 v[84:85], v[88:89], v[114:115] op_sel_hi:[1,0]
	v_pk_mul_f32 v[92:93], v[86:87], v[114:115] op_sel_hi:[1,0]
	v_max_f32_e64 v87, |v84|, |v85|
	v_max_f32_e64 v86, |v92|, |v93|
	v_max3_f32 v88, v86, 0, v87
	s_waitcnt vmcnt(14)
	v_pk_mul_f32 v[86:87], v[96:97], v[114:115] op_sel:[0,1]
	v_pk_mul_f32 v[94:95], v[94:95], v[114:115] op_sel:[0,1]
	v_max_f32_e64 v90, |v86|, |v87|
	v_max_f32_e64 v89, |v94|, |v95|
	v_max3_f32 v90, v88, v89, v90
	s_waitcnt vmcnt(13)
	v_pk_mul_f32 v[88:89], v[100:101], v[116:117] op_sel_hi:[1,0]
	v_pk_mul_f32 v[96:97], v[98:99], v[116:117] op_sel_hi:[1,0]
	v_max_f32_e64 v98, |v88|, |v89|
	v_max_f32_e64 v91, |v96|, |v97|
	v_max3_f32 v100, v90, v91, v98
	v_mov_b32_e32 v98, v117
	s_waitcnt vmcnt(12)
	v_pk_mul_f32 v[90:91], v[112:113], v[98:99] op_sel_hi:[1,0]
	v_pk_mul_f32 v[98:99], v[110:111], v[98:99] op_sel_hi:[1,0]
	v_max_f32_e64 v102, |v90|, |v91|
	v_max_f32_e64 v101, |v98|, |v99|
	v_max3_f32 v110, v100, v101, v102
	global_load_dwordx4 v[100:103], v[104:105], off offset:1024 sc1
	s_waitcnt vmcnt(0)
	v_pk_mul_f32 v[48:49], v[48:49], v[100:101] op_sel_hi:[1,0]
	v_pk_mul_f32 v[46:47], v[46:47], v[100:101] op_sel_hi:[1,0]
	v_max_f32_e64 v112, |v48|, |v49|
	v_max_f32_e64 v111, |v46|, |v47|
	v_pk_mul_f32 v[44:45], v[44:45], v[100:101] op_sel:[0,1]
	v_pk_mul_f32 v[42:43], v[42:43], v[100:101] op_sel:[0,1]
	v_max3_f32 v110, v110, v111, v112
	v_max_f32_e64 v100, |v42|, |v43|
	v_max_f32_e64 v101, |v44|, |v45|
	v_pk_mul_f32 v[40:41], v[40:41], v[102:103] op_sel_hi:[1,0]
	v_pk_mul_f32 v[38:39], v[38:39], v[102:103] op_sel_hi:[1,0]
	v_max3_f32 v100, v110, v100, v101
	v_max_f32_e64 v101, |v38|, |v39|
	v_max_f32_e64 v102, |v40|, |v41|
	v_max3_f32 v101, v100, v101, v102
	v_mov_b32_e32 v100, v103
	v_pk_mul_f32 v[36:37], v[36:37], v[100:101] op_sel_hi:[1,0]
	v_pk_mul_f32 v[34:35], v[34:35], v[100:101] op_sel_hi:[1,0]
	v_max_f32_e64 v102, |v36|, |v37|
	v_max_f32_e64 v100, |v34|, |v35|
	v_max3_f32 v110, v101, v100, v102
	global_load_dwordx4 v[100:103], v[104:105], off offset:2048 sc1
	s_waitcnt vmcnt(0)
	v_pk_mul_f32 v[32:33], v[32:33], v[100:101] op_sel_hi:[1,0]
	v_pk_mul_f32 v[30:31], v[30:31], v[100:101] op_sel_hi:[1,0]
	v_max_f32_e64 v112, |v32|, |v33|
	v_max_f32_e64 v111, |v30|, |v31|
	v_pk_mul_f32 v[28:29], v[28:29], v[100:101] op_sel:[0,1]
	v_pk_mul_f32 v[26:27], v[26:27], v[100:101] op_sel:[0,1]
	v_max3_f32 v110, v110, v111, v112
	v_max_f32_e64 v100, |v26|, |v27|
	v_max_f32_e64 v101, |v28|, |v29|
	v_max3_f32 v110, v110, v100, v101
	v_pk_mul_f32 v[24:25], v[24:25], v[102:103] op_sel_hi:[1,0]
	v_pk_mul_f32 v[100:101], v[22:23], v[102:103] op_sel_hi:[1,0]
	v_max_f32_e64 v23, |v24|, |v25|
	v_max_f32_e64 v22, |v100|, |v101|
	v_mov_b32_e32 v102, v103
	v_max3_f32 v110, v110, v22, v23
	v_pk_mul_f32 v[22:23], v[20:21], v[102:103] op_sel_hi:[1,0]
	v_pk_mul_f32 v[102:103], v[18:19], v[102:103] op_sel_hi:[1,0]
	v_max_f32_e64 v19, |v22|, |v23|
	v_max_f32_e64 v18, |v102|, |v103|
	v_max3_f32 v110, v110, v18, v19
	global_load_dwordx4 v[18:21], v[104:105], off offset:3072 sc1
	s_waitcnt vmcnt(0)
	v_pk_mul_f32 v[16:17], v[16:17], v[18:19] op_sel_hi:[1,0]
	v_pk_mul_f32 v[14:15], v[14:15], v[18:19] op_sel_hi:[1,0]
	v_max_f32_e64 v105, |v16|, |v17|
	v_max_f32_e64 v104, |v14|, |v15|
	v_pk_mul_f32 v[12:13], v[12:13], v[18:19] op_sel:[0,1]
	v_pk_mul_f32 v[10:11], v[10:11], v[18:19] op_sel:[0,1]
	v_max3_f32 v104, v110, v104, v105
	v_max_f32_e64 v18, |v10|, |v11|
	v_max_f32_e64 v19, |v12|, |v13|
	v_pk_mul_f32 v[8:9], v[8:9], v[20:21] op_sel_hi:[1,0]
	v_pk_mul_f32 v[6:7], v[6:7], v[20:21] op_sel_hi:[1,0]
	v_max3_f32 v18, v104, v18, v19
	v_max_f32_e64 v19, |v6|, |v7|
	v_max_f32_e64 v20, |v8|, |v9|
	v_max3_f32 v19, v18, v19, v20
	v_mov_b32_e32 v18, v21
	v_pk_mul_f32 v[4:5], v[4:5], v[18:19] op_sel_hi:[1,0]
	v_pk_mul_f32 v[2:3], v[2:3], v[18:19] op_sel_hi:[1,0]
	v_max_f32_e64 v20, |v4|, |v5|
	v_max_f32_e64 v18, |v2|, |v3|
	v_max3_f32 v18, v19, v18, v20
	ds_swizzle_b32 v19, v18 offset:swizzle(SWAP,1)
	s_waitcnt lgkmcnt(0)
	v_max_f32_e32 v19, v19, v19
	v_max_f32_e32 v18, v18, v19
	ds_swizzle_b32 v19, v18 offset:swizzle(SWAP,2)
	s_waitcnt lgkmcnt(0)
	v_max_f32_e32 v19, v19, v19
	v_max_f32_e32 v18, v18, v19
	ds_swizzle_b32 v19, v18 offset:swizzle(SWAP,4)
	s_waitcnt lgkmcnt(0)
	v_max_f32_e32 v19, v19, v19
	v_max_f32_e32 v18, v18, v19
	ds_swizzle_b32 v19, v18 offset:swizzle(SWAP,8)
	s_waitcnt lgkmcnt(0)
	v_max_f32_e32 v19, v19, v19
	v_max_f32_e32 v18, v18, v19
	ds_swizzle_b32 v19, v18 offset:swizzle(SWAP,16)
	s_waitcnt lgkmcnt(0)
	v_max_f32_e32 v19, v19, v19
	v_max_f32_e32 v18, v18, v19
	v_mov_b32_e32 v19, v18
	s_nop 1
	v_permlane32_swap_b32_e32 v18, v19
	s_and_saveexec_b64 s[10:11], s[2:3]
	v_max_f32_e32 v18, v18, v18
	v_max_f32_e32 v19, v19, v19
	v_max_f32_e32 v18, v18, v19
	v_add_u32_e32 v19, 0, v107
	ds_write_b32 v19, v18 offset:33280
	s_or_b64 exec, exec, s[10:11]
	s_waitcnt lgkmcnt(0)
	s_barrier
	ds_read_b128 v[18:21], v1 offset:33280
	ds_read_b128 v[110:113], v1 offset:33296
	s_mulk_i32 s16, 0x1600
	s_sub_i32 s10, s13, s16
	s_and_b32 s10, s10, 0x1f00
	s_waitcnt lgkmcnt(1)
	v_max_f32_e32 v19, v19, v19
	v_max_f32_e32 v18, v18, v18
	v_max_f32_e32 v18, v18, v19
	v_max_f32_e32 v19, v21, v21
	v_max_f32_e32 v20, v20, v20
	v_max_f32_e32 v19, v20, v19
	s_waitcnt lgkmcnt(0)
	v_max_f32_e32 v20, v113, v113
	v_max_f32_e32 v21, v112, v112
	v_max_f32_e32 v20, v21, v20
	s_cmpk_gt_u32 s17, 0x57
	v_max3_f32 v20, v110, v111, v20
	s_cselect_b32 s11, 0x80, 0
	v_max3_f32 v18, v18, v19, v20
	s_or_b32 s16, s10, s11
	v_div_scale_f32 v19, s[10:11], v18, v18, s34
	v_rcp_f32_e32 v20, v19
	s_and_b32 s17, s26, 0x60
	s_or_b32 s22, s16, s17
	s_add_u32 s16, s8, 0x1c80000
	v_fma_f32 v21, -v19, v20, 1.0
	v_fmac_f32_e32 v20, v21, v20
	v_div_scale_f32 v21, vcc, s34, v18, s34
	v_mul_f32_e32 v104, v21, v20
	v_fma_f32 v105, -v19, v104, v21
	v_fmac_f32_e32 v104, v105, v20
	v_fma_f32 v19, -v19, v104, v21
	v_div_fmas_f32 v19, v19, v20, v104
	v_div_fixup_f32 v19, v19, v18, s34
	v_cmp_lt_f32_e32 vcc, 0, v18
	s_addc_u32 s10, s9, 0
	s_and_b32 s17, s10, 0xffff
	v_cndmask_b32_e32 v19, 0, v19, vcc
	v_mul_f32_e32 v21, v94, v19
	v_mul_f32_e32 v42, v42, v19
	v_mul_f32_e32 v20, v92, v19
	v_mul_f32_e32 v92, v96, v19
	v_mul_f32_e32 v94, v98, v19
	v_rndne_f32_e32 v21, v21
	v_mul_f32_e32 v46, v46, v19
	v_mul_f32_e32 v38, v38, v19
	v_mul_f32_e32 v34, v34, v19
	v_rndne_f32_e32 v42, v42
	v_rndne_f32_e32 v20, v20
	v_cvt_i32_f32_e32 v21, v21
	v_rndne_f32_e32 v92, v92
	v_rndne_f32_e32 v94, v94
	v_rndne_f32_e32 v46, v46
	v_cvt_i32_f32_e32 v42, v42
	v_rndne_f32_e32 v38, v38
	v_rndne_f32_e32 v34, v34
	v_cvt_i32_f32_e32 v20, v20
	v_cvt_i32_f32_sdwa v92, v92 dst_sel:WORD_1 dst_unused:UNUSED_PAD src0_sel:DWORD
	v_cvt_i32_f32_e32 v94, v94
	v_cvt_i32_f32_e32 v46, v46
	v_cvt_i32_f32_sdwa v38, v38 dst_sel:WORD_1 dst_unused:UNUSED_PAD src0_sel:DWORD
	v_cvt_i32_f32_e32 v34, v34
	v_lshlrev_b32_e32 v21, 8, v21
	v_lshlrev_b32_e32 v42, 8, v42
	v_and_b32_e32 v21, 0xff00, v21
	v_and_b32_e32 v92, 0xff0000, v92
	v_perm_b32 v20, v94, v20, s35
	v_and_b32_e32 v42, 0xff00, v42
	v_and_b32_e32 v38, 0xff0000, v38
	v_perm_b32 v34, v34, v46, s35
	v_or3_b32 v20, v20, v21, v92
	v_or3_b32 v34, v34, v42, v38
	v_mul_f32_e32 v92, v95, v19
	ds_write2st64_b32 v106, v20, v34 offset1:1
	v_mul_f32_e32 v34, v43, v19
	v_mul_f32_e32 v21, v93, v19
	v_mul_f32_e32 v93, v97, v19
	v_mul_f32_e32 v94, v99, v19
	v_rndne_f32_e32 v92, v92
	v_mul_f32_e32 v20, v47, v19
	v_mul_f32_e32 v38, v39, v19
	v_mul_f32_e32 v35, v35, v19
	v_rndne_f32_e32 v34, v34
	v_rndne_f32_e32 v21, v21
	v_cvt_i32_f32_e32 v92, v92
	v_rndne_f32_e32 v93, v93
	v_rndne_f32_e32 v94, v94
	v_rndne_f32_e32 v20, v20
	v_cvt_i32_f32_e32 v34, v34
	v_rndne_f32_e32 v38, v38
	v_rndne_f32_e32 v35, v35
	v_cvt_i32_f32_e32 v21, v21
	v_cvt_i32_f32_sdwa v93, v93 dst_sel:WORD_1 dst_unused:UNUSED_PAD src0_sel:DWORD
	v_cvt_i32_f32_e32 v94, v94
	v_cvt_i32_f32_e32 v20, v20
	v_cvt_i32_f32_sdwa v38, v38 dst_sel:WORD_1 dst_unused:UNUSED_PAD src0_sel:DWORD
	v_cvt_i32_f32_e32 v35, v35
	v_lshlrev_b32_e32 v92, 8, v92
	v_lshlrev_b32_e32 v34, 8, v34
	v_and_b32_e32 v92, 0xff00, v92
	v_and_b32_e32 v93, 0xff0000, v93
	v_perm_b32 v21, v94, v21, s35
	v_and_b32_e32 v34, 0xff00, v34
	v_and_b32_e32 v38, 0xff0000, v38
	v_perm_b32 v20, v35, v20, s35
	v_or3_b32 v21, v21, v92, v93
	v_or3_b32 v20, v20, v34, v38
	v_add_u32_e32 v34, 16, v106
	v_mul_f32_e32 v86, v86, v19
	ds_write2st64_b32 v34, v21, v20 offset0:4 offset1:5
	v_mul_f32_e32 v21, v44, v19
	v_mul_f32_e32 v84, v84, v19
	v_mul_f32_e32 v88, v88, v19
	v_mul_f32_e32 v90, v90, v19
	v_rndne_f32_e32 v86, v86
	v_mul_f32_e32 v20, v48, v19
	v_mul_f32_e32 v35, v40, v19
	v_mul_f32_e32 v36, v36, v19
	v_rndne_f32_e32 v21, v21
	v_rndne_f32_e32 v84, v84
	v_cvt_i32_f32_e32 v86, v86
	v_rndne_f32_e32 v88, v88
	v_rndne_f32_e32 v90, v90
	v_rndne_f32_e32 v20, v20
	v_cvt_i32_f32_e32 v21, v21
	v_rndne_f32_e32 v35, v35
	v_rndne_f32_e32 v36, v36
	v_cvt_i32_f32_e32 v84, v84
	v_cvt_i32_f32_sdwa v88, v88 dst_sel:WORD_1 dst_unused:UNUSED_PAD src0_sel:DWORD
	v_cvt_i32_f32_e32 v90, v90
	v_cvt_i32_f32_e32 v20, v20
	v_cvt_i32_f32_sdwa v35, v35 dst_sel:WORD_1 dst_unused:UNUSED_PAD src0_sel:DWORD
	v_cvt_i32_f32_e32 v36, v36
	v_lshlrev_b32_e32 v86, 8, v86
	v_lshlrev_b32_e32 v21, 8, v21
	v_and_b32_e32 v86, 0xff00, v86
	v_and_b32_e32 v88, 0xff0000, v88
	v_perm_b32 v84, v90, v84, s35
	v_and_b32_e32 v21, 0xff00, v21
	v_and_b32_e32 v35, 0xff0000, v35
	v_perm_b32 v20, v36, v20, s35
	v_or3_b32 v84, v84, v86, v88
	v_mul_f32_e32 v86, v87, v19
	v_or3_b32 v20, v20, v21, v35
	v_add_u32_e32 v21, 32, v106
	v_mul_f32_e32 v35, v45, v19
	v_mul_f32_e32 v85, v85, v19
	v_mul_f32_e32 v87, v89, v19
	v_mul_f32_e32 v88, v91, v19
	v_rndne_f32_e32 v86, v86
	ds_write2st64_b32 v21, v84, v20 offset0:8 offset1:9
	v_mul_f32_e32 v20, v49, v19
	v_mul_f32_e32 v36, v41, v19
	v_mul_f32_e32 v37, v37, v19
	v_rndne_f32_e32 v35, v35
	v_rndne_f32_e32 v85, v85
	v_cvt_i32_f32_e32 v86, v86
	v_rndne_f32_e32 v87, v87
	v_rndne_f32_e32 v88, v88
	v_rndne_f32_e32 v20, v20
	v_cvt_i32_f32_e32 v35, v35
	v_rndne_f32_e32 v36, v36
	v_rndne_f32_e32 v37, v37
	v_cvt_i32_f32_e32 v85, v85
	v_cvt_i32_f32_sdwa v87, v87 dst_sel:WORD_1 dst_unused:UNUSED_PAD src0_sel:DWORD
	v_cvt_i32_f32_e32 v88, v88
	v_cvt_i32_f32_e32 v20, v20
	v_cvt_i32_f32_sdwa v36, v36 dst_sel:WORD_1 dst_unused:UNUSED_PAD src0_sel:DWORD
	v_cvt_i32_f32_e32 v37, v37
	v_lshlrev_b32_e32 v86, 8, v86
	v_lshlrev_b32_e32 v35, 8, v35
	v_and_b32_e32 v86, 0xff00, v86
	v_and_b32_e32 v87, 0xff0000, v87
	v_perm_b32 v85, v88, v85, s35
	v_and_b32_e32 v35, 0xff00, v35
	v_and_b32_e32 v36, 0xff0000, v36
	v_perm_b32 v20, v37, v20, s35
	v_or3_b32 v85, v85, v86, v87
	v_or3_b32 v20, v20, v35, v36
	v_add_u32_e32 v35, 48, v106
	v_mul_f32_e32 v26, v26, v19
	v_mul_f32_e32 v10, v10, v19
	ds_write2st64_b32 v35, v85, v20 offset0:12 offset1:13
	v_mul_f32_e32 v20, v30, v19
	v_mul_f32_e32 v30, v100, v19
	v_mul_f32_e32 v36, v102, v19
	v_rndne_f32_e32 v26, v26
	v_mul_f32_e32 v14, v14, v19
	v_mul_f32_e32 v6, v6, v19
	v_mul_f32_e32 v2, v2, v19
	v_rndne_f32_e32 v10, v10
	v_rndne_f32_e32 v20, v20
	v_cvt_i32_f32_e32 v26, v26
	v_rndne_f32_e32 v30, v30
	v_rndne_f32_e32 v36, v36
	v_rndne_f32_e32 v14, v14
	v_cvt_i32_f32_e32 v10, v10
	v_rndne_f32_e32 v6, v6
	v_rndne_f32_e32 v2, v2
	v_cvt_i32_f32_e32 v20, v20
	v_cvt_i32_f32_sdwa v30, v30 dst_sel:WORD_1 dst_unused:UNUSED_PAD src0_sel:DWORD
	v_cvt_i32_f32_e32 v36, v36
	v_cvt_i32_f32_e32 v14, v14
	v_cvt_i32_f32_sdwa v6, v6 dst_sel:WORD_1 dst_unused:UNUSED_PAD src0_sel:DWORD
	v_cvt_i32_f32_e32 v2, v2
	v_lshlrev_b32_e32 v26, 8, v26
	v_lshlrev_b32_e32 v10, 8, v10
	v_and_b32_e32 v26, 0xff00, v26
	v_and_b32_e32 v30, 0xff0000, v30
	v_perm_b32 v20, v36, v20, s35
	v_and_b32_e32 v10, 0xff00, v10
	v_and_b32_e32 v6, 0xff0000, v6
	v_perm_b32 v2, v2, v14, s35
	v_or3_b32 v20, v20, v26, v30
	v_mul_f32_e32 v27, v27, v19
	v_or3_b32 v2, v2, v10, v6
	v_mul_f32_e32 v6, v11, v19
	v_mul_f32_e32 v26, v31, v19
	v_mul_f32_e32 v30, v101, v19
	v_mul_f32_e32 v31, v103, v19
	v_rndne_f32_e32 v27, v27
	ds_write2st64_b32 v106, v20, v2 offset0:2 offset1:3
	v_mul_f32_e32 v2, v15, v19
	v_mul_f32_e32 v7, v7, v19
	v_mul_f32_e32 v3, v3, v19
	v_rndne_f32_e32 v6, v6
	v_rndne_f32_e32 v26, v26
	v_cvt_i32_f32_e32 v27, v27
	v_rndne_f32_e32 v30, v30
	v_rndne_f32_e32 v31, v31
	v_rndne_f32_e32 v2, v2
	v_cvt_i32_f32_e32 v6, v6
	v_rndne_f32_e32 v7, v7
	v_rndne_f32_e32 v3, v3
	v_cvt_i32_f32_e32 v26, v26
	v_cvt_i32_f32_sdwa v30, v30 dst_sel:WORD_1 dst_unused:UNUSED_PAD src0_sel:DWORD
	v_cvt_i32_f32_e32 v31, v31
	v_cvt_i32_f32_e32 v2, v2
	v_cvt_i32_f32_sdwa v7, v7 dst_sel:WORD_1 dst_unused:UNUSED_PAD src0_sel:DWORD
	v_cvt_i32_f32_e32 v3, v3
	v_lshlrev_b32_e32 v27, 8, v27
	v_lshlrev_b32_e32 v6, 8, v6
	v_and_b32_e32 v27, 0xff00, v27
	v_and_b32_e32 v30, 0xff0000, v30
	v_perm_b32 v26, v31, v26, s35
	v_and_b32_e32 v6, 0xff00, v6
	v_and_b32_e32 v7, 0xff0000, v7
	v_perm_b32 v2, v3, v2, s35
	v_or3_b32 v26, v26, v27, v30
	v_mul_f32_e32 v28, v28, v19
	v_or3_b32 v2, v2, v6, v7
	v_mul_f32_e32 v3, v12, v19
	v_mul_f32_e32 v27, v32, v19
	v_mul_f32_e32 v24, v24, v19
	v_mul_f32_e32 v22, v22, v19
	v_rndne_f32_e32 v28, v28
	ds_write2st64_b32 v34, v26, v2 offset0:6 offset1:7
	v_mul_f32_e32 v2, v16, v19
	v_mul_f32_e32 v6, v8, v19
	v_mul_f32_e32 v4, v4, v19
	v_rndne_f32_e32 v3, v3
	v_rndne_f32_e32 v27, v27
	v_cvt_i32_f32_e32 v28, v28
	v_rndne_f32_e32 v24, v24
	v_rndne_f32_e32 v22, v22
	v_rndne_f32_e32 v2, v2
	v_cvt_i32_f32_e32 v3, v3
	v_rndne_f32_e32 v6, v6
	v_rndne_f32_e32 v4, v4
	v_cvt_i32_f32_e32 v27, v27
	v_cvt_i32_f32_sdwa v24, v24 dst_sel:WORD_1 dst_unused:UNUSED_PAD src0_sel:DWORD
	v_cvt_i32_f32_e32 v22, v22
	v_cvt_i32_f32_e32 v2, v2
	v_cvt_i32_f32_sdwa v6, v6 dst_sel:WORD_1 dst_unused:UNUSED_PAD src0_sel:DWORD
	v_cvt_i32_f32_e32 v4, v4
	v_lshlrev_b32_e32 v28, 8, v28
	v_lshlrev_b32_e32 v3, 8, v3
	v_and_b32_e32 v28, 0xff00, v28
	v_and_b32_e32 v24, 0xff0000, v24
	v_perm_b32 v22, v22, v27, s35
	v_and_b32_e32 v3, 0xff00, v3
	v_and_b32_e32 v6, 0xff0000, v6
	v_perm_b32 v2, v4, v2, s35
	v_or3_b32 v22, v22, v28, v24
	v_mul_f32_e32 v27, v29, v19
	v_or3_b32 v2, v2, v3, v6
	v_mul_f32_e32 v3, v13, v19
	v_mul_f32_e32 v24, v33, v19
	v_mul_f32_e32 v25, v25, v19
	v_mul_f32_e32 v23, v23, v19
	v_rndne_f32_e32 v27, v27
	ds_write2st64_b32 v21, v22, v2 offset0:10 offset1:11
	v_mul_f32_e32 v2, v17, v19
	v_mul_f32_e32 v4, v9, v19
	v_mul_f32_e32 v5, v5, v19
	v_rndne_f32_e32 v3, v3
	v_rndne_f32_e32 v24, v24
	v_cvt_i32_f32_e32 v27, v27
	v_rndne_f32_e32 v25, v25
	v_rndne_f32_e32 v23, v23
	v_rndne_f32_e32 v2, v2
	v_cvt_i32_f32_e32 v3, v3
	v_rndne_f32_e32 v4, v4
	v_rndne_f32_e32 v5, v5
	v_cvt_i32_f32_e32 v24, v24
	v_cvt_i32_f32_sdwa v25, v25 dst_sel:WORD_1 dst_unused:UNUSED_PAD src0_sel:DWORD
	v_cvt_i32_f32_e32 v23, v23
	v_cvt_i32_f32_e32 v2, v2
	v_cvt_i32_f32_sdwa v4, v4 dst_sel:WORD_1 dst_unused:UNUSED_PAD src0_sel:DWORD
	v_cvt_i32_f32_e32 v5, v5
	v_lshlrev_b32_e32 v27, 8, v27
	v_lshlrev_b32_e32 v3, 8, v3
	v_and_b32_e32 v27, 0xff00, v27
	v_and_b32_e32 v25, 0xff0000, v25
	v_perm_b32 v23, v23, v24, s35
	v_and_b32_e32 v3, 0xff00, v3
	v_and_b32_e32 v4, 0xff0000, v4
	v_perm_b32 v2, v5, v2, s35
	v_or3_b32 v23, v23, v27, v25
	v_or3_b32 v2, v2, v3, v4
	ds_write2st64_b32 v35, v23, v2 offset0:14 offset1:15
	s_waitcnt lgkmcnt(0)
	s_barrier
	ds_read_b128 v[2:5], v109
	ds_read_b128 v[6:9], v109 offset:256
	ds_read_b128 v[10:13], v109 offset:512
	ds_read_b128 v[14:17], v109 offset:768
	v_add_u32_e32 v19, s22, v107
	v_lshl_or_b32 v19, v19, 10, v108
	s_waitcnt lgkmcnt(3)
	buffer_store_dwordx4 v[2:5], v19, s[16:19], 0 offen sc1
	s_waitcnt lgkmcnt(2)
	buffer_store_dwordx4 v[6:9], v19, s[16:19], 0 offen offset:256 sc1
	s_waitcnt lgkmcnt(1)
	buffer_store_dwordx4 v[10:13], v19, s[16:19], 0 offen offset:512 sc1
	s_waitcnt lgkmcnt(0)
	buffer_store_dwordx4 v[14:17], v19, s[16:19], 0 offen offset:768 sc1
	s_and_saveexec_b64 s[10:11], s[4:5]
	s_cbranch_execz .LBB0_1207
	s_lshr_b32 s16, s22, 3
	s_add_u32 s8, s8, s16
	v_mul_f32_e32 v2, 0x3c010204, v18
	s_addc_u32 s9, s9, 0
	v_cndmask_b32_e32 v2, 1.0, v2, vcc
	global_store_dword v237, v2, s[8:9] offset:704 sc1
	s_branch .LBB0_1207

.LBB0_1223:
	s_or_b64 exec, exec, s[10:11]
	s_waitcnt vmcnt(0)
	v_readfirstlane_b32 s6, v2
	s_nop 1
	v_add_u32_e32 v0, s6, v0
	v_and_b32_e32 v2, 31, v0
	v_cmp_ne_u32_e32 vcc, 31, v2
	s_and_saveexec_b64 s[6:7], vcc
	s_cbranch_execz .LBB0_1237
	global_load_dword v2, v1, s[4:5] sc1
	s_movk_i32 s10, 0xffe0
	v_bitop3_b32 v0, v0, s10, v0 bitop3:0xc
	s_waitcnt vmcnt(0)
	v_add_u32_e32 v2, v2, v0
	v_cmp_gt_i32_e32 vcc, 0, v2
	s_and_b64 exec, exec, vcc
	s_cbranch_execz .LBB0_1237
	s_add_u32 s8, s8, 0x4200
	s_addc_u32 s9, s9, 0
	s_mov_b32 s24, 1
	s_mov_b64 s[10:11], 0
	s_branch .LBB0_1227

.LBB0_1292:
	s_mov_b64 s[2:3], s[20:21]
	s_mov_b32 s4, 0x22174
	s_add_u32 s48, s2, 0x9800000
	s_addc_u32 s49, s3, 0
	s_add_i32 s4, s4, 0
	v_mov_b32_e32 v0, s4
	ds_read_b32 v0, v0
	s_mov_b32 s5, s33
	s_mov_b32 s6, -1
	v_mov_b64_e32 v[2:3], s[48:49]
	s_waitcnt lgkmcnt(0)
	v_readfirstlane_b32 s37, v0
	s_lshl_b32 s4, s37, 5
	s_and_b32 s42, s4, 0xe0
	s_ashr_i32 s41, s37, 3
	v_mbcnt_lo_u32_b32 v0, s6, 0
	s_add_i32 s42, s42, s41
	v_mbcnt_hi_u32_b32 v0, s6, v0
	s_ashr_i32 s4, s42, 5
	v_lshl_or_b32 v6, s5, 6, v0
	s_lshl_b32 s8, s4, 3
	v_ashrrev_i32_e32 v8, 6, v6
	s_bfe_u32 s12, s37, 0x30005
	v_add_u32_e32 v0, s8, v8
	v_and_b32_e32 v7, 63, v6
	v_mad_i64_i32 v[2:3], s[6:7], v0, s73, v[2:3]
	s_lshl_b32 s26, s12, 10
	v_lshl_add_u64 v[2:3], v[2:3], 0, s[26:27]
	v_lshlrev_b32_e32 v0, 4, v7
	v_lshl_add_u64 v[2:3], v[2:3], 0, v[0:1]
	s_mov_b32 s5, 0x140000
	v_add_co_u32_e32 v2, vcc, s5, v2
	v_lshlrev_b32_e32 v9, 2, v7
	s_nop 0
	v_addc_co_u32_e32 v3, vcc, 0, v3, vcc
	global_load_dwordx4 v[2:5], v[2:3], off sc1
	v_add_u32_e32 v0, -4, v9
	v_cmp_eq_u32_e32 vcc, 0, v7
	v_add_u32_e32 v10, -8, v9
	s_waitcnt vmcnt(0)
	v_add_f32_e32 v3, v2, v3
	v_add_f32_e32 v4, v4, v3
	v_add_f32_e32 v5, v5, v4
	ds_bpermute_b32 v0, v0, v5
	s_waitcnt lgkmcnt(0)
	v_add_f32_e32 v0, v5, v0
	v_cndmask_b32_e32 v0, v0, v5, vcc
	ds_bpermute_b32 v10, v10, v0
	v_cmp_gt_u32_e32 vcc, 2, v7
	s_waitcnt lgkmcnt(0)
	v_add_f32_e32 v10, v0, v10
	v_cndmask_b32_e32 v0, v10, v0, vcc
	v_add_u32_e32 v10, -16, v9
	ds_bpermute_b32 v10, v10, v0
	v_cmp_gt_u32_e32 vcc, 4, v7
	s_waitcnt lgkmcnt(0)
	v_add_f32_e32 v10, v0, v10
	v_cndmask_b32_e32 v0, v10, v0, vcc
	v_subrev_u32_e32 v10, 32, v9
	ds_bpermute_b32 v10, v10, v0
	v_cmp_gt_u32_e32 vcc, 8, v7
	s_waitcnt lgkmcnt(0)
	v_add_f32_e32 v10, v0, v10
	v_cndmask_b32_e32 v0, v10, v0, vcc
	v_subrev_u32_e32 v10, 64, v9
	ds_bpermute_b32 v10, v10, v0
	v_cmp_gt_u32_e32 vcc, 16, v7
	v_add_u32_e32 v9, 0xffffff80, v9
	s_waitcnt lgkmcnt(0)
	v_add_f32_e32 v10, v0, v10
	v_cndmask_b32_e32 v0, v10, v0, vcc
	ds_bpermute_b32 v9, v9, v0
	v_cmp_eq_u32_e32 vcc, 63, v7
	s_waitcnt lgkmcnt(0)
	v_add_f32_e32 v9, v0, v9
	s_and_saveexec_b64 s[6:7], vcc
	v_lshl_add_u32 v10, v8, 2, 0
	v_add_u32_e32 v10, 0x16800, v10
	ds_write_b32 v10, v9
	s_or_b64 exec, exec, s[6:7]
	s_waitcnt lgkmcnt(0)
	s_barrier
	v_cmp_lt_i32_e32 vcc, 0, v8
	v_mov_b32_e32 v10, 0
	s_and_saveexec_b64 s[6:7], vcc
	s_cbranch_execz .LBB0_1302
	s_add_i32 s5, 0, 0x16800
	v_mov_b32_e32 v10, s5
	ds_read_b32 v10, v10
	s_waitcnt lgkmcnt(0)
	v_add_f32_e32 v10, 0, v10
	s_or_b64 exec, exec, s[6:7]
	v_cmp_lt_i32_e32 vcc, 1, v8
	s_and_saveexec_b64 s[6:7], vcc
	s_cbranch_execnz .LBB0_1303

.LBB0_1312:
	s_and_b64 s[2:3], s[4:5], exec
	s_mov_b32 s2, s33
	s_mov_b32 s3, -1
	s_cselect_b32 s24, s43, s60
	v_mbcnt_lo_u32_b32 v0, s3, 0
	v_mbcnt_hi_u32_b32 v0, s3, v0
	v_lshl_or_b32 v216, s2, 6, v0
	s_mul_i32 s2, s24, 0x180000
	v_readfirstlane_b32 s17, v216
	s_ashr_i32 s70, s17, 6
	s_add_u32 s12, s61, s2
	s_addc_u32 s13, s66, 0
	s_lshl_b32 s14, s70, 5
	s_ashr_i32 s15, s14, 31
	s_lshl_b64 s[2:3], s[14:15], 11
	s_add_u32 s2, s12, s2
	s_addc_u32 s3, s13, s3
	v_and_b32_e32 v217, 63, v216
	s_add_u32 s12, s2, s69
	s_addc_u32 s13, s3, 0
	v_lshlrev_b32_e32 v0, 10, v217
	s_lshl_b32 s2, s70, 3
	s_waitcnt lgkmcnt(0)
	v_lshl_add_u64 v[2:3], s[6:7], 0, v[0:1]
	s_ashr_i32 s3, s2, 31
	v_lshl_add_u64 v[212:213], s[2:3], 1, v[2:3]
	s_lshl_b32 s2, s70, 4
	v_bfe_u32 v0, v216, 2, 4
	v_and_or_b32 v0, s2, 48, v0
	s_ashr_i32 s2, s17, 3
	s_andn2_b32 s2, s2, 31
	v_lshlrev_b32_e32 v0, 10, v0
	s_ashr_i32 s3, s2, 31
	s_lshl_b32 s16, s70, 10
	v_lshl_add_u64 v[2:3], s[8:9], 0, v[0:1]
	v_lshlrev_b32_e32 v0, 3, v216
	s_cmp_lg_u32 0, -1
	v_lshl_add_u64 v[2:3], s[2:3], 1, v[2:3]
	v_and_b32_e32 v220, 24, v0
	s_cselect_b32 s2, 0, 0
	v_lshlrev_b32_e32 v0, 1, v220
	s_add_i32 s74, s16, s2
	s_mov_b32 s2, m0
	s_mov_b32 m0, s74
	s_nop 0
	global_load_lds_dwordx4 v[212:213], off
	s_mov_b32 m0, s2
	v_bfe_u32 v219, v216, 5, 1
	v_lshl_add_u64 v[214:215], v[2:3], 0, v[0:1]
	s_add_i32 s75, s74, 0x6000
	s_mov_b32 s2, m0
	s_mov_b32 m0, s75
	s_nop 0
	global_load_lds_dwordx4 v[214:215], off
	s_mov_b32 m0, s2
	v_lshl_add_u64 v[2:3], v[212:213], 0, s[30:31]
	v_and_b32_e32 v218, 31, v216
	s_add_i32 s2, s74, 0x2000
	s_mov_b32 s3, m0
	s_mov_b32 m0, s2
	s_nop 0
	global_load_lds_dwordx4 v[2:3], off
	s_mov_b32 m0, s3
	v_lshlrev_b32_e32 v2, 4, v219
	v_lshl_or_b32 v3, v218, 11, v2
	global_load_dwordx4 v[140:143], v3, s[12:13] sc1
	global_load_dwordx4 v[136:139], v3, s[12:13] offset:32 sc1
	global_load_dwordx4 v[132:135], v3, s[12:13] offset:64 sc1
	global_load_dwordx4 v[128:131], v3, s[12:13] offset:96 sc1
	v_lshlrev_b32_e32 v0, 10, v219
	v_lshlrev_b32_e32 v4, 4, v218
	v_add_u32_e32 v2, 0, v2
	v_mov_b32_e32 v14, v1
	v_mov_b32_e32 v15, v1
	v_add_u32_e32 v225, 0x14800, v2
	v_add3_u32 v228, 0, v0, v4
	v_mov_b32_e32 v0, v1
	v_mov_b32_e32 v2, v1
	v_mov_b32_e32 v3, v1
	v_mov_b32_e32 v4, v1
	v_mov_b32_e32 v5, v1
	v_mov_b32_e32 v6, v1
	v_mov_b32_e32 v7, v1
	v_mov_b32_e32 v8, v1
	v_mov_b32_e32 v9, v1
	v_mov_b32_e32 v10, v1
	v_mov_b32_e32 v11, v1
	v_mov_b32_e32 v12, v1
	v_mov_b32_e32 v13, v1
	v_mov_b64_e32 v[32:33], v[14:15]
	v_mov_b64_e32 v[30:31], v[12:13]
	v_mov_b64_e32 v[28:29], v[10:11]
	v_mov_b64_e32 v[26:27], v[8:9]
	v_mov_b64_e32 v[24:25], v[6:7]
	v_mov_b64_e32 v[22:23], v[4:5]
	v_mov_b64_e32 v[20:21], v[2:3]
	v_mov_b64_e32 v[18:19], v[0:1]
	v_lshl_add_u64 v[2:3], v[212:213], 0, s[90:91]
	s_add_i32 s2, s74, 0x4000
	s_mov_b32 s3, m0
	s_mov_b32 m0, s2
	s_nop 0
	global_load_lds_dwordx4 v[2:3], off
	s_mov_b32 m0, s3
	s_waitcnt vmcnt(3) lgkmcnt(0)
	s_barrier
	ds_read_b128 v[34:37], v228 offset:512
	ds_read_b128 v[38:41], v228
	s_cmp_lg_u32 s24, 0
	s_cselect_b64 s[2:3], -1, 0
	v_lshlrev_b32_e32 v221, 2, v219
	v_or_b32_e32 v227, s14, v218
	s_and_b64 vcc, exec, s[2:3]
	s_waitcnt vmcnt(3) lgkmcnt(0)
	v_mfma_f32_32x32x16_bf16 v[2:17], v[38:41], v[140:143], v[18:33]
	v_mfma_f32_32x32x16_bf16 v[18:33], v[34:37], v[140:143], v[18:33]
	ds_read_b128 v[34:37], v228 offset:2560
	ds_read_b128 v[38:41], v228 offset:2048
	s_waitcnt vmcnt(2) lgkmcnt(0)
	v_mfma_f32_32x32x16_bf16 v[2:17], v[38:41], v[136:139], v[2:17]
	v_mfma_f32_32x32x16_bf16 v[18:33], v[34:37], v[136:139], v[18:33]
	ds_read_b128 v[34:37], v228 offset:4608
	ds_read_b128 v[38:41], v228 offset:4096
	s_waitcnt vmcnt(1) lgkmcnt(0)
	v_mfma_f32_32x32x16_bf16 v[2:17], v[38:41], v[132:135], v[2:17]
	v_mfma_f32_32x32x16_bf16 v[18:33], v[34:37], v[132:135], v[18:33]
	ds_read_b128 v[34:37], v228 offset:6656
	ds_read_b128 v[38:41], v228 offset:6144
	s_waitcnt vmcnt(0) lgkmcnt(0)
	v_mfma_f32_32x32x16_bf16 v[2:17], v[38:41], v[128:131], v[2:17]
	v_mfma_f32_32x32x16_bf16 v[18:33], v[34:37], v[128:131], v[18:33]
	s_nop 15
	s_nop 7
	ds_read_b128 v[34:37], v225
	ds_read_b128 v[38:41], v225 offset:32
	ds_read_b128 v[42:45], v225 offset:128
	s_waitcnt lgkmcnt(2)
	s_nop 6
	v_pk_add_f32 v[2:3], v[34:35], v[2:3]
	v_pk_add_f32 v[4:5], v[36:37], v[4:5]
	ds_read_b128 v[34:37], v225 offset:160
	s_waitcnt lgkmcnt(2)
	v_pk_add_f32 v[6:7], v[6:7], v[38:39]
	v_pk_add_f32 v[8:9], v[8:9], v[40:41]
	ds_read_b128 v[38:41], v225 offset:64
	ds_read_b128 v[46:49], v225 offset:192
	s_waitcnt lgkmcnt(3)
	v_pk_add_f32 v[20:21], v[20:21], v[44:45]
	s_waitcnt lgkmcnt(2)
	v_pk_add_f32 v[22:23], v[22:23], v[34:35]
	v_pk_add_f32 v[24:25], v[24:25], v[36:37]
	s_waitcnt lgkmcnt(1)
	v_pk_add_f32 v[10:11], v[10:11], v[38:39]
	v_pk_add_f32 v[12:13], v[12:13], v[40:41]
	ds_read_b128 v[38:41], v225 offset:96
	ds_read_b128 v[50:53], v225 offset:224
	s_waitcnt lgkmcnt(2)
	v_pk_add_f32 v[26:27], v[26:27], v[46:47]
	v_pk_add_f32 v[28:29], v[28:29], v[48:49]
	v_pk_add_f32 v[18:19], v[18:19], v[42:43]
	s_waitcnt lgkmcnt(1)
	v_pk_add_f32 v[14:15], v[14:15], v[38:39]
	v_pk_add_f32 v[16:17], v[16:17], v[40:41]
	s_waitcnt lgkmcnt(0)
	v_pk_add_f32 v[30:31], v[30:31], v[50:51]
	v_pk_add_f32 v[32:33], v[32:33], v[52:53]
	s_nop 0
	s_nop 3
	s_cbranch_vccnz .LBB0_1314
	v_or_b32_e32 v0, 32, v221
	v_cmp_le_i32_e32 vcc, v0, v227
	v_or_b32_e32 v0, 33, v221
	s_nop 0
	v_cndmask_b32_e32 v18, v238, v18, vcc
	v_cmp_lt_i32_e32 vcc, v221, v227
	s_nop 1
	v_cndmask_b32_e32 v3, v238, v3, vcc
	v_cmp_le_i32_e32 vcc, v221, v227
	s_nop 1
	v_cndmask_b32_e32 v2, v238, v2, vcc
	v_cmp_le_i32_e32 vcc, v0, v227
	v_or_b32_e32 v0, 2, v221
	s_nop 0
	v_cndmask_b32_e32 v19, v238, v19, vcc
	v_cmp_le_i32_e32 vcc, v0, v227
	v_or_b32_e32 v0, 34, v221
	s_nop 0
	v_cndmask_b32_e32 v4, v238, v4, vcc
	v_cmp_le_i32_e32 vcc, v0, v227
	v_or_b32_e32 v0, 3, v221
	s_nop 0
	v_cndmask_b32_e32 v20, v238, v20, vcc
	v_cmp_le_i32_e32 vcc, v0, v227
	v_or_b32_e32 v0, 35, v221
	s_nop 0
	v_cndmask_b32_e32 v5, v238, v5, vcc
	v_cmp_le_i32_e32 vcc, v0, v227
	v_or_b32_e32 v0, 8, v221
	s_nop 0
	v_cndmask_b32_e32 v21, v238, v21, vcc
	v_cmp_le_i32_e32 vcc, v0, v227
	v_or_b32_e32 v0, 40, v221
	s_nop 0
	v_cndmask_b32_e32 v6, v238, v6, vcc
	v_cmp_le_i32_e32 vcc, v0, v227
	v_or_b32_e32 v0, 9, v221
	s_nop 0
	v_cndmask_b32_e32 v22, v238, v22, vcc
	v_cmp_le_i32_e32 vcc, v0, v227
	v_or_b32_e32 v0, 41, v221
	s_nop 0
	v_cndmask_b32_e32 v7, v238, v7, vcc
	v_cmp_le_i32_e32 vcc, v0, v227
	v_or_b32_e32 v0, 10, v221
	s_nop 0
	v_cndmask_b32_e32 v23, v238, v23, vcc
	v_cmp_le_i32_e32 vcc, v0, v227
	v_or_b32_e32 v0, 42, v221
	s_nop 0
	v_cndmask_b32_e32 v8, v238, v8, vcc
	v_cmp_le_i32_e32 vcc, v0, v227
	v_or_b32_e32 v0, 11, v221
	s_nop 0
	v_cndmask_b32_e32 v24, v238, v24, vcc
	v_cmp_le_i32_e32 vcc, v0, v227
	v_or_b32_e32 v0, 43, v221
	s_nop 0
	v_cndmask_b32_e32 v9, v238, v9, vcc
	v_cmp_le_i32_e32 vcc, v0, v227
	v_or_b32_e32 v0, 16, v221
	s_nop 0
	v_cndmask_b32_e32 v25, v238, v25, vcc
	v_cmp_le_i32_e32 vcc, v0, v227
	v_or_b32_e32 v0, 48, v221
	s_nop 0
	v_cndmask_b32_e32 v10, v238, v10, vcc
	v_cmp_le_i32_e32 vcc, v0, v227
	v_or_b32_e32 v0, 17, v221
	s_nop 0
	v_cndmask_b32_e32 v26, v238, v26, vcc
	v_cmp_le_i32_e32 vcc, v0, v227
	v_or_b32_e32 v0, 49, v221
	s_nop 0
	v_cndmask_b32_e32 v11, v238, v11, vcc
	v_cmp_le_i32_e32 vcc, v0, v227
	v_or_b32_e32 v0, 18, v221
	s_nop 0
	v_cndmask_b32_e32 v27, v238, v27, vcc
	v_cmp_le_i32_e32 vcc, v0, v227
	v_or_b32_e32 v0, 50, v221
	s_nop 0
	v_cndmask_b32_e32 v12, v238, v12, vcc
	v_cmp_le_i32_e32 vcc, v0, v227
	v_or_b32_e32 v0, 19, v221
	s_nop 0
	v_cndmask_b32_e32 v28, v238, v28, vcc
	v_cmp_le_i32_e32 vcc, v0, v227
	v_or_b32_e32 v0, 51, v221
	s_nop 0
	v_cndmask_b32_e32 v13, v238, v13, vcc
	v_cmp_le_i32_e32 vcc, v0, v227
	v_or_b32_e32 v0, 24, v221
	s_nop 0
	v_cndmask_b32_e32 v29, v238, v29, vcc
	v_cmp_le_i32_e32 vcc, v0, v227
	v_or_b32_e32 v0, 56, v221
	s_nop 0
	v_cndmask_b32_e32 v14, v238, v14, vcc
	v_cmp_le_i32_e32 vcc, v0, v227
	v_or_b32_e32 v0, 25, v221
	s_nop 0
	v_cndmask_b32_e32 v30, v238, v30, vcc
	v_cmp_le_i32_e32 vcc, v0, v227
	v_or_b32_e32 v0, 57, v221
	s_nop 0
	v_cndmask_b32_e32 v15, v238, v15, vcc
	v_cmp_le_i32_e32 vcc, v0, v227
	v_or_b32_e32 v0, 26, v221
	s_nop 0
	v_cndmask_b32_e32 v31, v238, v31, vcc
	v_cmp_le_i32_e32 vcc, v0, v227
	v_or_b32_e32 v0, 58, v221
	s_nop 0
	v_cndmask_b32_e32 v16, v238, v16, vcc
	v_cmp_le_i32_e32 vcc, v0, v227
	v_or_b32_e32 v0, 27, v221
	s_nop 0
	v_cndmask_b32_e32 v32, v238, v32, vcc
	v_cmp_le_i32_e32 vcc, v0, v227
	v_or_b32_e32 v0, 59, v221
	s_nop 0
	v_cndmask_b32_e32 v17, v238, v17, vcc
	v_cmp_le_i32_e32 vcc, v0, v227
	s_nop 1
	v_cndmask_b32_e32 v33, v238, v33, vcc

.LBB0_1398:
	s_mov_b32 s2, 9
	s_waitcnt lgkmcnt(0)
	s_barrier
	s_ashr_i32 s3, s2, 31
	s_lshl_b64 s[2:3], s[2:3], 3
	s_add_u32 s2, s0, s2
	s_addc_u32 s3, s1, s3
	s_load_dwordx2 s[2:3], s[2:3], 0x0
	v_readlane_b32 s6, v255, 18
	s_mul_i32 s5, s6, 0xf800
	s_mov_b32 s4, s33
	v_mov_b32_e32 v2, 0
	s_waitcnt lgkmcnt(0)
	s_add_u32 s22, s2, s5
	s_mov_b32 s2, -1
	s_addc_u32 s23, s3, 0
	v_mbcnt_lo_u32_b32 v0, s2, 0
	v_mbcnt_hi_u32_b32 v0, s2, v0
	v_lshl_or_b32 v34, s4, 6, v0
	s_movk_i32 s2, 0xf80
	v_mov_b32_e32 v6, 0
	v_cmp_gt_i32_e64 s[2:3], s2, v34
	v_ashrrev_i32_e32 v35, 31, v34
	v_mov_b32_e32 v7, 0
	v_mov_b32_e32 v8, 0
	v_mov_b32_e32 v9, 0
	v_readlane_b32 s7, v255, 19
	s_and_saveexec_b64 s[4:5], s[2:3]
	s_cbranch_execz .LBB0_1400
	v_lshl_add_u64 v[4:5], v[34:35], 4, s[22:23]
	global_load_dwordx4 v[6:9], v[4:5], off sc1
.LBB0_1400:
	s_or_b64 exec, exec, s[4:5]
	s_movk_i32 s4, 0xd80
	v_cmp_gt_i32_e64 s[4:5], s4, v34
	v_mov_b32_e32 v3, 0
	v_mov_b32_e32 v4, 0
	v_mov_b32_e32 v5, 0
	s_and_saveexec_b64 s[6:7], s[4:5]
	s_cbranch_execz .LBB0_1402
	v_lshl_add_u64 v[2:3], v[34:35], 4, s[22:23]
	v_add_co_u32_e32 v2, vcc, 0x2000, v2
	s_nop 1
	v_addc_co_u32_e32 v3, vcc, 0, v3, vcc
	global_load_dwordx4 v[2:5], v[2:3], off sc1
.LBB0_1402:
	s_or_b64 exec, exec, s[6:7]
	s_movk_i32 s6, 0xb80
	v_cmp_gt_i32_e64 s[6:7], s6, v34
	v_mov_b32_e32 v10, 0
	v_mov_b32_e32 v14, 0
	v_mov_b32_e32 v15, 0
	v_mov_b32_e32 v16, 0
	v_mov_b32_e32 v17, 0
	s_and_saveexec_b64 s[8:9], s[6:7]
	s_cbranch_execz .LBB0_1404
	v_lshl_add_u64 v[12:13], v[34:35], 4, s[22:23]
	v_add_co_u32_e32 v12, vcc, 0x4000, v12
	s_nop 1
	v_addc_co_u32_e32 v13, vcc, 0, v13, vcc
	global_load_dwordx4 v[14:17], v[12:13], off sc1
.LBB0_1404:
	s_or_b64 exec, exec, s[8:9]
	s_movk_i32 s8, 0x980
	v_cmp_gt_i32_e64 s[8:9], s8, v34
	v_mov_b32_e32 v11, 0
	v_mov_b32_e32 v12, 0
	v_mov_b32_e32 v13, 0
	s_and_saveexec_b64 s[10:11], s[8:9]
	s_cbranch_execz .LBB0_1406
	v_lshl_add_u64 v[10:11], v[34:35], 4, s[22:23]
	v_add_co_u32_e32 v10, vcc, 0x6000, v10
	s_nop 1
	v_addc_co_u32_e32 v11, vcc, 0, v11, vcc
	global_load_dwordx4 v[10:13], v[10:11], off sc1
.LBB0_1406:
	s_or_b64 exec, exec, s[10:11]
	s_movk_i32 s10, 0x780
	v_cmp_gt_i32_e64 s[10:11], s10, v34
	v_mov_b32_e32 v18, 0
	v_mov_b32_e32 v22, 0
	v_mov_b32_e32 v23, 0
	v_mov_b32_e32 v24, 0
	v_mov_b32_e32 v25, 0
	s_and_saveexec_b64 s[12:13], s[10:11]
	s_cbranch_execz .LBB0_1408
	v_lshl_add_u64 v[20:21], v[34:35], 4, s[22:23]
	v_add_co_u32_e32 v20, vcc, 0x8000, v20
	s_nop 1
	v_addc_co_u32_e32 v21, vcc, 0, v21, vcc
	global_load_dwordx4 v[22:25], v[20:21], off sc1
.LBB0_1408:
	s_or_b64 exec, exec, s[12:13]
	s_movk_i32 s12, 0x580
	v_cmp_gt_i32_e64 s[12:13], s12, v34
	v_mov_b32_e32 v19, 0
	v_mov_b32_e32 v20, 0
	v_mov_b32_e32 v21, 0
	s_and_saveexec_b64 s[14:15], s[12:13]
	s_cbranch_execz .LBB0_1410
	v_lshl_add_u64 v[18:19], v[34:35], 4, s[22:23]
	v_add_co_u32_e32 v18, vcc, 0xa000, v18
	s_nop 1
	v_addc_co_u32_e32 v19, vcc, 0, v19, vcc
	global_load_dwordx4 v[18:21], v[18:19], off sc1
.LBB0_1410:
	s_or_b64 exec, exec, s[14:15]
	s_movk_i32 s14, 0x380
	v_cmp_gt_i32_e64 s[14:15], s14, v34
	v_mov_b32_e32 v26, 0
	v_mov_b32_e32 v30, 0
	v_mov_b32_e32 v31, 0
	v_mov_b32_e32 v32, 0
	v_mov_b32_e32 v33, 0
	s_and_saveexec_b64 s[16:17], s[14:15]
	s_cbranch_execz .LBB0_1412
	v_lshl_add_u64 v[28:29], v[34:35], 4, s[22:23]
	v_add_co_u32_e32 v28, vcc, 0xc000, v28
	s_nop 1
	v_addc_co_u32_e32 v29, vcc, 0, v29, vcc
	global_load_dwordx4 v[30:33], v[28:29], off sc1
.LBB0_1412:
	s_or_b64 exec, exec, s[16:17]
	s_movk_i32 s16, 0x180
	v_cmp_gt_i32_e64 s[16:17], s16, v34
	v_mov_b32_e32 v27, 0
	v_mov_b32_e32 v28, 0
	v_mov_b32_e32 v29, 0
	s_and_saveexec_b64 s[24:25], s[16:17]
	s_cbranch_execz .LBB0_1460
	v_lshl_add_u64 v[26:27], v[34:35], 4, s[22:23]
	v_add_co_u32_e32 v26, vcc, 0xe000, v26
	s_nop 1
	v_addc_co_u32_e32 v27, vcc, 0, v27, vcc
	global_load_dwordx4 v[26:29], v[26:27], off sc1
	s_or_b64 exec, exec, s[24:25]
	v_lshl_add_u32 v0, v34, 4, 0
	s_and_saveexec_b64 s[22:23], s[2:3]
	s_cbranch_execnz .LBB0_1461

.LBB0_1423:
	s_add_u32 s4, s48, s28
	s_addc_u32 s5, s49, s29
	s_add_u32 s6, s50, s28
	v_lshlrev_b32_e32 v0, 2, v18
	s_addc_u32 s7, s51, s29
	global_load_dwordx4 v[10:13], v0, s[4:5] sc1
	global_load_dwordx4 v[2:5], v0, s[4:5] offset:16 sc1
	global_load_dwordx4 v[14:17], v0, s[6:7] sc1
	global_load_dwordx4 v[6:9], v0, s[6:7] offset:16 sc1
	v_add_f32_e32 v0, 0, v44
	v_add_f32_e32 v0, v45, v0
	v_add_f32_e32 v0, v46, v0
	v_add_f32_e32 v0, v47, v0
	v_add_f32_e32 v0, v48, v0
	v_add_f32_e32 v0, v49, v0
	v_add_f32_e32 v0, v50, v0
	v_add_f32_e32 v0, v51, v0
	ds_swizzle_b32 v52, v0 offset:swizzle(SWAP,1)
	v_add_f32_e32 v19, 0, v36
	v_add_f32_e32 v19, v37, v19
	v_add_f32_e32 v19, v38, v19
	v_add_f32_e32 v19, v39, v19
	s_waitcnt lgkmcnt(0)
	v_add_f32_e32 v0, v0, v52
	ds_swizzle_b32 v52, v0 offset:swizzle(SWAP,2)
	v_add_f32_e32 v19, v40, v19
	v_add_f32_e32 v19, v41, v19
	v_add_f32_e32 v19, v42, v19
	v_add_f32_e32 v19, v43, v19
	s_waitcnt lgkmcnt(0)
	v_add_f32_e32 v0, v0, v52
	ds_swizzle_b32 v52, v0 offset:swizzle(SWAP,4)
	ds_swizzle_b32 v54, v19 offset:swizzle(SWAP,1)
	v_add_f32_e32 v53, 0, v20
	v_add_f32_e32 v53, v21, v53
	v_add_f32_e32 v53, v22, v53
	s_waitcnt lgkmcnt(1)
	v_add_f32_e32 v0, v0, v52
	ds_swizzle_b32 v52, v0 offset:swizzle(SWAP,8)
	s_waitcnt lgkmcnt(1)
	v_add_f32_e32 v19, v19, v54
	ds_swizzle_b32 v54, v19 offset:swizzle(SWAP,2)
	v_add_f32_e32 v53, v23, v53
	v_add_f32_e32 v53, v24, v53
	s_waitcnt lgkmcnt(1)
	v_add_f32_e32 v0, v0, v52
	ds_swizzle_b32 v52, v0 offset:swizzle(SWAP,16)
	v_add_f32_e32 v53, v25, v53
	v_add_f32_e32 v53, v26, v53
	s_waitcnt lgkmcnt(1)
	v_add_f32_e32 v19, v19, v54
	v_add_f32_e32 v60, v27, v53
	v_add_f32_e32 v53, 0, v28
	ds_swizzle_b32 v54, v19 offset:swizzle(SWAP,4)
	s_waitcnt lgkmcnt(1)
	v_add_f32_e32 v0, v0, v52
	v_add_f32_e32 v53, v29, v53
	v_mov_b32_e32 v52, v0
	v_add_f32_e32 v53, v30, v53
	s_nop 0
	v_permlane32_swap_b32_e32 v0, v52
	v_add_f32_e32 v53, v31, v53
	v_add_f32_e32 v0, v0, v52
	v_add_f32_e32 v53, v32, v53
	v_mul_f32_e32 v0, 0x3b000000, v0
	v_add_f32_e32 v53, v33, v53
	s_waitcnt lgkmcnt(0)
	v_add_f32_e32 v19, v19, v54
	v_pk_add_f32 v[44:45], v[44:45], v[0:1] op_sel_hi:[1,0] neg_lo:[0,1] neg_hi:[0,1]
	v_add_f32_e32 v61, v34, v53
	ds_swizzle_b32 v53, v19 offset:swizzle(SWAP,8)
	v_pk_add_f32 v[46:47], v[46:47], v[0:1] op_sel_hi:[1,0] neg_lo:[0,1] neg_hi:[0,1]
	v_pk_mul_f32 v[58:59], v[44:45], v[44:45]
	v_pk_add_f32 v[50:51], v[50:51], v[0:1] op_sel_hi:[1,0] neg_lo:[0,1] neg_hi:[0,1]
	v_pk_add_f32 v[48:49], v[48:49], v[0:1] op_sel_hi:[1,0] neg_lo:[0,1] neg_hi:[0,1]
	v_pk_mul_f32 v[56:57], v[46:47], v[46:47]
	v_add_f32_e32 v0, v58, v59
	v_add_f32_e32 v0, v56, v0
	v_pk_mul_f32 v[54:55], v[48:49], v[48:49]
	v_add_f32_e32 v0, v57, v0
	v_add_f32_e32 v0, v54, v0
	s_waitcnt lgkmcnt(0)
	v_add_f32_e32 v19, v19, v53
	v_pk_mul_f32 v[52:53], v[50:51], v[50:51]
	v_add_f32_e32 v0, v55, v0
	v_add_f32_e32 v0, v52, v0
	v_add_f32_e32 v0, v53, v0
	ds_swizzle_b32 v52, v0 offset:swizzle(SWAP,1)
	ds_swizzle_b32 v62, v19 offset:swizzle(SWAP,16)
	ds_swizzle_b32 v63, v60 offset:swizzle(SWAP,1)
	v_add_f32_e32 v53, v35, v61
	s_mov_b32 s4, 32
	s_waitcnt lgkmcnt(2)
	v_add_f32_e32 v0, v0, v52
	ds_swizzle_b32 v52, v0 offset:swizzle(SWAP,2)
	s_waitcnt lgkmcnt(2)
	v_add_f32_e32 v19, v19, v62
	v_mov_b32_e32 v54, v19
	s_nop 1
	v_permlane32_swap_b32_e32 v19, v54
	s_waitcnt lgkmcnt(0)
	v_add_f32_e32 v52, v0, v52
	v_add_f32_e32 v19, v19, v54
	ds_swizzle_b32 v54, v52 offset:swizzle(SWAP,4)
	v_add_f32_e32 v55, v60, v63
	ds_swizzle_b32 v56, v55 offset:swizzle(SWAP,2)
	v_mul_f32_e32 v0, 0x3b000000, v19
	ds_swizzle_b32 v19, v53 offset:swizzle(SWAP,1)
	s_waitcnt lgkmcnt(2)
	v_add_f32_e32 v52, v52, v54
	ds_swizzle_b32 v54, v52 offset:swizzle(SWAP,8)
	s_waitcnt lgkmcnt(2)
	v_add_f32_e32 v55, v55, v56
	ds_swizzle_b32 v56, v55 offset:swizzle(SWAP,4)
	s_waitcnt lgkmcnt(2)
	v_add_f32_e32 v19, v53, v19
	ds_swizzle_b32 v53, v19 offset:swizzle(SWAP,2)
	s_waitcnt lgkmcnt(2)
	v_add_f32_e32 v52, v52, v54
	ds_swizzle_b32 v54, v52 offset:swizzle(SWAP,16)
	s_waitcnt lgkmcnt(2)
	v_add_f32_e32 v55, v55, v56
	ds_swizzle_b32 v56, v55 offset:swizzle(SWAP,8)
	s_waitcnt lgkmcnt(2)
	v_add_f32_e32 v19, v19, v53
	ds_swizzle_b32 v53, v19 offset:swizzle(SWAP,4)
	s_waitcnt lgkmcnt(2)
	v_add_f32_e32 v52, v52, v54
	v_mov_b32_e32 v54, v52
	s_nop 1
	v_permlane32_swap_b32_e32 v52, v54
	v_add_f32_e32 v52, v52, v54
	v_fmamk_f32 v52, v52, 0x3b000000, v231
	v_rsq_f32_e32 v52, v52
	s_waitcnt lgkmcnt(1)
	v_add_f32_e32 v55, v55, v56
	ds_swizzle_b32 v56, v55 offset:swizzle(SWAP,16)
	s_waitcnt lgkmcnt(1)
	v_add_f32_e32 v19, v19, v53
	v_pk_mul_f32 v[44:45], v[44:45], v[52:53] op_sel_hi:[1,0]
	v_pk_add_f32 v[36:37], v[36:37], v[0:1] op_sel_hi:[1,0] neg_lo:[0,1] neg_hi:[0,1]
	s_waitcnt vmcnt(1)
	v_pk_fma_f32 v[44:45], v[10:11], v[44:45], v[14:15]
	s_waitcnt lgkmcnt(0)
	v_add_f32_e32 v60, v55, v56
	v_mul_f32_e32 v53, 0xbfb8aa3b, v44
	v_exp_f32_e32 v53, v53
	v_mul_f32_e32 v54, 0xbfb8aa3b, v45
	v_exp_f32_e32 v55, v54
	ds_swizzle_b32 v56, v19 offset:swizzle(SWAP,8)
	v_add_f32_e32 v53, 1.0, v53
	v_rcp_f32_e32 v54, v53
	v_add_f32_e32 v53, 1.0, v55
	v_rcp_f32_e32 v55, v53
	v_pk_mul_f32 v[46:47], v[46:47], v[52:53] op_sel_hi:[1,0]
	s_waitcnt lgkmcnt(0)
	v_add_f32_e32 v19, v19, v56
	v_pk_fma_f32 v[46:47], v[12:13], v[46:47], v[16:17]
	v_pk_mul_f32 v[44:45], v[44:45], v[54:55]
	v_mul_f32_e32 v53, 0xbfb8aa3b, v46
	v_exp_f32_e32 v53, v53
	v_mul_f32_e32 v54, 0xbfb8aa3b, v47
	v_exp_f32_e32 v57, v54
	v_pk_mul_f32 v[54:55], v[44:45], v[44:45]
	v_add_f32_e32 v53, 1.0, v53
	v_rcp_f32_e32 v56, v53
	v_add_f32_e32 v53, 1.0, v57
	v_pk_mul_f32 v[48:49], v[48:49], v[52:53] op_sel_hi:[1,0]
	v_rcp_f32_e32 v57, v53
	s_waitcnt vmcnt(0)
	v_pk_fma_f32 v[48:49], v[2:3], v[48:49], v[6:7]
	v_add_f32_e32 v54, v54, v55
	v_mul_f32_e32 v53, 0xbfb8aa3b, v48
	v_exp_f32_e32 v53, v53
	v_mul_f32_e32 v58, 0xbfb8aa3b, v49
	v_exp_f32_e32 v58, v58
	v_pk_mul_f32 v[46:47], v[46:47], v[56:57]
	v_add_f32_e32 v53, 1.0, v53
	v_rcp_f32_e32 v56, v53
	v_add_f32_e32 v53, 1.0, v58
	v_pk_mul_f32 v[50:51], v[50:51], v[52:53] op_sel_hi:[1,0]
	v_mov_b32_e32 v61, v60
	v_pk_fma_f32 v[50:51], v[4:5], v[50:51], v[8:9]
	s_nop 0
	v_permlane32_swap_b32_e32 v60, v61
	v_mul_f32_e32 v52, 0xbfb8aa3b, v50
	v_mul_f32_e32 v57, 0xbfb8aa3b, v51
	v_exp_f32_e32 v52, v52
	v_exp_f32_e32 v58, v57
	v_rcp_f32_e32 v57, v53
	v_pk_add_f32 v[42:43], v[42:43], v[0:1] op_sel_hi:[1,0] neg_lo:[0,1] neg_hi:[0,1]
	v_add_f32_e32 v52, 1.0, v52
	v_add_f32_e32 v53, 1.0, v58
	v_rcp_f32_e32 v52, v52
	v_rcp_f32_e32 v53, v53
	v_pk_mul_f32 v[58:59], v[46:47], v[46:47]
	v_pk_mul_f32 v[48:49], v[48:49], v[56:57]
	v_add_f32_e32 v54, v58, v54
	v_pk_mul_f32 v[56:57], v[48:49], v[48:49]
	v_add_f32_e32 v54, v59, v54
	v_pk_mul_f32 v[50:51], v[50:51], v[52:53]
	v_add_f32_e32 v54, v56, v54
	v_pk_mul_f32 v[52:53], v[50:51], v[50:51]
	v_add_f32_e32 v54, v57, v54
	v_add_f32_e32 v52, v52, v54
	v_add_f32_e32 v53, v53, v52
	ds_swizzle_b32 v54, v53 offset:swizzle(SWAP,1)
	v_add_f32_e32 v52, v60, v61
	v_pk_add_f32 v[58:59], v[38:39], v[0:1] op_sel_hi:[1,0] neg_lo:[0,1] neg_hi:[0,1]
	v_pk_mul_f32 v[60:61], v[36:37], v[36:37]
	v_pk_add_f32 v[40:41], v[40:41], v[0:1] op_sel_hi:[1,0] neg_lo:[0,1] neg_hi:[0,1]
	v_pk_mul_f32 v[38:39], v[58:59], v[58:59]
	v_add_f32_e32 v0, v60, v61
	v_add_f32_e32 v0, v38, v0
	v_pk_mul_f32 v[56:57], v[40:41], v[40:41]
	v_add_f32_e32 v0, v39, v0
	v_add_f32_e32 v0, v56, v0
	s_waitcnt lgkmcnt(0)
	v_add_f32_e32 v53, v53, v54
	v_pk_mul_f32 v[54:55], v[42:43], v[42:43]
	v_add_f32_e32 v0, v57, v0
	v_add_f32_e32 v0, v54, v0
	v_add_f32_e32 v0, v55, v0
	ds_swizzle_b32 v38, v0 offset:swizzle(SWAP,1)
	ds_swizzle_b32 v39, v53 offset:swizzle(SWAP,2)
	ds_swizzle_b32 v62, v19 offset:swizzle(SWAP,16)
	v_mul_f32_e32 v52, 0x3b000000, v52
	s_mov_b64 s[58:59], 0
	s_waitcnt lgkmcnt(2)
	v_add_f32_e32 v0, v0, v38
	ds_swizzle_b32 v54, v0 offset:swizzle(SWAP,2)
	s_waitcnt lgkmcnt(2)
	v_add_f32_e32 v39, v53, v39
	s_waitcnt lgkmcnt(1)
	v_add_f32_e32 v19, v19, v62
	ds_swizzle_b32 v53, v39 offset:swizzle(SWAP,4)
	v_mov_b32_e32 v62, v19
	s_waitcnt lgkmcnt(1)
	v_add_f32_e32 v0, v0, v54
	ds_swizzle_b32 v54, v0 offset:swizzle(SWAP,4)
	v_permlane32_swap_b32_e32 v19, v62
	v_add_f32_e32 v19, v19, v62
	v_mul_f32_e32 v38, 0x3b000000, v19
	s_waitcnt lgkmcnt(0)
	v_add_f32_e32 v0, v0, v54
	ds_swizzle_b32 v57, v0 offset:swizzle(SWAP,8)
	v_lshl_add_u32 v19, v78, 2, s41
	v_add_f32_e32 v39, v39, v53
	v_lshrrev_b32_e32 v56, 8, v19
	ds_swizzle_b32 v53, v39 offset:swizzle(SWAP,8)
	s_waitcnt lgkmcnt(1)
	v_add_f32_e32 v0, v0, v57
	v_mul_hi_i32_i24_e32 v55, 0x180000, v56
	v_mul_i32_i24_e32 v54, 0x180000, v56
	ds_swizzle_b32 v56, v0 offset:swizzle(SWAP,16)
	s_waitcnt lgkmcnt(1)
	v_add_f32_e32 v39, v39, v53
	ds_swizzle_b32 v53, v39 offset:swizzle(SWAP,16)
	v_lshl_add_u64 v[54:55], s[22:23], 0, v[54:55]
	s_waitcnt lgkmcnt(1)
	v_add_f32_e32 v0, v0, v56
	v_mov_b32_e32 v56, v0
	s_nop 1
	v_permlane32_swap_b32_e32 v0, v56
	v_add_f32_e32 v0, v0, v56
	v_fmamk_f32 v0, v0, 0x3b000000, v231
	v_rsq_f32_e32 v0, v0
	s_waitcnt lgkmcnt(0)
	v_add_f32_e32 v39, v39, v53
	v_mov_b32_e32 v53, v39
	s_nop 1
	v_permlane32_swap_b32_e32 v39, v53
	v_add_f32_e32 v39, v39, v53
	v_pk_mul_f32 v[36:37], v[36:37], v[0:1] op_sel_hi:[1,0]
	v_fmamk_f32 v39, v39, 0x3b000000, v231
	v_pk_fma_f32 v[36:37], v[10:11], v[36:37], v[14:15]
	v_rsq_f32_e32 v56, v39
	v_mul_f32_e32 v39, 0xbfb8aa3b, v36
	v_exp_f32_e32 v39, v39
	v_mul_f32_e32 v53, 0xbfb8aa3b, v37
	v_exp_f32_e32 v53, v53
	v_pk_mul_f32 v[44:45], v[44:45], v[56:57] op_sel_hi:[1,0]
	v_add_f32_e32 v39, 1.0, v39
	v_rcp_f32_e32 v60, v39
	v_add_f32_e32 v39, 1.0, v53
	v_rcp_f32_e32 v61, v39
	v_pk_mul_f32 v[46:47], v[46:47], v[56:57] op_sel_hi:[1,0]
	v_cvt_pk_bf16_f32 v44, v44, v45
	v_cvt_pk_bf16_f32 v45, v46, v47
	v_pk_mul_f32 v[60:61], v[36:37], v[60:61]
	v_pk_mul_f32 v[36:37], v[58:59], v[0:1] op_sel_hi:[1,0]
	v_pk_mul_f32 v[40:41], v[40:41], v[0:1] op_sel_hi:[1,0]
	v_pk_fma_f32 v[36:37], v[12:13], v[36:37], v[16:17]
	v_pk_fma_f32 v[62:63], v[2:3], v[40:41], v[6:7]
	v_mul_f32_e32 v39, 0xbfb8aa3b, v36
	v_exp_f32_e32 v39, v39
	v_mul_f32_e32 v46, 0xbfb8aa3b, v37
	v_exp_f32_e32 v53, v46
	v_mul_f32_e32 v40, 0xbfb8aa3b, v63
	v_add_f32_e32 v39, 1.0, v39
	v_rcp_f32_e32 v58, v39
	v_add_f32_e32 v39, 1.0, v53
	v_rcp_f32_e32 v59, v39
	v_mul_f32_e32 v39, 0xbfb8aa3b, v62
	v_exp_f32_e32 v39, v39
	v_pk_mul_f32 v[42:43], v[42:43], v[0:1] op_sel_hi:[1,0]
	v_exp_f32_e32 v53, v40
	v_pk_mul_f32 v[40:41], v[36:37], v[58:59]
	v_pk_fma_f32 v[58:59], v[4:5], v[42:43], v[8:9]
	v_add_f32_e32 v36, 1.0, v39
	v_mul_f32_e32 v0, 0xbfb8aa3b, v58
	v_exp_f32_e32 v0, v0
	v_mul_f32_e32 v39, 0xbfb8aa3b, v59
	v_exp_f32_e32 v39, v39
	v_add_f32_e32 v37, 1.0, v53
	v_rcp_f32_e32 v36, v36
	v_rcp_f32_e32 v37, v37
	v_add_f32_e32 v0, 1.0, v0
	v_rcp_f32_e32 v64, v0
	v_add_f32_e32 v0, 1.0, v39
	v_pk_mul_f32 v[46:47], v[60:61], v[60:61]
	v_rcp_f32_e32 v65, v0
	v_pk_mul_f32 v[66:67], v[40:41], v[40:41]
	v_add_f32_e32 v0, v46, v47
	v_pk_mul_f32 v[42:43], v[62:63], v[36:37]
	v_add_f32_e32 v0, v66, v0
	v_pk_mul_f32 v[62:63], v[42:43], v[42:43]
	v_add_f32_e32 v0, v67, v0
	v_pk_add_f32 v[20:21], v[20:21], v[52:53] op_sel_hi:[1,0] neg_lo:[0,1] neg_hi:[0,1]
	v_pk_mul_f32 v[36:37], v[58:59], v[64:65]
	v_add_f32_e32 v0, v62, v0
	v_pk_add_f32 v[26:27], v[26:27], v[52:53] op_sel_hi:[1,0] neg_lo:[0,1] neg_hi:[0,1]
	v_pk_add_f32 v[24:25], v[24:25], v[52:53] op_sel_hi:[1,0] neg_lo:[0,1] neg_hi:[0,1]
	v_pk_add_f32 v[22:23], v[22:23], v[52:53] op_sel_hi:[1,0] neg_lo:[0,1] neg_hi:[0,1]
	v_pk_mul_f32 v[52:53], v[20:21], v[20:21]
	v_pk_mul_f32 v[58:59], v[36:37], v[36:37]
	v_add_f32_e32 v0, v63, v0
	v_pk_mul_f32 v[62:63], v[22:23], v[22:23]
	v_add_f32_e32 v52, v52, v53
	v_add_f32_e32 v0, v58, v0
	v_add_f32_e32 v52, v62, v52
	v_add_f32_e32 v0, v59, v0
	v_pk_mul_f32 v[58:59], v[24:25], v[24:25]
	v_add_f32_e32 v52, v63, v52
	v_add_f32_e32 v52, v58, v52
	v_pk_mul_f32 v[46:47], v[26:27], v[26:27]
	v_add_f32_e32 v52, v59, v52
	v_add_f32_e32 v46, v46, v52
	v_add_f32_e32 v52, v47, v46
	ds_swizzle_b32 v53, v52 offset:swizzle(SWAP,1)
	ds_swizzle_b32 v39, v0 offset:swizzle(SWAP,1)
	v_pk_mul_f32 v[46:47], v[48:49], v[56:57] op_sel_hi:[1,0]
	v_pk_mul_f32 v[48:49], v[50:51], v[56:57] op_sel_hi:[1,0]
	v_cvt_pk_bf16_f32 v46, v46, v47
	s_waitcnt lgkmcnt(1)
	v_add_f32_e32 v52, v52, v53
	ds_swizzle_b32 v53, v52 offset:swizzle(SWAP,2)
	s_waitcnt lgkmcnt(1)
	v_add_f32_e32 v0, v0, v39
	v_cvt_pk_bf16_f32 v47, v48, v49
	ds_swizzle_b32 v39, v0 offset:swizzle(SWAP,2)
	s_waitcnt lgkmcnt(1)
	v_add_f32_e32 v49, v52, v53
	ds_swizzle_b32 v50, v49 offset:swizzle(SWAP,4)
	s_waitcnt lgkmcnt(1)
	v_add_f32_e32 v39, v0, v39
	ds_swizzle_b32 v48, v39 offset:swizzle(SWAP,4)
	v_lshlrev_b32_e32 v0, 11, v19
	s_waitcnt lgkmcnt(1)
	v_add_f32_e32 v50, v49, v50
	ds_swizzle_b32 v51, v50 offset:swizzle(SWAP,8)
	v_and_b32_e32 v0, 0x7e000, v0
	s_waitcnt lgkmcnt(1)
	v_add_f32_e32 v19, v39, v48
	ds_swizzle_b32 v39, v19 offset:swizzle(SWAP,8)
	v_lshl_add_u64 v[48:49], v[54:55], 0, v[0:1]
	s_waitcnt lgkmcnt(1)
	v_add_f32_e32 v50, v50, v51
	ds_swizzle_b32 v51, v50 offset:swizzle(SWAP,16)
	v_lshlrev_b32_e32 v0, 1, v18
	s_waitcnt lgkmcnt(1)
	v_add_f32_e32 v39, v19, v39
	v_lshl_add_u64 v[18:19], v[48:49], 0, v[0:1]
	global_store_dwordx4 v[18:19], v[44:47], off offset:1024
	s_waitcnt lgkmcnt(0)
	v_add_f32_e32 v0, v50, v51
	ds_swizzle_b32 v52, v39 offset:swizzle(SWAP,16)
	v_mov_b32_e32 v45, v0
	s_nop 1
	v_permlane32_swap_b32_e32 v0, v45
	v_add_f32_e32 v0, v0, v45
	v_fmamk_f32 v0, v0, 0x3b000000, v231
	v_rsq_f32_e32 v0, v0
	s_waitcnt lgkmcnt(0)
	v_add_f32_e32 v39, v39, v52
	v_mov_b32_e32 v44, v39
	s_nop 1
	v_permlane32_swap_b32_e32 v39, v44
	v_pk_mul_f32 v[20:21], v[20:21], v[0:1] op_sel_hi:[1,0]
	v_add_f32_e32 v39, v39, v44
	v_pk_fma_f32 v[20:21], v[10:11], v[20:21], v[14:15]
	v_pk_mul_f32 v[22:23], v[22:23], v[0:1] op_sel_hi:[1,0]
	v_mul_f32_e32 v44, 0xbfb8aa3b, v20
	v_exp_f32_e32 v45, v44
	v_mul_f32_e32 v44, 0xbfb8aa3b, v21
	v_exp_f32_e32 v47, v44
	v_fmamk_f32 v39, v39, 0x3b000000, v231
	v_pk_fma_f32 v[22:23], v[12:13], v[22:23], v[16:17]
	v_rsq_f32_e32 v44, v39
	v_add_f32_e32 v39, 1.0, v45
	v_mul_f32_e32 v45, 0xbfb8aa3b, v22
	v_rcp_f32_e32 v46, v39
	v_add_f32_e32 v39, 1.0, v47
	v_exp_f32_e32 v45, v45
	v_mul_f32_e32 v47, 0xbfb8aa3b, v23
	v_exp_f32_e32 v49, v47
	v_rcp_f32_e32 v47, v39
	v_add_f32_e32 v39, 1.0, v45
	v_rcp_f32_e32 v48, v39
	v_add_f32_e32 v39, 1.0, v49
	v_rcp_f32_e32 v49, v39
	v_pk_mul_f32 v[50:51], v[60:61], v[44:45] op_sel_hi:[1,0]
	v_pk_mul_f32 v[26:27], v[26:27], v[0:1] op_sel_hi:[1,0]
	v_pk_mul_f32 v[46:47], v[20:21], v[46:47]
	v_pk_mul_f32 v[48:49], v[22:23], v[48:49]
	v_pk_mul_f32 v[22:23], v[24:25], v[0:1] op_sel_hi:[1,0]
	v_pk_fma_f32 v[26:27], v[4:5], v[26:27], v[8:9]
	v_pk_fma_f32 v[22:23], v[2:3], v[22:23], v[6:7]
	v_mul_f32_e32 v0, 0xbfb8aa3b, v26
	v_mul_f32_e32 v24, 0xbfb8aa3b, v22
	v_exp_f32_e32 v39, v24
	v_mul_f32_e32 v24, 0xbfb8aa3b, v23
	v_exp_f32_e32 v45, v24
	v_exp_f32_e32 v0, v0
	v_add_f32_e32 v39, 1.0, v39
	v_rcp_f32_e32 v52, v39
	v_add_f32_e32 v39, 1.0, v45
	v_rcp_f32_e32 v53, v39
	v_mul_f32_e32 v39, 0xbfb8aa3b, v27
	v_pk_add_f32 v[28:29], v[28:29], v[38:39] op_sel_hi:[1,0] neg_lo:[0,1] neg_hi:[0,1]
	v_exp_f32_e32 v45, v39
	v_pk_add_f32 v[34:35], v[34:35], v[38:39] op_sel_hi:[1,0] neg_lo:[0,1] neg_hi:[0,1]
	v_pk_add_f32 v[32:33], v[32:33], v[38:39] op_sel_hi:[1,0] neg_lo:[0,1] neg_hi:[0,1]
	v_pk_add_f32 v[30:31], v[30:31], v[38:39] op_sel_hi:[1,0] neg_lo:[0,1] neg_hi:[0,1]
	v_pk_mul_f32 v[38:39], v[28:29], v[28:29]
	v_pk_mul_f32 v[58:59], v[30:31], v[30:31]
	v_add_f32_e32 v38, v38, v39
	v_add_f32_e32 v38, v58, v38
	v_pk_mul_f32 v[56:57], v[32:33], v[32:33]
	v_add_f32_e32 v38, v59, v38
	v_add_f32_e32 v38, v56, v38
	v_pk_mul_f32 v[54:55], v[34:35], v[34:35]
	v_add_f32_e32 v38, v57, v38
	v_add_f32_e32 v38, v54, v38
	v_add_f32_e32 v54, v55, v38
	ds_swizzle_b32 v55, v54 offset:swizzle(SWAP,1)
	v_add_f32_e32 v0, 1.0, v0
	v_rcp_f32_e32 v38, v0
	v_add_f32_e32 v0, 1.0, v45
	v_rcp_f32_e32 v39, v0
	s_waitcnt lgkmcnt(0)
	v_add_f32_e32 v0, v54, v55
	ds_swizzle_b32 v45, v0 offset:swizzle(SWAP,2)
	v_pk_mul_f32 v[20:21], v[46:47], v[46:47]
	v_pk_mul_f32 v[24:25], v[48:49], v[48:49]
	v_add_f32_e32 v20, v20, v21
	v_pk_mul_f32 v[52:53], v[22:23], v[52:53]
	s_waitcnt lgkmcnt(0)
	v_add_f32_e32 v0, v0, v45
	ds_swizzle_b32 v45, v0 offset:swizzle(SWAP,4)
	v_add_f32_e32 v20, v24, v20
	v_pk_mul_f32 v[22:23], v[52:53], v[52:53]
	v_add_f32_e32 v20, v25, v20
	v_pk_mul_f32 v[26:27], v[26:27], v[38:39]
	s_waitcnt lgkmcnt(0)
	v_add_f32_e32 v0, v0, v45
	ds_swizzle_b32 v21, v0 offset:swizzle(SWAP,8)
	v_add_f32_e32 v20, v22, v20
	v_pk_mul_f32 v[38:39], v[26:27], v[26:27]
	v_add_f32_e32 v20, v23, v20
	v_add_f32_e32 v20, v38, v20
	s_waitcnt lgkmcnt(0)
	v_add_f32_e32 v0, v0, v21
	ds_swizzle_b32 v21, v0 offset:swizzle(SWAP,16)
	v_add_f32_e32 v24, v39, v20
	ds_swizzle_b32 v25, v24 offset:swizzle(SWAP,1)
	v_pk_mul_f32 v[22:23], v[40:41], v[44:45] op_sel_hi:[1,0]
	v_cvt_pk_bf16_f32 v20, v50, v51
	s_waitcnt lgkmcnt(1)
	v_add_f32_e32 v0, v0, v21
	v_mov_b32_e32 v21, v0
	s_nop 1
	v_permlane32_swap_b32_e32 v0, v21
	s_waitcnt lgkmcnt(0)
	v_add_f32_e32 v24, v24, v25
	v_add_f32_e32 v0, v0, v21
	ds_swizzle_b32 v25, v24 offset:swizzle(SWAP,2)
	v_fmamk_f32 v0, v0, 0x3b000000, v231
	v_rsq_f32_e32 v0, v0
	v_cvt_pk_bf16_f32 v21, v22, v23
	v_pk_mul_f32 v[22:23], v[42:43], v[44:45] op_sel_hi:[1,0]
	s_waitcnt lgkmcnt(0)
	v_add_f32_e32 v38, v24, v25
	v_pk_mul_f32 v[24:25], v[28:29], v[0:1] op_sel_hi:[1,0]
	v_cvt_pk_bf16_f32 v22, v22, v23
	v_pk_fma_f32 v[10:11], v[10:11], v[24:25], v[14:15]
	ds_swizzle_b32 v24, v38 offset:swizzle(SWAP,4)
	v_mul_f32_e32 v14, 0xbfb8aa3b, v10
	v_mul_f32_e32 v15, 0xbfb8aa3b, v11
	v_exp_f32_e32 v14, v14
	v_exp_f32_e32 v15, v15
	s_waitcnt lgkmcnt(0)
	v_add_f32_e32 v23, v38, v24
	v_pk_mul_f32 v[24:25], v[32:33], v[0:1] op_sel_hi:[1,0]
	v_add_f32_e32 v14, 1.0, v14
	v_add_f32_e32 v15, 1.0, v15
	v_rcp_f32_e32 v14, v14
	v_rcp_f32_e32 v15, v15
	v_pk_fma_f32 v[2:3], v[2:3], v[24:25], v[6:7]
	ds_swizzle_b32 v28, v23 offset:swizzle(SWAP,8)
	v_mul_f32_e32 v6, 0xbfb8aa3b, v2
	v_pk_mul_f32 v[10:11], v[10:11], v[14:15]
	v_pk_mul_f32 v[14:15], v[30:31], v[0:1] op_sel_hi:[1,0]
	v_exp_f32_e32 v24, v6
	v_pk_fma_f32 v[12:13], v[12:13], v[14:15], v[16:17]
	v_mul_f32_e32 v6, 0xbfb8aa3b, v3
	v_mul_f32_e32 v14, 0xbfb8aa3b, v12
	v_exp_f32_e32 v16, v14
	v_mul_f32_e32 v14, 0xbfb8aa3b, v13
	v_exp_f32_e32 v17, v14
	v_exp_f32_e32 v25, v6
	v_add_f32_e32 v16, 1.0, v16
	v_rcp_f32_e32 v16, v16
	v_add_f32_e32 v17, 1.0, v17
	v_rcp_f32_e32 v17, v17
	v_pk_mul_f32 v[14:15], v[10:11], v[10:11]
	v_pk_mul_f32 v[6:7], v[12:13], v[16:17]
	v_pk_mul_f32 v[16:17], v[34:35], v[0:1] op_sel_hi:[1,0]
	v_add_f32_e32 v12, 1.0, v24
	v_pk_fma_f32 v[4:5], v[4:5], v[16:17], v[8:9]
	v_add_f32_e32 v13, 1.0, v25
	v_mul_f32_e32 v0, 0xbfb8aa3b, v4
	v_exp_f32_e32 v0, v0
	v_mul_f32_e32 v8, 0xbfb8aa3b, v5
	v_exp_f32_e32 v9, v8
	v_rcp_f32_e32 v12, v12
	v_rcp_f32_e32 v13, v13
	v_add_f32_e32 v0, 1.0, v0
	v_rcp_f32_e32 v8, v0
	v_add_f32_e32 v0, 1.0, v9
	v_rcp_f32_e32 v9, v0
	v_pk_mul_f32 v[16:17], v[6:7], v[6:7]
	v_add_f32_e32 v0, v14, v15
	v_pk_mul_f32 v[12:13], v[2:3], v[12:13]
	v_add_f32_e32 v0, v16, v0
	v_pk_mul_f32 v[2:3], v[12:13], v[12:13]
	v_add_f32_e32 v0, v17, v0
	v_pk_mul_f32 v[8:9], v[4:5], v[8:9]
	v_add_f32_e32 v0, v2, v0
	v_pk_mul_f32 v[4:5], v[8:9], v[8:9]
	v_add_f32_e32 v0, v3, v0
	v_add_f32_e32 v0, v4, v0
	v_add_f32_e32 v0, v5, v0
	ds_swizzle_b32 v4, v0 offset:swizzle(SWAP,1)
	v_pk_mul_f32 v[2:3], v[36:37], v[44:45] op_sel_hi:[1,0]
	s_waitcnt lgkmcnt(1)
	v_add_f32_e32 v5, v23, v28
	v_cvt_pk_bf16_f32 v23, v2, v3
	ds_swizzle_b32 v14, v5 offset:swizzle(SWAP,16)
	s_waitcnt lgkmcnt(1)
	v_add_f32_e32 v0, v0, v4
	ds_swizzle_b32 v2, v0 offset:swizzle(SWAP,2)
	global_store_dwordx4 v[18:19], v[20:23], off offset:3072
	s_waitcnt lgkmcnt(1)
	v_add_f32_e32 v3, v5, v14
	v_mov_b32_e32 v4, v3
	s_waitcnt lgkmcnt(0)
	v_add_f32_e32 v2, v0, v2
	ds_swizzle_b32 v5, v2 offset:swizzle(SWAP,4)
	v_permlane32_swap_b32_e32 v3, v4
	v_add_f32_e32 v0, v3, v4
	v_fmamk_f32 v0, v0, 0x3b000000, v231
	s_waitcnt lgkmcnt(0)
	v_add_f32_e32 v14, v2, v5
	ds_swizzle_b32 v15, v14 offset:swizzle(SWAP,8)
	v_rsq_f32_e32 v0, v0
	s_waitcnt lgkmcnt(0)
	v_add_f32_e32 v16, v14, v15
	ds_swizzle_b32 v17, v16 offset:swizzle(SWAP,16)
	v_pk_mul_f32 v[2:3], v[46:47], v[0:1] op_sel_hi:[1,0]
	v_pk_mul_f32 v[4:5], v[48:49], v[0:1] op_sel_hi:[1,0]
	v_cvt_pk_bf16_f32 v2, v2, v3
	v_cvt_pk_bf16_f32 v3, v4, v5
	v_pk_mul_f32 v[4:5], v[52:53], v[0:1] op_sel_hi:[1,0]
	v_pk_mul_f32 v[14:15], v[26:27], v[0:1] op_sel_hi:[1,0]
	s_waitcnt lgkmcnt(0)
	v_add_f32_e32 v0, v16, v17
	v_cvt_pk_bf16_f32 v4, v4, v5
	v_cvt_pk_bf16_f32 v5, v14, v15
	v_mov_b32_e32 v14, v0
	s_nop 1
	v_permlane32_swap_b32_e32 v0, v14
	v_add_f32_e32 v0, v0, v14
	v_fmamk_f32 v0, v0, 0x3b000000, v231
	v_rsq_f32_e32 v0, v0
	v_add_co_u32_e32 v14, vcc, s81, v18
	s_nop 1
	v_addc_co_u32_e32 v15, vcc, 0, v19, vcc
	global_store_dwordx4 v[14:15], v[2:5], off offset:1024
	s_and_b64 vcc, exec, s[2:3]
	s_nop 0
	v_pk_mul_f32 v[2:3], v[10:11], v[0:1] op_sel_hi:[1,0]
	v_pk_mul_f32 v[4:5], v[6:7], v[0:1] op_sel_hi:[1,0]
	v_cvt_pk_bf16_f32 v2, v2, v3
	v_cvt_pk_bf16_f32 v3, v4, v5
	v_pk_mul_f32 v[4:5], v[12:13], v[0:1] op_sel_hi:[1,0]
	v_pk_mul_f32 v[6:7], v[8:9], v[0:1] op_sel_hi:[1,0]
	v_cvt_pk_bf16_f32 v4, v4, v5
	v_cvt_pk_bf16_f32 v5, v6, v7
	global_store_dwordx4 v[14:15], v[2:5], off offset:3072
	s_barrier
	s_cbranch_vccnz .LBB0_1468
.LBB0_1424:
	s_mov_b32 s2, 10
	s_ashr_i32 s3, s2, 31
	s_lshl_b64 s[2:3], s[2:3], 3
	s_add_u32 s2, s0, s2
	s_addc_u32 s3, s1, s3
	s_load_dwordx2 s[46:47], s[2:3], 0x0
	s_mov_b32 s2, 11
	s_ashr_i32 s3, s2, 31
	s_lshl_b64 s[2:3], s[2:3], 3
	s_add_u32 s2, s0, s2
	s_addc_u32 s3, s1, s3
	s_load_dwordx2 s[48:49], s[2:3], 0x0
	s_mov_b32 s2, 12
	s_ashr_i32 s3, s2, 31
	s_lshl_b64 s[2:3], s[2:3], 3
	s_add_u32 s2, s0, s2
	s_addc_u32 s3, s1, s3
	s_load_dwordx2 s[50:51], s[2:3], 0x0
	s_mov_b32 s2, s33
	s_mov_b32 s3, -1
	s_or_b32 s41, s26, s4
	v_mbcnt_lo_u32_b32 v0, s3, 0
	v_mbcnt_hi_u32_b32 v0, s3, v0
	v_lshl_or_b32 v36, s2, 6, v0
	s_sub_i32 s24, s41, 30
	v_lshlrev_b32_e32 v0, 3, v36
	v_ashrrev_i32_e32 v78, 6, v36
	s_waitcnt vmcnt(0)
	v_and_b32_e32 v3, 0x1f8, v0
	v_add_u32_e32 v0, s24, v78
	s_movk_i32 s2, 0xf80
	v_cmp_gt_i32_e64 s[2:3], s2, v36
	v_cmp_lt_i32_e32 vcc, -1, v0
	v_mov_b32_e32 v2, 0
	s_and_b64 s[6:7], s[2:3], vcc
	v_lshlrev_b32_e32 v34, 1, v3
	v_mov_b32_e32 v6, 0
	v_mov_b32_e32 v7, 0
	v_mov_b32_e32 v8, 0
	v_mov_b32_e32 v9, 0
	s_and_saveexec_b64 s[4:5], s[6:7]
	s_cbranch_execz .LBB0_1426
	v_lshrrev_b32_e32 v3, 8, v0
	v_mov_b64_e32 v[4:5], s[22:23]
	v_lshlrev_b32_e32 v0, 10, v0
	v_mad_u64_u32 v[4:5], s[6:7], v3, s73, v[4:5]
	v_and_b32_e32 v0, 0x3fc00, v0
	v_lshl_add_u64 v[4:5], v[4:5], 0, v[0:1]
	v_mov_b32_e32 v35, v1
	v_lshl_add_u64 v[4:5], v[4:5], 0, v[34:35]
	v_add_co_u32_e32 v4, vcc, 0x100000, v4
	s_nop 1
	v_addc_co_u32_e32 v5, vcc, 0, v5, vcc
	global_load_dwordx4 v[6:9], v[4:5], off sc1
.LBB0_1426:
	s_or_b64 exec, exec, s[4:5]
	v_add_u32_e32 v37, 0x200, v36
	v_ashrrev_i32_e32 v0, 6, v37
	v_add_u32_e32 v0, s24, v0
	s_movk_i32 s4, 0xd80
	v_cmp_gt_i32_e64 s[4:5], s4, v36
	v_cmp_lt_i32_e32 vcc, -1, v0
	s_and_b64 s[8:9], s[4:5], vcc
	v_mov_b32_e32 v3, 0
	v_mov_b32_e32 v4, 0
	v_mov_b32_e32 v5, 0
	s_and_saveexec_b64 s[6:7], s[8:9]
	s_cbranch_execz .LBB0_1428
	v_lshrrev_b32_e32 v4, 8, v0
	v_mov_b64_e32 v[2:3], s[22:23]
	v_lshlrev_b32_e32 v0, 10, v0
	v_mad_u64_u32 v[2:3], s[8:9], v4, s73, v[2:3]
	v_and_b32_e32 v0, 0x3fc00, v0
	v_lshl_add_u64 v[2:3], v[2:3], 0, v[0:1]
	v_mov_b32_e32 v35, v1
	v_lshl_add_u64 v[2:3], v[2:3], 0, v[34:35]
	v_add_co_u32_e32 v2, vcc, 0x100000, v2
	s_nop 1
	v_addc_co_u32_e32 v3, vcc, 0, v3, vcc
	global_load_dwordx4 v[2:5], v[2:3], off sc1
.LBB0_1428:
	s_or_b64 exec, exec, s[6:7]
	v_add_u32_e32 v38, 0x400, v36
	v_ashrrev_i32_e32 v0, 6, v38
	v_add_u32_e32 v0, s24, v0
	s_movk_i32 s6, 0xb80
	v_cmp_gt_i32_e64 s[6:7], s6, v36
	v_cmp_lt_i32_e32 vcc, -1, v0
	s_and_b64 s[10:11], s[6:7], vcc
	v_mov_b32_e32 v10, 0
	v_mov_b32_e32 v14, 0
	v_mov_b32_e32 v15, 0
	v_mov_b32_e32 v16, 0
	v_mov_b32_e32 v17, 0
	s_and_saveexec_b64 s[8:9], s[10:11]
	s_cbranch_execz .LBB0_1430
	v_lshrrev_b32_e32 v11, 8, v0
	v_mov_b64_e32 v[12:13], s[22:23]
	v_lshlrev_b32_e32 v0, 10, v0
	v_mad_u64_u32 v[12:13], s[10:11], v11, s73, v[12:13]
	v_and_b32_e32 v0, 0x3fc00, v0
	v_lshl_add_u64 v[12:13], v[12:13], 0, v[0:1]
	v_mov_b32_e32 v35, v1
	v_lshl_add_u64 v[12:13], v[12:13], 0, v[34:35]
	v_add_co_u32_e32 v12, vcc, 0x100000, v12
	s_nop 1
	v_addc_co_u32_e32 v13, vcc, 0, v13, vcc
	global_load_dwordx4 v[14:17], v[12:13], off sc1
.LBB0_1430:
	s_or_b64 exec, exec, s[8:9]
	v_add_u32_e32 v39, 0x600, v36
	v_ashrrev_i32_e32 v0, 6, v39
	v_add_u32_e32 v0, s24, v0
	s_movk_i32 s8, 0x980
	v_cmp_gt_i32_e64 s[8:9], s8, v36
	v_cmp_lt_i32_e32 vcc, -1, v0
	s_and_b64 s[12:13], s[8:9], vcc
	v_mov_b32_e32 v11, 0
	v_mov_b32_e32 v12, 0
	v_mov_b32_e32 v13, 0
	s_and_saveexec_b64 s[10:11], s[12:13]
	s_cbranch_execz .LBB0_1432
	v_lshrrev_b32_e32 v12, 8, v0
	v_mov_b64_e32 v[10:11], s[22:23]
	v_lshlrev_b32_e32 v0, 10, v0
	v_mad_u64_u32 v[10:11], s[12:13], v12, s73, v[10:11]
	v_and_b32_e32 v0, 0x3fc00, v0
	v_lshl_add_u64 v[10:11], v[10:11], 0, v[0:1]
	v_mov_b32_e32 v35, v1
	v_lshl_add_u64 v[10:11], v[10:11], 0, v[34:35]
	v_add_co_u32_e32 v10, vcc, 0x100000, v10
	s_nop 1
	v_addc_co_u32_e32 v11, vcc, 0, v11, vcc
	global_load_dwordx4 v[10:13], v[10:11], off sc1
.LBB0_1432:
	s_or_b64 exec, exec, s[10:11]
	v_add_u32_e32 v40, 0x800, v36
	v_ashrrev_i32_e32 v0, 6, v40
	v_add_u32_e32 v0, s24, v0
	s_movk_i32 s10, 0x780
	v_cmp_gt_i32_e64 s[10:11], s10, v36
	v_cmp_lt_i32_e32 vcc, -1, v0
	s_and_b64 s[14:15], s[10:11], vcc
	v_mov_b32_e32 v18, 0
	v_mov_b32_e32 v22, 0
	v_mov_b32_e32 v23, 0
	v_mov_b32_e32 v24, 0
	v_mov_b32_e32 v25, 0
	s_and_saveexec_b64 s[12:13], s[14:15]
	s_cbranch_execz .LBB0_1434
	v_lshrrev_b32_e32 v19, 8, v0
	v_mov_b64_e32 v[20:21], s[22:23]
	v_lshlrev_b32_e32 v0, 10, v0
	v_mad_u64_u32 v[20:21], s[14:15], v19, s73, v[20:21]
	v_and_b32_e32 v0, 0x3fc00, v0
	v_lshl_add_u64 v[20:21], v[20:21], 0, v[0:1]
	v_mov_b32_e32 v35, v1
	v_lshl_add_u64 v[20:21], v[20:21], 0, v[34:35]
	v_add_co_u32_e32 v20, vcc, 0x100000, v20
	s_nop 1
	v_addc_co_u32_e32 v21, vcc, 0, v21, vcc
	global_load_dwordx4 v[22:25], v[20:21], off sc1
.LBB0_1434:
	s_or_b64 exec, exec, s[12:13]
	v_add_u32_e32 v41, 0xa00, v36
	v_ashrrev_i32_e32 v0, 6, v41
	v_add_u32_e32 v0, s24, v0
	s_movk_i32 s12, 0x580
	v_cmp_gt_i32_e64 s[12:13], s12, v36
	v_cmp_lt_i32_e32 vcc, -1, v0
	s_and_b64 s[16:17], s[12:13], vcc
	v_mov_b32_e32 v19, 0
	v_mov_b32_e32 v20, 0
	v_mov_b32_e32 v21, 0
	s_and_saveexec_b64 s[14:15], s[16:17]
	s_cbranch_execz .LBB0_1436
	v_lshrrev_b32_e32 v20, 8, v0
	v_mov_b64_e32 v[18:19], s[22:23]
	v_lshlrev_b32_e32 v0, 10, v0
	v_mad_u64_u32 v[18:19], s[16:17], v20, s73, v[18:19]
	v_and_b32_e32 v0, 0x3fc00, v0
	v_lshl_add_u64 v[18:19], v[18:19], 0, v[0:1]
	v_mov_b32_e32 v35, v1
	v_lshl_add_u64 v[18:19], v[18:19], 0, v[34:35]
	v_add_co_u32_e32 v18, vcc, 0x100000, v18
	s_nop 1
	v_addc_co_u32_e32 v19, vcc, 0, v19, vcc
	global_load_dwordx4 v[18:21], v[18:19], off sc1
.LBB0_1436:
	s_or_b64 exec, exec, s[14:15]
	v_add_u32_e32 v42, 0xc00, v36
	v_ashrrev_i32_e32 v0, 6, v42
	v_add_u32_e32 v0, s24, v0
	s_movk_i32 s14, 0x380
	v_cmp_gt_i32_e64 s[14:15], s14, v36
	v_cmp_lt_i32_e32 vcc, -1, v0
	s_and_b64 s[42:43], s[14:15], vcc
	v_mov_b32_e32 v26, 0
	v_mov_b32_e32 v30, 0
	v_mov_b32_e32 v31, 0
	v_mov_b32_e32 v32, 0
	v_mov_b32_e32 v33, 0
	s_and_saveexec_b64 s[16:17], s[42:43]
	s_cbranch_execz .LBB0_1438
	v_lshrrev_b32_e32 v27, 8, v0
	v_mov_b64_e32 v[28:29], s[22:23]
	v_lshlrev_b32_e32 v0, 10, v0
	v_mad_u64_u32 v[28:29], s[42:43], v27, s73, v[28:29]
	v_and_b32_e32 v0, 0x3fc00, v0
	v_lshl_add_u64 v[28:29], v[28:29], 0, v[0:1]
	v_mov_b32_e32 v35, v1
	v_lshl_add_u64 v[28:29], v[28:29], 0, v[34:35]
	v_add_co_u32_e32 v28, vcc, 0x100000, v28
	s_nop 1
	v_addc_co_u32_e32 v29, vcc, 0, v29, vcc
	global_load_dwordx4 v[30:33], v[28:29], off sc1
.LBB0_1438:
	s_or_b64 exec, exec, s[16:17]
	v_add_u32_e32 v43, 0xe00, v36
	v_ashrrev_i32_e32 v0, 6, v43
	v_add_u32_e32 v0, s24, v0
	s_movk_i32 s16, 0x180
	v_cmp_gt_i32_e64 s[16:17], s16, v36
	v_cmp_lt_i32_e32 vcc, -1, v0
	s_and_b64 s[42:43], s[16:17], vcc
	v_mov_b32_e32 v27, 0
	v_mov_b32_e32 v28, 0
	v_mov_b32_e32 v29, 0
	s_and_saveexec_b64 s[24:25], s[42:43]
	s_cbranch_execz .LBB0_1452
	v_lshrrev_b32_e32 v28, 8, v0
	v_mov_b64_e32 v[26:27], s[22:23]
	v_lshlrev_b32_e32 v0, 10, v0
	v_mad_u64_u32 v[26:27], s[42:43], v28, s73, v[26:27]
	v_and_b32_e32 v0, 0x3fc00, v0
	v_lshl_add_u64 v[26:27], v[26:27], 0, v[0:1]
	v_mov_b32_e32 v35, v1
	v_lshl_add_u64 v[26:27], v[26:27], 0, v[34:35]
	v_add_co_u32_e32 v26, vcc, 0x100000, v26
	s_nop 1
	v_addc_co_u32_e32 v27, vcc, 0, v27, vcc
	global_load_dwordx4 v[26:29], v[26:27], off sc1
	s_or_b64 exec, exec, s[24:25]
	s_and_saveexec_b64 s[24:25], s[2:3]
	s_cbranch_execnz .LBB0_1453

.LBB0_1448:
	s_or_b64 exec, exec, s[2:3]
	s_xor_b64 s[2:3], s[58:59], -1
	s_waitcnt lgkmcnt(0)
	s_add_u32 s4, s46, s28
	s_waitcnt vmcnt(0)
	v_and_b32_e32 v2, 63, v36
	s_addc_u32 s5, s47, s29
	v_lshlrev_b32_e32 v0, 5, v2
	s_barrier
	global_load_dwordx4 v[10:13], v0, s[4:5] offset:16 sc1
	global_load_dwordx4 v[14:17], v0, s[4:5] sc1
	v_lshlrev_b32_e32 v18, 3, v2
	v_lshlrev_b32_e32 v2, 4, v2
	s_mov_b32 s6, 28
	v_lshl_or_b32 v19, v78, 12, v2
	s_waitcnt vmcnt(1)
	v_mov_b32_e32 v68, v12
	v_mov_b32_e32 v69, v13
	v_mov_b32_e32 v70, v10
	v_mov_b32_e32 v71, v11
	s_waitcnt vmcnt(0)
	v_mov_b32_e32 v72, v16
	v_mov_b32_e32 v73, v17
	v_mov_b32_e32 v74, v14
	v_mov_b32_e32 v75, v15
	v_mov_b32_e32 v60, v12
	v_mov_b32_e32 v61, v13
	v_mov_b32_e32 v62, v10
	v_mov_b32_e32 v63, v11
	v_mov_b32_e32 v64, v16
	v_mov_b32_e32 v65, v17
	v_mov_b32_e32 v66, v14
	v_mov_b32_e32 v67, v15
	v_mov_b32_e32 v58, v12
	v_mov_b32_e32 v59, v13
	v_mov_b32_e32 v52, v10
	v_mov_b32_e32 v53, v11
	v_mov_b32_e32 v54, v16
	v_mov_b32_e32 v55, v17
	v_mov_b32_e32 v56, v14
	v_mov_b32_e32 v57, v15
	s_branch .LBB0_1450

.LBB0_1489:
	s_or_b64 exec, exec, s[16:17]
	s_waitcnt vmcnt(0)
	v_readfirstlane_b32 s2, v2
	s_nop 1
	v_add_u32_e32 v0, s2, v0
	v_and_b32_e32 v2, 0xffffffe0, v0
	v_and_b32_e32 v0, 31, v0
	v_cmp_eq_u32_e64 s[2:3], 31, v0
	v_add_u32_e32 v2, 32, v2
	s_and_b64 s[2:3], s[2:3], exec

.LBB0_1566:
	s_mov_b32 s2, s33
	s_mov_b32 s3, -1
	s_waitcnt vmcnt(63) expcnt(7) lgkmcnt(15)
	s_andn2_b64 vcc, exec, s[6:7]
	v_mbcnt_lo_u32_b32 v0, s3, 0
	v_mbcnt_hi_u32_b32 v0, s3, v0
	v_lshl_or_b32 v0, s2, 6, v0
	s_nop 0
	v_readfirstlane_b32 s14, v0
	s_cbranch_vccnz .LBB0_1592
	v_bfe_i32 v4, v0, 27, 1
	v_lshlrev_b32_e32 v2, 4, v0
	v_lshrrev_b32_e32 v4, 22, v4
	v_add_u32_e32 v4, v2, v4
	v_and_b32_e32 v4, 0xfffffc00, v4
	v_sub_u32_e32 v4, v2, v4
	v_ashrrev_i32_e32 v3, 31, v0
	v_lshrrev_b32_e32 v5, 4, v4
	v_lshrrev_b32_e32 v3, 26, v3
	v_bitop3_b32 v4, v5, v4, 32 bitop3:0x6c
	v_add_u32_e32 v3, v0, v3
	v_ashrrev_i32_e32 v6, 31, v4
	v_ashrrev_i32_e32 v3, 6, v3
	v_lshrrev_b32_e32 v6, 26, v6
	v_lshlrev_b32_e32 v5, 3, v3
	v_add_u32_e32 v6, v4, v6
	v_and_b32_e32 v5, -16, v5
	v_ashrrev_i32_e32 v67, 6, v6
	v_add_u32_e32 v66, v67, v5
	v_and_b32_e32 v5, 0xc0, v6
	v_sub_u32_e32 v4, v4, v5
	v_lshlrev_b32_e32 v3, 5, v3
	v_ashrrev_i16_sdwa v4, v230, sext(v4) dst_sel:DWORD dst_unused:UNUSED_PAD src0_sel:DWORD src1_sel:BYTE_0
	v_and_b32_e32 v3, 32, v3
	v_bfe_i32 v4, v4, 0, 16
	v_add_u32_e32 v2, 0x2000, v2
	v_add_lshl_u32 v68, v3, v4, 1
	v_ashrrev_i32_e32 v3, 31, v2
	v_lshrrev_b32_e32 v3, 22, v3
	v_add_u32_e32 v3, v2, v3
	v_ashrrev_i32_e32 v3, 10, v3
	s_ashr_i32 s7, s14, 6
	v_mul_i32_i24_e32 v4, 0x400, v3
	s_ashr_i32 s8, s14, 8
	v_sub_u32_e32 v2, v2, v4
	s_lshl_b32 s16, s7, 10
	s_lshl_b32 s9, s8, 6
	v_lshrrev_b32_e32 v4, 4, v2
	s_add_u32 s10, s4, 0xf900000
	v_bitop3_b32 v2, v4, v2, 32 bitop3:0x6c
	s_addc_u32 s11, s5, 0
	s_lshl_b32 s2, s65, 3
	v_ashrrev_i32_e32 v5, 31, v2
	s_and_b32 s2, s2, 56
	s_bfe_u32 s3, s65, 0x30003
	v_lshrrev_b32_e32 v5, 26, v5
	s_or_b32 s12, s2, s3
	v_lshlrev_b32_e32 v4, 3, v3
	v_add_u32_e32 v5, v2, v5
	s_mul_i32 s6, s12, 0x180000
	v_and_b32_e32 v4, -16, v4
	v_ashrrev_i32_e32 v70, 6, v5
	s_add_u32 s13, s4, s6
	v_add_u32_e32 v69, v70, v4
	v_and_b32_e32 v4, 0xc0, v5
	s_addc_u32 s23, s5, 0
	v_sub_u32_e32 v2, v2, v4
	s_add_u32 s2, s13, 0x9800000
	v_lshlrev_b32_e32 v3, 5, v3
	v_ashrrev_i16_sdwa v2, v230, sext(v2) dst_sel:DWORD dst_unused:UNUSED_PAD src0_sel:DWORD src1_sel:BYTE_0
	s_addc_u32 s3, s23, 0
	s_lshl_b32 s15, s12, 8
	v_and_b32_e32 v3, 32, v3
	v_bfe_i32 v2, v2, 0, 16
	v_and_b32_e32 v165, 15, v0
	s_add_i32 s15, s15, s9
	v_add_lshl_u32 v71, v3, v2, 1
	v_or_b32_e32 v2, s15, v165
	v_or_b32_e32 v6, 16, v2
	v_ashrrev_i32_e32 v3, 31, v2
	v_ashrrev_i32_e32 v7, 31, v6
	v_lshlrev_b64 v[4:5], 5, v[2:3]
	v_lshlrev_b64 v[6:7], 5, v[6:7]
	v_lshl_add_u64 v[4:5], s[10:11], 0, v[4:5]
	v_lshl_add_u64 v[6:7], s[10:11], 0, v[6:7]
	global_load_dwordx4 v[42:45], v[4:5], off offset:16 sc1
	global_load_dwordx4 v[58:61], v[4:5], off sc1
	global_load_dwordx4 v[34:37], v[6:7], off offset:16 sc1
	global_load_dwordx4 v[62:65], v[6:7], off sc1
	v_or_b32_e32 v6, 32, v2
	v_ashrrev_i32_e32 v7, 31, v6
	v_or_b32_e32 v2, 48, v2
	v_lshlrev_b64 v[6:7], 5, v[6:7]
	v_ashrrev_i32_e32 v3, 31, v2
	v_lshl_add_u64 v[6:7], s[10:11], 0, v[6:7]
	v_lshlrev_b64 v[2:3], 5, v[2:3]
	global_load_dwordx4 v[26:29], v[6:7], off offset:16 sc1
	global_load_dwordx4 v[54:57], v[6:7], off sc1
	v_lshl_add_u64 v[2:3], s[10:11], 0, v[2:3]
	s_mov_b64 s[10:11], 0x1000
	v_add_co_u32_e32 v6, vcc, s81, v4
	global_load_dwordx4 v[18:21], v[2:3], off offset:16 sc1
	global_load_dwordx4 v[50:53], v[2:3], off sc1
	v_lshl_add_u64 v[2:3], v[4:5], 0, s[10:11]
	v_addc_co_u32_e32 v7, vcc, 0, v5, vcc
	s_mov_b64 s[10:11], 0x1200
	global_load_dwordx4 v[38:41], v[6:7], off sc1
	global_load_dwordx4 v[22:25], v[2:3], off offset:16 sc1
	v_lshl_add_u64 v[2:3], v[4:5], 0, s[10:11]
	s_mov_b64 s[10:11], 0x1400
	v_lshl_add_u32 v164, v66, 11, v68
	v_lshl_add_u64 v[14:15], v[4:5], 0, s[10:11]
	s_mov_b64 s[10:11], 0x1600
	v_lshl_add_u64 v[4:5], v[4:5], 0, s[10:11]
	s_add_i32 s17, s16, 0
	v_mov_b32_e32 v72, v164
	v_lshl_add_u32 v166, v69, 11, v71
	global_load_dwordx4 v[30:33], v[6:7], off offset:512 sc1
	global_load_dwordx4 v[10:13], v[6:7], off offset:1024 sc1
	global_load_dwordx4 v[46:49], v[2:3], off offset:16 sc1
	s_nop 0
	global_load_dwordx4 v[6:9], v[6:7], off offset:1536 sc1
	s_nop 0
	global_load_dwordx4 v[14:17], v[14:15], off offset:16 sc1
	s_nop 0
	global_load_dwordx4 v[2:5], v[4:5], off offset:16 sc1
	s_mov_b32 m0, s17
	s_add_i32 s22, s17, 0x2000
	global_load_lds_dwordx4 v72, s[2:3]
	v_mov_b32_e32 v72, v166
	s_mov_b32 m0, s22
	s_add_u32 s10, s13, 0x9840000
	global_load_lds_dwordx4 v72, s[2:3]
	s_addc_u32 s11, s23, 0
	s_add_i32 s23, s17, 0x4000
	v_mov_b32_e32 v72, v164
	s_mov_b32 m0, s23
	s_add_i32 s24, s17, 0x6000
	global_load_lds_dwordx4 v72, s[10:11]
	v_mov_b32_e32 v72, v166
	s_mov_b32 m0, s24
	s_cmp_lg_u32 s8, 1
	global_load_lds_dwordx4 v72, s[10:11]
	s_cbranch_scc1 .LBB0_1569
	s_barrier

.LBB0_1575:
	s_add_u32 s6, s4, 0x6400000
	s_addc_u32 s7, s5, 0
	s_add_u32 s2, s4, 0x6300000
	s_addc_u32 s3, s5, 0
	s_lshl_b32 s4, s12, 5
	s_lshl_b32 s5, s13, 8
	s_or_b32 s4, s5, s4
	s_lshl_b32 s8, s13, 2
	v_lshl_add_u32 v2, v240, 3, s4
	v_add_u32_e32 v224, s15, v165
	v_ashrrev_i32_e32 v3, 31, v2
	v_lshlrev_b64 v[226:227], 1, v[2:3]
	v_ashrrev_i32_e32 v225, 31, v224
	v_lshl_add_u64 v[124:125], s[6:7], 0, v[226:227]
	v_lshlrev_b64 v[228:229], 11, v[224:225]
	v_lshl_add_u64 v[116:117], v[124:125], 0, v[228:229]
	global_load_dwordx4 v[192:195], v[116:117], off sc1
	global_load_dwordx4 v[188:191], v[116:117], off offset:256 sc1
	v_add_u32_e32 v220, 16, v224
	v_ashrrev_i32_e32 v221, 31, v220
	v_add_u32_e32 v216, 32, v224
	v_lshlrev_b64 v[222:223], 11, v[220:221]
	v_ashrrev_i32_e32 v217, 31, v216
	v_add_u32_e32 v212, 48, v224
	v_lshl_add_u64 v[116:117], v[124:125], 0, v[222:223]
	v_lshlrev_b64 v[218:219], 11, v[216:217]
	v_ashrrev_i32_e32 v213, 31, v212
	v_add_u32_e32 v208, 0x80, v224
	global_load_dwordx4 v[184:187], v[116:117], off sc1
	global_load_dwordx4 v[180:183], v[116:117], off offset:256 sc1
	v_lshl_add_u64 v[116:117], v[124:125], 0, v[218:219]
	v_lshlrev_b64 v[214:215], 11, v[212:213]
	v_ashrrev_i32_e32 v209, 31, v208
	v_add_u32_e32 v204, 0x90, v224
	global_load_dwordx4 v[176:179], v[116:117], off sc1
	global_load_dwordx4 v[172:175], v[116:117], off offset:256 sc1
	v_lshl_add_u64 v[116:117], v[124:125], 0, v[214:215]
	v_lshlrev_b64 v[210:211], 11, v[208:209]
	v_ashrrev_i32_e32 v205, 31, v204
	v_add_u32_e32 v198, 0xa0, v224
	v_add_u32_e32 v196, 0xb0, v224
	global_load_dwordx4 v[168:171], v[116:117], off sc1
	global_load_dwordx4 v[164:167], v[116:117], off offset:256 sc1
	v_lshl_add_u64 v[116:117], v[124:125], 0, v[210:211]
	v_lshlrev_b64 v[206:207], 11, v[204:205]
	v_ashrrev_i32_e32 v199, 31, v198
	v_ashrrev_i32_e32 v197, 31, v196
	global_load_dwordx4 v[152:155], v[116:117], off sc1
	global_load_dwordx4 v[148:151], v[116:117], off offset:256 sc1
	v_lshl_add_u64 v[116:117], v[124:125], 0, v[206:207]
	v_lshlrev_b64 v[202:203], 11, v[198:199]
	v_lshlrev_b64 v[200:201], 11, v[196:197]
	global_load_dwordx4 v[144:147], v[116:117], off sc1
	global_load_dwordx4 v[140:143], v[116:117], off offset:256 sc1
	v_lshl_add_u64 v[116:117], v[124:125], 0, v[202:203]
	v_lshl_add_u64 v[124:125], v[124:125], 0, v[200:201]
	global_load_dwordx4 v[132:135], v[116:117], off sc1
	s_nop 0
	global_load_dwordx4 v[116:119], v[116:117], off offset:256 sc1
	s_nop 0
	global_load_dwordx4 v[136:139], v[124:125], off sc1
	s_nop 0
	global_load_dwordx4 v[124:127], v[124:125], off offset:256 sc1
	v_cmp_eq_u32_e32 vcc, 0, v240
	s_waitcnt vmcnt(0)
	v_lshlrev_b32_e32 v232, 16, v192
	v_and_b32_e32 v233, 0xffff0000, v192
	v_lshlrev_b32_e32 v192, 16, v193
	v_and_b32_e32 v193, 0xffff0000, v193
	v_lshlrev_b32_e32 v234, 16, v194
	v_and_b32_e32 v235, 0xffff0000, v194
	v_lshlrev_b32_e32 v194, 16, v195
	v_and_b32_e32 v195, 0xffff0000, v195
	v_pk_add_f32 v[162:163], v[162:163], v[192:193]
	v_pk_add_f32 v[192:193], v[158:159], v[194:195]
	v_pk_add_f32 v[194:195], v[156:157], v[234:235]
	v_lshl_add_u64 v[156:157], s[6:7], 0, v[228:229]
	v_pk_add_f32 v[160:161], v[160:161], v[232:233]
	v_lshl_add_u64 v[226:227], v[156:157], 0, v[226:227]
	v_cvt_pk_bf16_f32 v156, v160, v161
	v_cvt_pk_bf16_f32 v157, v162, v163
	v_cvt_pk_bf16_f32 v158, v194, v195
	v_cvt_pk_bf16_f32 v159, v192, v193
	global_store_dwordx4 v[226:227], v[156:159], off
	v_mul_f32_e32 v0, v161, v161
	v_fmac_f32_e32 v0, v160, v160
	v_mul_f32_e32 v156, v163, v163
	v_fmac_f32_e32 v156, v162, v162
	v_add_f32_e32 v0, v0, v156
	v_mul_f32_e32 v156, v195, v195
	v_fmac_f32_e32 v156, v194, v194
	v_add_f32_e32 v0, v156, v0
	v_mul_f32_e32 v156, v193, v193
	v_fmac_f32_e32 v156, v192, v192
	v_add_f32_e32 v0, v156, v0
	v_lshlrev_b32_e32 v156, 16, v188
	v_and_b32_e32 v157, 0xffff0000, v188
	v_lshlrev_b32_e32 v158, 16, v189
	v_and_b32_e32 v159, 0xffff0000, v189
	v_lshlrev_b32_e32 v160, 16, v190
	v_and_b32_e32 v161, 0xffff0000, v190
	v_lshlrev_b32_e32 v162, 16, v191
	v_and_b32_e32 v163, 0xffff0000, v191
	v_pk_add_f32 v[130:131], v[130:131], v[158:159]
	v_pk_add_f32 v[128:129], v[128:129], v[156:157]
	v_pk_add_f32 v[158:159], v[120:121], v[160:161]
	v_cvt_pk_bf16_f32 v120, v128, v129
	v_cvt_pk_bf16_f32 v121, v130, v131
	v_pk_add_f32 v[156:157], v[122:123], v[162:163]
	v_cvt_pk_bf16_f32 v122, v158, v159
	s_nop 0
	v_cvt_pk_bf16_f32 v123, v156, v157
	global_store_dwordx4 v[226:227], v[120:123], off offset:256
	s_nop 1
	v_mul_f32_e32 v120, v129, v129
	v_mul_f32_e32 v121, v131, v131
	v_fmac_f32_e32 v120, v128, v128
	v_fmac_f32_e32 v121, v130, v130
	v_add_f32_e32 v120, v120, v121
	v_mul_f32_e32 v121, v159, v159
	v_fmac_f32_e32 v121, v158, v158
	v_add_f32_e32 v120, v121, v120
	v_mul_f32_e32 v121, v157, v157
	v_fmac_f32_e32 v121, v156, v156
	v_add_f32_e32 v120, v121, v120
	v_add_f32_e32 v0, v0, v120
	ds_swizzle_b32 v120, v0 offset:swizzle(SWAP,16)
	s_waitcnt lgkmcnt(0)
	v_add_f32_e32 v0, v0, v120
	v_mov_b32_e32 v120, v0
	s_nop 1
	v_permlane32_swap_b32_e32 v0, v120
	s_and_saveexec_b64 s[4:5], vcc
	s_cbranch_execz .LBB0_1577
	v_lshlrev_b64 v[122:123], 6, v[224:225]
	v_lshl_add_u64 v[122:123], s[2:3], 0, v[122:123]
	s_lshl_b32 s26, s8, 2
	v_lshl_add_u64 v[122:123], v[122:123], 0, s[26:27]
	s_lshl_b32 s26, s12, 2
	v_lshl_add_u64 v[122:123], v[122:123], 0, s[26:27]
	v_add_f32_e32 v0, v0, v120
	global_store_dword v[122:123], v0, off

.LBB0_1684:
	s_mov_b64 s[2:3], 0x6300000
	v_add_u32_e32 v130, s41, v133
	v_lshl_add_u32 v132, s14, 8, v130
	v_ashrrev_i32_e32 v133, 31, v132
	v_lshlrev_b64 v[132:133], 6, v[132:133]
	v_lshl_add_u64 v[142:143], s[4:5], 0, v[132:133]
	v_lshl_add_u64 v[132:133], v[142:143], 0, s[2:3]
	v_add_co_u32_e32 v142, vcc, 0x6300000, v142
	global_load_dwordx4 v[134:137], v[132:133], off offset:16 sc1
	global_load_dwordx4 v[138:141], v[132:133], off offset:32 sc1
	v_addc_co_u32_e32 v143, vcc, 0, v143, vcc
	global_load_dwordx4 v[142:145], v[142:143], off sc1
	s_nop 0
	global_load_dwordx4 v[146:149], v[132:133], off offset:48 sc1
	s_mov_b32 s2, 0xff61b1e6
	s_waitcnt vmcnt(0)
	v_mov_b32_e32 v154, v134
	v_mov_b32_e32 v151, v138
	v_mov_b32_e32 v153, v140
	v_mov_b32_e32 v134, v136
	v_mov_b32_e32 v150, v142
	v_mov_b32_e32 v138, v143
	v_mov_b32_e32 v152, v144
	v_mov_b32_e32 v140, v145
	v_mov_b32_e32 v155, v146
	v_mov_b32_e32 v146, v135
	v_mov_b32_e32 v135, v148
	v_mov_b32_e32 v148, v137
	v_pk_add_f32 v[136:137], v[150:151], v[138:139]
	v_pk_add_f32 v[138:139], v[152:153], v[140:141]
	v_pk_add_f32 v[140:141], v[154:155], v[146:147]
	v_pk_add_f32 v[134:135], v[134:135], v[148:149]
	v_pk_add_f32 v[136:137], v[136:137], v[138:139]
	v_pk_add_f32 v[134:135], v[140:141], v[134:135]
	s_nop 0
	v_pk_add_f32 v[134:135], v[136:137], v[134:135]
	s_nop 0
	v_add_f32_e32 v0, v134, v135
	v_fmamk_f32 v0, v0, 0x3a800000, v231
	v_rsq_f32_e32 v0, v0
	s_nop 0
	v_pk_mul_f32 v[128:129], v[128:129], v[0:1] op_sel_hi:[1,0]
	v_pk_mul_f32 v[124:125], v[124:125], v[0:1] op_sel_hi:[1,0]
	v_pk_mul_f32 v[126:127], v[126:127], v[0:1] op_sel_hi:[1,0]
	v_pk_mul_f32 v[122:123], v[122:123], v[0:1] op_sel_hi:[1,0]
	v_pk_mul_f32 v[120:121], v[120:121], v[0:1] op_sel_hi:[1,0]
	v_pk_mul_f32 v[118:119], v[118:119], v[0:1] op_sel_hi:[1,0]
	v_pk_mul_f32 v[116:117], v[116:117], v[0:1] op_sel_hi:[1,0]
	v_pk_mul_f32 v[114:115], v[114:115], v[0:1] op_sel_hi:[1,0]
	v_max_f32_e32 v0, v128, v129
	v_max_f32_e32 v134, v124, v125
	v_max_f32_e32 v135, v120, v121
	v_max_f32_e32 v136, v116, v117
	v_max3_f32 v0, v126, v127, v0
	v_max3_f32 v134, v122, v123, v134
	v_max3_f32 v135, v118, v119, v135
	v_max3_f32 v136, v114, v115, v136
	v_max3_f32 v0, v0, s2, v134
	v_max3_f32 v0, v0, v135, v136
	ds_swizzle_b32 v134, v0 offset:swizzle(SWAP,16)
	s_lshl_b32 s2, s16, 2
	s_add_i32 s8, s2, 0
	v_cmp_eq_u32_e64 s[2:3], 0, v131
	s_add_i32 s9, s8, 0x20000
	s_waitcnt lgkmcnt(0)
	v_max_f32_e32 v134, v134, v134
	v_max_f32_e32 v0, v0, v134
	v_mov_b32_e32 v134, v0
	s_nop 1
	v_permlane32_swap_b32_e32 v0, v134
	s_and_saveexec_b64 s[6:7], s[2:3]
	v_max_f32_e32 v0, v0, v0
	v_max_f32_e32 v134, v134, v134
	v_lshl_add_u32 v135, v130, 4, s9
	v_max_f32_e32 v0, v0, v134
	ds_write_b32 v135, v0
	s_or_b64 exec, exec, s[6:7]
	global_load_dwordx4 v[134:137], v[132:133], off offset:1024 sc1
	global_load_dwordx4 v[138:141], v[132:133], off offset:1056 sc1
	global_load_dwordx4 v[142:145], v[132:133], off offset:1040 sc1
	global_load_dwordx4 v[146:149], v[132:133], off offset:1072 sc1
	s_mov_b32 s6, 0xff61b1e6
	s_waitcnt vmcnt(3)
	v_mov_b32_e32 v150, v134
	s_waitcnt vmcnt(2)
	v_mov_b32_e32 v151, v138
	v_mov_b32_e32 v138, v135
	v_mov_b32_e32 v134, v136
	v_mov_b32_e32 v135, v140
	v_mov_b32_e32 v140, v137
	s_waitcnt vmcnt(1)
	v_mov_b32_e32 v136, v142
	s_waitcnt vmcnt(0)
	v_mov_b32_e32 v137, v146
	v_mov_b32_e32 v146, v143
	v_mov_b32_e32 v142, v144
	v_mov_b32_e32 v143, v148
	v_mov_b32_e32 v148, v145
	v_pk_add_f32 v[138:139], v[150:151], v[138:139]
	v_pk_add_f32 v[134:135], v[134:135], v[140:141]
	v_pk_add_f32 v[136:137], v[136:137], v[146:147]
	v_pk_add_f32 v[140:141], v[142:143], v[148:149]
	v_pk_add_f32 v[134:135], v[138:139], v[134:135]
	v_pk_add_f32 v[136:137], v[136:137], v[140:141]
	v_add_u32_e32 v140, 16, v130
	v_pk_add_f32 v[134:135], v[134:135], v[136:137]
	s_nop 0
	v_add_f32_e32 v0, v134, v135
	v_fmamk_f32 v0, v0, 0x3a800000, v231
	v_rsq_f32_e32 v0, v0
	s_nop 0
	v_pk_mul_f32 v[112:113], v[112:113], v[0:1] op_sel_hi:[1,0]
	v_pk_mul_f32 v[108:109], v[108:109], v[0:1] op_sel_hi:[1,0]
	v_pk_mul_f32 v[110:111], v[110:111], v[0:1] op_sel_hi:[1,0]
	v_pk_mul_f32 v[106:107], v[106:107], v[0:1] op_sel_hi:[1,0]
	v_pk_mul_f32 v[104:105], v[104:105], v[0:1] op_sel_hi:[1,0]
	v_pk_mul_f32 v[102:103], v[102:103], v[0:1] op_sel_hi:[1,0]
	v_pk_mul_f32 v[100:101], v[100:101], v[0:1] op_sel_hi:[1,0]
	v_pk_mul_f32 v[98:99], v[98:99], v[0:1] op_sel_hi:[1,0]
	v_max_f32_e32 v0, v112, v113
	v_max_f32_e32 v134, v108, v109
	v_max_f32_e32 v135, v104, v105
	v_max_f32_e32 v136, v100, v101
	v_max3_f32 v0, v110, v111, v0
	v_max3_f32 v134, v106, v107, v134
	v_max3_f32 v135, v102, v103, v135
	v_max3_f32 v136, v98, v99, v136
	v_max3_f32 v0, v0, s6, v134
	v_max3_f32 v0, v0, v135, v136
	ds_swizzle_b32 v134, v0 offset:swizzle(SWAP,16)
	s_waitcnt lgkmcnt(0)
	v_max_f32_e32 v134, v134, v134
	v_max_f32_e32 v0, v0, v134
	v_mov_b32_e32 v134, v0
	s_nop 1
	v_permlane32_swap_b32_e32 v0, v134
	s_and_saveexec_b64 s[6:7], s[2:3]
	v_max_f32_e32 v0, v0, v0
	v_max_f32_e32 v134, v134, v134
	v_lshl_add_u32 v135, v140, 4, s9
	v_max_f32_e32 v0, v0, v134
	ds_write_b32 v135, v0
	s_or_b64 exec, exec, s[6:7]
	global_load_dwordx4 v[134:137], v[132:133], off offset:2048 sc1
	global_load_dwordx4 v[142:145], v[132:133], off offset:2080 sc1
	global_load_dwordx4 v[146:149], v[132:133], off offset:2064 sc1
	global_load_dwordx4 v[150:153], v[132:133], off offset:2096 sc1
	s_mov_b32 s6, 0xff61b1e6
	v_add_u32_e32 v141, 32, v130
	s_waitcnt vmcnt(3)
	v_mov_b32_e32 v138, v134
	s_waitcnt vmcnt(2)
	v_mov_b32_e32 v139, v142
	v_mov_b32_e32 v142, v135
	v_mov_b32_e32 v134, v136
	v_mov_b32_e32 v135, v144
	v_mov_b32_e32 v144, v137
	s_waitcnt vmcnt(1)
	v_mov_b32_e32 v136, v146
	s_waitcnt vmcnt(0)
	v_mov_b32_e32 v137, v150
	v_mov_b32_e32 v150, v147
	v_mov_b32_e32 v146, v148
	v_mov_b32_e32 v147, v152
	v_mov_b32_e32 v152, v149
	v_pk_add_f32 v[138:139], v[138:139], v[142:143]
	v_pk_add_f32 v[134:135], v[134:135], v[144:145]
	v_pk_add_f32 v[136:137], v[136:137], v[150:151]
	v_pk_add_f32 v[142:143], v[146:147], v[152:153]
	v_pk_add_f32 v[134:135], v[138:139], v[134:135]
	v_pk_add_f32 v[136:137], v[136:137], v[142:143]
	s_nop 0
	v_pk_add_f32 v[134:135], v[134:135], v[136:137]
	s_nop 0
	v_add_f32_e32 v0, v134, v135
	v_fmamk_f32 v0, v0, 0x3a800000, v231
	v_rsq_f32_e32 v0, v0
	s_nop 0
	v_pk_mul_f32 v[96:97], v[96:97], v[0:1] op_sel_hi:[1,0]
	v_pk_mul_f32 v[92:93], v[92:93], v[0:1] op_sel_hi:[1,0]
	v_pk_mul_f32 v[94:95], v[94:95], v[0:1] op_sel_hi:[1,0]
	v_pk_mul_f32 v[90:91], v[90:91], v[0:1] op_sel_hi:[1,0]
	v_pk_mul_f32 v[88:89], v[88:89], v[0:1] op_sel_hi:[1,0]
	v_pk_mul_f32 v[86:87], v[86:87], v[0:1] op_sel_hi:[1,0]
	v_pk_mul_f32 v[84:85], v[84:85], v[0:1] op_sel_hi:[1,0]
	v_pk_mul_f32 v[82:83], v[82:83], v[0:1] op_sel_hi:[1,0]
	v_max_f32_e32 v0, v96, v97
	v_max_f32_e32 v134, v92, v93
	v_max_f32_e32 v135, v88, v89
	v_max_f32_e32 v136, v84, v85
	v_max3_f32 v0, v94, v95, v0
	v_max3_f32 v134, v90, v91, v134
	v_max3_f32 v135, v86, v87, v135
	v_max3_f32 v136, v82, v83, v136
	v_max3_f32 v0, v0, s6, v134
	v_max3_f32 v0, v0, v135, v136
	ds_swizzle_b32 v134, v0 offset:swizzle(SWAP,16)
	s_waitcnt lgkmcnt(0)
	v_max_f32_e32 v134, v134, v134
	v_max_f32_e32 v0, v0, v134
	v_mov_b32_e32 v134, v0
	s_nop 1
	v_permlane32_swap_b32_e32 v0, v134
	s_and_saveexec_b64 s[6:7], s[2:3]
	v_max_f32_e32 v0, v0, v0
	v_max_f32_e32 v134, v134, v134
	v_lshl_add_u32 v135, v141, 4, s9
	v_max_f32_e32 v0, v0, v134
	ds_write_b32 v135, v0
	s_or_b64 exec, exec, s[6:7]
	global_load_dwordx4 v[134:137], v[132:133], off offset:3072 sc1
	global_load_dwordx4 v[142:145], v[132:133], off offset:3104 sc1
	global_load_dwordx4 v[146:149], v[132:133], off offset:3088 sc1
	global_load_dwordx4 v[150:153], v[132:133], off offset:3120 sc1
	s_mov_b32 s6, 0xff61b1e6
	s_waitcnt vmcnt(3)
	v_mov_b32_e32 v138, v134
	s_waitcnt vmcnt(2)
	v_mov_b32_e32 v139, v142
	v_mov_b32_e32 v142, v135
	v_mov_b32_e32 v134, v136
	v_mov_b32_e32 v135, v144
	v_mov_b32_e32 v144, v137
	s_waitcnt vmcnt(1)
	v_mov_b32_e32 v136, v146
	s_waitcnt vmcnt(0)
	v_mov_b32_e32 v137, v150
	v_mov_b32_e32 v150, v147
	v_mov_b32_e32 v146, v148
	v_mov_b32_e32 v147, v152
	v_mov_b32_e32 v152, v149
	v_pk_add_f32 v[138:139], v[138:139], v[142:143]
	v_pk_add_f32 v[134:135], v[134:135], v[144:145]
	v_pk_add_f32 v[136:137], v[136:137], v[150:151]
	v_pk_add_f32 v[142:143], v[146:147], v[152:153]
	v_pk_add_f32 v[134:135], v[138:139], v[134:135]
	v_pk_add_f32 v[136:137], v[136:137], v[142:143]
	v_add_u32_e32 v142, 48, v130
	v_pk_add_f32 v[134:135], v[134:135], v[136:137]
	s_nop 0
	v_add_f32_e32 v0, v134, v135
	v_fmamk_f32 v0, v0, 0x3a800000, v231
	v_rsq_f32_e32 v0, v0
	s_nop 0
	v_pk_mul_f32 v[80:81], v[80:81], v[0:1] op_sel_hi:[1,0]
	v_pk_mul_f32 v[76:77], v[76:77], v[0:1] op_sel_hi:[1,0]
	v_pk_mul_f32 v[78:79], v[78:79], v[0:1] op_sel_hi:[1,0]
	v_pk_mul_f32 v[74:75], v[74:75], v[0:1] op_sel_hi:[1,0]
	v_pk_mul_f32 v[72:73], v[72:73], v[0:1] op_sel_hi:[1,0]
	v_pk_mul_f32 v[70:71], v[70:71], v[0:1] op_sel_hi:[1,0]
	v_pk_mul_f32 v[68:69], v[68:69], v[0:1] op_sel_hi:[1,0]
	v_pk_mul_f32 v[66:67], v[66:67], v[0:1] op_sel_hi:[1,0]
	v_max_f32_e32 v0, v80, v81
	v_max_f32_e32 v134, v76, v77
	v_max_f32_e32 v135, v72, v73
	v_max_f32_e32 v136, v68, v69
	v_max3_f32 v0, v78, v79, v0
	v_max3_f32 v134, v74, v75, v134
	v_max3_f32 v135, v70, v71, v135
	v_max3_f32 v136, v66, v67, v136
	v_max3_f32 v0, v0, s6, v134
	v_max3_f32 v0, v0, v135, v136
	ds_swizzle_b32 v134, v0 offset:swizzle(SWAP,16)
	s_waitcnt lgkmcnt(0)
	v_max_f32_e32 v134, v134, v134
	v_max_f32_e32 v0, v0, v134
	v_mov_b32_e32 v134, v0
	s_nop 1
	v_permlane32_swap_b32_e32 v0, v134
	s_and_saveexec_b64 s[6:7], s[2:3]
	v_max_f32_e32 v0, v0, v0
	v_max_f32_e32 v134, v134, v134
	v_lshl_add_u32 v135, v142, 4, s9
	v_max_f32_e32 v0, v0, v134
	ds_write_b32 v135, v0
	s_or_b64 exec, exec, s[6:7]
	v_add_co_u32_e32 v134, vcc, 0x2000, v132
	s_mov_b64 s[6:7], 0x2000
	s_nop 0
	v_addc_co_u32_e32 v135, vcc, 0, v133, vcc
	v_lshl_add_u64 v[138:139], v[132:133], 0, s[6:7]
	global_load_dwordx4 v[134:137], v[134:135], off sc1
	s_nop 0
	global_load_dwordx4 v[144:147], v[138:139], off offset:16 sc1
	global_load_dwordx4 v[148:151], v[138:139], off offset:48 sc1
	global_load_dwordx4 v[152:155], v[138:139], off offset:32 sc1
	s_mov_b32 s6, 0xff61b1e6
	v_add_u32_e32 v0, 0x80, v130
	s_waitcnt vmcnt(3)
	v_mov_b32_e32 v138, v134
	s_waitcnt vmcnt(0)
	v_mov_b32_e32 v139, v152
	v_mov_b32_e32 v152, v135
	v_pk_add_f32 v[134:135], v[138:139], v[152:153]
	v_mov_b32_e32 v138, v136
	v_mov_b32_e32 v139, v154
	v_mov_b32_e32 v154, v137
	v_pk_add_f32 v[136:137], v[138:139], v[154:155]
	v_mov_b32_e32 v138, v146
	v_pk_add_f32 v[134:135], v[134:135], v[136:137]
	v_mov_b32_e32 v136, v144
	v_mov_b32_e32 v137, v148
	v_mov_b32_e32 v148, v145
	v_mov_b32_e32 v139, v150
	v_mov_b32_e32 v150, v147
	v_pk_add_f32 v[136:137], v[136:137], v[148:149]
	v_pk_add_f32 v[138:139], v[138:139], v[150:151]
	s_nop 0
	v_pk_add_f32 v[136:137], v[136:137], v[138:139]
	s_nop 0
	v_pk_add_f32 v[134:135], v[134:135], v[136:137]
	s_nop 0
	v_add_f32_e32 v134, v134, v135
	v_fmamk_f32 v134, v134, 0x3a800000, v231
	v_rsq_f32_e32 v134, v134
	s_nop 0
	v_pk_mul_f32 v[64:65], v[64:65], v[134:135] op_sel_hi:[1,0]
	v_pk_mul_f32 v[62:63], v[62:63], v[134:135] op_sel_hi:[1,0]
	v_max_f32_e32 v135, v64, v65
	v_max3_f32 v135, v62, v63, v135
	v_pk_mul_f32 v[60:61], v[60:61], v[134:135] op_sel_hi:[1,0]
	v_pk_mul_f32 v[58:59], v[58:59], v[134:135] op_sel_hi:[1,0]
	v_max_f32_e32 v136, v60, v61
	v_max3_f32 v136, v58, v59, v136
	v_max3_f32 v135, v135, s6, v136
	v_pk_mul_f32 v[56:57], v[56:57], v[134:135] op_sel_hi:[1,0]
	v_pk_mul_f32 v[52:53], v[52:53], v[134:135] op_sel_hi:[1,0]
	v_pk_mul_f32 v[54:55], v[54:55], v[134:135] op_sel_hi:[1,0]
	v_max_f32_e32 v136, v56, v57
	v_pk_mul_f32 v[50:51], v[50:51], v[134:135] op_sel_hi:[1,0]
	v_max_f32_e32 v134, v52, v53
	v_max3_f32 v136, v54, v55, v136
	v_max3_f32 v134, v50, v51, v134
	v_max3_f32 v134, v135, v136, v134
	ds_swizzle_b32 v135, v134 offset:swizzle(SWAP,16)
	s_waitcnt lgkmcnt(0)
	v_max_f32_e32 v135, v135, v135
	v_max_f32_e32 v134, v134, v135
	v_mov_b32_e32 v135, v134
	s_nop 1
	v_permlane32_swap_b32_e32 v134, v135
	s_and_saveexec_b64 s[6:7], s[2:3]
	v_max_f32_e32 v134, v134, v134
	v_max_f32_e32 v135, v135, v135
	v_lshl_add_u32 v136, v0, 4, s9
	v_max_f32_e32 v134, v134, v135
	ds_write_b32 v136, v134
	s_or_b64 exec, exec, s[6:7]
	v_add_co_u32_e32 v134, vcc, 0x2000, v132
	s_mov_b64 s[6:7], 0x2400
	s_nop 0
	v_addc_co_u32_e32 v135, vcc, 0, v133, vcc
	v_lshl_add_u64 v[138:139], v[132:133], 0, s[6:7]
	global_load_dwordx4 v[134:137], v[134:135], off offset:1024 sc1
	s_nop 0
	global_load_dwordx4 v[144:147], v[138:139], off offset:16 sc1
	global_load_dwordx4 v[148:151], v[138:139], off offset:48 sc1
	global_load_dwordx4 v[152:155], v[138:139], off offset:32 sc1
	s_mov_b32 s6, 0xff61b1e6
	v_add_u32_e32 v143, 0x90, v130
	s_waitcnt vmcnt(3)
	v_mov_b32_e32 v138, v134
	s_waitcnt vmcnt(0)
	v_mov_b32_e32 v139, v152
	v_mov_b32_e32 v152, v135
	v_pk_add_f32 v[134:135], v[138:139], v[152:153]
	v_mov_b32_e32 v138, v136
	v_mov_b32_e32 v139, v154
	v_mov_b32_e32 v154, v137
	v_pk_add_f32 v[136:137], v[138:139], v[154:155]
	v_mov_b32_e32 v138, v146
	v_pk_add_f32 v[134:135], v[134:135], v[136:137]
	v_mov_b32_e32 v136, v144
	v_mov_b32_e32 v137, v148
	v_mov_b32_e32 v148, v145
	v_mov_b32_e32 v139, v150
	v_mov_b32_e32 v150, v147
	v_pk_add_f32 v[136:137], v[136:137], v[148:149]
	v_pk_add_f32 v[138:139], v[138:139], v[150:151]
	s_nop 0
	v_pk_add_f32 v[136:137], v[136:137], v[138:139]
	s_nop 0
	v_pk_add_f32 v[134:135], v[134:135], v[136:137]
	s_nop 0
	v_add_f32_e32 v134, v134, v135
	v_fmamk_f32 v134, v134, 0x3a800000, v231
	v_rsq_f32_e32 v134, v134
	s_nop 0
	v_pk_mul_f32 v[48:49], v[48:49], v[134:135] op_sel_hi:[1,0]
	v_pk_mul_f32 v[46:47], v[46:47], v[134:135] op_sel_hi:[1,0]
	v_max_f32_e32 v135, v48, v49
	v_max3_f32 v135, v46, v47, v135
	v_pk_mul_f32 v[44:45], v[44:45], v[134:135] op_sel_hi:[1,0]
	v_pk_mul_f32 v[42:43], v[42:43], v[134:135] op_sel_hi:[1,0]
	v_max_f32_e32 v136, v44, v45
	v_max3_f32 v136, v42, v43, v136
	v_max3_f32 v135, v135, s6, v136
	v_pk_mul_f32 v[40:41], v[40:41], v[134:135] op_sel_hi:[1,0]
	v_pk_mul_f32 v[36:37], v[36:37], v[134:135] op_sel_hi:[1,0]
	v_pk_mul_f32 v[38:39], v[38:39], v[134:135] op_sel_hi:[1,0]
	v_max_f32_e32 v136, v40, v41
	v_pk_mul_f32 v[34:35], v[34:35], v[134:135] op_sel_hi:[1,0]
	v_max_f32_e32 v134, v36, v37
	v_max3_f32 v136, v38, v39, v136
	v_max3_f32 v134, v34, v35, v134
	v_max3_f32 v134, v135, v136, v134
	ds_swizzle_b32 v135, v134 offset:swizzle(SWAP,16)
	s_waitcnt lgkmcnt(0)
	v_max_f32_e32 v135, v135, v135
	v_max_f32_e32 v134, v134, v135
	v_mov_b32_e32 v135, v134
	s_nop 1
	v_permlane32_swap_b32_e32 v134, v135
	s_and_saveexec_b64 s[6:7], s[2:3]
	v_max_f32_e32 v134, v134, v134
	v_max_f32_e32 v135, v135, v135
	v_lshl_add_u32 v136, v143, 4, s9
	v_max_f32_e32 v134, v134, v135
	ds_write_b32 v136, v134
	s_or_b64 exec, exec, s[6:7]
	v_add_co_u32_e32 v134, vcc, 0x2000, v132
	s_mov_b64 s[6:7], 0x2800
	s_nop 0
	v_addc_co_u32_e32 v135, vcc, 0, v133, vcc
	v_lshl_add_u64 v[138:139], v[132:133], 0, s[6:7]
	global_load_dwordx4 v[134:137], v[134:135], off offset:2048 sc1
	s_nop 0
	global_load_dwordx4 v[144:147], v[138:139], off offset:16 sc1
	global_load_dwordx4 v[148:151], v[138:139], off offset:48 sc1
	global_load_dwordx4 v[152:155], v[138:139], off offset:32 sc1
	s_mov_b32 s6, 0xff61b1e6
	s_waitcnt vmcnt(3)
	v_mov_b32_e32 v138, v134
	s_waitcnt vmcnt(0)
	v_mov_b32_e32 v139, v152
	v_mov_b32_e32 v152, v135
	v_pk_add_f32 v[134:135], v[138:139], v[152:153]
	v_mov_b32_e32 v138, v136
	v_mov_b32_e32 v139, v154
	v_mov_b32_e32 v154, v137
	v_pk_add_f32 v[136:137], v[138:139], v[154:155]
	v_mov_b32_e32 v138, v146
	v_pk_add_f32 v[134:135], v[134:135], v[136:137]
	v_mov_b32_e32 v136, v144
	v_mov_b32_e32 v137, v148
	v_mov_b32_e32 v148, v145
	v_mov_b32_e32 v139, v150
	v_mov_b32_e32 v150, v147
	v_pk_add_f32 v[136:137], v[136:137], v[148:149]
	v_pk_add_f32 v[138:139], v[138:139], v[150:151]
	v_add_u32_e32 v144, 0xa0, v130
	v_pk_add_f32 v[136:137], v[136:137], v[138:139]
	s_nop 0
	v_pk_add_f32 v[134:135], v[134:135], v[136:137]
	s_nop 0
	v_add_f32_e32 v134, v134, v135
	v_fmamk_f32 v134, v134, 0x3a800000, v231
	v_rsq_f32_e32 v134, v134
	s_nop 0
	v_pk_mul_f32 v[32:33], v[32:33], v[134:135] op_sel_hi:[1,0]
	v_pk_mul_f32 v[30:31], v[30:31], v[134:135] op_sel_hi:[1,0]
	v_max_f32_e32 v135, v32, v33
	v_max3_f32 v135, v30, v31, v135
	v_pk_mul_f32 v[28:29], v[28:29], v[134:135] op_sel_hi:[1,0]
	v_pk_mul_f32 v[26:27], v[26:27], v[134:135] op_sel_hi:[1,0]
	v_max_f32_e32 v136, v28, v29
	v_max3_f32 v136, v26, v27, v136
	v_max3_f32 v135, v135, s6, v136
	v_pk_mul_f32 v[24:25], v[24:25], v[134:135] op_sel_hi:[1,0]
	v_pk_mul_f32 v[20:21], v[20:21], v[134:135] op_sel_hi:[1,0]
	v_pk_mul_f32 v[22:23], v[22:23], v[134:135] op_sel_hi:[1,0]
	v_max_f32_e32 v136, v24, v25
	v_pk_mul_f32 v[18:19], v[18:19], v[134:135] op_sel_hi:[1,0]
	v_max_f32_e32 v134, v20, v21
	v_max3_f32 v136, v22, v23, v136
	v_max3_f32 v134, v18, v19, v134
	v_max3_f32 v134, v135, v136, v134
	ds_swizzle_b32 v135, v134 offset:swizzle(SWAP,16)
	s_waitcnt lgkmcnt(0)
	v_max_f32_e32 v135, v135, v135
	v_max_f32_e32 v134, v134, v135
	v_mov_b32_e32 v135, v134
	s_nop 1
	v_permlane32_swap_b32_e32 v134, v135
	s_and_saveexec_b64 s[6:7], s[2:3]
	v_max_f32_e32 v134, v134, v134
	v_max_f32_e32 v135, v135, v135
	v_lshl_add_u32 v136, v144, 4, s9
	v_max_f32_e32 v134, v134, v135
	ds_write_b32 v136, v134
	s_or_b64 exec, exec, s[6:7]
	s_mov_b64 s[6:7], 0x2c00
	v_lshl_add_u64 v[150:151], v[132:133], 0, s[6:7]
	v_add_co_u32_e32 v132, vcc, 0x2000, v132
	s_mov_b32 s6, 0xff61b1e6
	s_nop 0
	v_addc_co_u32_e32 v133, vcc, 0, v133, vcc
	global_load_dwordx4 v[132:135], v[132:133], off offset:3072 sc1
	s_nop 0
	global_load_dwordx4 v[136:139], v[150:151], off offset:16 sc1
	global_load_dwordx4 v[146:149], v[150:151], off offset:48 sc1
	s_nop 0
	global_load_dwordx4 v[150:153], v[150:151], off offset:32 sc1
	v_add_u32_e32 v145, 0xb0, v130
	s_waitcnt vmcnt(3)
	v_mov_b32_e32 v154, v132
	s_waitcnt vmcnt(0)
	v_mov_b32_e32 v155, v150
	v_mov_b32_e32 v150, v133
	v_pk_add_f32 v[132:133], v[154:155], v[150:151]
	v_mov_b32_e32 v150, v134
	v_mov_b32_e32 v151, v152
	v_mov_b32_e32 v152, v135
	v_pk_add_f32 v[134:135], v[150:151], v[152:153]
	s_nop 0
	v_pk_add_f32 v[132:133], v[132:133], v[134:135]
	v_mov_b32_e32 v134, v136
	v_mov_b32_e32 v135, v146
	v_mov_b32_e32 v146, v137
	v_mov_b32_e32 v136, v138
	v_mov_b32_e32 v137, v148
	v_mov_b32_e32 v148, v139
	v_pk_add_f32 v[134:135], v[134:135], v[146:147]
	v_pk_add_f32 v[136:137], v[136:137], v[148:149]
	s_nop 0
	v_pk_add_f32 v[134:135], v[134:135], v[136:137]
	s_nop 0
	v_pk_add_f32 v[132:133], v[132:133], v[134:135]
	s_nop 0
	v_add_f32_e32 v132, v132, v133
	v_fmamk_f32 v132, v132, 0x3a800000, v231
	v_rsq_f32_e32 v134, v132
	s_nop 0
	v_pk_mul_f32 v[16:17], v[16:17], v[134:135] op_sel_hi:[1,0]
	v_pk_mul_f32 v[14:15], v[14:15], v[134:135] op_sel_hi:[1,0]
	v_max_f32_e32 v132, v16, v17
	v_max3_f32 v135, v14, v15, v132
	v_pk_mul_f32 v[132:133], v[12:13], v[134:135] op_sel_hi:[1,0]
	v_pk_mul_f32 v[12:13], v[10:11], v[134:135] op_sel_hi:[1,0]
	v_max_f32_e32 v10, v132, v133
	v_max3_f32 v10, v12, v13, v10
	v_pk_mul_f32 v[136:137], v[8:9], v[134:135] op_sel_hi:[1,0]
	v_pk_mul_f32 v[138:139], v[4:5], v[134:135] op_sel_hi:[1,0]
	v_max3_f32 v10, v135, s6, v10
	v_pk_mul_f32 v[8:9], v[6:7], v[134:135] op_sel_hi:[1,0]
	v_max_f32_e32 v6, v136, v137
	v_pk_mul_f32 v[134:135], v[2:3], v[134:135] op_sel_hi:[1,0]
	v_max_f32_e32 v2, v138, v139
	v_max3_f32 v6, v8, v9, v6
	v_max3_f32 v2, v134, v135, v2
	v_max3_f32 v2, v10, v6, v2
	ds_swizzle_b32 v3, v2 offset:swizzle(SWAP,16)
	s_waitcnt lgkmcnt(0)
	v_max_f32_e32 v3, v3, v3
	v_max_f32_e32 v2, v2, v3
	v_mov_b32_e32 v3, v2
	s_nop 1
	v_permlane32_swap_b32_e32 v2, v3
	s_and_saveexec_b64 s[6:7], s[2:3]
	v_max_f32_e32 v2, v2, v2
	v_max_f32_e32 v3, v3, v3
	v_lshl_add_u32 v4, v145, 4, s9
	v_max_f32_e32 v2, v2, v3
	ds_write_b32 v4, v2
	s_or_b64 exec, exec, s[6:7]
	v_lshl_add_u32 v2, v130, 4, 0
	s_waitcnt lgkmcnt(0)
	s_barrier
	v_add_u32_e32 v2, 0x20000, v2
	ds_read_b128 v[4:7], v2
	s_add_i32 s8, s8, 0x21000
	s_waitcnt lgkmcnt(0)
	v_max_f32_e32 v3, v7, v7
	v_max_f32_e32 v6, v6, v6
	v_max_f32_e32 v3, v6, v3
	v_max3_f32 v3, v4, v5, v3
	v_sub_f32_e32 v4, v129, v3
	v_sub_f32_e32 v5, v128, v3
	v_sub_f32_e32 v6, v127, v3
	v_sub_f32_e32 v7, v126, v3
	v_exp_f32_e32 v126, v7
	v_exp_f32_e32 v127, v6
	v_exp_f32_e32 v128, v5
	v_exp_f32_e32 v129, v4
	v_sub_f32_e32 v6, v125, v3
	v_sub_f32_e32 v7, v124, v3
	v_sub_f32_e32 v10, v123, v3
	v_sub_f32_e32 v11, v122, v3
	v_exp_f32_e32 v122, v11
	v_exp_f32_e32 v123, v10
	v_exp_f32_e32 v124, v7
	v_exp_f32_e32 v125, v6
	v_sub_f32_e32 v7, v121, v3
	v_sub_f32_e32 v10, v120, v3
	v_sub_f32_e32 v11, v119, v3
	v_sub_f32_e32 v118, v118, v3
	v_exp_f32_e32 v118, v118
	v_exp_f32_e32 v119, v11
	v_exp_f32_e32 v120, v10
	v_exp_f32_e32 v121, v7
	v_add_f32_e32 v4, v126, v127
	v_add_f32_e32 v5, v128, v129
	v_sub_f32_e32 v7, v117, v3
	v_sub_f32_e32 v10, v116, v3
	v_sub_f32_e32 v11, v115, v3
	v_sub_f32_e32 v3, v114, v3
	v_add_f32_e32 v4, v4, v5
	v_add_f32_e32 v5, v122, v123
	v_add_f32_e32 v6, v124, v125
	v_exp_f32_e32 v114, v3
	v_exp_f32_e32 v115, v11
	v_exp_f32_e32 v116, v10
	v_exp_f32_e32 v117, v7
	v_add_f32_e32 v4, 0, v4
	v_add_f32_e32 v5, v5, v6
	v_add_f32_e32 v4, v5, v4
	v_add_f32_e32 v5, v118, v119
	v_add_f32_e32 v6, v120, v121
	v_add_f32_e32 v3, v5, v6
	v_add_f32_e32 v3, v3, v4
	v_add_f32_e32 v4, v114, v115
	v_add_f32_e32 v5, v116, v117
	v_add_f32_e32 v4, v4, v5
	v_add_f32_e32 v3, v4, v3
	ds_swizzle_b32 v4, v3 offset:swizzle(SWAP,16)
	v_lshlrev_b32_e32 v5, 2, v130
	v_lshl_add_u32 v146, v5, 2, s8
	s_waitcnt lgkmcnt(0)
	v_add_f32_e32 v3, v3, v4
	v_mov_b32_e32 v4, v3
	s_nop 1
	v_permlane32_swap_b32_e32 v3, v4
	s_and_saveexec_b64 s[6:7], s[2:3]
	v_add_f32_e32 v3, v3, v4
	ds_write_b32 v146, v3
	s_or_b64 exec, exec, s[6:7]
	ds_read_b128 v[4:7], v2 offset:256
	s_waitcnt lgkmcnt(0)
	v_max_f32_e32 v3, v7, v7
	v_max_f32_e32 v6, v6, v6
	v_max_f32_e32 v3, v6, v3
	v_max3_f32 v3, v4, v5, v3
	v_sub_f32_e32 v4, v113, v3
	v_sub_f32_e32 v5, v112, v3
	v_sub_f32_e32 v6, v111, v3
	v_sub_f32_e32 v7, v110, v3
	v_exp_f32_e32 v110, v7
	v_exp_f32_e32 v111, v6
	v_exp_f32_e32 v112, v5
	v_exp_f32_e32 v113, v4
	v_sub_f32_e32 v6, v109, v3
	v_sub_f32_e32 v7, v108, v3
	v_sub_f32_e32 v10, v107, v3
	v_sub_f32_e32 v11, v106, v3
	v_exp_f32_e32 v106, v11
	v_exp_f32_e32 v107, v10
	v_exp_f32_e32 v108, v7
	v_exp_f32_e32 v109, v6
	v_sub_f32_e32 v7, v105, v3
	v_sub_f32_e32 v10, v104, v3
	v_sub_f32_e32 v11, v103, v3
	v_sub_f32_e32 v102, v102, v3
	v_exp_f32_e32 v102, v102
	v_exp_f32_e32 v103, v11
	v_exp_f32_e32 v104, v10
	v_exp_f32_e32 v105, v7
	v_add_f32_e32 v4, v110, v111
	v_add_f32_e32 v5, v112, v113
	v_sub_f32_e32 v7, v101, v3
	v_sub_f32_e32 v10, v100, v3
	v_sub_f32_e32 v11, v99, v3
	v_sub_f32_e32 v3, v98, v3
	v_add_f32_e32 v4, v4, v5
	v_add_f32_e32 v5, v106, v107
	v_add_f32_e32 v6, v108, v109
	v_exp_f32_e32 v98, v3
	v_exp_f32_e32 v99, v11
	v_exp_f32_e32 v100, v10
	v_exp_f32_e32 v101, v7
	v_add_f32_e32 v4, 0, v4
	v_add_f32_e32 v5, v5, v6
	v_add_f32_e32 v4, v5, v4
	v_add_f32_e32 v5, v102, v103
	v_add_f32_e32 v6, v104, v105
	v_add_f32_e32 v3, v5, v6
	v_add_f32_e32 v3, v3, v4
	v_add_f32_e32 v4, v98, v99
	v_add_f32_e32 v5, v100, v101
	v_add_f32_e32 v4, v4, v5
	v_add_f32_e32 v3, v4, v3
	ds_swizzle_b32 v4, v3 offset:swizzle(SWAP,16)
	s_waitcnt lgkmcnt(0)
	v_add_f32_e32 v3, v3, v4
	v_mov_b32_e32 v4, v3
	s_nop 1
	v_permlane32_swap_b32_e32 v3, v4
	s_and_saveexec_b64 s[6:7], s[2:3]
	v_add_f32_e32 v3, v3, v4
	ds_write_b32 v146, v3 offset:256
	s_or_b64 exec, exec, s[6:7]
	v_mad_u64_u32 v[4:5], s[6:7], v130, 3, v[0:1]
	v_lshl_add_u32 v3, v4, 2, 0
	v_add_u32_e32 v3, 0x20000, v3
	ds_read_b128 v[4:7], v3
	s_waitcnt lgkmcnt(0)
	v_max_f32_e32 v3, v7, v7
	v_max_f32_e32 v6, v6, v6
	v_max_f32_e32 v3, v6, v3
	v_max3_f32 v3, v4, v5, v3
	v_sub_f32_e32 v4, v97, v3
	v_sub_f32_e32 v5, v96, v3
	v_sub_f32_e32 v6, v95, v3
	v_sub_f32_e32 v7, v94, v3
	v_exp_f32_e32 v94, v7
	v_exp_f32_e32 v95, v6
	v_exp_f32_e32 v96, v5
	v_exp_f32_e32 v97, v4
	v_sub_f32_e32 v6, v93, v3
	v_sub_f32_e32 v7, v92, v3
	v_sub_f32_e32 v10, v91, v3
	v_sub_f32_e32 v11, v90, v3
	v_exp_f32_e32 v90, v11
	v_exp_f32_e32 v91, v10
	v_exp_f32_e32 v92, v7
	v_exp_f32_e32 v93, v6
	v_sub_f32_e32 v7, v89, v3
	v_sub_f32_e32 v10, v88, v3
	v_sub_f32_e32 v11, v87, v3
	v_sub_f32_e32 v86, v86, v3
	v_exp_f32_e32 v86, v86
	v_exp_f32_e32 v87, v11
	v_exp_f32_e32 v88, v10
	v_exp_f32_e32 v89, v7
	v_add_f32_e32 v4, v94, v95
	v_add_f32_e32 v5, v96, v97
	v_sub_f32_e32 v7, v85, v3
	v_sub_f32_e32 v10, v84, v3
	v_sub_f32_e32 v11, v83, v3
	v_sub_f32_e32 v3, v82, v3
	v_add_f32_e32 v4, v4, v5
	v_add_f32_e32 v5, v90, v91
	v_add_f32_e32 v6, v92, v93
	v_exp_f32_e32 v82, v3
	v_exp_f32_e32 v83, v11
	v_exp_f32_e32 v84, v10
	v_exp_f32_e32 v85, v7
	v_add_f32_e32 v4, 0, v4
	v_add_f32_e32 v5, v5, v6
	v_add_f32_e32 v4, v5, v4
	v_add_f32_e32 v5, v86, v87
	v_add_f32_e32 v6, v88, v89
	v_add_f32_e32 v3, v5, v6
	v_add_f32_e32 v3, v3, v4
	v_add_f32_e32 v4, v82, v83
	v_add_f32_e32 v5, v84, v85
	v_add_f32_e32 v4, v4, v5
	v_add_f32_e32 v3, v4, v3
	ds_swizzle_b32 v4, v3 offset:swizzle(SWAP,16)
	s_waitcnt lgkmcnt(0)
	v_add_f32_e32 v3, v3, v4
	v_mov_b32_e32 v4, v3
	s_nop 1
	v_permlane32_swap_b32_e32 v3, v4
	s_and_saveexec_b64 s[6:7], s[2:3]
	v_add_f32_e32 v3, v3, v4
	ds_write_b32 v146, v3 offset:512
	s_or_b64 exec, exec, s[6:7]
	ds_read_b128 v[4:7], v2 offset:768
	s_waitcnt lgkmcnt(0)
	v_max_f32_e32 v3, v7, v7
	v_max_f32_e32 v6, v6, v6
	v_max_f32_e32 v3, v6, v3
	v_max3_f32 v3, v4, v5, v3
	v_sub_f32_e32 v4, v81, v3
	v_sub_f32_e32 v5, v80, v3
	v_sub_f32_e32 v6, v79, v3
	v_sub_f32_e32 v7, v78, v3
	v_exp_f32_e32 v78, v7
	v_exp_f32_e32 v79, v6
	v_exp_f32_e32 v80, v5
	v_exp_f32_e32 v81, v4
	v_sub_f32_e32 v6, v77, v3
	v_sub_f32_e32 v7, v76, v3
	v_sub_f32_e32 v10, v75, v3
	v_sub_f32_e32 v11, v74, v3
	v_exp_f32_e32 v74, v11
	v_exp_f32_e32 v75, v10
	v_exp_f32_e32 v76, v7
	v_exp_f32_e32 v77, v6
	v_sub_f32_e32 v7, v73, v3
	v_sub_f32_e32 v10, v72, v3
	v_sub_f32_e32 v11, v71, v3
	v_sub_f32_e32 v70, v70, v3
	v_exp_f32_e32 v70, v70
	v_exp_f32_e32 v71, v11
	v_exp_f32_e32 v72, v10
	v_exp_f32_e32 v73, v7
	v_add_f32_e32 v4, v78, v79
	v_add_f32_e32 v5, v80, v81
	v_sub_f32_e32 v7, v69, v3
	v_sub_f32_e32 v10, v68, v3
	v_sub_f32_e32 v11, v67, v3
	v_sub_f32_e32 v3, v66, v3
	v_add_f32_e32 v4, v4, v5
	v_add_f32_e32 v5, v74, v75
	v_add_f32_e32 v6, v76, v77
	v_exp_f32_e32 v66, v3
	v_exp_f32_e32 v67, v11
	v_exp_f32_e32 v68, v10
	v_exp_f32_e32 v69, v7
	v_add_f32_e32 v4, 0, v4
	v_add_f32_e32 v5, v5, v6
	v_add_f32_e32 v4, v5, v4
	v_add_f32_e32 v5, v70, v71
	v_add_f32_e32 v6, v72, v73
	v_add_f32_e32 v3, v5, v6
	v_add_f32_e32 v3, v3, v4
	v_add_f32_e32 v4, v66, v67
	v_add_f32_e32 v5, v68, v69
	v_add_f32_e32 v4, v4, v5
	v_add_f32_e32 v3, v4, v3
	ds_swizzle_b32 v4, v3 offset:swizzle(SWAP,16)
	s_waitcnt lgkmcnt(0)
	v_add_f32_e32 v3, v3, v4
	v_mov_b32_e32 v4, v3
	s_nop 1
	v_permlane32_swap_b32_e32 v3, v4
	s_and_saveexec_b64 s[6:7], s[2:3]
	v_add_f32_e32 v3, v3, v4
	ds_write_b32 v146, v3 offset:768
	s_or_b64 exec, exec, s[6:7]
	ds_read_b128 v[4:7], v2 offset:2048
	s_waitcnt lgkmcnt(0)
	v_max_f32_e32 v3, v7, v7
	v_max_f32_e32 v6, v6, v6
	v_max_f32_e32 v3, v6, v3
	v_max3_f32 v3, v4, v5, v3
	v_sub_f32_e32 v4, v65, v3
	v_sub_f32_e32 v5, v64, v3
	v_sub_f32_e32 v6, v63, v3
	v_sub_f32_e32 v7, v62, v3
	v_exp_f32_e32 v62, v7
	v_exp_f32_e32 v63, v6
	v_exp_f32_e32 v64, v5
	v_exp_f32_e32 v65, v4
	v_sub_f32_e32 v6, v61, v3
	v_sub_f32_e32 v7, v60, v3
	v_sub_f32_e32 v10, v59, v3
	v_sub_f32_e32 v11, v58, v3
	v_exp_f32_e32 v58, v11
	v_exp_f32_e32 v59, v10
	v_exp_f32_e32 v60, v7
	v_exp_f32_e32 v61, v6
	v_sub_f32_e32 v7, v57, v3
	v_sub_f32_e32 v56, v56, v3
	v_sub_f32_e32 v11, v55, v3
	v_sub_f32_e32 v10, v54, v3
	v_exp_f32_e32 v10, v10
	v_exp_f32_e32 v11, v11
	v_exp_f32_e32 v54, v56
	v_exp_f32_e32 v55, v7
	v_add_f32_e32 v4, v62, v63
	v_add_f32_e32 v5, v64, v65
	v_sub_f32_e32 v7, v53, v3
	v_sub_f32_e32 v52, v52, v3
	v_sub_f32_e32 v51, v51, v3
	v_sub_f32_e32 v3, v50, v3
	v_add_f32_e32 v4, v4, v5
	v_add_f32_e32 v5, v58, v59
	v_add_f32_e32 v6, v60, v61
	v_exp_f32_e32 v50, v3
	v_exp_f32_e32 v51, v51
	v_exp_f32_e32 v52, v52
	v_exp_f32_e32 v53, v7
	v_add_f32_e32 v4, 0, v4
	v_add_f32_e32 v5, v5, v6
	v_add_f32_e32 v4, v5, v4
	v_add_f32_e32 v5, v10, v11
	v_add_f32_e32 v6, v54, v55
	v_add_f32_e32 v3, v5, v6
	v_add_f32_e32 v3, v3, v4
	v_add_f32_e32 v4, v50, v51
	v_add_f32_e32 v5, v52, v53
	v_add_f32_e32 v4, v4, v5
	v_add_f32_e32 v3, v4, v3
	ds_swizzle_b32 v4, v3 offset:swizzle(SWAP,16)
	s_waitcnt lgkmcnt(0)
	v_add_f32_e32 v3, v3, v4
	v_mov_b32_e32 v4, v3
	s_nop 1
	v_permlane32_swap_b32_e32 v3, v4
	s_and_saveexec_b64 s[6:7], s[2:3]
	v_add_f32_e32 v3, v3, v4
	ds_write_b32 v146, v3 offset:2048
	s_or_b64 exec, exec, s[6:7]
	ds_read_b128 v[4:7], v2 offset:2304
	s_waitcnt lgkmcnt(0)
	v_max_f32_e32 v3, v7, v7
	v_max_f32_e32 v6, v6, v6
	v_max_f32_e32 v3, v6, v3
	v_max3_f32 v3, v4, v5, v3
	v_sub_f32_e32 v4, v49, v3
	v_sub_f32_e32 v5, v48, v3
	v_sub_f32_e32 v6, v47, v3
	v_sub_f32_e32 v7, v46, v3
	v_exp_f32_e32 v46, v7
	v_exp_f32_e32 v47, v6
	v_exp_f32_e32 v48, v5
	v_exp_f32_e32 v49, v4
	v_sub_f32_e32 v6, v45, v3
	v_sub_f32_e32 v7, v44, v3
	v_sub_f32_e32 v43, v43, v3
	v_sub_f32_e32 v42, v42, v3
	v_exp_f32_e32 v42, v42
	v_exp_f32_e32 v43, v43
	v_exp_f32_e32 v56, v7
	v_exp_f32_e32 v57, v6
	v_sub_f32_e32 v41, v41, v3
	v_sub_f32_e32 v40, v40, v3
	v_sub_f32_e32 v7, v39, v3
	v_sub_f32_e32 v6, v38, v3
	v_exp_f32_e32 v6, v6
	v_exp_f32_e32 v7, v7
	v_exp_f32_e32 v38, v40
	v_exp_f32_e32 v39, v41
	v_add_f32_e32 v4, v46, v47
	v_add_f32_e32 v5, v48, v49
	v_sub_f32_e32 v37, v37, v3
	v_sub_f32_e32 v36, v36, v3
	v_sub_f32_e32 v35, v35, v3
	v_sub_f32_e32 v3, v34, v3
	v_add_f32_e32 v4, v4, v5
	v_add_f32_e32 v5, v42, v43
	v_add_f32_e32 v44, v56, v57
	v_exp_f32_e32 v34, v3
	v_exp_f32_e32 v35, v35
	v_exp_f32_e32 v36, v36
	v_exp_f32_e32 v37, v37
	v_add_f32_e32 v4, 0, v4
	v_add_f32_e32 v5, v5, v44
	v_add_f32_e32 v4, v5, v4
	v_add_f32_e32 v5, v6, v7
	v_add_f32_e32 v40, v38, v39
	v_add_f32_e32 v3, v5, v40
	v_add_f32_e32 v3, v3, v4
	v_add_f32_e32 v4, v34, v35
	v_add_f32_e32 v5, v36, v37
	v_add_f32_e32 v4, v4, v5
	v_add_f32_e32 v3, v4, v3
	ds_swizzle_b32 v4, v3 offset:swizzle(SWAP,16)
	s_waitcnt lgkmcnt(0)
	v_add_f32_e32 v3, v3, v4
	v_mov_b32_e32 v4, v3
	s_nop 1
	v_permlane32_swap_b32_e32 v3, v4
	s_and_saveexec_b64 s[6:7], s[2:3]
	v_add_f32_e32 v3, v3, v4
	ds_write_b32 v146, v3 offset:2304
	s_or_b64 exec, exec, s[6:7]
	ds_read_b128 v[148:151], v2 offset:2560
	s_waitcnt lgkmcnt(0)
	v_max_f32_e32 v3, v151, v151
	v_max_f32_e32 v4, v150, v150
	v_max_f32_e32 v3, v4, v3
	v_max3_f32 v3, v148, v149, v3
	v_sub_f32_e32 v4, v33, v3
	v_sub_f32_e32 v5, v32, v3
	v_sub_f32_e32 v31, v31, v3
	v_sub_f32_e32 v30, v30, v3
	v_exp_f32_e32 v30, v30
	v_exp_f32_e32 v31, v31
	v_exp_f32_e32 v32, v5
	v_exp_f32_e32 v33, v4
	v_sub_f32_e32 v40, v29, v3
	v_sub_f32_e32 v41, v28, v3
	v_sub_f32_e32 v27, v27, v3
	v_sub_f32_e32 v26, v26, v3
	v_exp_f32_e32 v28, v26
	v_exp_f32_e32 v29, v27
	v_exp_f32_e32 v44, v41
	v_exp_f32_e32 v45, v40
	v_add_f32_e32 v4, v30, v31
	v_add_f32_e32 v5, v32, v33
	v_add_f32_e32 v4, v4, v5
	v_add_f32_e32 v26, 0, v4
	v_add_f32_e32 v27, v28, v29
	v_add_f32_e32 v40, v44, v45
	v_sub_f32_e32 v25, v25, v3
	v_sub_f32_e32 v24, v24, v3
	v_sub_f32_e32 v5, v23, v3
	v_sub_f32_e32 v4, v22, v3
	v_exp_f32_e32 v4, v4
	v_exp_f32_e32 v5, v5
	v_exp_f32_e32 v22, v24
	v_exp_f32_e32 v23, v25
	v_add_f32_e32 v24, v27, v40
	v_sub_f32_e32 v21, v21, v3
	v_sub_f32_e32 v20, v20, v3
	v_sub_f32_e32 v19, v19, v3
	v_sub_f32_e32 v3, v18, v3
	v_add_f32_e32 v24, v24, v26
	v_exp_f32_e32 v18, v3
	v_exp_f32_e32 v19, v19
	v_exp_f32_e32 v26, v20
	v_exp_f32_e32 v27, v21
	v_add_f32_e32 v25, v4, v5
	v_add_f32_e32 v40, v22, v23
	v_add_f32_e32 v3, v25, v40
	v_add_f32_e32 v20, v18, v19
	v_add_f32_e32 v21, v26, v27
	v_add_f32_e32 v3, v3, v24
	v_add_f32_e32 v20, v20, v21
	v_add_f32_e32 v3, v20, v3
	ds_swizzle_b32 v20, v3 offset:swizzle(SWAP,16)
	s_waitcnt lgkmcnt(0)
	v_add_f32_e32 v3, v3, v20
	v_mov_b32_e32 v20, v3
	s_nop 1
	v_permlane32_swap_b32_e32 v3, v20
	s_and_saveexec_b64 s[6:7], s[2:3]
	v_add_f32_e32 v3, v3, v20
	ds_write_b32 v146, v3 offset:2560
	s_or_b64 exec, exec, s[6:7]
	ds_read_b128 v[148:151], v2 offset:2816
	s_waitcnt lgkmcnt(0)
	v_max_f32_e32 v2, v151, v151
	v_max_f32_e32 v3, v150, v150
	v_max_f32_e32 v2, v3, v2
	v_max3_f32 v147, v148, v149, v2
	v_sub_f32_e32 v2, v17, v147
	v_sub_f32_e32 v3, v16, v147
	v_sub_f32_e32 v15, v15, v147
	v_sub_f32_e32 v14, v14, v147
	v_exp_f32_e32 v14, v14
	v_exp_f32_e32 v15, v15
	v_exp_f32_e32 v20, v3
	v_exp_f32_e32 v21, v2
	v_sub_f32_e32 v16, v133, v147
	v_sub_f32_e32 v17, v132, v147
	v_sub_f32_e32 v13, v13, v147
	v_sub_f32_e32 v12, v12, v147
	v_exp_f32_e32 v24, v12
	v_exp_f32_e32 v25, v13
	v_exp_f32_e32 v40, v17
	v_exp_f32_e32 v41, v16
	v_add_f32_e32 v2, v14, v15
	v_add_f32_e32 v3, v20, v21
	v_add_f32_e32 v2, v2, v3
	v_add_f32_e32 v12, 0, v2
	v_add_f32_e32 v13, v24, v25
	v_add_f32_e32 v16, v40, v41
	v_sub_f32_e32 v17, v137, v147
	v_sub_f32_e32 v132, v136, v147
	v_sub_f32_e32 v3, v9, v147
	v_sub_f32_e32 v2, v8, v147
	v_exp_f32_e32 v2, v2
	v_exp_f32_e32 v3, v3
	v_exp_f32_e32 v8, v132
	v_exp_f32_e32 v9, v17
	v_add_f32_e32 v13, v13, v16
	v_add_f32_e32 v132, v13, v12
	v_sub_f32_e32 v17, v139, v147
	v_sub_f32_e32 v16, v138, v147
	v_sub_f32_e32 v13, v135, v147
	v_sub_f32_e32 v12, v134, v147
	v_exp_f32_e32 v12, v12
	v_exp_f32_e32 v13, v13
	v_exp_f32_e32 v16, v16
	v_exp_f32_e32 v17, v17
	v_add_f32_e32 v133, v2, v3
	v_add_f32_e32 v136, v8, v9
	v_add_f32_e32 v133, v133, v136
	v_add_f32_e32 v132, v133, v132
	v_add_f32_e32 v133, v12, v13
	v_add_f32_e32 v134, v16, v17
	v_add_f32_e32 v133, v133, v134
	v_add_f32_e32 v132, v133, v132
	ds_swizzle_b32 v133, v132 offset:swizzle(SWAP,16)
	s_waitcnt lgkmcnt(0)
	v_add_f32_e32 v132, v132, v133
	v_mov_b32_e32 v133, v132
	s_nop 1
	v_permlane32_swap_b32_e32 v132, v133
	s_and_saveexec_b64 s[6:7], s[2:3]
	v_add_f32_e32 v132, v132, v133
	ds_write_b32 v146, v132 offset:2816
	s_or_b64 exec, exec, s[6:7]
	s_lshl_b32 s2, s16, 5
	s_or_b32 s3, s15, s2
	s_mul_i32 s6, s14, 0x180000
	s_mul_hi_i32 s2, s14, 0x180000
	s_add_u32 s4, s4, s6
	s_addc_u32 s5, s5, s2
	s_add_i32 s2, 0, 0x21000
	s_waitcnt lgkmcnt(0)
	s_barrier
	v_lshl_add_u32 v132, v130, 4, s2
	ds_read_b128 v[132:135], v132
	v_lshl_add_u32 v136, v131, 3, s3
	v_ashrrev_i32_e32 v131, 31, v130
	v_lshlrev_b64 v[130:131], 11, v[130:131]
	v_lshl_add_u64 v[130:131], s[4:5], 0, v[130:131]
	s_waitcnt lgkmcnt(0)
	v_mov_b32_e32 v138, v133
	v_mov_b32_e32 v139, v134
	v_mov_b32_e32 v133, v135
	v_pk_add_f32 v[132:133], v[138:139], v[132:133]
	v_ashrrev_i32_e32 v137, 31, v136
	v_add_f32_e32 v132, v132, v133
	v_rcp_f32_e32 v132, v132
	v_lshl_add_u64 v[130:131], v[136:137], 1, v[130:131]
	s_mov_b32 s3, 0x9800000
	s_mov_b64 s[4:5], 0x9800000
	v_pk_mul_f32 v[126:127], v[126:127], v[132:133] op_sel_hi:[1,0]
	v_pk_mul_f32 v[134:135], v[124:125], v[132:133] op_sel_hi:[1,0]
	v_pk_mul_f32 v[124:125], v[122:123], v[132:133] op_sel_hi:[1,0]
	v_cvt_pk_bf16_f32 v122, v126, v127
	v_add_co_u32_e32 v126, vcc, s3, v130
	v_pk_mul_f32 v[128:129], v[128:129], v[132:133] op_sel_hi:[1,0]
	s_nop 0
	v_addc_co_u32_e32 v127, vcc, 0, v131, vcc
	v_cvt_pk_bf16_f32 v123, v128, v129
	v_pk_mul_f32 v[118:119], v[118:119], v[132:133] op_sel_hi:[1,0]
	v_cvt_pk_bf16_f32 v124, v124, v125
	v_cvt_pk_bf16_f32 v125, v134, v135
	global_store_dwordx4 v[126:127], v[122:125], off
	v_pk_mul_f32 v[120:121], v[120:121], v[132:133] op_sel_hi:[1,0]
	s_mov_b32 s3, 0x9808000
	v_pk_mul_f32 v[122:123], v[116:117], v[132:133] op_sel_hi:[1,0]
	v_pk_mul_f32 v[116:117], v[114:115], v[132:133] op_sel_hi:[1,0]
	v_cvt_pk_bf16_f32 v114, v118, v119
	v_lshl_add_u32 v118, v140, 4, s2
	v_cvt_pk_bf16_f32 v115, v120, v121
	v_cvt_pk_bf16_f32 v116, v116, v117
	v_cvt_pk_bf16_f32 v117, v122, v123
	ds_read_b128 v[118:121], v118
	v_lshl_add_u32 v0, v0, 4, s2
	s_waitcnt lgkmcnt(0)
	v_mov_b32_e32 v122, v119
	v_mov_b32_e32 v123, v120
	v_mov_b32_e32 v119, v121
	v_pk_add_f32 v[118:119], v[122:123], v[118:119]
	v_lshl_add_u64 v[120:121], v[130:131], 0, s[4:5]
	v_add_f32_e32 v118, v118, v119
	v_rcp_f32_e32 v118, v118
	global_store_dwordx4 v[120:121], v[114:117], off offset:256
	v_pk_mul_f32 v[110:111], v[110:111], v[118:119] op_sel_hi:[1,0]
	s_nop 0
	v_pk_mul_f32 v[114:115], v[108:109], v[118:119] op_sel_hi:[1,0]
	v_pk_mul_f32 v[108:109], v[106:107], v[118:119] op_sel_hi:[1,0]
	v_cvt_pk_bf16_f32 v106, v110, v111
	v_add_co_u32_e32 v110, vcc, s3, v130
	v_pk_mul_f32 v[112:113], v[112:113], v[118:119] op_sel_hi:[1,0]
	s_nop 0
	v_addc_co_u32_e32 v111, vcc, 0, v131, vcc
	v_cvt_pk_bf16_f32 v107, v112, v113
	v_pk_mul_f32 v[102:103], v[102:103], v[118:119] op_sel_hi:[1,0]
	v_cvt_pk_bf16_f32 v108, v108, v109
	v_cvt_pk_bf16_f32 v109, v114, v115
	global_store_dwordx4 v[110:111], v[106:109], off
	v_pk_mul_f32 v[104:105], v[104:105], v[118:119] op_sel_hi:[1,0]
	s_mov_b32 s3, 0x9810000
	v_pk_mul_f32 v[106:107], v[100:101], v[118:119] op_sel_hi:[1,0]
	v_pk_mul_f32 v[100:101], v[98:99], v[118:119] op_sel_hi:[1,0]
	v_cvt_pk_bf16_f32 v98, v102, v103
	v_lshl_add_u32 v102, v141, 4, s2
	v_cvt_pk_bf16_f32 v99, v104, v105
	v_cvt_pk_bf16_f32 v100, v100, v101
	v_cvt_pk_bf16_f32 v101, v106, v107
	ds_read_b128 v[102:105], v102
	global_store_dwordx4 v[110:111], v[98:101], off offset:256
	s_waitcnt lgkmcnt(0)
	v_mov_b32_e32 v106, v103
	v_mov_b32_e32 v107, v104
	v_mov_b32_e32 v103, v105
	v_pk_add_f32 v[102:103], v[106:107], v[102:103]
	s_nop 0
	v_add_f32_e32 v102, v102, v103
	v_rcp_f32_e32 v102, v102
	s_nop 0
	v_pk_mul_f32 v[94:95], v[94:95], v[102:103] op_sel_hi:[1,0]
	v_pk_mul_f32 v[98:99], v[92:93], v[102:103] op_sel_hi:[1,0]
	v_pk_mul_f32 v[92:93], v[90:91], v[102:103] op_sel_hi:[1,0]
	v_cvt_pk_bf16_f32 v90, v94, v95
	v_add_co_u32_e32 v94, vcc, s3, v130
	v_pk_mul_f32 v[96:97], v[96:97], v[102:103] op_sel_hi:[1,0]
	s_nop 0
	v_addc_co_u32_e32 v95, vcc, 0, v131, vcc
	v_cvt_pk_bf16_f32 v91, v96, v97
	v_pk_mul_f32 v[86:87], v[86:87], v[102:103] op_sel_hi:[1,0]
	v_cvt_pk_bf16_f32 v92, v92, v93
	v_cvt_pk_bf16_f32 v93, v98, v99
	global_store_dwordx4 v[94:95], v[90:93], off
	v_pk_mul_f32 v[88:89], v[88:89], v[102:103] op_sel_hi:[1,0]
	s_mov_b32 s3, 0x9818000
	v_pk_mul_f32 v[90:91], v[84:85], v[102:103] op_sel_hi:[1,0]
	v_pk_mul_f32 v[84:85], v[82:83], v[102:103] op_sel_hi:[1,0]
	v_cvt_pk_bf16_f32 v82, v86, v87
	v_lshl_add_u32 v86, v142, 4, s2
	v_cvt_pk_bf16_f32 v83, v88, v89
	v_cvt_pk_bf16_f32 v84, v84, v85
	v_cvt_pk_bf16_f32 v85, v90, v91
	ds_read_b128 v[86:89], v86
	global_store_dwordx4 v[94:95], v[82:85], off offset:256
	s_waitcnt lgkmcnt(0)
	v_mov_b32_e32 v90, v87
	v_mov_b32_e32 v91, v88
	v_mov_b32_e32 v87, v89
	v_pk_add_f32 v[86:87], v[90:91], v[86:87]
	s_nop 0
	v_add_f32_e32 v86, v86, v87
	v_rcp_f32_e32 v86, v86
	s_nop 0
	v_pk_mul_f32 v[78:79], v[78:79], v[86:87] op_sel_hi:[1,0]
	v_pk_mul_f32 v[82:83], v[76:77], v[86:87] op_sel_hi:[1,0]
	v_pk_mul_f32 v[76:77], v[74:75], v[86:87] op_sel_hi:[1,0]
	v_cvt_pk_bf16_f32 v74, v78, v79
	v_add_co_u32_e32 v78, vcc, s3, v130
	v_pk_mul_f32 v[80:81], v[80:81], v[86:87] op_sel_hi:[1,0]
	s_nop 0
	v_addc_co_u32_e32 v79, vcc, 0, v131, vcc
	v_cvt_pk_bf16_f32 v75, v80, v81
	v_cvt_pk_bf16_f32 v76, v76, v77
	v_cvt_pk_bf16_f32 v77, v82, v83
	global_store_dwordx4 v[78:79], v[74:77], off
	v_pk_mul_f32 v[72:73], v[72:73], v[86:87] op_sel_hi:[1,0]
	v_pk_mul_f32 v[70:71], v[70:71], v[86:87] op_sel_hi:[1,0]
	v_pk_mul_f32 v[74:75], v[68:69], v[86:87] op_sel_hi:[1,0]
	v_pk_mul_f32 v[68:69], v[66:67], v[86:87] op_sel_hi:[1,0]
	v_cvt_pk_bf16_f32 v66, v70, v71
	v_cvt_pk_bf16_f32 v67, v72, v73
	s_mov_b32 s3, 0x9840000
	v_cvt_pk_bf16_f32 v68, v68, v69
	v_cvt_pk_bf16_f32 v69, v74, v75
	ds_read_b128 v[70:73], v0
	global_store_dwordx4 v[78:79], v[66:69], off offset:256
	s_waitcnt lgkmcnt(0)
	v_mov_b32_e32 v74, v71
	v_mov_b32_e32 v75, v72
	v_mov_b32_e32 v71, v73
	v_pk_add_f32 v[70:71], v[74:75], v[70:71]
	s_nop 0
	v_add_f32_e32 v0, v70, v71
	v_rcp_f32_e32 v0, v0
	s_nop 0
	v_pk_mul_f32 v[62:63], v[62:63], v[0:1] op_sel_hi:[1,0]
	v_pk_mul_f32 v[66:67], v[60:61], v[0:1] op_sel_hi:[1,0]
	v_pk_mul_f32 v[60:61], v[58:59], v[0:1] op_sel_hi:[1,0]
	v_cvt_pk_bf16_f32 v58, v62, v63
	v_add_co_u32_e32 v62, vcc, s3, v130
	v_pk_mul_f32 v[64:65], v[64:65], v[0:1] op_sel_hi:[1,0]
	s_nop 0
	v_addc_co_u32_e32 v63, vcc, 0, v131, vcc
	v_cvt_pk_bf16_f32 v59, v64, v65
	v_cvt_pk_bf16_f32 v60, v60, v61
	v_cvt_pk_bf16_f32 v61, v66, v67
	global_store_dwordx4 v[62:63], v[58:61], off
	v_pk_mul_f32 v[54:55], v[54:55], v[0:1] op_sel_hi:[1,0]
	v_pk_mul_f32 v[10:11], v[10:11], v[0:1] op_sel_hi:[1,0]
	v_pk_mul_f32 v[58:59], v[52:53], v[0:1] op_sel_hi:[1,0]
	v_pk_mul_f32 v[52:53], v[50:51], v[0:1] op_sel_hi:[1,0]
	v_lshl_add_u32 v0, v143, 4, s2
	v_cvt_pk_bf16_f32 v50, v10, v11
	v_cvt_pk_bf16_f32 v51, v54, v55
	v_cvt_pk_bf16_f32 v52, v52, v53
	v_cvt_pk_bf16_f32 v53, v58, v59
	ds_read_b128 v[58:61], v0
	s_mov_b32 s3, 0x9848000
	global_store_dwordx4 v[62:63], v[50:53], off offset:256
	s_waitcnt lgkmcnt(0)
	v_mov_b32_e32 v10, v59
	v_mov_b32_e32 v11, v60
	v_mov_b32_e32 v59, v61
	v_pk_add_f32 v[10:11], v[10:11], v[58:59]
	s_nop 0
	v_add_f32_e32 v0, v10, v11
	v_rcp_f32_e32 v0, v0
	s_nop 0
	v_pk_mul_f32 v[10:11], v[48:49], v[0:1] op_sel_hi:[1,0]
	v_pk_mul_f32 v[46:47], v[46:47], v[0:1] op_sel_hi:[1,0]
	v_pk_mul_f32 v[42:43], v[42:43], v[0:1] op_sel_hi:[1,0]
	v_cvt_pk_bf16_f32 v46, v46, v47
	v_cvt_pk_bf16_f32 v47, v10, v11
	v_add_co_u32_e32 v10, vcc, s3, v130
	v_pk_mul_f32 v[50:51], v[56:57], v[0:1] op_sel_hi:[1,0]
	v_cvt_pk_bf16_f32 v48, v42, v43
	s_nop 0
	v_addc_co_u32_e32 v11, vcc, 0, v131, vcc
	v_cvt_pk_bf16_f32 v49, v50, v51
	v_pk_mul_f32 v[38:39], v[38:39], v[0:1] op_sel_hi:[1,0]
	v_pk_mul_f32 v[6:7], v[6:7], v[0:1] op_sel_hi:[1,0]
	v_pk_mul_f32 v[42:43], v[36:37], v[0:1] op_sel_hi:[1,0]
	v_pk_mul_f32 v[36:37], v[34:35], v[0:1] op_sel_hi:[1,0]
	v_lshl_add_u32 v0, v144, 4, s2
	global_store_dwordx4 v[10:11], v[46:49], off
	v_cvt_pk_bf16_f32 v34, v6, v7
	v_cvt_pk_bf16_f32 v35, v38, v39
	v_cvt_pk_bf16_f32 v36, v36, v37
	v_cvt_pk_bf16_f32 v37, v42, v43
	ds_read_b128 v[46:49], v0
	global_store_dwordx4 v[10:11], v[34:37], off offset:256
	s_mov_b32 s3, 0x9850000
	s_waitcnt lgkmcnt(0)
	v_mov_b32_e32 v6, v47
	v_mov_b32_e32 v7, v48
	v_mov_b32_e32 v47, v49
	v_pk_add_f32 v[6:7], v[6:7], v[46:47]
	s_nop 0
	v_add_f32_e32 v0, v6, v7
	v_rcp_f32_e32 v0, v0
	s_nop 0
	v_pk_mul_f32 v[10:11], v[30:31], v[0:1] op_sel_hi:[1,0]
	v_pk_mul_f32 v[6:7], v[32:33], v[0:1] op_sel_hi:[1,0]
	v_pk_mul_f32 v[30:31], v[28:29], v[0:1] op_sel_hi:[1,0]
	v_cvt_pk_bf16_f32 v28, v10, v11
	v_add_co_u32_e32 v10, vcc, s3, v130
	v_pk_mul_f32 v[32:33], v[44:45], v[0:1] op_sel_hi:[1,0]
	v_cvt_pk_bf16_f32 v29, v6, v7
	s_nop 0
	v_addc_co_u32_e32 v11, vcc, 0, v131, vcc
	v_pk_mul_f32 v[6:7], v[22:23], v[0:1] op_sel_hi:[1,0]
	v_pk_mul_f32 v[4:5], v[4:5], v[0:1] op_sel_hi:[1,0]
	v_pk_mul_f32 v[22:23], v[26:27], v[0:1] op_sel_hi:[1,0]
	v_pk_mul_f32 v[18:19], v[18:19], v[0:1] op_sel_hi:[1,0]
	v_lshl_add_u32 v0, v145, 4, s2
	v_cvt_pk_bf16_f32 v30, v30, v31
	v_cvt_pk_bf16_f32 v31, v32, v33
	global_store_dwordx4 v[10:11], v[28:31], off
	v_cvt_pk_bf16_f32 v4, v4, v5
	v_cvt_pk_bf16_f32 v5, v6, v7
	v_cvt_pk_bf16_f32 v6, v18, v19
	v_cvt_pk_bf16_f32 v7, v22, v23
	ds_read_b128 v[26:29], v0
	global_store_dwordx4 v[10:11], v[4:7], off offset:256
	s_mov_b32 s2, 0x9858000
	s_waitcnt lgkmcnt(0)
	v_mov_b32_e32 v18, v27
	v_mov_b32_e32 v19, v28
	v_mov_b32_e32 v27, v29
	v_pk_add_f32 v[18:19], v[18:19], v[26:27]
	s_nop 0
	v_add_f32_e32 v0, v18, v19
	v_rcp_f32_e32 v0, v0
	s_nop 0
	v_pk_mul_f32 v[6:7], v[20:21], v[0:1] op_sel_hi:[1,0]
	v_pk_mul_f32 v[4:5], v[14:15], v[0:1] op_sel_hi:[1,0]
	v_pk_mul_f32 v[10:11], v[40:41], v[0:1] op_sel_hi:[1,0]
	v_pk_mul_f32 v[14:15], v[24:25], v[0:1] op_sel_hi:[1,0]
	v_cvt_pk_bf16_f32 v4, v4, v5
	v_cvt_pk_bf16_f32 v5, v6, v7
	v_pk_mul_f32 v[2:3], v[2:3], v[0:1] op_sel_hi:[1,0]
	v_cvt_pk_bf16_f32 v6, v14, v15
	v_cvt_pk_bf16_f32 v7, v10, v11
	v_add_co_u32_e32 v10, vcc, s2, v130
	s_nop 1
	v_addc_co_u32_e32 v11, vcc, 0, v131, vcc
	global_store_dwordx4 v[10:11], v[4:7], off
	v_cvt_pk_bf16_f32 v2, v2, v3
	s_nop 1
	v_pk_mul_f32 v[4:5], v[8:9], v[0:1] op_sel_hi:[1,0]
	v_pk_mul_f32 v[6:7], v[16:17], v[0:1] op_sel_hi:[1,0]
	v_pk_mul_f32 v[8:9], v[12:13], v[0:1] op_sel_hi:[1,0]
	v_cvt_pk_bf16_f32 v3, v4, v5
	s_nop 0
	v_cvt_pk_bf16_f32 v4, v8, v9
	v_cvt_pk_bf16_f32 v5, v6, v7
	global_store_dwordx4 v[10:11], v[2:5], off offset:256
	s_waitcnt vmcnt(0)
	s_barrier

.LBB0_1723:
	s_or_b64 exec, exec, s[22:23]
	s_waitcnt vmcnt(0)
	v_readfirstlane_b32 s2, v2
	s_nop 1
	v_add_u32_e32 v0, s2, v0
	v_and_b32_e32 v2, -4, v0
	v_and_b32_e32 v0, 3, v0
	v_cmp_eq_u32_e64 s[2:3], 3, v0
	v_add_u32_e32 v2, 4, v2
	s_and_b64 s[2:3], s[2:3], exec

.LBB0_1810:
	s_add_u32 s16, s8, 0x6400000
	s_addc_u32 s17, s9, 0
	s_add_u32 s12, s8, 0x6300000
	s_addc_u32 s13, s9, 0
	s_add_u32 s14, s8, 0xfa00000
	s_addc_u32 s15, s9, 0
	s_add_i32 s5, s25, s49
	s_lshl_b32 s4, s61, 5
	s_nop 0
	v_add_u32_e32 v166, s5, v159
	s_lshl_b32 s5, s60, 8
	s_or_b32 s4, s5, s4
	v_lshl_add_u32 v168, v158, 3, s4
	v_ashrrev_i32_e32 v169, 31, v168
	v_lshlrev_b64 v[180:181], 1, v[168:169]
	v_ashrrev_i32_e32 v167, 31, v166
	v_lshl_add_u64 v[184:185], s[16:17], 0, v[180:181]
	v_lshlrev_b64 v[182:183], 11, v[166:167]
	v_lshl_add_u64 v[122:123], v[184:185], 0, v[182:183]
	global_load_dwordx4 v[176:179], v[122:123], off sc1
	global_load_dwordx4 v[154:157], v[122:123], off offset:256 sc1
	v_add_u32_e32 v164, 16, v166
	v_ashrrev_i32_e32 v165, 31, v164
	v_add_u32_e32 v162, 32, v166
	v_lshlrev_b64 v[172:173], 11, v[164:165]
	v_ashrrev_i32_e32 v163, 31, v162
	v_add_u32_e32 v160, 48, v166
	v_lshl_add_u64 v[122:123], v[184:185], 0, v[172:173]
	v_lshlrev_b64 v[170:171], 11, v[162:163]
	v_ashrrev_i32_e32 v161, 31, v160
	global_load_dwordx4 v[150:153], v[122:123], off sc1
	global_load_dwordx4 v[146:149], v[122:123], off offset:256 sc1
	v_lshl_add_u64 v[122:123], v[184:185], 0, v[170:171]
	v_lshlrev_b64 v[174:175], 11, v[160:161]
	global_load_dwordx4 v[142:145], v[122:123], off sc1
	global_load_dwordx4 v[130:133], v[122:123], off offset:256 sc1
	v_lshl_add_u64 v[122:123], v[184:185], 0, v[174:175]
	global_load_dwordx4 v[126:129], v[122:123], off sc1
	s_nop 0
	global_load_dwordx4 v[122:125], v[122:123], off offset:256 sc1
	v_cmp_eq_u32_e64 s[4:5], 0, v158
	s_waitcnt vmcnt(0)
	v_lshlrev_b32_e32 v186, 16, v176
	v_and_b32_e32 v187, 0xffff0000, v176
	v_lshlrev_b32_e32 v176, 16, v177
	v_and_b32_e32 v177, 0xffff0000, v177
	v_pk_add_f32 v[140:141], v[140:141], v[176:177]
	v_lshl_add_u64 v[176:177], s[16:17], 0, v[182:183]
	v_lshlrev_b32_e32 v188, 16, v178
	v_and_b32_e32 v189, 0xffff0000, v178
	v_lshlrev_b32_e32 v178, 16, v179
	v_and_b32_e32 v179, 0xffff0000, v179
	v_pk_add_f32 v[138:139], v[138:139], v[186:187]
	v_lshl_add_u64 v[180:181], v[176:177], 0, v[180:181]
	v_cvt_pk_bf16_f32 v176, v138, v139
	v_pk_add_f32 v[136:137], v[136:137], v[178:179]
	v_pk_add_f32 v[134:135], v[134:135], v[188:189]
	v_cvt_pk_bf16_f32 v177, v140, v141
	v_mul_f32_e32 v0, v139, v139
	v_cvt_pk_bf16_f32 v178, v134, v135
	v_cvt_pk_bf16_f32 v179, v136, v137
	global_store_dwordx4 v[180:181], v[176:179], off
	v_fmac_f32_e32 v0, v138, v138
	s_nop 0
	v_mul_f32_e32 v176, v141, v141
	v_fmac_f32_e32 v176, v140, v140
	v_add_f32_e32 v0, v0, v176
	v_mul_f32_e32 v176, v135, v135
	v_fmac_f32_e32 v176, v134, v134
	v_add_f32_e32 v0, v176, v0
	v_mul_f32_e32 v176, v137, v137
	v_fmac_f32_e32 v176, v136, v136
	v_add_f32_e32 v0, v176, v0
	v_max_f32_e64 v176, |v138|, |v139|
	v_max_f32_e64 v177, |v140|, |v141|
	v_max3_f32 v182, v176, 0, v177
	v_max_f32_e64 v176, |v136|, |v137|
	v_max3_f32 v183, |v134|, |v135|, v176
	v_lshlrev_b32_e32 v176, 16, v154
	v_and_b32_e32 v177, 0xffff0000, v154
	v_lshlrev_b32_e32 v154, 16, v155
	v_and_b32_e32 v155, 0xffff0000, v155
	v_lshlrev_b32_e32 v178, 16, v156
	v_and_b32_e32 v179, 0xffff0000, v156
	v_lshlrev_b32_e32 v156, 16, v157
	v_and_b32_e32 v157, 0xffff0000, v157
	v_pk_add_f32 v[120:121], v[120:121], v[154:155]
	v_pk_add_f32 v[118:119], v[118:119], v[176:177]
	v_pk_add_f32 v[116:117], v[116:117], v[156:157]
	v_cvt_pk_bf16_f32 v154, v118, v119
	v_cvt_pk_bf16_f32 v155, v120, v121
	v_pk_add_f32 v[114:115], v[114:115], v[178:179]
	v_lshlrev_b64 v[178:179], 6, v[166:167]
	v_cvt_pk_bf16_f32 v156, v114, v115
	v_cvt_pk_bf16_f32 v157, v116, v117
	global_store_dwordx4 v[180:181], v[154:157], off offset:256
	s_nop 1
	v_mul_f32_e32 v154, v119, v119
	v_mul_f32_e32 v155, v121, v121
	v_fmac_f32_e32 v154, v118, v118
	v_fmac_f32_e32 v155, v120, v120
	v_add_f32_e32 v154, v154, v155
	v_mul_f32_e32 v155, v115, v115
	v_fmac_f32_e32 v155, v114, v114
	v_add_f32_e32 v154, v155, v154
	v_mul_f32_e32 v155, v117, v117
	v_fmac_f32_e32 v155, v116, v116
	v_add_f32_e32 v154, v155, v154
	v_add_f32_e32 v0, v0, v154
	v_max_f32_e64 v154, |v118|, |v119|
	v_max_f32_e64 v156, |v116|, |v117|
	v_max3_f32 v154, v182, v183, v154
	v_max_f32_e64 v155, |v120|, |v121|
	v_max3_f32 v156, |v114|, |v115|, v156
	v_max3_f32 v155, v154, v155, v156
	ds_swizzle_b32 v156, v155 offset:swizzle(SWAP,16)
	ds_swizzle_b32 v154, v0 offset:swizzle(SWAP,16)
	s_waitcnt lgkmcnt(1)
	v_max_f32_e32 v156, v156, v156
	s_waitcnt lgkmcnt(0)
	v_add_f32_e32 v0, v0, v154
	v_max_f32_e32 v155, v155, v156
	v_mov_b32_e32 v154, v0
	v_mov_b32_e32 v156, v155
	s_nop 0
	v_permlane32_swap_b32_e32 v0, v154
	v_permlane32_swap_b32_e32 v155, v156
	s_and_saveexec_b64 s[22:23], s[4:5]
	s_cbranch_execz .LBB0_1812
	s_lshl_b32 s42, s60, 2
	v_max_f32_e32 v155, v155, v155
	v_max_f32_e32 v156, v156, v156
	s_ashr_i32 s43, s42, 31
	v_max_f32_e32 v156, v155, v156
	v_add_f32_e32 v0, v0, v154
	v_lshl_add_u64 v[154:155], s[12:13], 0, v[178:179]
	s_lshl_b64 s[42:43], s[42:43], 2
	v_lshl_add_u64 v[154:155], v[154:155], 0, s[42:43]
	s_lshl_b32 s26, s61, 2
	v_lshl_add_u64 v[154:155], v[154:155], 0, s[26:27]
	global_store_dword v[154:155], v0, off
	v_lshl_add_u64 v[154:155], s[14:15], 0, v[178:179]
	v_lshl_add_u64 v[154:155], v[154:155], 0, s[42:43]
	v_lshl_add_u64 v[154:155], v[154:155], 0, s[26:27]
	global_store_dword v[154:155], v156, off

.LBB0_1818:
	s_or_b64 exec, exec, s[22:23]
	v_add_u32_e32 v100, 0x80, v166
	v_ashrrev_i32_e32 v101, 31, v100
	v_lshlrev_b64 v[190:191], 11, v[100:101]
	v_lshl_add_u64 v[66:67], v[184:185], 0, v[190:191]
	global_load_dwordx4 v[196:199], v[66:67], off sc1
	global_load_dwordx4 v[90:93], v[66:67], off offset:256 sc1
	v_add_u32_e32 v98, 0x90, v166
	v_ashrrev_i32_e32 v99, 31, v98
	v_add_u32_e32 v96, 0xa0, v166
	v_lshlrev_b64 v[192:193], 11, v[98:99]
	v_ashrrev_i32_e32 v97, 31, v96
	v_add_u32_e32 v94, 0xb0, v166
	v_lshl_add_u64 v[66:67], v[184:185], 0, v[192:193]
	v_lshlrev_b64 v[194:195], 11, v[96:97]
	v_ashrrev_i32_e32 v95, 31, v94
	global_load_dwordx4 v[86:89], v[66:67], off sc1
	global_load_dwordx4 v[82:85], v[66:67], off offset:256 sc1
	v_lshl_add_u64 v[66:67], v[184:185], 0, v[194:195]
	v_lshlrev_b64 v[186:187], 11, v[94:95]
	global_load_dwordx4 v[78:81], v[66:67], off sc1
	global_load_dwordx4 v[74:77], v[66:67], off offset:256 sc1
	v_lshl_add_u64 v[66:67], v[184:185], 0, v[186:187]
	global_load_dwordx4 v[70:73], v[66:67], off sc1
	s_nop 0
	global_load_dwordx4 v[66:69], v[66:67], off offset:256 sc1
	s_waitcnt vmcnt(7)
	v_lshlrev_b32_e32 v184, 16, v196
	v_and_b32_e32 v185, 0xffff0000, v196
	v_lshlrev_b32_e32 v196, 16, v197
	v_and_b32_e32 v197, 0xffff0000, v197
	v_pk_add_f32 v[64:65], v[64:65], v[196:197]
	v_pk_add_f32 v[62:63], v[62:63], v[184:185]
	v_lshlrev_b32_e32 v200, 16, v198
	v_and_b32_e32 v201, 0xffff0000, v198
	v_lshl_add_u64 v[184:185], s[16:17], 0, v[190:191]
	v_mul_f32_e32 v0, v63, v63
	v_mul_f32_e32 v190, v65, v65
	v_pk_add_f32 v[58:59], v[58:59], v[200:201]
	v_fmac_f32_e32 v0, v62, v62
	v_fmac_f32_e32 v190, v64, v64
	v_lshlrev_b32_e32 v198, 16, v199
	v_and_b32_e32 v199, 0xffff0000, v199
	v_add_f32_e32 v0, v0, v190
	v_mul_f32_e32 v190, v59, v59
	v_pk_add_f32 v[60:61], v[60:61], v[198:199]
	v_fmac_f32_e32 v190, v58, v58
	v_add_f32_e32 v0, v190, v0
	v_mul_f32_e32 v190, v61, v61
	v_fmac_f32_e32 v190, v60, v60
	v_lshl_add_u64 v[184:185], v[168:169], 1, v[184:185]
	v_cvt_pk_bf16_f32 v196, v62, v63
	v_cvt_pk_bf16_f32 v197, v64, v65
	v_cvt_pk_bf16_f32 v198, v58, v59
	v_add_f32_e32 v0, v190, v0
	v_max_f32_e64 v190, |v62|, |v63|
	v_max_f32_e64 v191, |v64|, |v65|
	v_cvt_pk_bf16_f32 v199, v60, v61
	global_store_dwordx4 v[184:185], v[196:199], off
	s_nop 1
	v_max3_f32 v198, v190, 0, v191
	v_max_f32_e64 v190, |v60|, |v61|
	v_max3_f32 v199, |v58|, |v59|, v190
	s_waitcnt vmcnt(7)
	v_lshlrev_b32_e32 v190, 16, v90
	v_and_b32_e32 v191, 0xffff0000, v90
	v_lshlrev_b32_e32 v90, 16, v91
	v_and_b32_e32 v91, 0xffff0000, v91
	v_lshlrev_b32_e32 v196, 16, v92
	v_and_b32_e32 v197, 0xffff0000, v92
	v_lshlrev_b32_e32 v92, 16, v93
	v_and_b32_e32 v93, 0xffff0000, v93
	v_pk_add_f32 v[56:57], v[56:57], v[90:91]
	v_pk_add_f32 v[54:55], v[54:55], v[190:191]
	v_pk_add_f32 v[52:53], v[52:53], v[92:93]
	v_cvt_pk_bf16_f32 v90, v54, v55
	v_cvt_pk_bf16_f32 v91, v56, v57
	v_pk_add_f32 v[50:51], v[50:51], v[196:197]
	v_lshlrev_b64 v[190:191], 6, v[100:101]
	v_cvt_pk_bf16_f32 v92, v50, v51
	v_cvt_pk_bf16_f32 v93, v52, v53
	global_store_dwordx4 v[184:185], v[90:93], off offset:256
	s_nop 1
	v_mul_f32_e32 v90, v55, v55
	v_mul_f32_e32 v91, v57, v57
	v_fmac_f32_e32 v90, v54, v54
	v_fmac_f32_e32 v91, v56, v56
	v_add_f32_e32 v90, v90, v91
	v_mul_f32_e32 v91, v51, v51
	v_fmac_f32_e32 v91, v50, v50
	v_add_f32_e32 v90, v91, v90
	v_mul_f32_e32 v91, v53, v53
	v_fmac_f32_e32 v91, v52, v52
	v_add_f32_e32 v90, v91, v90
	v_add_f32_e32 v0, v0, v90
	v_max_f32_e64 v90, |v54|, |v55|
	v_max_f32_e64 v92, |v52|, |v53|
	v_max3_f32 v90, v198, v199, v90
	v_max_f32_e64 v91, |v56|, |v57|
	v_max3_f32 v92, |v50|, |v51|, v92
	v_max3_f32 v91, v90, v91, v92
	ds_swizzle_b32 v92, v91 offset:swizzle(SWAP,16)
	ds_swizzle_b32 v90, v0 offset:swizzle(SWAP,16)
	s_waitcnt lgkmcnt(1)
	v_max_f32_e32 v92, v92, v92
	s_waitcnt lgkmcnt(0)
	v_add_f32_e32 v0, v0, v90
	v_max_f32_e32 v91, v91, v92
	v_mov_b32_e32 v90, v0
	v_mov_b32_e32 v92, v91
	s_nop 0
	v_permlane32_swap_b32_e32 v0, v90
	v_permlane32_swap_b32_e32 v91, v92
	s_and_saveexec_b64 s[22:23], s[4:5]
	s_cbranch_execz .LBB0_1820
	s_lshl_b32 s42, s60, 2
	v_max_f32_e32 v91, v91, v91
	v_max_f32_e32 v92, v92, v92
	s_ashr_i32 s43, s42, 31
	v_max_f32_e32 v92, v91, v92
	v_add_f32_e32 v0, v0, v90
	v_lshl_add_u64 v[90:91], s[12:13], 0, v[190:191]
	s_lshl_b64 s[42:43], s[42:43], 2
	v_lshl_add_u64 v[90:91], v[90:91], 0, s[42:43]
	s_lshl_b32 s26, s61, 2
	v_lshl_add_u64 v[90:91], v[90:91], 0, s[26:27]
	global_store_dword v[90:91], v0, off
	v_lshl_add_u64 v[90:91], s[14:15], 0, v[190:191]
	v_lshl_add_u64 v[90:91], v[90:91], 0, s[42:43]
	v_lshl_add_u64 v[90:91], v[90:91], 0, s[26:27]
	global_store_dword v[90:91], v92, off

.LBB0_1829:
	s_or_b64 exec, exec, s[40:41]
	s_waitcnt vmcnt(0)
	v_readfirstlane_b32 s24, v2
	s_nop 1
	v_add_u32_e32 v0, s24, v0
	v_and_b32_e32 v2, 3, v0
	v_cmp_ne_u32_e32 vcc, 3, v2
	s_and_saveexec_b64 s[24:25], vcc
	s_cbranch_execz .LBB0_1843
	global_load_dword v2, v1, s[22:23] sc1
	v_bitop3_b32 v0, v0, -4, v0 bitop3:0xc
	s_waitcnt vmcnt(0)
	v_add_u32_e32 v2, v2, v0
	v_cmp_gt_i32_e32 vcc, 0, v2
	s_and_b64 exec, exec, vcc
	s_cbranch_execz .LBB0_1843
	s_add_u32 s6, s6, 0x4200
	s_addc_u32 s7, s7, 0
	s_mov_b32 s26, 1
	s_mov_b64 s[40:41], 0
	s_branch .LBB0_1833

.LBB0_1844:
	s_or_b64 exec, exec, s[16:17]
	v_ashrrev_i32_e32 v159, 31, v158
	v_lshlrev_b64 v[2:3], 4, v[158:159]
	v_lshl_add_u64 v[200:201], s[14:15], 0, v[2:3]
	s_waitcnt lgkmcnt(0)
	s_barrier
	v_lshl_add_u64 v[4:5], v[200:201], 0, v[178:179]
	v_lshl_add_u64 v[6:7], v[200:201], 0, v[180:181]
	global_load_dwordx4 v[30:33], v[4:5], off sc1
	global_load_dwordx4 v[26:29], v[6:7], off sc1
	v_lshl_add_u64 v[4:5], v[200:201], 0, v[182:183]
	v_lshl_add_u64 v[6:7], v[200:201], 0, v[188:189]
	global_load_dwordx4 v[22:25], v[4:5], off sc1
	global_load_dwordx4 v[18:21], v[6:7], off sc1
	s_or_b32 s6, s60, s61
	s_cmp_eq_u32 s6, 0
	s_cselect_b64 s[14:15], -1, 0
	s_cmp_lg_u32 s6, 0
	v_lshl_add_u64 v[198:199], s[12:13], 0, v[2:3]
	v_mov_b32_e32 v14, 0
	v_mov_b32_e32 v15, 0
	v_mov_b32_e32 v16, 0
	v_mov_b32_e32 v17, 0
	v_mov_b32_e32 v10, 0
	v_mov_b32_e32 v11, 0
	v_mov_b32_e32 v12, 0
	v_mov_b32_e32 v13, 0
	v_mov_b32_e32 v6, 0
	v_mov_b32_e32 v7, 0
	v_mov_b32_e32 v8, 0
	v_mov_b32_e32 v9, 0
	v_mov_b32_e32 v2, 0
	v_mov_b32_e32 v3, 0
	v_mov_b32_e32 v4, 0
	v_mov_b32_e32 v5, 0
	s_cbranch_scc1 .LBB0_1846
	v_lshl_add_u64 v[2:3], v[198:199], 0, v[178:179]
	v_lshl_add_u64 v[4:5], v[198:199], 0, v[180:181]
	global_load_dwordx4 v[14:17], v[2:3], off sc1
	global_load_dwordx4 v[10:13], v[4:5], off sc1
	v_lshl_add_u64 v[2:3], v[198:199], 0, v[182:183]
	v_lshl_add_u64 v[4:5], v[198:199], 0, v[188:189]
	global_load_dwordx4 v[6:9], v[2:3], off sc1
	s_nop 0
	global_load_dwordx4 v[2:5], v[4:5], off sc1

.LBB0_1889:
	s_lshl_b32 s6, s15, 8
	s_add_u32 s4, s8, 0x6400000
	s_addc_u32 s5, s9, 0
	s_add_u32 s2, s8, 0x6300000
	s_addc_u32 s3, s9, 0
	s_add_i32 s6, s6, s25
	s_lshl_b32 s7, s13, 5
	s_nop 0
	v_add_u32_e32 v224, s6, v124
	s_lshl_b32 s6, s12, 8
	s_or_b32 s6, s6, s7
	v_lshl_add_u32 v194, v240, 3, s6
	v_ashrrev_i32_e32 v195, 31, v194
	v_ashrrev_i32_e32 v225, 31, v224
	v_lshlrev_b64 v[226:227], 1, v[194:195]
	v_lshl_add_u64 v[126:127], s[4:5], 0, v[226:227]
	v_lshlrev_b64 v[228:229], 11, v[224:225]
	v_lshl_add_u64 v[122:123], v[126:127], 0, v[228:229]
	global_load_dwordx4 v[190:193], v[122:123], off sc1
	global_load_dwordx4 v[186:189], v[122:123], off offset:256 sc1
	v_add_u32_e32 v220, 16, v224
	v_ashrrev_i32_e32 v221, 31, v220
	v_add_u32_e32 v216, 32, v224
	v_lshlrev_b64 v[222:223], 11, v[220:221]
	v_ashrrev_i32_e32 v217, 31, v216
	v_add_u32_e32 v212, 48, v224
	v_lshl_add_u64 v[122:123], v[126:127], 0, v[222:223]
	v_lshlrev_b64 v[218:219], 11, v[216:217]
	v_ashrrev_i32_e32 v213, 31, v212
	v_add_u32_e32 v208, 0x80, v224
	global_load_dwordx4 v[182:185], v[122:123], off sc1
	global_load_dwordx4 v[178:181], v[122:123], off offset:256 sc1
	v_lshl_add_u64 v[122:123], v[126:127], 0, v[218:219]
	v_lshlrev_b64 v[214:215], 11, v[212:213]
	v_ashrrev_i32_e32 v209, 31, v208
	v_add_u32_e32 v204, 0x90, v224
	global_load_dwordx4 v[174:177], v[122:123], off sc1
	global_load_dwordx4 v[170:173], v[122:123], off offset:256 sc1
	v_lshl_add_u64 v[122:123], v[126:127], 0, v[214:215]
	v_lshlrev_b64 v[210:211], 11, v[208:209]
	v_ashrrev_i32_e32 v205, 31, v204
	v_add_u32_e32 v198, 0xa0, v224
	v_add_u32_e32 v196, 0xb0, v224
	global_load_dwordx4 v[166:169], v[122:123], off sc1
	global_load_dwordx4 v[162:165], v[122:123], off offset:256 sc1
	v_lshl_add_u64 v[122:123], v[126:127], 0, v[210:211]
	v_lshlrev_b64 v[206:207], 11, v[204:205]
	v_ashrrev_i32_e32 v199, 31, v198
	v_ashrrev_i32_e32 v197, 31, v196
	global_load_dwordx4 v[158:161], v[122:123], off sc1
	global_load_dwordx4 v[146:149], v[122:123], off offset:256 sc1
	v_lshl_add_u64 v[122:123], v[126:127], 0, v[206:207]
	v_lshlrev_b64 v[202:203], 11, v[198:199]
	v_lshlrev_b64 v[200:201], 11, v[196:197]
	global_load_dwordx4 v[142:145], v[122:123], off sc1
	global_load_dwordx4 v[138:141], v[122:123], off offset:256 sc1
	v_lshl_add_u64 v[122:123], v[126:127], 0, v[202:203]
	v_lshl_add_u64 v[126:127], v[126:127], 0, v[200:201]
	global_load_dwordx4 v[130:133], v[122:123], off sc1
	s_nop 0
	global_load_dwordx4 v[122:125], v[122:123], off offset:256 sc1
	s_nop 0
	global_load_dwordx4 v[134:137], v[126:127], off sc1
	s_nop 0
	global_load_dwordx4 v[126:129], v[126:127], off offset:256 sc1
	v_cmp_eq_u32_e32 vcc, 0, v240
	s_waitcnt vmcnt(0)
	v_lshlrev_b32_e32 v232, 16, v190
	v_and_b32_e32 v233, 0xffff0000, v190
	v_lshlrev_b32_e32 v190, 16, v191
	v_and_b32_e32 v191, 0xffff0000, v191
	v_lshlrev_b32_e32 v234, 16, v192
	v_and_b32_e32 v235, 0xffff0000, v192
	v_lshlrev_b32_e32 v192, 16, v193
	v_and_b32_e32 v193, 0xffff0000, v193
	v_pk_add_f32 v[156:157], v[156:157], v[190:191]
	v_pk_add_f32 v[190:191], v[152:153], v[192:193]
	v_pk_add_f32 v[192:193], v[150:151], v[234:235]
	v_lshl_add_u64 v[150:151], s[4:5], 0, v[228:229]
	v_pk_add_f32 v[154:155], v[154:155], v[232:233]
	v_lshl_add_u64 v[226:227], v[150:151], 0, v[226:227]
	v_cvt_pk_bf16_f32 v150, v154, v155
	v_cvt_pk_bf16_f32 v151, v156, v157
	v_cvt_pk_bf16_f32 v152, v192, v193
	v_cvt_pk_bf16_f32 v153, v190, v191
	global_store_dwordx4 v[226:227], v[150:153], off
	v_mul_f32_e32 v0, v155, v155
	v_fmac_f32_e32 v0, v154, v154
	v_mul_f32_e32 v150, v157, v157
	v_fmac_f32_e32 v150, v156, v156
	v_add_f32_e32 v0, v0, v150
	v_mul_f32_e32 v150, v193, v193
	v_fmac_f32_e32 v150, v192, v192
	v_add_f32_e32 v0, v150, v0
	v_mul_f32_e32 v150, v191, v191
	v_fmac_f32_e32 v150, v190, v190
	v_add_f32_e32 v0, v150, v0
	v_lshlrev_b32_e32 v150, 16, v186
	v_and_b32_e32 v151, 0xffff0000, v186
	v_lshlrev_b32_e32 v152, 16, v187
	v_and_b32_e32 v153, 0xffff0000, v187
	v_lshlrev_b32_e32 v154, 16, v188
	v_and_b32_e32 v155, 0xffff0000, v188
	v_lshlrev_b32_e32 v156, 16, v189
	v_and_b32_e32 v157, 0xffff0000, v189
	v_pk_add_f32 v[120:121], v[120:121], v[152:153]
	v_pk_add_f32 v[118:119], v[118:119], v[150:151]
	v_pk_add_f32 v[152:153], v[114:115], v[154:155]
	v_cvt_pk_bf16_f32 v114, v118, v119
	v_cvt_pk_bf16_f32 v115, v120, v121
	v_pk_add_f32 v[150:151], v[116:117], v[156:157]
	v_cvt_pk_bf16_f32 v116, v152, v153
	s_nop 0
	v_cvt_pk_bf16_f32 v117, v150, v151
	global_store_dwordx4 v[226:227], v[114:117], off offset:256
	s_nop 1
	v_mul_f32_e32 v114, v119, v119
	v_mul_f32_e32 v115, v121, v121
	v_fmac_f32_e32 v114, v118, v118
	v_fmac_f32_e32 v115, v120, v120
	v_add_f32_e32 v114, v114, v115
	v_mul_f32_e32 v115, v153, v153
	v_fmac_f32_e32 v115, v152, v152
	v_add_f32_e32 v114, v115, v114
	v_mul_f32_e32 v115, v151, v151
	v_fmac_f32_e32 v115, v150, v150
	v_add_f32_e32 v114, v115, v114
	v_add_f32_e32 v0, v0, v114
	ds_swizzle_b32 v114, v0 offset:swizzle(SWAP,16)
	s_waitcnt lgkmcnt(0)
	v_add_f32_e32 v0, v0, v114
	v_mov_b32_e32 v114, v0
	s_nop 1
	v_permlane32_swap_b32_e32 v0, v114
	s_and_saveexec_b64 s[6:7], vcc
	s_cbranch_execz .LBB0_1891
	v_add_f32_e32 v0, v0, v114
	v_lshlrev_b64 v[114:115], 6, v[224:225]
	v_lshl_add_u64 v[114:115], s[2:3], 0, v[114:115]
	s_lshl_b32 s26, s12, 4
	v_lshl_add_u64 v[114:115], v[114:115], 0, s[26:27]
	s_lshl_b32 s26, s13, 2
	v_lshl_add_u64 v[114:115], v[114:115], 0, s[26:27]
	global_store_dword v[114:115], v0, off

.LBB0_1911:
	s_or_b64 exec, exec, s[10:11]
	s_waitcnt vmcnt(0)
	v_readfirstlane_b32 s6, v2
	s_nop 1
	v_add_u32_e32 v0, s6, v0
	v_and_b32_e32 v2, 3, v0
	v_cmp_ne_u32_e32 vcc, 3, v2
	s_and_saveexec_b64 s[6:7], vcc
	s_cbranch_execz .LBB0_1925
	global_load_dword v2, v1, s[4:5] sc1
	v_bitop3_b32 v0, v0, -4, v0 bitop3:0xc
	s_waitcnt vmcnt(0)
	v_add_u32_e32 v2, v2, v0
	v_cmp_gt_i32_e32 vcc, 0, v2
	s_and_b64 exec, exec, vcc
	s_cbranch_execz .LBB0_1925
	s_add_u32 s8, s8, 0x4200
	s_addc_u32 s9, s9, 0
	s_mov_b32 s24, 1
	s_mov_b64 s[10:11], 0
	s_branch .LBB0_1915

.LBB0_2129:
	s_load_dwordx2 s[2:3], s[0:1], 0xd0
	s_mov_b32 s4, -1
	s_waitcnt lgkmcnt(0)
	s_waitcnt vmcnt(0)
	v_mov_b32_e32 v17, 0
	v_mbcnt_lo_u32_b32 v0, s4, 0
	v_mbcnt_hi_u32_b32 v0, s4, v0
	v_lshl_or_b32 v0, s33, 6, v0
	s_mov_b32 s4, 0x22174
	s_add_i32 s4, s4, 0
	v_mov_b32_e32 v1, s4
	ds_read_b32 v1, v1
	v_readfirstlane_b32 s4, v0
	s_ashr_i32 s4, s4, 3
	s_and_b32 s8, s4, -8
	s_mov_b32 s4, 25
	s_waitcnt lgkmcnt(0)
	v_readfirstlane_b32 s6, v1
	s_ashr_i32 s5, s4, 31
	s_and_b32 s7, s6, 0xffffffc0
	s_lshl_b64 s[4:5], s[4:5], 3
	s_add_u32 s0, s0, s4
	s_addc_u32 s1, s1, s5
	s_load_dwordx2 s[0:1], s[0:1], 0x0
	v_and_b32_e32 v20, 63, v0
	v_lshlrev_b32_e32 v16, 4, v20
	s_waitcnt lgkmcnt(0)
	global_load_dwordx4 v[0:3], v16, s[0:1] sc1
	global_load_dwordx4 v[4:7], v16, s[0:1] offset:1024 sc1
	global_load_dwordx4 v[8:11], v16, s[0:1] offset:2048 sc1
	global_load_dwordx4 v[12:15], v16, s[0:1] offset:3072 sc1
	s_and_b32 s0, s6, 7
	s_lshl_b32 s1, s6, 5
	s_lshl_b32 s0, s0, 11
	s_and_b32 s1, s1, 0x700
	s_or_b32 s0, s0, s1
	s_add_i32 s0, s0, s7
	s_add_i32 s0, s0, s8
	s_ashr_i32 s1, s0, 31
	s_lshl_b64 s[4:5], s[0:1], 12
	s_add_u32 s2, s2, s4
	s_addc_u32 s3, s3, s5
	v_lshl_add_u64 v[18:19], s[2:3], 0, v[16:17]
	s_lshl_b64 s[2:3], s[0:1], 11
	v_lshl_or_b32 v20, v20, 3, s2
	v_mov_b32_e32 v21, s3
	s_lshl_b64 s[0:1], s[0:1], 6
	s_mov_b64 s[2:3], 0
	v_mov_b32_e32 v16, 0x6300000
	v_mov_b32_e32 v22, 0x358637bd
	s_mov_b32 s8, 0x6400000
	s_movk_i32 s9, 0x1000
	s_mov_b64 s[4:5], 0x1000
.LBB0_2130:
	s_add_u32 s6, s20, s0
	v_lshl_add_u64 v[24:25], s[20:21], 0, v[20:21]
	s_addc_u32 s7, s21, s1
	v_add_co_u32_e32 v42, vcc, s8, v24
	s_add_u32 s10, s6, 0x6300000
	s_nop 0
	v_addc_co_u32_e32 v43, vcc, 0, v25, vcc
	global_load_dwordx4 v[24:27], v16, s[6:7] sc1
	s_addc_u32 s11, s7, 0
	global_load_dwordx4 v[28:31], v17, s[10:11] offset:48 sc1
	global_load_dwordx4 v[32:35], v17, s[10:11] offset:16 sc1
	global_load_dwordx4 v[36:39], v17, s[10:11] offset:32 sc1
	global_load_dwordx2 v[44:45], v[42:43], off sc1
	v_lshl_add_u64 v[40:41], v[18:19], 0, s[2:3]
	s_add_u32 s10, s6, 0x6300040
	s_addc_u32 s11, s7, 0
	s_add_u32 s2, s2, 0x2000
	s_addc_u32 s3, s3, 0
	s_add_u32 s0, s0, 0x80
	s_addc_u32 s1, s1, 0
	v_lshl_add_u64 v[20:21], v[20:21], 0, s[4:5]
	s_cmpk_lg_u32 s2, 0x8000
	s_waitcnt vmcnt(4)
	v_mov_b32_e32 v46, v24
	v_mov_b32_e32 v24, v26
	s_waitcnt vmcnt(1)
	v_mov_b32_e32 v47, v36
	v_mov_b32_e32 v36, v25
	v_mov_b32_e32 v25, v38
	v_mov_b32_e32 v38, v27
	v_mov_b32_e32 v26, v32
	v_mov_b32_e32 v27, v28
	v_mov_b32_e32 v28, v33
	v_mov_b32_e32 v32, v34
	v_mov_b32_e32 v33, v30
	v_mov_b32_e32 v30, v35
	v_pk_add_f32 v[34:35], v[46:47], v[36:37]
	v_pk_add_f32 v[24:25], v[24:25], v[38:39]
	v_pk_add_f32 v[26:27], v[26:27], v[28:29]
	v_pk_add_f32 v[28:29], v[32:33], v[30:31]
	v_pk_add_f32 v[24:25], v[34:35], v[24:25]
	v_pk_add_f32 v[26:27], v[26:27], v[28:29]
	s_waitcnt vmcnt(0)
	v_lshlrev_b32_e32 v48, 16, v44
	v_pk_add_f32 v[24:25], v[24:25], v[26:27]
	v_and_b32_e32 v49, 0xffff0000, v44
	v_add_f32_e32 v23, v24, v25
	v_fmamk_f32 v23, v23, 0x3a800000, v22
	v_rsq_f32_e32 v28, v23
	v_lshlrev_b32_e32 v44, 16, v45
	v_and_b32_e32 v45, 0xffff0000, v45
	v_pk_mul_f32 v[24:25], v[28:29], v[48:49] op_sel_hi:[0,1]
	v_pk_mul_f32 v[26:27], v[28:29], v[44:45] op_sel_hi:[0,1]
	v_pk_mul_f32 v[26:27], v[2:3], v[26:27]
	v_pk_mul_f32 v[24:25], v[0:1], v[24:25]
	global_store_dwordx4 v[40:41], v[24:27], off nt
	global_load_dwordx2 v[24:25], v[42:43], off offset:512 sc1
	s_waitcnt vmcnt(0)
	v_lshlrev_b32_e32 v26, 16, v24
	v_and_b32_e32 v27, 0xffff0000, v24
	v_lshlrev_b32_e32 v24, 16, v25
	v_and_b32_e32 v25, 0xffff0000, v25
	v_pk_mul_f32 v[30:31], v[28:29], v[26:27] op_sel_hi:[0,1]
	v_pk_mul_f32 v[24:25], v[28:29], v[24:25] op_sel_hi:[0,1]
	v_pk_mul_f32 v[26:27], v[6:7], v[24:25]
	v_pk_mul_f32 v[24:25], v[4:5], v[30:31]
	global_store_dwordx4 v[40:41], v[24:27], off offset:1024 nt
	global_load_dwordx2 v[24:25], v[42:43], off offset:1024 sc1
	s_waitcnt vmcnt(0)
	v_lshlrev_b32_e32 v26, 16, v24
	v_and_b32_e32 v27, 0xffff0000, v24
	v_lshlrev_b32_e32 v24, 16, v25
	v_and_b32_e32 v25, 0xffff0000, v25
	v_pk_mul_f32 v[30:31], v[28:29], v[26:27] op_sel_hi:[0,1]
	v_pk_mul_f32 v[24:25], v[28:29], v[24:25] op_sel_hi:[0,1]
	v_pk_mul_f32 v[26:27], v[10:11], v[24:25]
	v_pk_mul_f32 v[24:25], v[8:9], v[30:31]
	global_store_dwordx4 v[40:41], v[24:27], off offset:2048 nt
	global_load_dwordx2 v[24:25], v[42:43], off offset:1536 sc1
	s_waitcnt vmcnt(0)
	v_lshlrev_b32_e32 v26, 16, v24
	v_and_b32_e32 v27, 0xffff0000, v24
	v_lshlrev_b32_e32 v24, 16, v25
	v_and_b32_e32 v25, 0xffff0000, v25
	v_pk_mul_f32 v[30:31], v[28:29], v[26:27] op_sel_hi:[0,1]
	v_pk_mul_f32 v[24:25], v[28:29], v[24:25] op_sel_hi:[0,1]
	v_pk_mul_f32 v[26:27], v[14:15], v[24:25]
	v_pk_mul_f32 v[24:25], v[12:13], v[30:31]
	global_store_dwordx4 v[40:41], v[24:27], off offset:3072 nt
	global_load_dwordx4 v[24:27], v16, s[6:7] offset:64 sc1
	s_nop 0
	global_load_dwordx4 v[28:31], v17, s[10:11] offset:32 sc1
	global_load_dwordx4 v[32:35], v17, s[10:11] offset:16 sc1
	global_load_dwordx4 v[36:39], v17, s[10:11] offset:48 sc1
	global_load_dwordx2 v[44:45], v[42:43], off offset:2048 sc1
	v_add_co_u32_e32 v40, vcc, s9, v40
	s_waitcnt vmcnt(4)
	v_mov_b32_e32 v46, v24
	s_waitcnt vmcnt(3)
	v_mov_b32_e32 v47, v28
	v_mov_b32_e32 v28, v25
	v_mov_b32_e32 v24, v26
	v_mov_b32_e32 v25, v30
	v_mov_b32_e32 v30, v27
	s_waitcnt vmcnt(2)
	v_mov_b32_e32 v26, v32
	s_waitcnt vmcnt(1)
	v_mov_b32_e32 v27, v36
	v_mov_b32_e32 v36, v33
	v_mov_b32_e32 v32, v34
	v_mov_b32_e32 v33, v38
	v_mov_b32_e32 v38, v35
	v_pk_add_f32 v[28:29], v[46:47], v[28:29]
	v_pk_add_f32 v[24:25], v[24:25], v[30:31]
	v_pk_add_f32 v[26:27], v[26:27], v[36:37]
	v_pk_add_f32 v[30:31], v[32:33], v[38:39]
	v_pk_add_f32 v[24:25], v[28:29], v[24:25]
	v_pk_add_f32 v[26:27], v[26:27], v[30:31]
	s_waitcnt vmcnt(0)
	v_lshlrev_b32_e32 v34, 16, v44
	v_pk_add_f32 v[24:25], v[24:25], v[26:27]
	v_and_b32_e32 v35, 0xffff0000, v44
	v_add_f32_e32 v23, v24, v25
	v_fmamk_f32 v23, v23, 0x3a800000, v22
	v_rsq_f32_e32 v28, v23
	v_lshlrev_b32_e32 v44, 16, v45
	v_and_b32_e32 v45, 0xffff0000, v45
	v_addc_co_u32_e32 v41, vcc, 0, v41, vcc
	v_pk_mul_f32 v[24:25], v[28:29], v[34:35] op_sel_hi:[0,1]
	v_pk_mul_f32 v[26:27], v[28:29], v[44:45] op_sel_hi:[0,1]
	v_pk_mul_f32 v[26:27], v[2:3], v[26:27]
	v_pk_mul_f32 v[24:25], v[0:1], v[24:25]
	global_store_dwordx4 v[40:41], v[24:27], off nt
	global_load_dwordx2 v[24:25], v[42:43], off offset:2560 sc1
	s_waitcnt vmcnt(0)
	v_lshlrev_b32_e32 v26, 16, v24
	v_and_b32_e32 v27, 0xffff0000, v24
	v_lshlrev_b32_e32 v24, 16, v25
	v_and_b32_e32 v25, 0xffff0000, v25
	v_pk_mul_f32 v[30:31], v[28:29], v[26:27] op_sel_hi:[0,1]
	v_pk_mul_f32 v[24:25], v[28:29], v[24:25] op_sel_hi:[0,1]
	v_pk_mul_f32 v[26:27], v[6:7], v[24:25]
	v_pk_mul_f32 v[24:25], v[4:5], v[30:31]
	global_store_dwordx4 v[40:41], v[24:27], off offset:1024 nt
	global_load_dwordx2 v[24:25], v[42:43], off offset:3072 sc1
	s_waitcnt vmcnt(0)
	v_lshlrev_b32_e32 v26, 16, v24
	v_and_b32_e32 v27, 0xffff0000, v24
	v_lshlrev_b32_e32 v24, 16, v25
	v_and_b32_e32 v25, 0xffff0000, v25
	v_pk_mul_f32 v[30:31], v[28:29], v[26:27] op_sel_hi:[0,1]
	v_pk_mul_f32 v[24:25], v[28:29], v[24:25] op_sel_hi:[0,1]
	v_pk_mul_f32 v[26:27], v[10:11], v[24:25]
	v_pk_mul_f32 v[24:25], v[8:9], v[30:31]
	global_store_dwordx4 v[40:41], v[24:27], off offset:2048 nt
	global_load_dwordx2 v[24:25], v[42:43], off offset:3584 sc1
	s_waitcnt vmcnt(0)
	v_lshlrev_b32_e32 v26, 16, v24
	v_and_b32_e32 v27, 0xffff0000, v24
	v_lshlrev_b32_e32 v24, 16, v25
	v_and_b32_e32 v25, 0xffff0000, v25
	v_pk_mul_f32 v[30:31], v[28:29], v[26:27] op_sel_hi:[0,1]
	v_pk_mul_f32 v[24:25], v[28:29], v[24:25] op_sel_hi:[0,1]
	v_pk_mul_f32 v[26:27], v[14:15], v[24:25]
	v_pk_mul_f32 v[24:25], v[12:13], v[30:31]
	global_store_dwordx4 v[40:41], v[24:27], off offset:3072 nt
	s_cbranch_scc1 .LBB0_2130
